# v83 + write-through (sc1) on all bulk dwordx4 result stores except G1 in-loop split epilogue: move L2 write-back out of the grid barriers
# baseline (speedup 1.0000x reference)
; #define LAS __attribute__((address_space(3)))
; __device__ __forceinline__ unsigned pk2(float lo, float hi) { return pg8::cvt_pk_bf16(lo, hi); }
; __device__ __forceinline__ void item_store(const TItem& t, LAS float* scr, int lane) {
;     ...
;     for (int j = 0; j < 8; ++j) { const int n = nn + 8 * j; const LAS float* s = scr + (8 * c) * 65 + n;
;         v4u o; o.x = pk2(s[0 * 65], s[1 * 65]); o.y = pk2(s[2 * 65], s[3 * 65]); o.z = pk2(s[4 * 65], s[5 * 65]); o.w = pk2(s[6 * 65], s[7 * 65]);
;         *(v4u*)(t.WT + (size_t)rowmap(t.mode, n0 + n) * t.K + k0 + 8 * c) = o; }
.LBB0_48:
	s_waitcnt lgkmcnt(3)
	v_cvt_pk_bf16_f32 v4, v4, v5
	s_waitcnt lgkmcnt(2)
	v_cvt_pk_bf16_f32 v5, v6, v7
	s_waitcnt lgkmcnt(1)
	v_cvt_pk_bf16_f32 v6, v8, v9
	v_mad_u64_u32 v[8:9], s[12:13], v94, s16, 0
	s_waitcnt lgkmcnt(0)
	v_cvt_pk_bf16_f32 v7, v10, v11
	v_ashrrev_i32_e32 v1, 31, v94
	v_mov_b32_e32 v10, v9
	v_mad_u64_u32 v[10:11], s[12:13], v1, s16, v[10:11]
	v_mov_b32_e32 v9, v10
	v_lshl_add_u64 v[8:9], v[8:9], 1, s[0:1]
	v_lshl_add_u64 v[8:9], s[8:9], 1, v[8:9]
	v_mov_b32_e32 v1, v3
	v_lshl_add_u64 v[8:9], v[8:9], 0, v[0:1]
	global_store_dwordx4 v[8:9], v[4:7], off sc1
	s_waitcnt lgkmcnt(0)
	s_andn2_b64 vcc, exec, s[28:29]
	s_mov_b32 s24, s25
	s_mov_b32 s17, s27
	s_mov_b32 s8, s6
	s_mov_b32 s16, s26
	s_mov_b64 s[0:1], s[30:31]
	s_cbranch_vccz .LBB0_148

; #define LAS __attribute__((address_space(3)))
; __device__ __forceinline__ unsigned pk2(float lo, float hi) { return pg8::cvt_pk_bf16(lo, hi); }
; __device__ __forceinline__ int rowmap(int mode, int n) {
;     if (mode == 1) return n < 10240 ? n : (n < 10304 ? n + (PC_DT - 10240) : n - 64);
;     if (mode == 2) { const int isup = n >= DFF ? 1 : 0; const int f = n - isup * DFF;
;         return 256 * (f >> 7) + 128 * ((f >> 2) & 1) + 32 * ((f >> 5) & 3) + 16 * isup + 4 * ((f >> 3) & 3) + (f & 3); }
; __device__ __forceinline__ void item_store(const TItem& t, LAS float* scr, int lane) {
;     ...
;     for (int j = 0; j < 8; ++j) { const int n = nn + 8 * j; const LAS float* s = scr + (8 * c) * 65 + n;
;         v4u o; o.x = pk2(s[0 * 65], s[1 * 65]); o.y = pk2(s[2 * 65], s[3 * 65]); o.z = pk2(s[4 * 65], s[5 * 65]); o.w = pk2(s[6 * 65], s[7 * 65]);
;         *(v4u*)(t.WT + (size_t)rowmap(t.mode, n0 + n) * t.K + k0 + 8 * c) = o; }
.LBB0_92:
	s_lshl_b32 s8, s12, 6
	s_waitcnt lgkmcnt(3)
	v_cvt_pk_bf16_f32 v4, v4, v5
	s_waitcnt lgkmcnt(2)
	v_cvt_pk_bf16_f32 v5, v6, v7
	s_waitcnt lgkmcnt(1)
	v_cvt_pk_bf16_f32 v6, v8, v9
	v_mad_u64_u32 v[8:9], s[12:13], v95, s16, 0
	s_waitcnt lgkmcnt(0)
	v_cvt_pk_bf16_f32 v7, v10, v11
	v_ashrrev_i32_e32 v1, 31, v95
	v_mov_b32_e32 v10, v9
	v_mad_u64_u32 v[10:11], s[12:13], v1, s16, v[10:11]
	v_mov_b32_e32 v9, v10
	s_ashr_i32 s9, s8, 31
	v_lshl_add_u64 v[8:9], v[8:9], 1, s[0:1]
	v_lshl_add_u64 v[8:9], s[8:9], 1, v[8:9]
	v_mov_b32_e32 v1, v3
	v_lshl_add_u64 v[8:9], v[8:9], 0, v[0:1]
	global_store_dwordx4 v[8:9], v[4:7], off sc1
	ds_read2_b32 v[4:5], v16 offset0:8 offset1:73
	ds_read2_b32 v[6:7], v16 offset0:138 offset1:203
	ds_read2_b32 v[8:9], v94 offset0:12 offset1:77
	ds_read2_b32 v[10:11], v94 offset0:142 offset1:207
	v_or_b32_e32 v1, s24, v17
	s_cmp_lt_i32 s17, 2
	s_mov_b64 s[12:13], -1
	s_cbranch_scc1 .LBB0_96
	s_cmp_eq_u32 s17, 2
	v_mov_b32_e32 v95, v1
	s_cbranch_scc0 .LBB0_95
	v_cmp_lt_i32_e32 vcc, s18, v1
	s_nop 1
	v_cndmask_b32_e32 v95, 0, v28, vcc
	v_add_lshl_u32 v95, v95, v1, 1
	v_cndmask_b32_e64 v96, 0, 16, vcc
	v_and_b32_e32 v95, 0xffffff00, v95
	v_and_or_b32 v96, v1, s19, v96
	v_or3_b32 v95, v96, v95, v24

; #define LAS __attribute__((address_space(3)))
; __device__ __forceinline__ unsigned pk2(float lo, float hi) { return pg8::cvt_pk_bf16(lo, hi); }
; __device__ __forceinline__ int rowmap(int mode, int n) {
;     if (mode == 1) return n < 10240 ? n : (n < 10304 ? n + (PC_DT - 10240) : n - 64);
;     if (mode == 2) { const int isup = n >= DFF ? 1 : 0; const int f = n - isup * DFF;
;         return 256 * (f >> 7) + 128 * ((f >> 2) & 1) + 32 * ((f >> 5) & 3) + 16 * isup + 4 * ((f >> 3) & 3) + (f & 3); }
; __device__ __forceinline__ void item_store(const TItem& t, LAS float* scr, int lane) {
;     ...
;     for (int j = 0; j < 8; ++j) { const int n = nn + 8 * j; const LAS float* s = scr + (8 * c) * 65 + n;
;         v4u o; o.x = pk2(s[0 * 65], s[1 * 65]); o.y = pk2(s[2 * 65], s[3 * 65]); o.z = pk2(s[4 * 65], s[5 * 65]); o.w = pk2(s[6 * 65], s[7 * 65]);
;         *(v4u*)(t.WT + (size_t)rowmap(t.mode, n0 + n) * t.K + k0 + 8 * c) = o; }
.LBB0_100:
	s_waitcnt lgkmcnt(3)
	v_cvt_pk_bf16_f32 v4, v4, v5
	s_waitcnt lgkmcnt(2)
	v_cvt_pk_bf16_f32 v5, v6, v7
	s_waitcnt lgkmcnt(1)
	v_cvt_pk_bf16_f32 v6, v8, v9
	v_mad_u64_u32 v[8:9], s[12:13], v95, s16, 0
	s_waitcnt lgkmcnt(0)
	v_cvt_pk_bf16_f32 v7, v10, v11
	v_ashrrev_i32_e32 v1, 31, v95
	v_mov_b32_e32 v10, v9
	v_mad_u64_u32 v[10:11], s[12:13], v1, s16, v[10:11]
	v_mov_b32_e32 v9, v10
	v_lshl_add_u64 v[8:9], v[8:9], 1, s[0:1]
	v_lshl_add_u64 v[8:9], s[8:9], 1, v[8:9]
	v_mov_b32_e32 v1, v3
	v_lshl_add_u64 v[8:9], v[8:9], 0, v[0:1]
	global_store_dwordx4 v[8:9], v[4:7], off sc1
	ds_read2_b32 v[4:5], v16 offset0:16 offset1:81
	ds_read2_b32 v[6:7], v16 offset0:146 offset1:211
	ds_read2_b32 v[8:9], v94 offset0:20 offset1:85
	ds_read2_b32 v[10:11], v94 offset0:150 offset1:215
	v_or_b32_e32 v1, s24, v18
	s_cmp_lt_i32 s17, 2
	s_mov_b64 s[12:13], -1
	s_cbranch_scc1 .LBB0_104
	s_cmp_eq_u32 s17, 2
	v_mov_b32_e32 v95, v1
	s_cbranch_scc0 .LBB0_103
	v_cmp_lt_i32_e32 vcc, s18, v1
	s_nop 1
	v_cndmask_b32_e32 v95, 0, v28, vcc
	v_add_lshl_u32 v95, v95, v1, 1
	v_cndmask_b32_e64 v96, 0, 16, vcc
	v_and_b32_e32 v95, 0xffffff00, v95
	v_and_or_b32 v96, v1, s19, v96
	v_or3_b32 v95, v96, v95, v25

; #define LAS __attribute__((address_space(3)))
; __device__ __forceinline__ unsigned pk2(float lo, float hi) { return pg8::cvt_pk_bf16(lo, hi); }
; __device__ __forceinline__ int rowmap(int mode, int n) {
;     if (mode == 1) return n < 10240 ? n : (n < 10304 ? n + (PC_DT - 10240) : n - 64);
;     if (mode == 2) { const int isup = n >= DFF ? 1 : 0; const int f = n - isup * DFF;
;         return 256 * (f >> 7) + 128 * ((f >> 2) & 1) + 32 * ((f >> 5) & 3) + 16 * isup + 4 * ((f >> 3) & 3) + (f & 3); }
;     return n;
; __device__ __forceinline__ void item_store(const TItem& t, LAS float* scr, int lane) {
;     const int nblk = t.N / 64, kb = t.item / nblk, nb = t.item % nblk, k0 = 64 * kb, n0 = 64 * nb;
;     const int c = lane & 7, nn = lane >> 3;
; #pragma unroll
;     for (int j = 0; j < 8; ++j) { const int n = nn + 8 * j; const LAS float* s = scr + (8 * c) * 65 + n;
;         v4u o; o.x = pk2(s[0 * 65], s[1 * 65]); o.y = pk2(s[2 * 65], s[3 * 65]); o.z = pk2(s[4 * 65], s[5 * 65]); o.w = pk2(s[6 * 65], s[7 * 65]);
;         *(v4u*)(t.WT + (size_t)rowmap(t.mode, n0 + n) * t.K + k0 + 8 * c) = o; }
; }
.LBB0_108:
	s_waitcnt lgkmcnt(3)
	v_cvt_pk_bf16_f32 v4, v4, v5
	s_waitcnt lgkmcnt(2)
	v_cvt_pk_bf16_f32 v5, v6, v7
	s_waitcnt lgkmcnt(1)
	v_cvt_pk_bf16_f32 v6, v8, v9
	v_mad_u64_u32 v[8:9], s[12:13], v95, s16, 0
	s_waitcnt lgkmcnt(0)
	v_cvt_pk_bf16_f32 v7, v10, v11
	v_ashrrev_i32_e32 v1, 31, v95
	v_mov_b32_e32 v10, v9
	v_mad_u64_u32 v[10:11], s[12:13], v1, s16, v[10:11]
	v_mov_b32_e32 v9, v10
	v_lshl_add_u64 v[8:9], v[8:9], 1, s[0:1]
	v_lshl_add_u64 v[8:9], s[8:9], 1, v[8:9]
	v_mov_b32_e32 v1, v3
	v_lshl_add_u64 v[8:9], v[8:9], 0, v[0:1]
	global_store_dwordx4 v[8:9], v[4:7], off sc1
	ds_read2_b32 v[4:5], v16 offset0:24 offset1:89
	ds_read2_b32 v[6:7], v16 offset0:154 offset1:219
	ds_read2_b32 v[8:9], v94 offset0:28 offset1:93
	ds_read2_b32 v[10:11], v94 offset0:158 offset1:223
	v_or_b32_e32 v1, s24, v19
	s_cmp_lt_i32 s17, 2
	s_mov_b64 s[12:13], -1
	s_cbranch_scc1 .LBB0_112
	s_cmp_eq_u32 s17, 2
	v_mov_b32_e32 v95, v1
	s_cbranch_scc0 .LBB0_111
	v_cmp_lt_i32_e32 vcc, s18, v1
	s_nop 1
	v_cndmask_b32_e32 v95, 0, v28, vcc
	v_add_lshl_u32 v95, v95, v1, 1
	v_cndmask_b32_e64 v96, 0, 16, vcc
	v_and_b32_e32 v95, 0xffffff00, v95
	v_and_or_b32 v96, v1, s19, v96
	v_or3_b32 v95, v96, v95, v26

; #define LAS __attribute__((address_space(3)))
; __device__ __forceinline__ unsigned pk2(float lo, float hi) { return pg8::cvt_pk_bf16(lo, hi); }
; __device__ __forceinline__ int rowmap(int mode, int n) {
;     if (mode == 1) return n < 10240 ? n : (n < 10304 ? n + (PC_DT - 10240) : n - 64);
;     if (mode == 2) { const int isup = n >= DFF ? 1 : 0; const int f = n - isup * DFF;
;         return 256 * (f >> 7) + 128 * ((f >> 2) & 1) + 32 * ((f >> 5) & 3) + 16 * isup + 4 * ((f >> 3) & 3) + (f & 3); }
;     return n;
; __device__ __forceinline__ void item_store(const TItem& t, LAS float* scr, int lane) {
;     const int nblk = t.N / 64, kb = t.item / nblk, nb = t.item % nblk, k0 = 64 * kb, n0 = 64 * nb;
;     const int c = lane & 7, nn = lane >> 3;
; #pragma unroll
;     for (int j = 0; j < 8; ++j) { const int n = nn + 8 * j; const LAS float* s = scr + (8 * c) * 65 + n;
;         v4u o; o.x = pk2(s[0 * 65], s[1 * 65]); o.y = pk2(s[2 * 65], s[3 * 65]); o.z = pk2(s[4 * 65], s[5 * 65]); o.w = pk2(s[6 * 65], s[7 * 65]);
;         *(v4u*)(t.WT + (size_t)rowmap(t.mode, n0 + n) * t.K + k0 + 8 * c) = o; }
; }
.LBB0_116:
	s_waitcnt lgkmcnt(3)
	v_cvt_pk_bf16_f32 v4, v4, v5
	s_waitcnt lgkmcnt(2)
	v_cvt_pk_bf16_f32 v5, v6, v7
	s_waitcnt lgkmcnt(1)
	v_cvt_pk_bf16_f32 v6, v8, v9
	v_mad_u64_u32 v[8:9], s[12:13], v95, s16, 0
	s_waitcnt lgkmcnt(0)
	v_cvt_pk_bf16_f32 v7, v10, v11
	v_ashrrev_i32_e32 v1, 31, v95
	v_mov_b32_e32 v10, v9
	v_mad_u64_u32 v[10:11], s[12:13], v1, s16, v[10:11]
	v_mov_b32_e32 v9, v10
	v_lshl_add_u64 v[8:9], v[8:9], 1, s[0:1]
	v_lshl_add_u64 v[8:9], s[8:9], 1, v[8:9]
	v_mov_b32_e32 v1, v3
	v_lshl_add_u64 v[8:9], v[8:9], 0, v[0:1]
	global_store_dwordx4 v[8:9], v[4:7], off sc1
	ds_read2_b32 v[4:5], v16 offset0:32 offset1:97
	ds_read2_b32 v[6:7], v16 offset0:162 offset1:227
	ds_read2_b32 v[8:9], v94 offset0:36 offset1:101
	ds_read2_b32 v[10:11], v94 offset0:166 offset1:231
	v_or_b32_e32 v1, s24, v20
	s_cmp_lt_i32 s17, 2
	s_mov_b64 s[12:13], -1
	s_cbranch_scc1 .LBB0_120
	s_cmp_eq_u32 s17, 2
	v_mov_b32_e32 v95, v1
	s_cbranch_scc0 .LBB0_119
	v_cmp_lt_i32_e32 vcc, s18, v1
	s_nop 1
	v_cndmask_b32_e32 v95, 0, v28, vcc
	v_add_lshl_u32 v95, v95, v1, 1
	v_cndmask_b32_e64 v96, 0, 16, vcc
	v_and_b32_e32 v95, 0xffffff00, v95
	v_and_or_b32 v96, v1, s22, v96
	v_or3_b32 v95, v96, v95, v15

; #define LAS __attribute__((address_space(3)))
; __device__ __forceinline__ unsigned pk2(float lo, float hi) { return pg8::cvt_pk_bf16(lo, hi); }
; __device__ __forceinline__ int rowmap(int mode, int n) {
;     if (mode == 1) return n < 10240 ? n : (n < 10304 ? n + (PC_DT - 10240) : n - 64);
;     if (mode == 2) { const int isup = n >= DFF ? 1 : 0; const int f = n - isup * DFF;
;         return 256 * (f >> 7) + 128 * ((f >> 2) & 1) + 32 * ((f >> 5) & 3) + 16 * isup + 4 * ((f >> 3) & 3) + (f & 3); }
;     return n;
; __device__ __forceinline__ void item_store(const TItem& t, LAS float* scr, int lane) {
;     const int nblk = t.N / 64, kb = t.item / nblk, nb = t.item % nblk, k0 = 64 * kb, n0 = 64 * nb;
;     const int c = lane & 7, nn = lane >> 3;
; #pragma unroll
;     for (int j = 0; j < 8; ++j) { const int n = nn + 8 * j; const LAS float* s = scr + (8 * c) * 65 + n;
;         v4u o; o.x = pk2(s[0 * 65], s[1 * 65]); o.y = pk2(s[2 * 65], s[3 * 65]); o.z = pk2(s[4 * 65], s[5 * 65]); o.w = pk2(s[6 * 65], s[7 * 65]);
;         *(v4u*)(t.WT + (size_t)rowmap(t.mode, n0 + n) * t.K + k0 + 8 * c) = o; }
; }
.LBB0_124:
	s_waitcnt lgkmcnt(3)
	v_cvt_pk_bf16_f32 v4, v4, v5
	s_waitcnt lgkmcnt(2)
	v_cvt_pk_bf16_f32 v5, v6, v7
	s_waitcnt lgkmcnt(1)
	v_cvt_pk_bf16_f32 v6, v8, v9
	v_mad_u64_u32 v[8:9], s[12:13], v95, s16, 0
	s_waitcnt lgkmcnt(0)
	v_cvt_pk_bf16_f32 v7, v10, v11
	v_ashrrev_i32_e32 v1, 31, v95
	v_mov_b32_e32 v10, v9
	v_mad_u64_u32 v[10:11], s[12:13], v1, s16, v[10:11]
	v_mov_b32_e32 v9, v10
	v_lshl_add_u64 v[8:9], v[8:9], 1, s[0:1]
	v_lshl_add_u64 v[8:9], s[8:9], 1, v[8:9]
	v_mov_b32_e32 v1, v3
	v_lshl_add_u64 v[8:9], v[8:9], 0, v[0:1]
	global_store_dwordx4 v[8:9], v[4:7], off sc1
	ds_read2_b32 v[4:5], v16 offset0:40 offset1:105
	ds_read2_b32 v[6:7], v16 offset0:170 offset1:235
	ds_read2_b32 v[8:9], v94 offset0:44 offset1:109
	ds_read2_b32 v[10:11], v94 offset0:174 offset1:239
	v_or_b32_e32 v1, s24, v21
	s_cmp_lt_i32 s17, 2
	s_mov_b64 s[12:13], -1
	s_cbranch_scc1 .LBB0_128
	s_cmp_eq_u32 s17, 2
	v_mov_b32_e32 v95, v1
	s_cbranch_scc0 .LBB0_127
	v_cmp_lt_i32_e32 vcc, s18, v1
	s_nop 1
	v_cndmask_b32_e32 v95, 0, v28, vcc
	v_add_lshl_u32 v95, v95, v1, 1
	v_cndmask_b32_e64 v96, 0, 16, vcc
	v_and_b32_e32 v95, 0xffffff00, v95
	v_and_or_b32 v96, v1, s22, v96
	v_or3_b32 v95, v96, v95, v24

; #define LAS __attribute__((address_space(3)))
; __device__ __forceinline__ unsigned pk2(float lo, float hi) { return pg8::cvt_pk_bf16(lo, hi); }
; __device__ __forceinline__ int rowmap(int mode, int n) {
;     if (mode == 1) return n < 10240 ? n : (n < 10304 ? n + (PC_DT - 10240) : n - 64);
;     if (mode == 2) { const int isup = n >= DFF ? 1 : 0; const int f = n - isup * DFF;
;         return 256 * (f >> 7) + 128 * ((f >> 2) & 1) + 32 * ((f >> 5) & 3) + 16 * isup + 4 * ((f >> 3) & 3) + (f & 3); }
;     return n;
; __device__ __forceinline__ void item_store(const TItem& t, LAS float* scr, int lane) {
;     const int nblk = t.N / 64, kb = t.item / nblk, nb = t.item % nblk, k0 = 64 * kb, n0 = 64 * nb;
;     const int c = lane & 7, nn = lane >> 3;
; #pragma unroll
;     for (int j = 0; j < 8; ++j) { const int n = nn + 8 * j; const LAS float* s = scr + (8 * c) * 65 + n;
;         v4u o; o.x = pk2(s[0 * 65], s[1 * 65]); o.y = pk2(s[2 * 65], s[3 * 65]); o.z = pk2(s[4 * 65], s[5 * 65]); o.w = pk2(s[6 * 65], s[7 * 65]);
;         *(v4u*)(t.WT + (size_t)rowmap(t.mode, n0 + n) * t.K + k0 + 8 * c) = o; }
; }
.LBB0_132:
	s_waitcnt lgkmcnt(3)
	v_cvt_pk_bf16_f32 v4, v4, v5
	s_waitcnt lgkmcnt(2)
	v_cvt_pk_bf16_f32 v5, v6, v7
	s_waitcnt lgkmcnt(1)
	v_cvt_pk_bf16_f32 v6, v8, v9
	v_mad_u64_u32 v[8:9], s[12:13], v95, s16, 0
	s_waitcnt lgkmcnt(0)
	v_cvt_pk_bf16_f32 v7, v10, v11
	v_ashrrev_i32_e32 v1, 31, v95
	v_mov_b32_e32 v10, v9
	v_mad_u64_u32 v[10:11], s[12:13], v1, s16, v[10:11]
	v_mov_b32_e32 v9, v10
	v_lshl_add_u64 v[8:9], v[8:9], 1, s[0:1]
	v_lshl_add_u64 v[8:9], s[8:9], 1, v[8:9]
	v_mov_b32_e32 v1, v3
	v_lshl_add_u64 v[8:9], v[8:9], 0, v[0:1]
	global_store_dwordx4 v[8:9], v[4:7], off sc1
	ds_read2_b32 v[4:5], v16 offset0:48 offset1:113
	ds_read2_b32 v[6:7], v16 offset0:178 offset1:243
	ds_read2_b32 v[8:9], v94 offset0:52 offset1:117
	ds_read2_b32 v[10:11], v94 offset0:182 offset1:247
	v_or_b32_e32 v1, s24, v22
	s_cmp_lt_i32 s17, 2
	s_mov_b64 s[12:13], -1
	s_cbranch_scc1 .LBB0_136
	s_cmp_eq_u32 s17, 2
	v_mov_b32_e32 v95, v1
	s_cbranch_scc0 .LBB0_135
	v_cmp_lt_i32_e32 vcc, s18, v1
	s_nop 1
	v_cndmask_b32_e32 v95, 0, v28, vcc
	v_add_lshl_u32 v95, v95, v1, 1
	v_cndmask_b32_e64 v96, 0, 16, vcc
	v_and_b32_e32 v95, 0xffffff00, v95
	v_and_or_b32 v96, v1, s22, v96
	v_or3_b32 v95, v96, v95, v25

; #define LAS __attribute__((address_space(3)))
; __device__ __forceinline__ unsigned pk2(float lo, float hi) { return pg8::cvt_pk_bf16(lo, hi); }
; __device__ __forceinline__ int rowmap(int mode, int n) {
;     if (mode == 1) return n < 10240 ? n : (n < 10304 ? n + (PC_DT - 10240) : n - 64);
;     if (mode == 2) { const int isup = n >= DFF ? 1 : 0; const int f = n - isup * DFF;
;         return 256 * (f >> 7) + 128 * ((f >> 2) & 1) + 32 * ((f >> 5) & 3) + 16 * isup + 4 * ((f >> 3) & 3) + (f & 3); }
;     return n;
; __device__ __forceinline__ void item_store(const TItem& t, LAS float* scr, int lane) {
;     const int nblk = t.N / 64, kb = t.item / nblk, nb = t.item % nblk, k0 = 64 * kb, n0 = 64 * nb;
;     const int c = lane & 7, nn = lane >> 3;
; #pragma unroll
;     for (int j = 0; j < 8; ++j) { const int n = nn + 8 * j; const LAS float* s = scr + (8 * c) * 65 + n;
;         v4u o; o.x = pk2(s[0 * 65], s[1 * 65]); o.y = pk2(s[2 * 65], s[3 * 65]); o.z = pk2(s[4 * 65], s[5 * 65]); o.w = pk2(s[6 * 65], s[7 * 65]);
;         *(v4u*)(t.WT + (size_t)rowmap(t.mode, n0 + n) * t.K + k0 + 8 * c) = o; }
; }
.LBB0_140:
	s_waitcnt lgkmcnt(3)
	v_cvt_pk_bf16_f32 v4, v4, v5
	s_waitcnt lgkmcnt(2)
	v_cvt_pk_bf16_f32 v5, v6, v7
	s_waitcnt lgkmcnt(1)
	v_cvt_pk_bf16_f32 v6, v8, v9
	v_mad_u64_u32 v[8:9], s[12:13], v95, s16, 0
	s_waitcnt lgkmcnt(0)
	v_cvt_pk_bf16_f32 v7, v10, v11
	v_ashrrev_i32_e32 v1, 31, v95
	v_mov_b32_e32 v10, v9
	v_mad_u64_u32 v[10:11], s[12:13], v1, s16, v[10:11]
	v_mov_b32_e32 v9, v10
	v_lshl_add_u64 v[8:9], v[8:9], 1, s[0:1]
	v_lshl_add_u64 v[8:9], s[8:9], 1, v[8:9]
	v_mov_b32_e32 v1, v3
	v_lshl_add_u64 v[8:9], v[8:9], 0, v[0:1]
	global_store_dwordx4 v[8:9], v[4:7], off sc1
	ds_read2_b32 v[4:5], v16 offset0:56 offset1:121
	ds_read2_b32 v[6:7], v16 offset0:186 offset1:251
	ds_read2_b32 v[8:9], v94 offset0:60 offset1:125
	ds_read2_b32 v[10:11], v94 offset0:190 offset1:255
	v_or_b32_e32 v1, s24, v23
	s_cmp_lt_i32 s17, 2
	s_mov_b64 s[12:13], -1
	s_cbranch_scc1 .LBB0_144
	s_cmp_eq_u32 s17, 2
	v_mov_b32_e32 v94, v1
	s_cbranch_scc0 .LBB0_143
	v_cmp_lt_i32_e32 vcc, s18, v1
	s_nop 1
	v_cndmask_b32_e32 v94, 0, v28, vcc
	v_add_lshl_u32 v94, v94, v1, 1
	v_cndmask_b32_e64 v95, 0, 16, vcc
	v_and_b32_e32 v94, 0xffffff00, v94
	v_and_or_b32 v95, v1, s22, v95
	v_or3_b32 v94, v95, v94, v26

; __device__ __forceinline__ void prologue(const Params& P, LAS unsigned char* L, int gw, int NGW, int wave, int lane, int nitems) {
;     ...
;     { constexpr int PADV = (NP - DIN) * D * 2 / 16;
;       const int gt = gw * 64 + lane, NT = NGW * 64;
;       for (int i = gt; i < DEPTH * PADV; i += NT) { const int layer = i / PADV, j = i - layer * PADV;
;           *((v4u*)(ws + WS_W + (size_t)layer * WL_STRIDE + WL_WIN + (size_t)DIN * D * 2) + j) = (v4u){0u, 0u, 0u, 0u}; }
.LBB0_150:
	v_mul_hi_i32 v7, v6, s5
	v_lshrrev_b32_e32 v8, 31, v7
	v_ashrrev_i32_e32 v7, 13, v7
	v_add_u32_e32 v7, v7, v8
	v_mad_i32_i24 v8, v7, s8, v6
	v_mad_i64_i32 v[10:11], s[12:13], v7, s9, v[4:5]
	v_add_u32_e32 v6, s36, v6
	v_ashrrev_i32_e32 v9, 31, v8
	v_cmp_lt_i32_e32 vcc, s10, v6
	v_lshl_add_u64 v[8:9], v[8:9], 4, v[10:11]
	s_or_b64 s[6:7], vcc, s[6:7]
	v_add_co_u32_e32 v8, vcc, 0x5140000, v8
	s_nop 1
	v_addc_co_u32_e32 v9, vcc, 0, v9, vcc
	global_store_dwordx4 v[8:9], v[0:3], off sc1
	s_andn2_b64 exec, exec, s[6:7]
	s_cbranch_execnz .LBB0_150

; __device__ __forceinline__ unsigned cvt_pk_bf16(float lo, float hi) { const f32x2_t v = {lo, hi}; const bf16x2_t c = __builtin_convertvector(v, bf16x2_t); return __builtin_bit_cast(unsigned, c); }
;     __device__ __forceinline__ void operator()(const f32x4 (&acc)[2][2][4][2], const Unit& u, int wr, int wc, int fr, int fq) const {
;         const int row0 = u.pm * BM + wr * 64 + fr, col0 = u.pn * BM + wc * 32 + 8 * fq;
; #pragma unroll
;         for (int ai = 0; ai < 2; ++ai)
; #pragma unroll
;             for (int m = 0; m < 4; ++m) { bf16_t* rowp = O + (size_t)(row0 + ai * HALF + m * 16) * ldc + col0;
; #pragma unroll
;                 for (int bj = 0; bj < 2; ++bj) { const f32x4 v0 = acc[ai][bj][m][0], v1 = acc[ai][bj][m][1];
;                     u32x4 w; w.x = cvt_pk_bf16(v0[0], v0[1]); w.y = cvt_pk_bf16(v0[2], v0[3]); w.z = cvt_pk_bf16(v1[0], v1[1]); w.w = cvt_pk_bf16(v1[2], v1[3]);
;                     *(u32x4*)(rowp + bj * HALF) = w; } }
;     }
.LBB0_266:
	v_lshl_add_u32 v150, s12, 8, v140
	v_lshl_or_b32 v144, s10, 8, v142
	v_ashrrev_i32_e32 v145, 31, v144
	v_mov_b64_e32 v[146:147], s[76:77]
	v_cvt_pk_bf16_f32 v70, v70, v71
	v_cvt_pk_bf16_f32 v71, v72, v73
	v_cvt_pk_bf16_f32 v72, v66, v67
	v_add_u32_e32 v66, 0x80, v150
	v_mad_i64_i32 v[148:149], s[10:11], v150, s67, v[146:147]
	v_lshlrev_b64 v[144:145], 1, v[144:145]
	v_cvt_pk_bf16_f32 v110, v110, v111
	v_cvt_pk_bf16_f32 v111, v112, v113
	v_cvt_pk_bf16_f32 v112, v106, v107
	v_or_b32_e32 v106, 16, v150
	v_mad_i64_i32 v[66:67], s[10:11], v66, s67, v[146:147]
	v_cvt_pk_bf16_f32 v46, v46, v47
	v_cvt_pk_bf16_f32 v47, v48, v49
	v_cvt_pk_bf16_f32 v48, v42, v43
	v_add_u32_e32 v42, 0x90, v150
	v_lshl_add_u64 v[148:149], v[148:149], 0, v[144:145]
	v_cvt_pk_bf16_f32 v113, v108, v109
	v_mad_i64_i32 v[106:107], s[10:11], v106, s67, v[146:147]
	v_cvt_pk_bf16_f32 v94, v94, v95
	v_cvt_pk_bf16_f32 v95, v96, v97
	v_cvt_pk_bf16_f32 v96, v90, v91
	v_or_b32_e32 v90, 32, v150
	v_lshl_add_u64 v[66:67], v[66:67], 0, v[144:145]
	v_cvt_pk_bf16_f32 v49, v44, v45
	v_mad_i64_i32 v[42:43], s[10:11], v42, s67, v[146:147]
	v_cvt_pk_bf16_f32 v28, v28, v29
	v_cvt_pk_bf16_f32 v29, v30, v31
	v_cvt_pk_bf16_f32 v30, v24, v25
	v_add_u32_e32 v24, 0xa0, v150
	global_store_dwordx4 v[148:149], v[110:113], off offset:256 sc1
	v_cvt_pk_bf16_f32 v97, v92, v93
	v_mad_i64_i32 v[90:91], s[10:11], v90, s67, v[146:147]
	v_lshl_add_u64 v[110:111], v[106:107], 0, v[144:145]
	v_cvt_pk_bf16_f32 v78, v78, v79
	v_cvt_pk_bf16_f32 v79, v80, v81
	v_cvt_pk_bf16_f32 v80, v74, v75
	v_or_b32_e32 v74, 48, v150
	global_store_dwordx4 v[66:67], v[46:49], off offset:256 sc1
	v_cvt_pk_bf16_f32 v31, v26, v27
	v_mad_i64_i32 v[24:25], s[10:11], v24, s67, v[146:147]
	v_lshl_add_u64 v[46:47], v[42:43], 0, v[144:145]
	v_cvt_pk_bf16_f32 v12, v12, v13
	v_cvt_pk_bf16_f32 v13, v14, v15
	v_cvt_pk_bf16_f32 v14, v8, v9
	v_add_u32_e32 v8, 0xb0, v150
	global_store_dwordx4 v[110:111], v[94:97], off offset:256 sc1
	v_cvt_pk_bf16_f32 v81, v76, v77
	v_mad_i64_i32 v[74:75], s[10:11], v74, s67, v[146:147]
	v_lshl_add_u64 v[94:95], v[90:91], 0, v[144:145]
	global_store_dwordx4 v[46:47], v[28:31], off offset:256 sc1
	v_cvt_pk_bf16_f32 v15, v10, v11
	v_mad_i64_i32 v[8:9], s[10:11], v8, s67, v[146:147]
	v_lshl_add_u64 v[28:29], v[24:25], 0, v[144:145]
	v_cvt_pk_bf16_f32 v126, v126, v127
	v_cvt_pk_bf16_f32 v127, v128, v129
	v_cvt_pk_bf16_f32 v128, v122, v123
	v_cvt_pk_bf16_f32 v129, v124, v125
	v_cvt_pk_bf16_f32 v106, v118, v119
	v_cvt_pk_bf16_f32 v107, v120, v121
	v_cvt_pk_bf16_f32 v108, v114, v115
	v_cvt_pk_bf16_f32 v109, v116, v117
	v_cvt_pk_bf16_f32 v90, v102, v103
	v_cvt_pk_bf16_f32 v91, v104, v105
	v_cvt_pk_bf16_f32 v92, v98, v99
	v_cvt_pk_bf16_f32 v93, v100, v101
	global_store_dwordx4 v[94:95], v[78:81], off offset:256 sc1
	v_cvt_pk_bf16_f32 v76, v82, v83
	v_cvt_pk_bf16_f32 v77, v84, v85
	v_lshl_add_u64 v[78:79], v[74:75], 0, v[144:145]
	v_cvt_pk_bf16_f32 v74, v86, v87
	v_cvt_pk_bf16_f32 v75, v88, v89
	v_cvt_pk_bf16_f32 v73, v68, v69
	v_cvt_pk_bf16_f32 v62, v62, v63
	v_cvt_pk_bf16_f32 v63, v64, v65
	v_cvt_pk_bf16_f32 v64, v58, v59
	v_cvt_pk_bf16_f32 v65, v60, v61
	v_cvt_pk_bf16_f32 v42, v54, v55
	v_cvt_pk_bf16_f32 v43, v56, v57
	v_cvt_pk_bf16_f32 v44, v50, v51
	v_cvt_pk_bf16_f32 v45, v52, v53
	v_cvt_pk_bf16_f32 v24, v38, v39
	v_cvt_pk_bf16_f32 v25, v40, v41
	v_cvt_pk_bf16_f32 v26, v34, v35
	v_cvt_pk_bf16_f32 v27, v36, v37
	global_store_dwordx4 v[28:29], v[12:15], off offset:256 sc1
	v_cvt_pk_bf16_f32 v10, v16, v17
	v_cvt_pk_bf16_f32 v11, v18, v19
	v_lshl_add_u64 v[12:13], v[8:9], 0, v[144:145]
	v_cvt_pk_bf16_f32 v8, v20, v21
	v_cvt_pk_bf16_f32 v9, v22, v23
	v_cvt_pk_bf16_f32 v4, v4, v5
	v_cvt_pk_bf16_f32 v5, v6, v7
	v_cvt_pk_bf16_f32 v6, v0, v1
	v_cvt_pk_bf16_f32 v7, v2, v3
	s_andn2_b64 vcc, exec, s[22:23]
	s_mov_b64 s[10:11], -1
	global_store_dwordx4 v[148:149], v[126:129], off sc1
	global_store_dwordx4 v[110:111], v[106:109], off sc1
	global_store_dwordx4 v[94:95], v[90:93], off sc1
	global_store_dwordx4 v[78:79], v[74:77], off sc1
	global_store_dwordx4 v[78:79], v[70:73], off offset:256 sc1
	global_store_dwordx4 v[66:67], v[62:65], off sc1
	global_store_dwordx4 v[46:47], v[42:45], off sc1
	global_store_dwordx4 v[28:29], v[24:27], off sc1
	global_store_dwordx4 v[12:13], v[8:11], off sc1
	global_store_dwordx4 v[12:13], v[4:7], off offset:256 sc1
	s_cbranch_vccnz .LBB0_258
	s_andn2_b64 vcc, exec, s[6:7]
	s_cbranch_vccnz .LBB0_257
	s_barrier
	s_branch .LBB0_257

; #define LAS __attribute__((address_space(3)))
; __device__ __forceinline__ unsigned pk2(float lo, float hi) { return pg8::cvt_pk_bf16(lo, hi); }
; __device__ __forceinline__ void item_store(const TItem& t, LAS float* scr, int lane) {
;     const int nblk = t.N / 64, kb = t.item / nblk, nb = t.item % nblk, k0 = 64 * kb, n0 = 64 * nb;
;     const int c = lane & 7, nn = lane >> 3;
; #pragma unroll
;     for (int j = 0; j < 8; ++j) { const int n = nn + 8 * j; const LAS float* s = scr + (8 * c) * 65 + n;
;         v4u o; o.x = pk2(s[0 * 65], s[1 * 65]); o.y = pk2(s[2 * 65], s[3 * 65]); o.z = pk2(s[4 * 65], s[5 * 65]); o.w = pk2(s[6 * 65], s[7 * 65]);
;         *(v4u*)(t.WT + (size_t)rowmap(t.mode, n0 + n) * t.K + k0 + 8 * c) = o; }
; }
.LBB0_346:
	s_lshl_b32 s8, s16, 6
	s_waitcnt lgkmcnt(3)
	v_cvt_pk_bf16_f32 v4, v4, v5
	s_waitcnt lgkmcnt(2)
	v_cvt_pk_bf16_f32 v5, v6, v7
	s_waitcnt lgkmcnt(1)
	v_cvt_pk_bf16_f32 v6, v8, v9
	v_mad_u64_u32 v[8:9], s[16:17], v32, s37, 0
	s_waitcnt lgkmcnt(0)
	v_cvt_pk_bf16_f32 v7, v10, v11
	v_ashrrev_i32_e32 v11, 31, v32
	v_mov_b32_e32 v10, v9
	v_mad_u64_u32 v[10:11], s[16:17], v11, s37, v[10:11]
	v_mov_b32_e32 v9, v10
	s_ashr_i32 s9, s8, 31
	v_lshl_add_u64 v[8:9], v[8:9], 1, s[6:7]
	v_lshl_add_u64 v[8:9], s[8:9], 1, v[8:9]
	v_lshlrev_b32_e32 v32, 1, v2
	v_lshl_add_u64 v[8:9], v[8:9], 0, v[32:33]
	v_mov_b64_e32 v[102:103], v[8:9]
	global_store_dwordx4 v[8:9], v[4:7], off sc1
	ds_read2_b32 v[4:5], v14 offset0:8 offset1:73
	ds_read2_b32 v[6:7], v14 offset0:138 offset1:203
	ds_read2_b32 v[8:9], v95 offset0:12 offset1:77
	ds_read2_b32 v[10:11], v95 offset0:142 offset1:207
	s_cmp_eq_u32 s38, 2
	s_cselect_b32 s8, 8, 16
	s_cselect_b32 s9, 40, 16
	s_mul_i32 s8, s8, s37
	s_mul_i32 s9, s9, s37
	s_mov_b32 s101, 0
	s_mov_b32 s100, s8
	ds_read2_b32 v[16:17], v14 offset0:16 offset1:81
	ds_read2_b32 v[18:19], v14 offset0:146 offset1:211
	ds_read2_b32 v[20:21], v95 offset0:20 offset1:85
	ds_read2_b32 v[22:23], v95 offset0:150 offset1:215
	ds_read2_b32 v[96:97], v14 offset0:24 offset1:89
	ds_read2_b32 v[98:99], v14 offset0:154 offset1:219
	ds_read2_b32 v[100:101], v95 offset0:28 offset1:93
	ds_read2_b32 v[24:25], v95 offset0:158 offset1:223
	s_waitcnt lgkmcnt(8)
	v_cvt_pk_bf16_f32 v4, v4, v5
	v_cvt_pk_bf16_f32 v5, v6, v7
	v_cvt_pk_bf16_f32 v6, v8, v9
	v_cvt_pk_bf16_f32 v7, v10, v11
	v_lshl_add_u64 v[102:103], v[102:103], 0, s[100:101]
	global_store_dwordx4 v[102:103], v[4:7], off sc1
	ds_read2_b32 v[4:5], v14 offset0:32 offset1:97
	ds_read2_b32 v[6:7], v14 offset0:162 offset1:227
	ds_read2_b32 v[8:9], v95 offset0:36 offset1:101
	ds_read2_b32 v[10:11], v95 offset0:166 offset1:231
	s_waitcnt lgkmcnt(8)
	v_cvt_pk_bf16_f32 v16, v16, v17
	v_cvt_pk_bf16_f32 v17, v18, v19
	v_cvt_pk_bf16_f32 v18, v20, v21
	v_cvt_pk_bf16_f32 v19, v22, v23
	v_lshl_add_u64 v[102:103], v[102:103], 0, s[100:101]
	global_store_dwordx4 v[102:103], v[16:19], off sc1
	ds_read2_b32 v[16:17], v14 offset0:40 offset1:105
	ds_read2_b32 v[18:19], v14 offset0:170 offset1:235
	ds_read2_b32 v[20:21], v95 offset0:44 offset1:109
	ds_read2_b32 v[22:23], v95 offset0:174 offset1:239
	s_waitcnt lgkmcnt(8)
	v_cvt_pk_bf16_f32 v96, v96, v97
	v_cvt_pk_bf16_f32 v97, v98, v99
	v_cvt_pk_bf16_f32 v98, v100, v101
	v_cvt_pk_bf16_f32 v99, v24, v25
	v_lshl_add_u64 v[102:103], v[102:103], 0, s[100:101]
	global_store_dwordx4 v[102:103], v[96:99], off sc1
	ds_read2_b32 v[96:97], v14 offset0:48 offset1:113
	ds_read2_b32 v[98:99], v14 offset0:178 offset1:243
	ds_read2_b32 v[100:101], v95 offset0:52 offset1:117
	ds_read2_b32 v[24:25], v95 offset0:182 offset1:247
	s_mov_b32 s100, s9
	s_waitcnt lgkmcnt(8)
	v_cvt_pk_bf16_f32 v4, v4, v5
	v_cvt_pk_bf16_f32 v5, v6, v7
	v_cvt_pk_bf16_f32 v6, v8, v9
	v_cvt_pk_bf16_f32 v7, v10, v11
	v_lshl_add_u64 v[102:103], v[102:103], 0, s[100:101]
	global_store_dwordx4 v[102:103], v[4:7], off sc1
	s_mov_b32 s100, s8
	ds_read2_b32 v[4:5], v14 offset0:56 offset1:121
	ds_read2_b32 v[6:7], v14 offset0:186 offset1:251
	ds_read2_b32 v[8:9], v95 offset0:60 offset1:125
	ds_read2_b32 v[10:11], v95 offset0:190 offset1:255
	s_waitcnt lgkmcnt(8)
	v_cvt_pk_bf16_f32 v16, v16, v17
	v_cvt_pk_bf16_f32 v17, v18, v19
	v_cvt_pk_bf16_f32 v18, v20, v21
	v_cvt_pk_bf16_f32 v19, v22, v23
	v_lshl_add_u64 v[102:103], v[102:103], 0, s[100:101]
	global_store_dwordx4 v[102:103], v[16:19], off sc1
	s_waitcnt lgkmcnt(4)
	v_cvt_pk_bf16_f32 v96, v96, v97
	v_cvt_pk_bf16_f32 v97, v98, v99
	v_cvt_pk_bf16_f32 v98, v100, v101
	v_cvt_pk_bf16_f32 v99, v24, v25
	v_lshl_add_u64 v[102:103], v[102:103], 0, s[100:101]
	global_store_dwordx4 v[102:103], v[96:99], off sc1
	s_waitcnt lgkmcnt(0)
	v_cvt_pk_bf16_f32 v4, v4, v5
	v_cvt_pk_bf16_f32 v5, v6, v7
	v_cvt_pk_bf16_f32 v6, v8, v9
	v_cvt_pk_bf16_f32 v7, v10, v11
	v_lshl_add_u64 v[102:103], v[102:103], 0, s[100:101]
	global_store_dwordx4 v[102:103], v[4:7], off sc1
	s_branch .Lconv_tail_g1

;     __device__ __forceinline__ void operator()(const f32x4 (&acc)[2][2][4][2], const Unit& u, int wr, int wc, int fr, int fq) const {
;         if (wc >= 2) return;
;         const int row0 = u.pm * BM + wr * 64 + fr, col0 = wc * 32 + 4 * fq;
; #pragma unroll
;         for (int ai = 0; ai < 2; ++ai)
; #pragma unroll
;             for (int m4 = 0; m4 < 4; ++m4) { float* rowp = P + ((size_t)u.pn * m + row0 + ai * HALF + m4 * 16) * 64 + col0;
; #pragma unroll
;                 for (int n = 0; n < 2; ++n) *(f32x4*)(rowp + n * 16) = acc[ai][0][m4][n]; }
;     }
.LBB0_422:
	v_lshl_add_u32 v74, s15, 8, v70
	s_ashr_i32 s15, s14, 31
	v_ashrrev_i32_e32 v75, 31, v74
	s_lshl_b64 s[14:15], s[14:15], 21
	v_lshlrev_b64 v[74:75], 8, v[74:75]
	v_lshl_add_u64 v[76:77], v[68:69], 0, s[14:15]
	v_lshl_add_u64 v[74:75], v[76:77], 0, v[74:75]
	global_store_dwordx4 v[74:75], v[24:27], off sc1
	global_store_dwordx4 v[74:75], v[28:31], off offset:64 sc1
	s_movk_i32 s11, 0x2000
	v_add_co_u32_e32 v24, vcc, 0x1000, v74
	s_nop 1
	v_addc_co_u32_e32 v25, vcc, 0, v75, vcc
	global_store_dwordx4 v[24:25], v[16:19], off sc1
	global_store_dwordx4 v[24:25], v[20:23], off offset:64 sc1
	s_nop 0
	v_add_co_u32_e32 v16, vcc, s11, v74
	s_mov_b32 s11, 0x8000
	s_nop 0
	v_addc_co_u32_e32 v17, vcc, 0, v75, vcc
	global_store_dwordx4 v[16:17], v[8:11], off sc1
	global_store_dwordx4 v[16:17], v[12:15], off offset:64 sc1
	s_nop 0
	v_add_co_u32_e32 v8, vcc, 0x3000, v74
	s_nop 1
	v_addc_co_u32_e32 v9, vcc, 0, v75, vcc
	global_store_dwordx4 v[8:9], v[0:3], off sc1
	global_store_dwordx4 v[8:9], v[4:7], off offset:64 sc1
	s_nop 0
	v_add_co_u32_e32 v0, vcc, s11, v74
	s_nop 1
	v_addc_co_u32_e32 v1, vcc, 0, v75, vcc
	global_store_dwordx4 v[0:1], v[58:61], off sc1
	global_store_dwordx4 v[0:1], v[62:65], off offset:64 sc1
	v_add_co_u32_e32 v0, vcc, 0x9000, v74
	s_nop 1
	v_addc_co_u32_e32 v1, vcc, 0, v75, vcc
	global_store_dwordx4 v[0:1], v[50:53], off sc1
	global_store_dwordx4 v[0:1], v[54:57], off offset:64 sc1
	v_add_co_u32_e32 v0, vcc, 0xa000, v74
	s_nop 1
	v_addc_co_u32_e32 v1, vcc, 0, v75, vcc
	global_store_dwordx4 v[0:1], v[42:45], off sc1
	global_store_dwordx4 v[0:1], v[46:49], off offset:64 sc1
	v_add_co_u32_e32 v0, vcc, 0xb000, v74
	s_nop 1
	v_addc_co_u32_e32 v1, vcc, 0, v75, vcc
	global_store_dwordx4 v[0:1], v[34:37], off sc1
	global_store_dwordx4 v[0:1], v[38:41], off offset:64 sc1
	s_andn2_b64 vcc, exec, s[16:17]
	s_cbranch_vccz .LBB0_419

; __device__ __forceinline__ void cv_phase(unsigned char* ws, int layer, int tid) {
;     ...
;     { const f32x4* dp4 = (const f32x4*)(ws + WS_DTP); f32x4* ds4 = (f32x4*)(ws + WS_DTS);
;       for (int i = (int)blockIdx.x * 512 + tid; i < M * 16; i += (int)gridDim.x * 512) { f32x4 a = dp4[i];
; #pragma unroll
;           for (int k8 = 1; k8 < 8; ++k8) a += dp4[(size_t)k8 * M * 16 + i];
;           ds4[i] = a; } }
.LBB0_487:
	v_add_co_u32_e32 v6, vcc, 0xff200000, v2
	s_mov_b64 s[0:1], vcc
	v_add_co_u32_e32 v10, vcc, 0xff400000, v2
	s_mov_b64 s[4:5], vcc
	v_addc_co_u32_e64 v7, vcc, -1, v3, s[0:1]
	v_add_co_u32_e32 v14, vcc, 0xff600000, v2
	s_mov_b64 s[0:1], vcc
	v_addc_co_u32_e64 v11, vcc, -1, v3, s[4:5]
	v_add_co_u32_e32 v18, vcc, 0xff800000, v2
	s_mov_b64 s[4:5], vcc
	v_addc_co_u32_e64 v15, vcc, -1, v3, s[0:1]
	v_add_co_u32_e32 v22, vcc, 0xffa00000, v2
	global_load_dwordx4 v[6:9], v[6:7], off
	s_mov_b64 s[0:1], vcc
	global_load_dwordx4 v[10:13], v[10:11], off
	v_addc_co_u32_e64 v19, vcc, -1, v3, s[4:5]
	global_load_dwordx4 v[14:17], v[14:15], off
	v_add_co_u32_e32 v26, vcc, 0xffc00000, v2
	s_mov_b64 s[4:5], vcc
	global_load_dwordx4 v[18:21], v[18:19], off
	v_addc_co_u32_e64 v23, vcc, -1, v3, s[0:1]
	v_addc_co_u32_e64 v27, s[0:1], -1, v3, s[4:5]
	v_add_co_u32_e32 v30, vcc, 0xffe00000, v2
	global_load_dwordx4 v[22:25], v[22:23], off
	s_nop 0
	global_load_dwordx4 v[26:29], v[26:27], off
	v_addc_co_u32_e32 v31, vcc, -1, v3, vcc
	global_load_dwordx4 v[34:37], v[30:31], off
	global_load_dwordx4 v[38:41], v[2:3], off
	v_add_u32_e32 v0, s2, v0
	s_mov_b32 s0, 0x1ffff
	v_cmp_lt_i32_e32 vcc, s0, v0
	s_or_b64 s[8:9], vcc, s[8:9]
	v_add_co_u32_e32 v30, vcc, 0xf1600000, v2
	s_waitcnt vmcnt(6)
	v_pk_add_f32 v[8:9], v[8:9], v[12:13]
	v_pk_add_f32 v[6:7], v[6:7], v[10:11]
	v_addc_co_u32_e32 v31, vcc, -1, v3, vcc
	s_waitcnt vmcnt(5)
	v_pk_add_f32 v[8:9], v[8:9], v[16:17]
	v_pk_add_f32 v[6:7], v[6:7], v[14:15]
	v_lshl_add_u64 v[2:3], v[2:3], 0, s[36:37]
	s_waitcnt vmcnt(4)
	v_pk_add_f32 v[8:9], v[8:9], v[20:21]
	v_pk_add_f32 v[6:7], v[6:7], v[18:19]
	s_waitcnt vmcnt(3)
	v_pk_add_f32 v[8:9], v[8:9], v[24:25]
	v_pk_add_f32 v[6:7], v[6:7], v[22:23]
	s_waitcnt vmcnt(2)
	v_pk_add_f32 v[8:9], v[8:9], v[28:29]
	v_pk_add_f32 v[6:7], v[6:7], v[26:27]
	s_waitcnt vmcnt(1)
	v_pk_add_f32 v[8:9], v[8:9], v[36:37]
	v_pk_add_f32 v[6:7], v[6:7], v[34:35]
	s_waitcnt vmcnt(0)
	v_pk_add_f32 v[8:9], v[8:9], v[40:41]
	v_pk_add_f32 v[6:7], v[6:7], v[38:39]
	global_store_dwordx4 v[30:31], v[6:9], off sc1
	s_andn2_b64 exec, exec, s[8:9]
	s_cbranch_execnz .LBB0_487

; __device__ __forceinline__ float blo(unsigned w) { return __uint_as_float(w << 16); }
; __device__ __forceinline__ float bhi(unsigned w) { return __uint_as_float(w & 0xffff0000u); }
; __device__ __forceinline__ float silu(float x) { return x * sigm(x); }
; __device__ __forceinline__ unsigned cvtpk(float lo, float hi) { return pg8::cvt_pk_bf16(lo, hi); }
; __device__ __forceinline__ void cv_phase(unsigned char* ws, int layer, int tid) {
;     ...
;     for (int tile = blockIdx.x; tile < BATCH * (SEQ / 128) * GROUPS; tile += gridDim.x) {
;         const int b = tile >> 7, c = (tile >> 3) & 15, g = tile & 7;
;         const int ch = SSD_INNER + isC * (GROUPS * NSTATE) + g * NSTATE + 8 * vcl;
;         v4u raw[11];
;         load_rows<11>(raw, proj + (size_t)b * SEQ * NP, PC_XBC + ch, c * 128 + 8 * tgb - 3);
;         f32x4 wq[4][2], bq[2];
; #pragma unroll
;         for (int k = 0; k < 4; ++k) { wq[k][0] = *(const f32x4*)(cw + k * XBC + ch); wq[k][1] = *(const f32x4*)(cw + k * XBC + ch + 4); }
;         bq[0] = *(const f32x4*)(cb + ch); bq[1] = *(const f32x4*)(cb + ch + 4);
;         v4u nat[8];
; #pragma unroll
;         for (int wi = 0; wi < 4; ++wi) {
;             float w0[4], w1[4];
; #pragma unroll
;             for (int k = 0; k < 4; ++k) { w0[k] = wq[k][wi >> 1][2 * (wi & 1)]; w1[k] = wq[k][wi >> 1][2 * (wi & 1) + 1]; }
;             const float b0 = bq[wi >> 1][2 * (wi & 1)], b1 = bq[wi >> 1][2 * (wi & 1) + 1];
;             float lo[11], hi[11];
; #pragma unroll
;             for (int i = 0; i < 11; ++i) { lo[i] = blo(raw[i][wi]); hi[i] = bhi(raw[i][wi]); }
;             float t0[8], t1[8];
; #pragma unroll
;             for (int j = 0; j < 8; ++j) {
;                 t0[j] = silu(b0 + w0[0] * lo[j] + w0[1] * lo[j + 1] + w0[2] * lo[j + 2] + w0[3] * lo[j + 3]);
;                 t1[j] = silu(b1 + w1[0] * hi[j] + w1[1] * hi[j + 1] + w1[2] * hi[j + 2] + w1[3] * hi[j + 3]);
;                 nat[j][wi] = cvtpk(t0[j], t1[j]);
;             }
;         }
.LBB0_490:
	s_or_b64 exec, exec, s[6:7]
	v_lshl_or_b32 v32, v32, 2, v242
	v_lshl_add_u64 v[42:43], s[30:31], 0, v[32:33]
	v_add_co_u32_e32 v34, vcc, 0x6000, v42
	global_load_dwordx4 v[66:69], v32, s[30:31]
	global_load_dwordx4 v[70:73], v32, s[22:23]
	v_addc_co_u32_e32 v35, vcc, 0, v43, vcc
	global_load_dwordx4 v[74:77], v[34:35], off
	v_add_co_u32_e32 v34, vcc, 0xc000, v42
	s_mov_b32 s1, 0x12000
	s_nop 0
	v_addc_co_u32_e32 v35, vcc, 0, v43, vcc
	global_load_dwordx4 v[78:81], v[34:35], off
	v_add_co_u32_e32 v34, vcc, s1, v42
	s_waitcnt vmcnt(4)
	v_lshlrev_b32_e32 v122, 16, v4
	v_addc_co_u32_e32 v35, vcc, 0, v43, vcc
	global_load_dwordx4 v[82:85], v[34:35], off
	v_and_b32_e32 v123, 0xffff0000, v4
	v_lshlrev_b32_e32 v124, 16, v0
	v_and_b32_e32 v125, 0xffff0000, v0
	v_lshlrev_b32_e32 v120, 16, v8
	v_and_b32_e32 v121, 0xffff0000, v8
	v_lshlrev_b32_e32 v118, 16, v12
	v_and_b32_e32 v119, 0xffff0000, v12
	v_lshlrev_b32_e32 v116, 16, v16
	v_and_b32_e32 v117, 0xffff0000, v16
	s_mov_b64 s[4:5], 0x6000
	global_load_dwordx4 v[34:37], v32, s[30:31] offset:16
	global_load_dwordx4 v[38:41], v32, s[22:23] offset:16
	v_lshl_add_u64 v[44:45], v[42:43], 0, s[4:5]
	s_mov_b64 s[4:5], 0xc000
	v_lshl_add_u64 v[46:47], v[42:43], 0, s[4:5]
	s_mov_b64 s[4:5], 0x12000
	v_lshlrev_b32_e32 v114, 16, v20
	v_and_b32_e32 v115, 0xffff0000, v20
	v_lshl_add_u64 v[50:51], v[42:43], 0, s[4:5]
	v_lshlrev_b32_e32 v112, 16, v24
	v_and_b32_e32 v113, 0xffff0000, v24
	global_load_dwordx4 v[42:45], v[44:45], off offset:16
	s_nop 0
	global_load_dwordx4 v[46:49], v[46:47], off offset:16
	s_nop 0
	global_load_dwordx4 v[50:53], v[50:51], off offset:16
	v_lshlrev_b32_e32 v102, 16, v28
	v_and_b32_e32 v103, 0xffff0000, v28
	v_lshlrev_b32_e32 v104, 16, v58
	v_and_b32_e32 v105, 0xffff0000, v58
	v_lshlrev_b32_e32 v108, 16, v54
	v_and_b32_e32 v109, 0xffff0000, v54
	v_lshlrev_b32_e32 v110, 16, v62
	v_and_b32_e32 v111, 0xffff0000, v62
	v_lshlrev_b32_e32 v58, 16, v59
	v_and_b32_e32 v59, 0xffff0000, v59
	v_lshlrev_b32_e32 v54, 16, v55
	v_and_b32_e32 v55, 0xffff0000, v55
	v_lshlrev_b32_e32 v62, 16, v63
	v_and_b32_e32 v63, 0xffff0000, v63
	s_ashr_i32 s1, s0, 31
	s_lshl_b64 s[4:5], s[0:1], 16
	s_add_u32 s4, s84, s4
	s_addc_u32 s5, s85, s5
	v_readlane_b32 s1, v254, 45
	s_add_i32 s8, s8, s1
	v_readlane_b32 s1, v254, 47
	s_add_i32 s0, s0, s94
	s_add_i32 s2, s2, s1
	s_cmpk_lt_i32 s0, 0x200
	s_waitcnt vmcnt(8)
	v_pk_fma_f32 v[136:137], v[66:67], v[122:123], v[70:71]
	v_pk_fma_f32 v[124:125], v[66:67], v[124:125], v[70:71]
	v_pk_fma_f32 v[134:135], v[66:67], v[120:121], v[70:71]
	s_waitcnt vmcnt(7)
	v_pk_fma_f32 v[136:137], v[74:75], v[120:121], v[136:137]
	v_pk_fma_f32 v[122:123], v[74:75], v[122:123], v[124:125]
	v_pk_fma_f32 v[132:133], v[66:67], v[118:119], v[70:71]
	v_pk_fma_f32 v[134:135], v[74:75], v[118:119], v[134:135]
	v_pk_fma_f32 v[130:131], v[66:67], v[116:117], v[70:71]
	v_pk_fma_f32 v[132:133], v[74:75], v[116:117], v[132:133]
	s_waitcnt vmcnt(6)
	v_pk_fma_f32 v[120:121], v[78:79], v[120:121], v[122:123]
	v_pk_fma_f32 v[122:123], v[78:79], v[118:119], v[136:137]
	v_pk_fma_f32 v[124:125], v[78:79], v[116:117], v[134:135]
	v_pk_fma_f32 v[132:133], v[78:79], v[114:115], v[132:133]
	v_pk_fma_f32 v[128:129], v[66:67], v[114:115], v[70:71]
	v_pk_fma_f32 v[130:131], v[74:75], v[114:115], v[130:131]
	s_waitcnt vmcnt(5)
	v_pk_fma_f32 v[116:117], v[82:83], v[116:117], v[122:123]
	v_pk_fma_f32 v[118:119], v[82:83], v[118:119], v[120:121]
	v_mul_f32_e32 v8, 0xbfb8aa3b, v116
	v_mul_f32_e32 v12, 0xbfb8aa3b, v117
	v_exp_f32_e32 v8, v8
	v_exp_f32_e32 v12, v12
	v_mul_f32_e32 v0, 0xbfb8aa3b, v118
	v_exp_f32_e32 v0, v0
	v_add_f32_e32 v8, 1.0, v8
	v_add_f32_e32 v12, 1.0, v12
	v_rcp_f32_e32 v122, v8
	v_rcp_f32_e32 v123, v12
	v_mul_f32_e32 v4, 0xbfb8aa3b, v119
	v_exp_f32_e32 v4, v4
	v_add_f32_e32 v0, 1.0, v0
	v_pk_mul_f32 v[116:117], v[116:117], v[122:123]
	v_rcp_f32_e32 v120, v0
	v_cvt_pk_bf16_f32 v0, v116, v117
	v_pk_fma_f32 v[116:117], v[82:83], v[112:113], v[132:133]
	v_pk_fma_f32 v[114:115], v[82:83], v[114:115], v[124:125]
	v_add_f32_e32 v4, 1.0, v4
	v_mul_f32_e32 v8, 0xbfb8aa3b, v116
	v_mul_f32_e32 v16, 0xbfb8aa3b, v114
	v_mul_f32_e32 v20, 0xbfb8aa3b, v115
	v_rcp_f32_e32 v121, v4
	v_exp_f32_e32 v8, v8
	v_mul_f32_e32 v12, 0xbfb8aa3b, v117
	v_exp_f32_e32 v16, v16
	v_exp_f32_e32 v20, v20
	v_exp_f32_e32 v12, v12
	v_pk_fma_f32 v[126:127], v[66:67], v[112:113], v[70:71]
	v_pk_fma_f32 v[128:129], v[74:75], v[112:113], v[128:129]
	v_pk_fma_f32 v[112:113], v[78:79], v[112:113], v[130:131]
	v_pk_mul_f32 v[118:119], v[118:119], v[120:121]
	v_add_f32_e32 v8, 1.0, v8
	v_pk_fma_f32 v[112:113], v[82:83], v[102:103], v[112:113]
	v_add_f32_e32 v16, 1.0, v16
	v_add_f32_e32 v20, 1.0, v20
	v_cvt_pk_bf16_f32 v4, v118, v119
	v_rcp_f32_e32 v118, v8
	v_add_f32_e32 v8, 1.0, v12
	v_mul_f32_e32 v12, 0xbfb8aa3b, v112
	v_rcp_f32_e32 v124, v16
	v_rcp_f32_e32 v125, v20
	v_exp_f32_e32 v12, v12
	v_mul_f32_e32 v16, 0xbfb8aa3b, v113
	v_exp_f32_e32 v16, v16
	v_rcp_f32_e32 v119, v8
	v_pk_mul_f32 v[114:115], v[114:115], v[124:125]
	v_add_f32_e32 v8, 1.0, v12
	v_rcp_f32_e32 v120, v8
	v_add_f32_e32 v8, 1.0, v16
	v_cvt_pk_bf16_f32 v12, v114, v115
	v_pk_mul_f32 v[114:115], v[116:117], v[118:119]
	v_rcp_f32_e32 v121, v8
	v_cvt_pk_bf16_f32 v8, v114, v115
	v_pk_fma_f32 v[114:115], v[78:79], v[102:103], v[128:129]
	v_pk_fma_f32 v[116:117], v[74:75], v[102:103], v[126:127]
	v_pk_fma_f32 v[114:115], v[82:83], v[104:105], v[114:115]
	v_pk_mul_f32 v[112:113], v[112:113], v[120:121]
	v_mul_f32_e32 v16, 0xbfb8aa3b, v114
	v_exp_f32_e32 v20, v16
	v_mul_f32_e32 v16, 0xbfb8aa3b, v115
	v_exp_f32_e32 v24, v16
	v_pk_fma_f32 v[116:117], v[78:79], v[104:105], v[116:117]
; __device__ __forceinline__ float blo(unsigned w) { return __uint_as_float(w << 16); }
; __device__ __forceinline__ float bhi(unsigned w) { return __uint_as_float(w & 0xffff0000u); }
; __device__ __forceinline__ float silu(float x) { return x * sigm(x); }
; __device__ __forceinline__ unsigned cvtpk(float lo, float hi) { return pg8::cvt_pk_bf16(lo, hi); }
; __device__ __forceinline__ void cv_phase(unsigned char* ws, int layer, int tid) {
;     ...
;         for (int wi = 0; wi < 4; ++wi) {
;             float w0[4], w1[4];
; #pragma unroll
;             for (int k = 0; k < 4; ++k) { w0[k] = wq[k][wi >> 1][2 * (wi & 1)]; w1[k] = wq[k][wi >> 1][2 * (wi & 1) + 1]; }
;             const float b0 = bq[wi >> 1][2 * (wi & 1)], b1 = bq[wi >> 1][2 * (wi & 1) + 1];
;             float lo[11], hi[11];
; #pragma unroll
;             for (int i = 0; i < 11; ++i) { lo[i] = blo(raw[i][wi]); hi[i] = bhi(raw[i][wi]); }
;             float t0[8], t1[8];
; #pragma unroll
;             for (int j = 0; j < 8; ++j) {
;                 t0[j] = silu(b0 + w0[0] * lo[j] + w0[1] * lo[j + 1] + w0[2] * lo[j + 2] + w0[3] * lo[j + 3]);
;                 t1[j] = silu(b1 + w1[0] * hi[j] + w1[1] * hi[j + 1] + w1[2] * hi[j + 2] + w1[3] * hi[j + 3]);
;                 nat[j][wi] = cvtpk(t0[j], t1[j]);
;             }
;         }
	v_add_f32_e32 v20, 1.0, v20
	v_cvt_pk_bf16_f32 v16, v112, v113
	v_rcp_f32_e32 v112, v20
	v_add_f32_e32 v20, 1.0, v24
	v_pk_fma_f32 v[116:117], v[82:83], v[108:109], v[116:117]
	v_rcp_f32_e32 v113, v20
	v_mul_f32_e32 v20, 0xbfb8aa3b, v116
	v_exp_f32_e32 v20, v20
	v_mul_f32_e32 v24, 0xbfb8aa3b, v117
	v_exp_f32_e32 v24, v24
	v_pk_fma_f32 v[66:67], v[66:67], v[102:103], v[70:71]
	v_add_f32_e32 v20, 1.0, v20
	v_pk_fma_f32 v[66:67], v[74:75], v[104:105], v[66:67]
	v_pk_mul_f32 v[112:113], v[114:115], v[112:113]
	v_pk_fma_f32 v[66:67], v[78:79], v[108:109], v[66:67]
	v_rcp_f32_e32 v114, v20
	v_add_f32_e32 v20, 1.0, v24
	v_pk_fma_f32 v[66:67], v[82:83], v[110:111], v[66:67]
	v_rcp_f32_e32 v115, v20
	v_mul_f32_e32 v24, 0xbfb8aa3b, v66
	v_exp_f32_e32 v24, v24
	v_lshlrev_b32_e32 v102, 16, v1
	v_and_b32_e32 v103, 0xffff0000, v1
	v_lshlrev_b32_e32 v82, 16, v5
	v_and_b32_e32 v83, 0xffff0000, v5
	v_pk_fma_f32 v[102:103], v[68:69], v[102:103], v[72:73]
	v_pk_mul_f32 v[74:75], v[116:117], v[114:115]
	v_lshlrev_b32_e32 v78, 16, v9
	v_and_b32_e32 v79, 0xffff0000, v9
	v_pk_fma_f32 v[102:103], v[76:77], v[82:83], v[102:103]
	v_add_f32_e32 v20, 1.0, v24
	v_cvt_pk_bf16_f32 v24, v74, v75
	v_lshlrev_b32_e32 v74, 16, v13
	v_and_b32_e32 v75, 0xffff0000, v13
	v_pk_fma_f32 v[102:103], v[80:81], v[78:79], v[102:103]
	v_pk_fma_f32 v[82:83], v[68:69], v[82:83], v[72:73]
	v_pk_fma_f32 v[102:103], v[84:85], v[74:75], v[102:103]
	v_pk_fma_f32 v[82:83], v[76:77], v[78:79], v[82:83]
	v_mul_f32_e32 v1, 0xbfb8aa3b, v102
	v_exp_f32_e32 v1, v1
	v_mul_f32_e32 v5, 0xbfb8aa3b, v103
	v_exp_f32_e32 v5, v5
	v_lshlrev_b32_e32 v104, 16, v17
	v_add_f32_e32 v1, 1.0, v1
	v_and_b32_e32 v105, 0xffff0000, v17
	v_pk_fma_f32 v[82:83], v[80:81], v[74:75], v[82:83]
	v_rcp_f32_e32 v108, v1
	v_add_f32_e32 v1, 1.0, v5
	v_pk_fma_f32 v[82:83], v[84:85], v[104:105], v[82:83]
	v_rcp_f32_e32 v109, v1
	v_mul_f32_e32 v1, 0xbfb8aa3b, v82
	v_exp_f32_e32 v1, v1
	v_mul_f32_e32 v5, 0xbfb8aa3b, v83
	v_mul_f32_e32 v28, 0xbfb8aa3b, v67
	v_exp_f32_e32 v5, v5
	v_exp_f32_e32 v28, v28
	v_pk_fma_f32 v[78:79], v[68:69], v[78:79], v[72:73]
	v_add_f32_e32 v1, 1.0, v1
	v_pk_fma_f32 v[78:79], v[76:77], v[74:75], v[78:79]
	v_lshlrev_b32_e32 v110, 16, v21
	v_and_b32_e32 v111, 0xffff0000, v21
	v_pk_fma_f32 v[78:79], v[80:81], v[104:105], v[78:79]
	v_pk_mul_f32 v[102:103], v[102:103], v[108:109]
	v_rcp_f32_e32 v108, v1
	v_add_f32_e32 v1, 1.0, v5
	v_pk_fma_f32 v[78:79], v[84:85], v[110:111], v[78:79]
	v_rcp_f32_e32 v70, v20
	v_add_f32_e32 v20, 1.0, v28
	v_rcp_f32_e32 v109, v1
	v_mul_f32_e32 v1, 0xbfb8aa3b, v78
	v_rcp_f32_e32 v71, v20
	v_exp_f32_e32 v9, v1
	v_mul_f32_e32 v1, 0xbfb8aa3b, v79
	v_exp_f32_e32 v13, v1
	v_pk_fma_f32 v[74:75], v[68:69], v[74:75], v[72:73]
	v_pk_mul_f32 v[66:67], v[66:67], v[70:71]
	v_pk_fma_f32 v[74:75], v[76:77], v[104:105], v[74:75]
	v_lshlrev_b32_e32 v70, 16, v25
	v_and_b32_e32 v71, 0xffff0000, v25
	v_pk_mul_f32 v[82:83], v[82:83], v[108:109]
	v_add_f32_e32 v9, 1.0, v9
	v_pk_fma_f32 v[74:75], v[80:81], v[110:111], v[74:75]
	v_cvt_pk_bf16_f32 v1, v82, v83
	v_rcp_f32_e32 v82, v9
	v_add_f32_e32 v9, 1.0, v13
	v_pk_fma_f32 v[74:75], v[84:85], v[70:71], v[74:75]
	v_rcp_f32_e32 v83, v9
	v_mul_f32_e32 v9, 0xbfb8aa3b, v74
	v_exp_f32_e32 v9, v9
	v_mul_f32_e32 v13, 0xbfb8aa3b, v75
	v_cvt_pk_bf16_f32 v5, v102, v103
	v_pk_fma_f32 v[102:103], v[68:69], v[104:105], v[72:73]
	v_exp_f32_e32 v13, v13
	v_pk_fma_f32 v[102:103], v[76:77], v[110:111], v[102:103]
	v_cvt_pk_bf16_f32 v20, v66, v67
	v_lshlrev_b32_e32 v66, 16, v29
	v_and_b32_e32 v67, 0xffff0000, v29
	v_pk_fma_f32 v[102:103], v[80:81], v[70:71], v[102:103]
	v_add_f32_e32 v9, 1.0, v9
	v_pk_fma_f32 v[102:103], v[84:85], v[66:67], v[102:103]
	v_pk_mul_f32 v[78:79], v[78:79], v[82:83]
	v_rcp_f32_e32 v82, v9
	v_add_f32_e32 v9, 1.0, v13
	v_mul_f32_e32 v13, 0xbfb8aa3b, v102
	v_exp_f32_e32 v13, v13
	v_mul_f32_e32 v17, 0xbfb8aa3b, v103
	v_exp_f32_e32 v17, v17
	v_rcp_f32_e32 v83, v9
	v_add_f32_e32 v9, 1.0, v13
	v_cvt_pk_bf16_f32 v13, v78, v79
	v_pk_fma_f32 v[78:79], v[68:69], v[110:111], v[72:73]
	v_rcp_f32_e32 v104, v9
	v_pk_fma_f32 v[78:79], v[76:77], v[70:71], v[78:79]
	v_add_f32_e32 v9, 1.0, v17
	v_pk_fma_f32 v[78:79], v[80:81], v[66:67], v[78:79]
	v_rcp_f32_e32 v105, v9
	v_pk_fma_f32 v[78:79], v[84:85], v[58:59], v[78:79]
	v_pk_fma_f32 v[70:71], v[68:69], v[70:71], v[72:73]
	v_mul_f32_e32 v17, 0xbfb8aa3b, v78
	v_exp_f32_e32 v21, v17
	v_mul_f32_e32 v17, 0xbfb8aa3b, v79
	v_pk_fma_f32 v[70:71], v[76:77], v[66:67], v[70:71]
	v_pk_fma_f32 v[66:67], v[68:69], v[66:67], v[72:73]
	v_pk_mul_f32 v[74:75], v[74:75], v[82:83]
	v_exp_f32_e32 v25, v17
	v_pk_fma_f32 v[70:71], v[80:81], v[58:59], v[70:71]
	v_pk_fma_f32 v[58:59], v[76:77], v[58:59], v[66:67]
	v_lshlrev_b32_e32 v110, 16, v2
	v_and_b32_e32 v111, 0xffff0000, v2
	v_cvt_pk_bf16_f32 v9, v74, v75
	v_pk_mul_f32 v[74:75], v[102:103], v[104:105]
	v_pk_fma_f32 v[70:71], v[84:85], v[54:55], v[70:71]
	v_pk_fma_f32 v[54:55], v[80:81], v[54:55], v[58:59]
	v_lshlrev_b32_e32 v104, 16, v6
	v_and_b32_e32 v105, 0xffff0000, v6
	s_waitcnt vmcnt(3)
	v_pk_fma_f32 v[110:111], v[34:35], v[110:111], v[38:39]
	v_pk_fma_f32 v[54:55], v[84:85], v[62:63], v[54:55]
	v_lshlrev_b32_e32 v84, 16, v10
	v_and_b32_e32 v85, 0xffff0000, v10
	v_pk_fma_f32 v[108:109], v[34:35], v[104:105], v[38:39]
	s_waitcnt vmcnt(2)
	v_pk_fma_f32 v[104:105], v[42:43], v[104:105], v[110:111]
	v_add_f32_e32 v21, 1.0, v21
	v_lshlrev_b32_e32 v80, 16, v14
	v_and_b32_e32 v81, 0xffff0000, v14
	s_waitcnt vmcnt(1)
	v_pk_fma_f32 v[104:105], v[46:47], v[84:85], v[104:105]
	v_cvt_pk_bf16_f32 v17, v74, v75
	v_rcp_f32_e32 v74, v21
	v_add_f32_e32 v21, 1.0, v25
	s_waitcnt vmcnt(0)
; __device__ __forceinline__ float blo(unsigned w) { return __uint_as_float(w << 16); }
; __device__ __forceinline__ float bhi(unsigned w) { return __uint_as_float(w & 0xffff0000u); }
; __device__ __forceinline__ float silu(float x) { return x * sigm(x); }
; __device__ __forceinline__ unsigned cvtpk(float lo, float hi) { return pg8::cvt_pk_bf16(lo, hi); }
; __device__ __forceinline__ void cv_phase(unsigned char* ws, int layer, int tid) {
;     ...
;         for (int wi = 0; wi < 4; ++wi) {
;             float w0[4], w1[4];
; #pragma unroll
;             for (int k = 0; k < 4; ++k) { w0[k] = wq[k][wi >> 1][2 * (wi & 1)]; w1[k] = wq[k][wi >> 1][2 * (wi & 1) + 1]; }
;             const float b0 = bq[wi >> 1][2 * (wi & 1)], b1 = bq[wi >> 1][2 * (wi & 1) + 1];
;             float lo[11], hi[11];
; #pragma unroll
;             for (int i = 0; i < 11; ++i) { lo[i] = blo(raw[i][wi]); hi[i] = bhi(raw[i][wi]); }
;             float t0[8], t1[8];
; #pragma unroll
;             for (int j = 0; j < 8; ++j) {
;                 t0[j] = silu(b0 + w0[0] * lo[j] + w0[1] * lo[j + 1] + w0[2] * lo[j + 2] + w0[3] * lo[j + 3]);
;                 t1[j] = silu(b1 + w1[0] * hi[j] + w1[1] * hi[j + 1] + w1[2] * hi[j + 2] + w1[3] * hi[j + 3]);
;                 nat[j][wi] = cvtpk(t0[j], t1[j]);
;             }
;         }
	v_pk_fma_f32 v[104:105], v[50:51], v[80:81], v[104:105]
	v_rcp_f32_e32 v75, v21
	v_mul_f32_e32 v21, 0xbfb8aa3b, v70
	v_mul_f32_e32 v2, 0xbfb8aa3b, v104
	v_exp_f32_e32 v21, v21
	v_mul_f32_e32 v25, 0xbfb8aa3b, v71
	v_exp_f32_e32 v2, v2
	v_mul_f32_e32 v6, 0xbfb8aa3b, v105
	v_exp_f32_e32 v25, v25
	v_exp_f32_e32 v6, v6
	v_pk_fma_f32 v[102:103], v[34:35], v[84:85], v[38:39]
	v_pk_fma_f32 v[84:85], v[42:43], v[84:85], v[108:109]
	v_lshlrev_b32_e32 v76, 16, v18
	v_and_b32_e32 v77, 0xffff0000, v18
	v_pk_fma_f32 v[84:85], v[46:47], v[80:81], v[84:85]
	v_add_f32_e32 v21, 1.0, v21
	v_add_f32_e32 v2, 1.0, v2
	v_pk_fma_f32 v[84:85], v[50:51], v[76:77], v[84:85]
	v_pk_mul_f32 v[74:75], v[78:79], v[74:75]
	v_rcp_f32_e32 v78, v21
	v_add_f32_e32 v21, 1.0, v25
	v_rcp_f32_e32 v108, v2
	v_add_f32_e32 v2, 1.0, v6
	v_mul_f32_e32 v6, 0xbfb8aa3b, v84
	v_rcp_f32_e32 v79, v21
	v_exp_f32_e32 v6, v6
	v_mul_f32_e32 v10, 0xbfb8aa3b, v85
	v_exp_f32_e32 v10, v10
	v_pk_fma_f32 v[82:83], v[34:35], v[80:81], v[38:39]
	v_pk_fma_f32 v[80:81], v[42:43], v[80:81], v[102:103]
	v_pk_mul_f32 v[62:63], v[70:71], v[78:79]
	v_lshlrev_b32_e32 v72, 16, v22
	v_and_b32_e32 v73, 0xffff0000, v22
	v_pk_fma_f32 v[78:79], v[34:35], v[76:77], v[38:39]
	v_pk_fma_f32 v[82:83], v[42:43], v[76:77], v[82:83]
	v_rcp_f32_e32 v109, v2
	v_add_f32_e32 v2, 1.0, v6
	v_pk_fma_f32 v[76:77], v[46:47], v[76:77], v[80:81]
	v_mul_f32_e32 v25, 0xbfb8aa3b, v54
	v_rcp_f32_e32 v110, v2
	v_add_f32_e32 v2, 1.0, v10
	v_pk_fma_f32 v[76:77], v[50:51], v[72:73], v[76:77]
	v_exp_f32_e32 v25, v25
	v_mul_f32_e32 v29, 0xbfb8aa3b, v55
	v_rcp_f32_e32 v111, v2
	v_mul_f32_e32 v2, 0xbfb8aa3b, v76
	v_exp_f32_e32 v29, v29
	v_exp_f32_e32 v10, v2
	v_mul_f32_e32 v2, 0xbfb8aa3b, v77
	v_exp_f32_e32 v14, v2
	v_add_f32_e32 v21, 1.0, v25
	v_rcp_f32_e32 v58, v21
	v_add_f32_e32 v21, 1.0, v29
	v_cvt_pk_bf16_f32 v29, v74, v75
	v_lshlrev_b32_e32 v68, 16, v26
	v_and_b32_e32 v69, 0xffff0000, v26
	v_pk_fma_f32 v[74:75], v[34:35], v[72:73], v[38:39]
	v_pk_fma_f32 v[78:79], v[42:43], v[72:73], v[78:79]
	v_add_f32_e32 v10, 1.0, v10
	v_pk_fma_f32 v[72:73], v[46:47], v[72:73], v[82:83]
	v_rcp_f32_e32 v59, v21
	v_rcp_f32_e32 v80, v10
	v_add_f32_e32 v10, 1.0, v14
	v_pk_fma_f32 v[72:73], v[50:51], v[68:69], v[72:73]
	v_rcp_f32_e32 v81, v10
	v_mul_f32_e32 v10, 0xbfb8aa3b, v72
	v_exp_f32_e32 v10, v10
	v_mul_f32_e32 v14, 0xbfb8aa3b, v73
	v_exp_f32_e32 v14, v14
	v_pk_mul_f32 v[54:55], v[54:55], v[58:59]
	v_pk_fma_f32 v[70:71], v[34:35], v[68:69], v[38:39]
	v_cvt_pk_bf16_f32 v21, v54, v55
	v_lshlrev_b32_e32 v54, 16, v30
	v_and_b32_e32 v55, 0xffff0000, v30
	v_pk_fma_f32 v[74:75], v[42:43], v[68:69], v[74:75]
	v_pk_fma_f32 v[68:69], v[46:47], v[68:69], v[78:79]
	v_add_f32_e32 v10, 1.0, v10
	v_pk_fma_f32 v[68:69], v[50:51], v[54:55], v[68:69]
	v_pk_mul_f32 v[76:77], v[76:77], v[80:81]
	v_rcp_f32_e32 v80, v10
	v_add_f32_e32 v10, 1.0, v14
	v_mul_f32_e32 v14, 0xbfb8aa3b, v68
	v_exp_f32_e32 v14, v14
	v_mul_f32_e32 v18, 0xbfb8aa3b, v69
	v_exp_f32_e32 v18, v18
	v_rcp_f32_e32 v81, v10
	v_add_f32_e32 v10, 1.0, v14
	v_rcp_f32_e32 v78, v10
	v_add_f32_e32 v10, 1.0, v18
	v_pk_mul_f32 v[72:73], v[72:73], v[80:81]
	v_lshlrev_b32_e32 v58, 16, v60
	v_and_b32_e32 v59, 0xffff0000, v60
	v_rcp_f32_e32 v79, v10
	v_cvt_pk_bf16_f32 v10, v72, v73
	v_pk_fma_f32 v[72:73], v[46:47], v[54:55], v[74:75]
	v_pk_fma_f32 v[70:71], v[42:43], v[54:55], v[70:71]
	v_pk_fma_f32 v[72:73], v[50:51], v[58:59], v[72:73]
	v_cvt_pk_bf16_f32 v25, v62, v63
	v_mul_f32_e32 v18, 0xbfb8aa3b, v72
	v_exp_f32_e32 v22, v18
	v_mul_f32_e32 v18, 0xbfb8aa3b, v73
	v_exp_f32_e32 v26, v18
	v_lshlrev_b32_e32 v62, 16, v56
	v_and_b32_e32 v63, 0xffff0000, v56
	v_pk_mul_f32 v[68:69], v[68:69], v[78:79]
	v_add_f32_e32 v22, 1.0, v22
	v_pk_fma_f32 v[70:71], v[46:47], v[58:59], v[70:71]
	v_cvt_pk_bf16_f32 v18, v68, v69
	v_rcp_f32_e32 v68, v22
	v_add_f32_e32 v22, 1.0, v26
	v_pk_fma_f32 v[70:71], v[50:51], v[62:63], v[70:71]
	v_rcp_f32_e32 v69, v22
	v_mul_f32_e32 v22, 0xbfb8aa3b, v70
	v_exp_f32_e32 v22, v22
	v_mul_f32_e32 v26, 0xbfb8aa3b, v71
	v_exp_f32_e32 v26, v26
	v_pk_fma_f32 v[34:35], v[34:35], v[54:55], v[38:39]
	v_lshlrev_b32_e32 v66, 16, v64
	v_pk_fma_f32 v[34:35], v[42:43], v[58:59], v[34:35]
	v_and_b32_e32 v67, 0xffff0000, v64
	v_pk_fma_f32 v[34:35], v[46:47], v[62:63], v[34:35]
	v_add_f32_e32 v22, 1.0, v22
	v_pk_fma_f32 v[34:35], v[50:51], v[66:67], v[34:35]
	v_pk_mul_f32 v[68:69], v[72:73], v[68:69]
	v_rcp_f32_e32 v72, v22
	v_add_f32_e32 v22, 1.0, v26
	v_mul_f32_e32 v26, 0xbfb8aa3b, v34
	v_exp_f32_e32 v26, v26
	v_mul_f32_e32 v30, 0xbfb8aa3b, v35
	v_rcp_f32_e32 v73, v22
	v_exp_f32_e32 v30, v30
	v_cvt_pk_bf16_f32 v14, v76, v77
	v_lshlrev_b32_e32 v76, 16, v3
	v_and_b32_e32 v77, 0xffff0000, v3
	v_add_f32_e32 v22, 1.0, v26
	v_pk_mul_f32 v[42:43], v[70:71], v[72:73]
	v_lshlrev_b32_e32 v72, 16, v7
	v_and_b32_e32 v73, 0xffff0000, v7
	v_pk_fma_f32 v[76:77], v[36:37], v[76:77], v[40:41]
	v_rcp_f32_e32 v38, v22
	v_add_f32_e32 v22, 1.0, v30
	v_cvt_pk_bf16_f32 v30, v68, v69
	v_lshlrev_b32_e32 v68, 16, v11
	v_and_b32_e32 v69, 0xffff0000, v11
	v_pk_fma_f32 v[74:75], v[36:37], v[72:73], v[40:41]
	v_pk_fma_f32 v[72:73], v[44:45], v[72:73], v[76:77]
	v_lshlrev_b32_e32 v46, 16, v65
	v_and_b32_e32 v47, 0xffff0000, v65
	v_lshlrev_b32_e32 v64, 16, v15
	v_and_b32_e32 v65, 0xffff0000, v15
	v_pk_fma_f32 v[72:73], v[48:49], v[68:69], v[72:73]
	v_rcp_f32_e32 v39, v22
; __device__ __forceinline__ float blo(unsigned w) { return __uint_as_float(w << 16); }
; __device__ __forceinline__ float bhi(unsigned w) { return __uint_as_float(w & 0xffff0000u); }
; __device__ __forceinline__ float silu(float x) { return x * sigm(x); }
; __device__ __forceinline__ int offb(int row, int chunk) { return row * 256 + ((chunk ^ swb(row)) << 4); }
; __device__ __forceinline__ int tile_off(int row, int chunk) { return row * 256 + ((chunk ^ swz(row)) << 4); }
; __device__ __forceinline__ unsigned cvtpk(float lo, float hi) { return pg8::cvt_pk_bf16(lo, hi); }
; __device__ __forceinline__ void cv_phase(unsigned char* ws, int layer, int tid) {
;     ...
;         for (int wi = 0; wi < 4; ++wi) {
;             float w0[4], w1[4];
; #pragma unroll
;             for (int k = 0; k < 4; ++k) { w0[k] = wq[k][wi >> 1][2 * (wi & 1)]; w1[k] = wq[k][wi >> 1][2 * (wi & 1) + 1]; }
;             const float b0 = bq[wi >> 1][2 * (wi & 1)], b1 = bq[wi >> 1][2 * (wi & 1) + 1];
;             float lo[11], hi[11];
; #pragma unroll
;             for (int i = 0; i < 11; ++i) { lo[i] = blo(raw[i][wi]); hi[i] = bhi(raw[i][wi]); }
;             float t0[8], t1[8];
; #pragma unroll
;             for (int j = 0; j < 8; ++j) {
;                 t0[j] = silu(b0 + w0[0] * lo[j] + w0[1] * lo[j + 1] + w0[2] * lo[j + 2] + w0[3] * lo[j + 3]);
;                 t1[j] = silu(b1 + w1[0] * hi[j] + w1[1] * hi[j + 1] + w1[2] * hi[j + 2] + w1[3] * hi[j + 3]);
;                 nat[j][wi] = cvtpk(t0[j], t1[j]);
;             }
;         }
;         unsigned char* im = img + (size_t)tile * IMG_BYTES;
; #pragma unroll
;         for (int j = 0; j < 8; ++j) *(v4u*)(im + (isC ? tile_off(8 * tgb + j, vcl) : 32768 + offb(8 * tgb + j, vcl))) = nat[j];
	v_pk_fma_f32 v[72:73], v[52:53], v[64:65], v[72:73]
	v_pk_fma_f32 v[70:71], v[36:37], v[68:69], v[40:41]
	v_mul_f32_e32 v3, 0xbfb8aa3b, v72
	v_exp_f32_e32 v3, v3
	v_mul_f32_e32 v7, 0xbfb8aa3b, v73
	v_exp_f32_e32 v7, v7
	v_pk_fma_f32 v[68:69], v[44:45], v[68:69], v[74:75]
	v_pk_mul_f32 v[34:35], v[34:35], v[38:39]
	v_lshlrev_b32_e32 v38, 16, v61
	v_and_b32_e32 v39, 0xffff0000, v61
	v_lshlrev_b32_e32 v60, 16, v19
	v_and_b32_e32 v61, 0xffff0000, v19
	v_pk_fma_f32 v[68:69], v[48:49], v[64:65], v[68:69]
	v_add_f32_e32 v3, 1.0, v3
	v_pk_fma_f32 v[68:69], v[52:53], v[60:61], v[68:69]
	v_rcp_f32_e32 v74, v3
	v_add_f32_e32 v3, 1.0, v7
	v_mul_f32_e32 v7, 0xbfb8aa3b, v68
	v_exp_f32_e32 v7, v7
	v_mul_f32_e32 v11, 0xbfb8aa3b, v69
	v_exp_f32_e32 v11, v11
	v_pk_fma_f32 v[66:67], v[36:37], v[64:65], v[40:41]
	v_pk_fma_f32 v[64:65], v[44:45], v[64:65], v[70:71]
	v_cvt_pk_bf16_f32 v26, v42, v43
	v_lshlrev_b32_e32 v42, 16, v57
	v_and_b32_e32 v43, 0xffff0000, v57
	v_lshlrev_b32_e32 v56, 16, v23
	v_and_b32_e32 v57, 0xffff0000, v23
	v_pk_fma_f32 v[62:63], v[36:37], v[60:61], v[40:41]
	v_pk_fma_f32 v[66:67], v[44:45], v[60:61], v[66:67]
	v_rcp_f32_e32 v75, v3
	v_add_f32_e32 v3, 1.0, v7
	v_pk_fma_f32 v[60:61], v[48:49], v[60:61], v[64:65]
	v_rcp_f32_e32 v76, v3
	v_add_f32_e32 v3, 1.0, v11
	v_pk_fma_f32 v[60:61], v[52:53], v[56:57], v[60:61]
	v_rcp_f32_e32 v77, v3
	v_mul_f32_e32 v3, 0xbfb8aa3b, v60
	v_exp_f32_e32 v11, v3
	v_mul_f32_e32 v3, 0xbfb8aa3b, v61
	v_exp_f32_e32 v15, v3
	v_lshlrev_b32_e32 v50, 16, v27
	v_and_b32_e32 v51, 0xffff0000, v27
	v_pk_fma_f32 v[58:59], v[36:37], v[56:57], v[40:41]
	v_pk_fma_f32 v[62:63], v[44:45], v[56:57], v[62:63]
	v_add_f32_e32 v11, 1.0, v11
	v_pk_fma_f32 v[56:57], v[48:49], v[56:57], v[66:67]
	v_rcp_f32_e32 v64, v11
	v_add_f32_e32 v11, 1.0, v15
	v_pk_fma_f32 v[56:57], v[52:53], v[50:51], v[56:57]
	v_rcp_f32_e32 v65, v11
	v_mul_f32_e32 v11, 0xbfb8aa3b, v56
	v_exp_f32_e32 v11, v11
	v_mul_f32_e32 v15, 0xbfb8aa3b, v57
	v_exp_f32_e32 v15, v15
	v_cvt_pk_bf16_f32 v22, v34, v35
	v_lshlrev_b32_e32 v34, 16, v31
	v_and_b32_e32 v35, 0xffff0000, v31
	v_pk_fma_f32 v[54:55], v[36:37], v[50:51], v[40:41]
	v_pk_fma_f32 v[58:59], v[44:45], v[50:51], v[58:59]
	v_pk_fma_f32 v[50:51], v[48:49], v[50:51], v[62:63]
	v_add_f32_e32 v11, 1.0, v11
	v_pk_fma_f32 v[50:51], v[52:53], v[34:35], v[50:51]
	v_pk_mul_f32 v[60:61], v[60:61], v[64:65]
	v_rcp_f32_e32 v64, v11
	v_add_f32_e32 v11, 1.0, v15
	v_mul_f32_e32 v15, 0xbfb8aa3b, v50
	v_exp_f32_e32 v15, v15
	v_mul_f32_e32 v19, 0xbfb8aa3b, v51
	v_exp_f32_e32 v19, v19
	v_rcp_f32_e32 v65, v11
	v_add_f32_e32 v11, 1.0, v15
	v_rcp_f32_e32 v62, v11
	v_add_f32_e32 v11, 1.0, v19
	v_pk_mul_f32 v[56:57], v[56:57], v[64:65]
	v_rcp_f32_e32 v63, v11
	v_cvt_pk_bf16_f32 v11, v56, v57
	v_pk_fma_f32 v[56:57], v[48:49], v[34:35], v[58:59]
	v_pk_fma_f32 v[54:55], v[44:45], v[34:35], v[54:55]
	v_pk_fma_f32 v[56:57], v[52:53], v[38:39], v[56:57]
	v_pk_mul_f32 v[50:51], v[50:51], v[62:63]
	v_mul_f32_e32 v19, 0xbfb8aa3b, v56
	v_exp_f32_e32 v23, v19
	v_mul_f32_e32 v19, 0xbfb8aa3b, v57
	v_exp_f32_e32 v27, v19
	v_pk_fma_f32 v[54:55], v[48:49], v[38:39], v[54:55]
	v_add_f32_e32 v23, 1.0, v23
	v_cvt_pk_bf16_f32 v19, v50, v51
	v_rcp_f32_e32 v50, v23
	v_add_f32_e32 v23, 1.0, v27
	v_pk_fma_f32 v[54:55], v[52:53], v[42:43], v[54:55]
	v_rcp_f32_e32 v51, v23
	v_mul_f32_e32 v23, 0xbfb8aa3b, v54
	v_exp_f32_e32 v23, v23
	v_mul_f32_e32 v27, 0xbfb8aa3b, v55
	v_exp_f32_e32 v27, v27
	v_pk_fma_f32 v[34:35], v[36:37], v[34:35], v[40:41]
	v_add_f32_e32 v23, 1.0, v23
	v_pk_fma_f32 v[34:35], v[44:45], v[38:39], v[34:35]
	v_pk_mul_f32 v[50:51], v[56:57], v[50:51]
	v_pk_fma_f32 v[34:35], v[48:49], v[42:43], v[34:35]
	v_rcp_f32_e32 v56, v23
	v_pk_fma_f32 v[34:35], v[52:53], v[46:47], v[34:35]
	v_add_f32_e32 v23, 1.0, v27
	v_mul_f32_e32 v27, 0xbfb8aa3b, v34
	v_exp_f32_e32 v27, v27
	v_mul_f32_e32 v31, 0xbfb8aa3b, v35
	v_exp_f32_e32 v31, v31
	v_rcp_f32_e32 v57, v23
	v_add_f32_e32 v23, 1.0, v27
	v_rcp_f32_e32 v36, v23
	v_add_f32_e32 v23, 1.0, v31
	v_rcp_f32_e32 v37, v23
	v_pk_mul_f32 v[102:103], v[104:105], v[108:109]
	v_pk_mul_f32 v[70:71], v[72:73], v[74:75]
	v_cvt_pk_bf16_f32 v6, v102, v103
	v_pk_mul_f32 v[34:35], v[34:35], v[36:37]
	v_pk_mul_f32 v[84:85], v[84:85], v[110:111]
	v_cvt_pk_bf16_f32 v7, v70, v71
	v_pk_mul_f32 v[68:69], v[68:69], v[76:77]
	v_cvt_pk_bf16_f32 v23, v34, v35
	v_lshl_add_u64 v[34:35], s[4:5], 0, v[86:87]
	v_cvt_pk_bf16_f32 v2, v84, v85
	v_cvt_pk_bf16_f32 v3, v68, v69
	global_store_dwordx4 v[34:35], v[4:7], off sc1
	v_cvt_pk_bf16_f32 v15, v60, v61
	v_cvt_pk_bf16_f32 v28, v112, v113
	v_lshl_add_u64 v[4:5], s[4:5], 0, v[88:89]
	global_store_dwordx4 v[4:5], v[0:3], off sc1
	v_cvt_pk_bf16_f32 v31, v50, v51
	v_pk_mul_f32 v[38:39], v[54:55], v[56:57]
	v_lshl_add_u64 v[0:1], s[4:5], 0, v[90:91]
	global_store_dwordx4 v[0:1], v[12:15], off sc1
	v_lshl_add_u64 v[0:1], s[4:5], 0, v[92:93]
	global_store_dwordx4 v[0:1], v[8:11], off sc1
	v_lshl_add_u64 v[0:1], s[4:5], 0, v[94:95]
	global_store_dwordx4 v[0:1], v[16:19], off sc1
	v_lshl_add_u64 v[0:1], s[4:5], 0, v[96:97]
	v_cvt_pk_bf16_f32 v27, v38, v39
	global_store_dwordx4 v[0:1], v[28:31], off sc1
	v_lshl_add_u64 v[0:1], s[4:5], 0, v[98:99]
	global_store_dwordx4 v[0:1], v[24:27], off sc1
	v_lshl_add_u64 v[0:1], s[4:5], 0, v[100:101]
	global_store_dwordx4 v[0:1], v[20:23], off sc1
	s_cbranch_scc0 .LBB0_513

; __device__ __forceinline__ unsigned pk2(float lo, float hi) { return pg8::cvt_pk_bf16(lo, hi); }
; __device__ __forceinline__ float blo(unsigned w) { return __uint_as_float(w << 16); }
; __device__ __forceinline__ float bhi(unsigned w) { return __uint_as_float(w & 0xffff0000u); }
; __device__ __forceinline__ void n2_phase(unsigned char* ws, int layer, int gw, int NGW, int lane) {
;     ...
;             for (int rr = 0; rr < 4; ++rr) {
;                 const v4u cv = *(const v4u*)(proj + (size_t)(r0 + rr) * NP + PC_SCC + c);
;                 float a[8];
; #pragma unroll
;                 for (int j = 0; j < 8; ++j) a[j] = wk[0][j] * pr[rr][j] + wk[1][j] * pr[rr + 1][j] + wk[2][j] * pr[rr + 2][j];
;                 v4u o; o.x = pk2(blo(cv.x) * a[0], bhi(cv.x) * a[1]); o.y = pk2(blo(cv.y) * a[2], bhi(cv.y) * a[3]); o.z = pk2(blo(cv.z) * a[4], bhi(cv.z) * a[5]); o.w = pk2(blo(cv.w) * a[6], bhi(cv.w) * a[7]);
;                 *(v4u*)(ysc + (size_t)(r0 + rr) * D + c) = o;
;             }
.LBB0_756:
	v_add_co_u32_e32 v104, vcc, s3, v104
	s_waitcnt vmcnt(3)
	v_pk_mul_f32 v[114:115], v[18:19], v[72:73]
	v_addc_co_u32_e32 v105, vcc, 0, v105, vcc
	v_mov_b32_e32 v110, v168
	v_mov_b32_e32 v111, v169
	v_mov_b32_e32 v112, v170
	v_mov_b32_e32 v113, v171
	v_pk_mul_f32 v[104:105], v[16:17], v[78:79]
	v_pk_fma_f32 v[86:87], v[14:15], v[86:87], v[114:115]
	v_pk_fma_f32 v[84:85], v[12:13], v[84:85], v[104:105]
	s_waitcnt vmcnt(2)
	v_pk_fma_f32 v[86:87], v[22:23], v[62:63], v[86:87]
	v_pk_fma_f32 v[84:85], v[20:21], v[66:67], v[84:85]
	v_pk_mul_f32 v[116:117], v[4:5], v[68:69]
	v_pk_mul_f32 v[118:119], v[6:7], v[56:57]
	s_mov_b64 s[24:25], 0x800
	v_lshl_add_u64 v[48:49], v[48:49], 0, s[24:25]
	v_lshl_add_u64 v[36:37], v[36:37], 0, s[62:63]
	v_lshl_add_u64 v[38:39], v[38:39], 0, s[62:63]
	v_lshl_add_u64 v[40:41], v[40:41], 0, s[62:63]
	v_lshl_add_u64 v[42:43], v[42:43], 0, s[62:63]
	v_lshl_add_u64 v[44:45], v[44:45], 0, s[62:63]
	v_lshl_add_u64 v[46:47], v[46:47], 0, s[62:63]
	s_waitcnt vmcnt(0)
	v_lshlrev_b32_e32 v104, 16, v110
	v_and_b32_e32 v105, 0xffff0000, v110
	v_pk_mul_f32 v[84:85], v[84:85], v[104:105]
	v_lshlrev_b32_e32 v104, 16, v111
	v_and_b32_e32 v105, 0xffff0000, v111
	v_pk_mul_f32 v[86:87], v[86:87], v[104:105]
	v_cvt_pk_bf16_f32 v84, v84, v85
	v_cvt_pk_bf16_f32 v85, v86, v87
	v_pk_fma_f32 v[86:87], v[0:1], v[88:89], v[116:117]
	v_lshlrev_b32_e32 v88, 16, v112
	v_pk_fma_f32 v[86:87], v[8:9], v[60:61], v[86:87]
	v_and_b32_e32 v89, 0xffff0000, v112
	v_pk_mul_f32 v[86:87], v[86:87], v[88:89]
	v_pk_fma_f32 v[88:89], v[2:3], v[90:91], v[118:119]
	v_lshlrev_b32_e32 v90, 16, v113
	v_pk_fma_f32 v[88:89], v[10:11], v[64:65], v[88:89]
	v_and_b32_e32 v91, 0xffff0000, v113
	v_pk_mul_f32 v[88:89], v[88:89], v[90:91]
	v_cvt_pk_bf16_f32 v86, v86, v87
	v_cvt_pk_bf16_f32 v87, v88, v89
	v_lshl_add_u64 v[88:89], v[34:35], 0, s[0:1]
	global_store_dwordx4 v[88:89], v[84:87], off sc1
	v_pk_mul_f32 v[88:89], v[16:17], v[66:67]
	s_add_u32 s0, s0, 0x400
	v_add_co_u32_e32 v84, vcc, s3, v102
	v_pk_fma_f32 v[78:79], v[12:13], v[78:79], v[88:89]
	s_nop 0
	v_addc_co_u32_e32 v85, vcc, 0, v103, vcc
	v_mov_b32_e32 v84, v172
	v_mov_b32_e32 v85, v173
	v_mov_b32_e32 v86, v174
	v_mov_b32_e32 v87, v175
	v_pk_fma_f32 v[78:79], v[20:21], v[58:59], v[78:79]
	s_addc_u32 s1, s1, 0
	s_waitcnt vmcnt(0)
	v_lshlrev_b32_e32 v88, 16, v84
	v_and_b32_e32 v89, 0xffff0000, v84
	v_pk_mul_f32 v[78:79], v[78:79], v[88:89]
	s_nop 0
	v_cvt_pk_bf16_f32 v84, v78, v79
	v_pk_mul_f32 v[78:79], v[18:19], v[62:63]
	s_nop 0
	v_pk_fma_f32 v[72:73], v[14:15], v[72:73], v[78:79]
	v_lshlrev_b32_e32 v78, 16, v85
	v_pk_fma_f32 v[72:73], v[22:23], v[54:55], v[72:73]
	v_and_b32_e32 v79, 0xffff0000, v85
	v_pk_mul_f32 v[72:73], v[72:73], v[78:79]
	s_nop 0
	v_cvt_pk_bf16_f32 v85, v72, v73
	v_pk_mul_f32 v[72:73], v[4:5], v[60:61]
	s_nop 0
	v_pk_fma_f32 v[68:69], v[0:1], v[68:69], v[72:73]
	v_lshlrev_b32_e32 v72, 16, v86
	v_pk_fma_f32 v[68:69], v[8:9], v[52:53], v[68:69]
	v_and_b32_e32 v73, 0xffff0000, v86
	v_pk_mul_f32 v[68:69], v[68:69], v[72:73]
	s_nop 0
	v_cvt_pk_bf16_f32 v86, v68, v69
	v_pk_mul_f32 v[68:69], v[6:7], v[64:65]
	s_nop 0
	v_pk_fma_f32 v[56:57], v[2:3], v[56:57], v[68:69]
	v_lshlrev_b32_e32 v68, 16, v87
	v_pk_fma_f32 v[56:57], v[10:11], v[50:51], v[56:57]
	v_and_b32_e32 v69, 0xffff0000, v87
	v_pk_mul_f32 v[56:57], v[56:57], v[68:69]
	s_nop 0
	v_cvt_pk_bf16_f32 v87, v56, v57
	v_lshl_add_u64 v[56:57], v[34:35], 0, s[16:17]
	global_store_dwordx4 v[56:57], v[84:87], off sc1
	v_add_co_u32_e32 v56, vcc, s3, v100
	s_add_u32 s16, s16, 0x400
	s_nop 0
	v_addc_co_u32_e32 v57, vcc, 0, v101, vcc
	v_mov_b32_e32 v84, v176
	v_mov_b32_e32 v85, v177
	v_mov_b32_e32 v86, v178
	v_mov_b32_e32 v87, v179
	v_pk_mul_f32 v[56:57], v[16:17], v[58:59]
	v_pk_mul_f32 v[16:17], v[16:17], v[82:83]
	v_pk_fma_f32 v[56:57], v[12:13], v[66:67], v[56:57]
	v_pk_fma_f32 v[12:13], v[12:13], v[58:59], v[16:17]
	v_pk_fma_f32 v[56:57], v[20:21], v[82:83], v[56:57]
	v_pk_fma_f32 v[12:13], v[20:21], v[98:99], v[12:13]
	s_addc_u32 s17, s17, 0
	s_waitcnt vmcnt(0)
	v_lshlrev_b32_e32 v66, 16, v84
	v_and_b32_e32 v67, 0xffff0000, v84
	v_pk_mul_f32 v[56:57], v[56:57], v[66:67]
	s_nop 0
	v_cvt_pk_bf16_f32 v66, v56, v57
	v_pk_mul_f32 v[56:57], v[18:19], v[54:55]
	s_nop 0
	v_pk_fma_f32 v[56:57], v[14:15], v[62:63], v[56:57]
	v_lshlrev_b32_e32 v62, 16, v85
	v_pk_fma_f32 v[56:57], v[22:23], v[74:75], v[56:57]
	v_and_b32_e32 v63, 0xffff0000, v85
	v_pk_mul_f32 v[56:57], v[56:57], v[62:63]
	s_nop 0
	v_cvt_pk_bf16_f32 v67, v56, v57
	v_pk_mul_f32 v[56:57], v[4:5], v[52:53]
	v_pk_mul_f32 v[4:5], v[4:5], v[70:71]
	v_pk_fma_f32 v[56:57], v[0:1], v[60:61], v[56:57]
	v_lshlrev_b32_e32 v60, 16, v86
	v_pk_fma_f32 v[56:57], v[8:9], v[70:71], v[56:57]
	v_and_b32_e32 v61, 0xffff0000, v86
	v_pk_mul_f32 v[56:57], v[56:57], v[60:61]
	v_lshlrev_b32_e32 v60, 16, v87
	v_cvt_pk_bf16_f32 v68, v56, v57
	v_pk_mul_f32 v[56:57], v[6:7], v[50:51]
	v_and_b32_e32 v61, 0xffff0000, v87
	v_pk_fma_f32 v[56:57], v[2:3], v[64:65], v[56:57]
	v_pk_fma_f32 v[0:1], v[0:1], v[52:53], v[4:5]
	v_pk_fma_f32 v[56:57], v[10:11], v[76:77], v[56:57]
	v_pk_fma_f32 v[0:1], v[8:9], v[92:93], v[0:1]
	v_pk_mul_f32 v[56:57], v[56:57], v[60:61]
	s_nop 0
	v_cvt_pk_bf16_f32 v69, v56, v57
	v_lshl_add_u64 v[56:57], v[34:35], 0, s[22:23]
	global_store_dwordx4 v[56:57], v[66:69], off sc1
	v_add_co_u32_e32 v56, vcc, s3, v94
	s_add_u32 s22, s22, 0x400
	s_nop 0
	v_addc_co_u32_e32 v57, vcc, 0, v95, vcc
	v_mov_b32_e32 v60, v180
	v_mov_b32_e32 v61, v181
	v_mov_b32_e32 v62, v182
	v_mov_b32_e32 v63, v183
	s_addc_u32 s23, s23, 0
	s_waitcnt vmcnt(0)
	v_lshlrev_b32_e32 v16, 16, v60
	v_and_b32_e32 v17, 0xffff0000, v60
	v_pk_mul_f32 v[12:13], v[12:13], v[16:17]
	v_pk_mul_f32 v[16:17], v[18:19], v[74:75]
	v_lshlrev_b32_e32 v4, 16, v62
	v_pk_fma_f32 v[14:15], v[14:15], v[54:55], v[16:17]
	v_lshlrev_b32_e32 v16, 16, v61
	v_pk_fma_f32 v[14:15], v[22:23], v[96:97], v[14:15]
	v_and_b32_e32 v17, 0xffff0000, v61
	v_and_b32_e32 v5, 0xffff0000, v62
	v_pk_mul_f32 v[14:15], v[14:15], v[16:17]
	v_pk_mul_f32 v[0:1], v[0:1], v[4:5]
	v_cvt_pk_bf16_f32 v12, v12, v13
	v_cvt_pk_bf16_f32 v13, v14, v15
	v_cvt_pk_bf16_f32 v14, v0, v1
	v_pk_mul_f32 v[0:1], v[6:7], v[76:77]
	s_nop 0
	v_pk_fma_f32 v[0:1], v[2:3], v[50:51], v[0:1]
	v_lshlrev_b32_e32 v2, 16, v63
	v_pk_fma_f32 v[0:1], v[10:11], v[80:81], v[0:1]
	v_and_b32_e32 v3, 0xffff0000, v63
	v_pk_mul_f32 v[0:1], v[0:1], v[2:3]
	s_nop 0
	v_cvt_pk_bf16_f32 v15, v0, v1
	v_lshl_add_u64 v[0:1], v[34:35], 0, s[26:27]
	s_add_u32 s26, s26, 0x400
	s_addc_u32 s27, s27, 0
	s_add_i32 s9, s9, -1
	s_cmp_eq_u32 s9, 0
	global_store_dwordx4 v[0:1], v[12:15], off sc1
	s_cbranch_scc1 .LBB0_752

; __device__ __forceinline__ unsigned cvt_pk_bf16(float lo, float hi) { const f32x2_t v = {lo, hi}; const bf16x2_t c = __builtin_convertvector(v, bf16x2_t); return __builtin_bit_cast(unsigned, c); }
; __device__ __forceinline__ float bf_lo(unsigned w) { return __uint_as_float(w << 16); }
; __device__ __forceinline__ float bf_hi(unsigned w) { return __uint_as_float(w & 0xffff0000u); }
; __device__ __forceinline__ float sigmoidf_fast(float x) { return __builtin_amdgcn_rcpf(1.0f + __expf(-x)); }
;     __device__ __forceinline__ void operator()(const f32x4 (&acc)[2][2][4][2], const Unit& u, int wr, int wc, int fr, int fq) const {
;         const int row0 = u.pm * BM + wr * 64 + fr, col0 = u.pn * BM + wc * 32 + 8 * fq;
; #pragma unroll
;         for (int ai = 0; ai < 2; ++ai) { u32x4 gq[4][2];
; #pragma unroll
;             for (int m = 0; m < 4; ++m)
; #pragma unroll
;                 for (int bj = 0; bj < 2; ++bj) gq[m][bj] = *(const u32x4*)(G + (size_t)(row0 + ai * HALF + m * 16) * ldg + col0 + bj * HALF);
; #pragma unroll
;             for (int m = 0; m < 4; ++m) { const size_t r = (size_t)(row0 + ai * HALF + m * 16);
; #pragma unroll
;                 for (int bj = 0; bj < 2; ++bj) { const u32x4 gw = gq[m][bj]; const f32x4 a0 = acc[ai][bj][m][0], a1 = acc[ai][bj][m][1];
;                     u32x4 w; w.x = cvt_pk_bf16(sigmoidf_fast(bf_lo(gw.x)) * a0[0], sigmoidf_fast(bf_hi(gw.x)) * a0[1]); w.y = cvt_pk_bf16(sigmoidf_fast(bf_lo(gw.y)) * a0[2], sigmoidf_fast(bf_hi(gw.y)) * a0[3]);
;                     w.z = cvt_pk_bf16(sigmoidf_fast(bf_lo(gw.z)) * a1[0], sigmoidf_fast(bf_hi(gw.z)) * a1[1]); w.w = cvt_pk_bf16(sigmoidf_fast(bf_lo(gw.w)) * a1[2], sigmoidf_fast(bf_hi(gw.w)) * a1[3]);
;                     *(u32x4*)(T + r * ldt + col0 + bj * HALF) = w; } }
;             asm volatile("" ::: "memory"); }
.LBB0_849:
	v_lshl_or_b32 v34, s25, 8, v189
	v_ashrrev_i32_e32 v35, 31, v34
	v_readlane_b32 s16, v253, 18
	v_lshlrev_b64 v[34:35], 1, v[34:35]
	v_readlane_b32 s17, v253, 19
	v_lshl_add_u32 v174, s24, 8, v186
	v_or_b32_e32 v182, 16, v174
	v_lshl_add_u64 v[176:177], s[16:17], 0, v[34:35]
	v_mad_i64_i32 v[100:101], s[16:17], v174, s67, v[176:177]
	global_load_dwordx4 v[198:201], v[100:101], off
	global_load_dwordx4 v[152:155], v[100:101], off offset:256
	v_mad_i64_i32 v[100:101], s[16:17], v182, s67, v[176:177]
	global_load_dwordx4 v[144:147], v[100:101], off
	global_load_dwordx4 v[140:143], v[100:101], off offset:256
	v_or_b32_e32 v180, 32, v174
	v_mad_i64_i32 v[100:101], s[16:17], v180, s67, v[176:177]
	global_load_dwordx4 v[136:139], v[100:101], off
	global_load_dwordx4 v[124:127], v[100:101], off offset:256
	v_or_b32_e32 v178, 48, v174
	v_mad_i64_i32 v[100:101], s[16:17], v178, s67, v[176:177]
	global_load_dwordx4 v[112:115], v[100:101], off
	s_nop 0
	global_load_dwordx4 v[100:103], v[100:101], off offset:256
	v_ashrrev_i32_e32 v175, 31, v174
	v_ashrrev_i32_e32 v183, 31, v182
	v_ashrrev_i32_e32 v181, 31, v180
	v_ashrrev_i32_e32 v179, 31, v178
	v_readlane_b32 s22, v252, 55
	v_readlane_b32 s23, v252, 56
	s_andn2_b64 vcc, exec, s[12:13]
	v_add_u32_e32 v226, 0x80, v174
	v_mad_i64_i32 v[248:249], s[16:17], v226, s67, v[176:177]
	global_load_dwordx4 v[202:205], v[248:249], off
	global_load_dwordx4 v[206:209], v[248:249], off offset:256
	v_add_u32_e32 v226, 0x90, v174
	v_mad_i64_i32 v[248:249], s[16:17], v226, s67, v[176:177]
	global_load_dwordx4 v[210:213], v[248:249], off
	global_load_dwordx4 v[214:217], v[248:249], off offset:256
	v_add_u32_e32 v226, 0xa0, v174
	v_mad_i64_i32 v[248:249], s[16:17], v226, s67, v[176:177]
	global_load_dwordx4 v[218:221], v[248:249], off
	global_load_dwordx4 v[222:225], v[248:249], off offset:256
	s_waitcnt vmcnt(6)
	v_lshlrev_b32_e32 v32, 16, v198
	v_mul_f32_e32 v32, 0xbfb8aa3b, v32
	v_exp_f32_e32 v32, v32
	s_nop 0
	v_add_f32_e32 v32, 1.0, v32
	v_rcp_f32_e32 v192, v32
	v_and_b32_e32 v32, 0xffff0000, v198
	v_mul_f32_e32 v32, 0xbfb8aa3b, v32
	v_exp_f32_e32 v32, v32
	s_nop 0
	v_add_f32_e32 v32, 1.0, v32
	v_rcp_f32_e32 v193, v32
	v_lshlrev_b32_e32 v32, 16, v199
	v_mul_f32_e32 v32, 0xbfb8aa3b, v32
	v_exp_f32_e32 v32, v32
	v_pk_mul_f32 v[156:157], v[156:157], v[192:193]
	v_add_f32_e32 v32, 1.0, v32
	v_rcp_f32_e32 v192, v32
	v_and_b32_e32 v32, 0xffff0000, v199
	v_mul_f32_e32 v32, 0xbfb8aa3b, v32
	v_exp_f32_e32 v32, v32
	v_cvt_pk_bf16_f32 v156, v156, v157
	v_add_f32_e32 v32, 1.0, v32
	v_rcp_f32_e32 v193, v32
	v_lshlrev_b32_e32 v32, 16, v200
	v_mul_f32_e32 v32, 0xbfb8aa3b, v32
	v_exp_f32_e32 v32, v32
	v_pk_mul_f32 v[158:159], v[158:159], v[192:193]
	v_add_f32_e32 v32, 1.0, v32
	v_cvt_pk_bf16_f32 v157, v158, v159
	v_rcp_f32_e32 v158, v32
	v_and_b32_e32 v32, 0xffff0000, v200
	v_mul_f32_e32 v32, 0xbfb8aa3b, v32
	v_exp_f32_e32 v32, v32
	s_nop 0
	v_add_f32_e32 v32, 1.0, v32
	v_rcp_f32_e32 v159, v32
	v_lshlrev_b32_e32 v32, 16, v201
	v_mul_f32_e32 v32, 0xbfb8aa3b, v32
	v_exp_f32_e32 v32, v32
	v_pk_mul_f32 v[148:149], v[148:149], v[158:159]
	v_add_f32_e32 v32, 1.0, v32
	v_cvt_pk_bf16_f32 v158, v148, v149
	v_rcp_f32_e32 v148, v32
	v_and_b32_e32 v32, 0xffff0000, v201
	v_mul_f32_e32 v32, 0xbfb8aa3b, v32
	v_exp_f32_e32 v32, v32
	s_nop 0
	v_add_f32_e32 v32, 1.0, v32
	v_rcp_f32_e32 v149, v32
	v_lshlrev_b32_e32 v32, 16, v152
	v_mul_f32_e32 v32, 0xbfb8aa3b, v32
	v_exp_f32_e32 v32, v32
	v_pk_mul_f32 v[148:149], v[150:151], v[148:149]
	v_add_f32_e32 v32, 1.0, v32
	v_rcp_f32_e32 v150, v32
	v_and_b32_e32 v32, 0xffff0000, v152
	v_mul_f32_e32 v32, 0xbfb8aa3b, v32
	v_exp_f32_e32 v32, v32
	v_cvt_pk_bf16_f32 v159, v148, v149
	v_lshlrev_b64 v[148:149], 12, v[174:175]
	v_lshl_add_u64 v[148:149], s[22:23], 0, v[148:149]
	v_add_f32_e32 v32, 1.0, v32
	v_rcp_f32_e32 v151, v32
	v_lshlrev_b32_e32 v32, 16, v153
	v_mul_f32_e32 v32, 0xbfb8aa3b, v32
	v_exp_f32_e32 v32, v32
	v_pk_mul_f32 v[132:133], v[132:133], v[150:151]
	v_lshl_add_u64 v[148:149], v[148:149], 0, v[34:35]
	v_cvt_pk_bf16_f32 v132, v132, v133
	v_add_f32_e32 v32, 1.0, v32
	v_rcp_f32_e32 v150, v32
	v_and_b32_e32 v32, 0xffff0000, v153
	v_mul_f32_e32 v32, 0xbfb8aa3b, v32
	v_exp_f32_e32 v32, v32
	global_store_dwordx4 v[148:149], v[156:159], off sc1
	v_add_f32_e32 v32, 1.0, v32
	v_rcp_f32_e32 v151, v32
	v_lshlrev_b32_e32 v32, 16, v154
	v_mul_f32_e32 v32, 0xbfb8aa3b, v32
	v_exp_f32_e32 v32, v32
	v_pk_mul_f32 v[134:135], v[134:135], v[150:151]
	v_add_f32_e32 v32, 1.0, v32
	v_cvt_pk_bf16_f32 v133, v134, v135
	v_rcp_f32_e32 v134, v32
	v_and_b32_e32 v32, 0xffff0000, v154
	v_mul_f32_e32 v32, 0xbfb8aa3b, v32
	v_exp_f32_e32 v32, v32
	s_nop 0
	v_add_f32_e32 v32, 1.0, v32
	v_rcp_f32_e32 v135, v32
	v_lshlrev_b32_e32 v32, 16, v155
	v_mul_f32_e32 v32, 0xbfb8aa3b, v32
	v_exp_f32_e32 v32, v32
	v_pk_mul_f32 v[128:129], v[128:129], v[134:135]
	v_add_f32_e32 v32, 1.0, v32
	v_cvt_pk_bf16_f32 v134, v128, v129
	v_rcp_f32_e32 v128, v32
	v_and_b32_e32 v32, 0xffff0000, v155
	v_mul_f32_e32 v32, 0xbfb8aa3b, v32
	v_exp_f32_e32 v32, v32
	s_nop 0
	v_add_f32_e32 v32, 1.0, v32
	v_rcp_f32_e32 v129, v32
	v_lshlrev_b32_e32 v32, 16, v144
	v_mul_f32_e32 v32, 0xbfb8aa3b, v32
	v_exp_f32_e32 v32, v32
	v_pk_mul_f32 v[128:129], v[130:131], v[128:129]
	v_add_f32_e32 v32, 1.0, v32
	v_cvt_pk_bf16_f32 v135, v128, v129
	v_rcp_f32_e32 v128, v32
	v_and_b32_e32 v32, 0xffff0000, v144
	v_mul_f32_e32 v32, 0xbfb8aa3b, v32
	v_exp_f32_e32 v32, v32
	global_store_dwordx4 v[148:149], v[132:135], off offset:256 sc1
	v_add_f32_e32 v32, 1.0, v32
	v_rcp_f32_e32 v129, v32
	v_lshlrev_b32_e32 v32, 16, v145
	v_mul_f32_e32 v32, 0xbfb8aa3b, v32
	v_exp_f32_e32 v32, v32
; __device__ __forceinline__ unsigned cvt_pk_bf16(float lo, float hi) { const f32x2_t v = {lo, hi}; const bf16x2_t c = __builtin_convertvector(v, bf16x2_t); return __builtin_bit_cast(unsigned, c); }
; __device__ __forceinline__ float bf_lo(unsigned w) { return __uint_as_float(w << 16); }
; __device__ __forceinline__ float bf_hi(unsigned w) { return __uint_as_float(w & 0xffff0000u); }
; __device__ __forceinline__ float sigmoidf_fast(float x) { return __builtin_amdgcn_rcpf(1.0f + __expf(-x)); }
;     __device__ __forceinline__ void operator()(const f32x4 (&acc)[2][2][4][2], const Unit& u, int wr, int wc, int fr, int fq) const {
;     ...
;             for (int m = 0; m < 4; ++m) { const size_t r = (size_t)(row0 + ai * HALF + m * 16);
; #pragma unroll
;                 for (int bj = 0; bj < 2; ++bj) { const u32x4 gw = gq[m][bj]; const f32x4 a0 = acc[ai][bj][m][0], a1 = acc[ai][bj][m][1];
;                     u32x4 w; w.x = cvt_pk_bf16(sigmoidf_fast(bf_lo(gw.x)) * a0[0], sigmoidf_fast(bf_hi(gw.x)) * a0[1]); w.y = cvt_pk_bf16(sigmoidf_fast(bf_lo(gw.y)) * a0[2], sigmoidf_fast(bf_hi(gw.y)) * a0[3]);
;                     w.z = cvt_pk_bf16(sigmoidf_fast(bf_lo(gw.z)) * a1[0], sigmoidf_fast(bf_hi(gw.z)) * a1[1]); w.w = cvt_pk_bf16(sigmoidf_fast(bf_lo(gw.w)) * a1[2], sigmoidf_fast(bf_hi(gw.w)) * a1[3]);
;                     *(u32x4*)(T + r * ldt + col0 + bj * HALF) = w; } }
;             asm volatile("" ::: "memory"); }
	v_pk_mul_f32 v[120:121], v[120:121], v[128:129]
	v_add_f32_e32 v32, 1.0, v32
	v_rcp_f32_e32 v128, v32
	v_and_b32_e32 v32, 0xffff0000, v145
	v_mul_f32_e32 v32, 0xbfb8aa3b, v32
	v_exp_f32_e32 v32, v32
	v_cvt_pk_bf16_f32 v120, v120, v121
	v_add_f32_e32 v32, 1.0, v32
	v_rcp_f32_e32 v129, v32
	v_lshlrev_b32_e32 v32, 16, v146
	v_mul_f32_e32 v32, 0xbfb8aa3b, v32
	v_exp_f32_e32 v32, v32
	v_pk_mul_f32 v[122:123], v[122:123], v[128:129]
	v_add_f32_e32 v32, 1.0, v32
	v_cvt_pk_bf16_f32 v121, v122, v123
	v_rcp_f32_e32 v122, v32
	v_and_b32_e32 v32, 0xffff0000, v146
	v_mul_f32_e32 v32, 0xbfb8aa3b, v32
	v_exp_f32_e32 v32, v32
	s_nop 0
	v_add_f32_e32 v32, 1.0, v32
	v_rcp_f32_e32 v123, v32
	v_lshlrev_b32_e32 v32, 16, v147
	v_mul_f32_e32 v32, 0xbfb8aa3b, v32
	v_exp_f32_e32 v32, v32
	v_pk_mul_f32 v[116:117], v[116:117], v[122:123]
	v_add_f32_e32 v32, 1.0, v32
	v_cvt_pk_bf16_f32 v122, v116, v117
	v_rcp_f32_e32 v116, v32
	v_and_b32_e32 v32, 0xffff0000, v147
	v_mul_f32_e32 v32, 0xbfb8aa3b, v32
	v_exp_f32_e32 v32, v32
	s_nop 0
	v_add_f32_e32 v32, 1.0, v32
	v_rcp_f32_e32 v117, v32
	v_lshlrev_b32_e32 v32, 16, v140
	v_mul_f32_e32 v32, 0xbfb8aa3b, v32
	v_exp_f32_e32 v32, v32
	v_pk_mul_f32 v[116:117], v[118:119], v[116:117]
	v_add_f32_e32 v32, 1.0, v32
	v_rcp_f32_e32 v118, v32
	v_and_b32_e32 v32, 0xffff0000, v140
	v_mul_f32_e32 v32, 0xbfb8aa3b, v32
	v_exp_f32_e32 v32, v32
	v_cvt_pk_bf16_f32 v123, v116, v117
	v_lshlrev_b64 v[116:117], 12, v[182:183]
	v_lshl_add_u64 v[116:117], s[22:23], 0, v[116:117]
	v_add_f32_e32 v32, 1.0, v32
	v_rcp_f32_e32 v119, v32
	v_lshlrev_b32_e32 v32, 16, v141
	v_mul_f32_e32 v32, 0xbfb8aa3b, v32
	v_exp_f32_e32 v32, v32
	v_pk_mul_f32 v[108:109], v[108:109], v[118:119]
	v_lshl_add_u64 v[116:117], v[116:117], 0, v[34:35]
	v_cvt_pk_bf16_f32 v108, v108, v109
	v_add_f32_e32 v32, 1.0, v32
	v_rcp_f32_e32 v118, v32
	v_and_b32_e32 v32, 0xffff0000, v141
	v_mul_f32_e32 v32, 0xbfb8aa3b, v32
	v_exp_f32_e32 v32, v32
	global_store_dwordx4 v[116:117], v[120:123], off sc1
	v_add_f32_e32 v32, 1.0, v32
	v_rcp_f32_e32 v119, v32
	v_lshlrev_b32_e32 v32, 16, v142
	v_mul_f32_e32 v32, 0xbfb8aa3b, v32
	v_exp_f32_e32 v32, v32
	v_pk_mul_f32 v[110:111], v[110:111], v[118:119]
	v_add_f32_e32 v32, 1.0, v32
	v_cvt_pk_bf16_f32 v109, v110, v111
	v_rcp_f32_e32 v110, v32
	v_and_b32_e32 v32, 0xffff0000, v142
	v_mul_f32_e32 v32, 0xbfb8aa3b, v32
	v_exp_f32_e32 v32, v32
	s_nop 0
	v_add_f32_e32 v32, 1.0, v32
	v_rcp_f32_e32 v111, v32
	v_lshlrev_b32_e32 v32, 16, v143
	v_mul_f32_e32 v32, 0xbfb8aa3b, v32
	v_exp_f32_e32 v32, v32
	v_pk_mul_f32 v[104:105], v[104:105], v[110:111]
	v_add_f32_e32 v32, 1.0, v32
	v_cvt_pk_bf16_f32 v110, v104, v105
	v_rcp_f32_e32 v104, v32
	v_and_b32_e32 v32, 0xffff0000, v143
	v_mul_f32_e32 v32, 0xbfb8aa3b, v32
	v_exp_f32_e32 v32, v32
	s_nop 0
	v_add_f32_e32 v32, 1.0, v32
	v_rcp_f32_e32 v105, v32
	v_lshlrev_b32_e32 v32, 16, v136
	v_mul_f32_e32 v32, 0xbfb8aa3b, v32
	v_exp_f32_e32 v32, v32
	v_pk_mul_f32 v[104:105], v[106:107], v[104:105]
	v_add_u32_e32 v106, 0x80, v174
	v_cvt_pk_bf16_f32 v111, v104, v105
	v_add_f32_e32 v32, 1.0, v32
	v_rcp_f32_e32 v104, v32
	v_and_b32_e32 v32, 0xffff0000, v136
	v_mul_f32_e32 v32, 0xbfb8aa3b, v32
	v_exp_f32_e32 v32, v32
	global_store_dwordx4 v[116:117], v[108:111], off offset:256 sc1
	v_ashrrev_i32_e32 v107, 31, v106
	v_add_f32_e32 v32, 1.0, v32
	v_rcp_f32_e32 v105, v32
	v_lshlrev_b32_e32 v32, 16, v137
	v_mul_f32_e32 v32, 0xbfb8aa3b, v32
	v_exp_f32_e32 v32, v32
	v_pk_mul_f32 v[96:97], v[96:97], v[104:105]
	v_add_f32_e32 v32, 1.0, v32
	v_rcp_f32_e32 v104, v32
	v_and_b32_e32 v32, 0xffff0000, v137
	v_mul_f32_e32 v32, 0xbfb8aa3b, v32
	v_exp_f32_e32 v32, v32
	v_cvt_pk_bf16_f32 v96, v96, v97
	v_add_f32_e32 v32, 1.0, v32
	v_rcp_f32_e32 v105, v32
	v_lshlrev_b32_e32 v32, 16, v138
	v_mul_f32_e32 v32, 0xbfb8aa3b, v32
	v_exp_f32_e32 v32, v32
	v_pk_mul_f32 v[98:99], v[98:99], v[104:105]
	v_add_f32_e32 v32, 1.0, v32
	v_cvt_pk_bf16_f32 v97, v98, v99
	v_rcp_f32_e32 v98, v32
	v_and_b32_e32 v32, 0xffff0000, v138
	v_mul_f32_e32 v32, 0xbfb8aa3b, v32
	v_exp_f32_e32 v32, v32
	s_nop 0
	v_add_f32_e32 v32, 1.0, v32
	v_rcp_f32_e32 v99, v32
	v_lshlrev_b32_e32 v32, 16, v139
	v_mul_f32_e32 v32, 0xbfb8aa3b, v32
	v_exp_f32_e32 v32, v32
	v_pk_mul_f32 v[92:93], v[92:93], v[98:99]
	v_add_f32_e32 v32, 1.0, v32
	v_cvt_pk_bf16_f32 v98, v92, v93
	v_rcp_f32_e32 v92, v32
	v_and_b32_e32 v32, 0xffff0000, v139
	v_mul_f32_e32 v32, 0xbfb8aa3b, v32
	v_exp_f32_e32 v32, v32
	s_nop 0
	v_add_f32_e32 v32, 1.0, v32
	v_rcp_f32_e32 v93, v32
	v_lshlrev_b32_e32 v32, 16, v124
	v_mul_f32_e32 v32, 0xbfb8aa3b, v32
	v_exp_f32_e32 v32, v32
	v_pk_mul_f32 v[92:93], v[94:95], v[92:93]
	v_add_f32_e32 v32, 1.0, v32
	v_rcp_f32_e32 v94, v32
	v_and_b32_e32 v32, 0xffff0000, v124
	v_mul_f32_e32 v32, 0xbfb8aa3b, v32
	v_exp_f32_e32 v32, v32
	v_cvt_pk_bf16_f32 v99, v92, v93
	v_lshlrev_b64 v[92:93], 12, v[180:181]
	v_lshl_add_u64 v[92:93], s[22:23], 0, v[92:93]
	v_add_f32_e32 v32, 1.0, v32
	v_rcp_f32_e32 v95, v32
	v_lshlrev_b32_e32 v32, 16, v125
	v_mul_f32_e32 v32, 0xbfb8aa3b, v32
	v_exp_f32_e32 v32, v32
	v_pk_mul_f32 v[88:89], v[88:89], v[94:95]
	v_lshl_add_u64 v[92:93], v[92:93], 0, v[34:35]
	v_cvt_pk_bf16_f32 v88, v88, v89
	v_add_f32_e32 v32, 1.0, v32
	v_rcp_f32_e32 v94, v32
	v_and_b32_e32 v32, 0xffff0000, v125
	v_mul_f32_e32 v32, 0xbfb8aa3b, v32
	v_exp_f32_e32 v32, v32
	global_store_dwordx4 v[92:93], v[96:99], off sc1
	v_add_f32_e32 v32, 1.0, v32
	v_rcp_f32_e32 v95, v32
	v_lshlrev_b32_e32 v32, 16, v126
	v_mul_f32_e32 v32, 0xbfb8aa3b, v32
	v_exp_f32_e32 v32, v32
	v_pk_mul_f32 v[90:91], v[90:91], v[94:95]
	v_add_u32_e32 v98, 0xa0, v174
	v_cvt_pk_bf16_f32 v89, v90, v91
	v_add_f32_e32 v32, 1.0, v32
; __device__ __forceinline__ unsigned cvt_pk_bf16(float lo, float hi) { const f32x2_t v = {lo, hi}; const bf16x2_t c = __builtin_convertvector(v, bf16x2_t); return __builtin_bit_cast(unsigned, c); }
; __device__ __forceinline__ float bf_lo(unsigned w) { return __uint_as_float(w << 16); }
; __device__ __forceinline__ float bf_hi(unsigned w) { return __uint_as_float(w & 0xffff0000u); }
; __device__ __forceinline__ float sigmoidf_fast(float x) { return __builtin_amdgcn_rcpf(1.0f + __expf(-x)); }
;     __device__ __forceinline__ void operator()(const f32x4 (&acc)[2][2][4][2], const Unit& u, int wr, int wc, int fr, int fq) const {
;     ...
;         for (int ai = 0; ai < 2; ++ai) { u32x4 gq[4][2];
; #pragma unroll
;             for (int m = 0; m < 4; ++m)
; #pragma unroll
;                 for (int bj = 0; bj < 2; ++bj) gq[m][bj] = *(const u32x4*)(G + (size_t)(row0 + ai * HALF + m * 16) * ldg + col0 + bj * HALF);
; #pragma unroll
;             for (int m = 0; m < 4; ++m) { const size_t r = (size_t)(row0 + ai * HALF + m * 16);
; #pragma unroll
;                 for (int bj = 0; bj < 2; ++bj) { const u32x4 gw = gq[m][bj]; const f32x4 a0 = acc[ai][bj][m][0], a1 = acc[ai][bj][m][1];
;                     u32x4 w; w.x = cvt_pk_bf16(sigmoidf_fast(bf_lo(gw.x)) * a0[0], sigmoidf_fast(bf_hi(gw.x)) * a0[1]); w.y = cvt_pk_bf16(sigmoidf_fast(bf_lo(gw.y)) * a0[2], sigmoidf_fast(bf_hi(gw.y)) * a0[3]);
;                     w.z = cvt_pk_bf16(sigmoidf_fast(bf_lo(gw.z)) * a1[0], sigmoidf_fast(bf_hi(gw.z)) * a1[1]); w.w = cvt_pk_bf16(sigmoidf_fast(bf_lo(gw.w)) * a1[2], sigmoidf_fast(bf_hi(gw.w)) * a1[3]);
;                     *(u32x4*)(T + r * ldt + col0 + bj * HALF) = w; } }
;             asm volatile("" ::: "memory"); }
	v_rcp_f32_e32 v90, v32
	v_and_b32_e32 v32, 0xffff0000, v126
	v_mul_f32_e32 v32, 0xbfb8aa3b, v32
	v_exp_f32_e32 v32, v32
	v_add_u32_e32 v96, 0xb0, v174
	v_ashrrev_i32_e32 v99, 31, v98
	v_ashrrev_i32_e32 v97, 31, v96
	v_add_f32_e32 v32, 1.0, v32
	v_rcp_f32_e32 v91, v32
	v_lshlrev_b32_e32 v32, 16, v127
	v_mul_f32_e32 v32, 0xbfb8aa3b, v32
	v_exp_f32_e32 v32, v32
	v_pk_mul_f32 v[84:85], v[84:85], v[90:91]
	v_add_f32_e32 v32, 1.0, v32
	v_cvt_pk_bf16_f32 v90, v84, v85
	v_rcp_f32_e32 v84, v32
	v_and_b32_e32 v32, 0xffff0000, v127
	v_mul_f32_e32 v32, 0xbfb8aa3b, v32
	v_exp_f32_e32 v32, v32
	s_nop 0
	v_add_f32_e32 v32, 1.0, v32
	v_rcp_f32_e32 v85, v32
	v_lshlrev_b32_e32 v32, 16, v112
	v_mul_f32_e32 v32, 0xbfb8aa3b, v32
	v_exp_f32_e32 v32, v32
	v_pk_mul_f32 v[84:85], v[86:87], v[84:85]
	v_add_f32_e32 v32, 1.0, v32
	v_cvt_pk_bf16_f32 v91, v84, v85
	v_rcp_f32_e32 v84, v32
	v_and_b32_e32 v32, 0xffff0000, v112
	v_mul_f32_e32 v32, 0xbfb8aa3b, v32
	v_exp_f32_e32 v32, v32
	global_store_dwordx4 v[92:93], v[88:91], off offset:256 sc1
	v_add_f32_e32 v32, 1.0, v32
	v_rcp_f32_e32 v85, v32
	v_lshlrev_b32_e32 v32, 16, v113
	v_mul_f32_e32 v32, 0xbfb8aa3b, v32
	v_exp_f32_e32 v32, v32
	v_pk_mul_f32 v[80:81], v[80:81], v[84:85]
	v_add_f32_e32 v32, 1.0, v32
	v_rcp_f32_e32 v84, v32
	v_and_b32_e32 v32, 0xffff0000, v113
	v_mul_f32_e32 v32, 0xbfb8aa3b, v32
	v_exp_f32_e32 v32, v32
	v_cvt_pk_bf16_f32 v80, v80, v81
	v_add_f32_e32 v32, 1.0, v32
	v_rcp_f32_e32 v85, v32
	v_lshlrev_b32_e32 v32, 16, v114
	v_mul_f32_e32 v32, 0xbfb8aa3b, v32
	v_exp_f32_e32 v32, v32
	v_pk_mul_f32 v[82:83], v[82:83], v[84:85]
	v_add_f32_e32 v32, 1.0, v32
	v_cvt_pk_bf16_f32 v81, v82, v83
	v_rcp_f32_e32 v82, v32
	v_and_b32_e32 v32, 0xffff0000, v114
	v_mul_f32_e32 v32, 0xbfb8aa3b, v32
	v_exp_f32_e32 v32, v32
	s_nop 0
	v_add_f32_e32 v32, 1.0, v32
	v_rcp_f32_e32 v83, v32
	v_lshlrev_b32_e32 v32, 16, v115
	v_mul_f32_e32 v32, 0xbfb8aa3b, v32
	v_exp_f32_e32 v32, v32
	v_pk_mul_f32 v[76:77], v[76:77], v[82:83]
	v_add_f32_e32 v32, 1.0, v32
	v_cvt_pk_bf16_f32 v82, v76, v77
	v_rcp_f32_e32 v76, v32
	v_and_b32_e32 v32, 0xffff0000, v115
	v_mul_f32_e32 v32, 0xbfb8aa3b, v32
	v_exp_f32_e32 v32, v32
	s_nop 0
	v_add_f32_e32 v32, 1.0, v32
	v_rcp_f32_e32 v77, v32
	v_lshlrev_b32_e32 v32, 16, v100
	v_mul_f32_e32 v32, 0xbfb8aa3b, v32
	v_exp_f32_e32 v32, v32
	v_pk_mul_f32 v[76:77], v[78:79], v[76:77]
	v_add_f32_e32 v32, 1.0, v32
	v_rcp_f32_e32 v78, v32
	v_and_b32_e32 v32, 0xffff0000, v100
	v_mul_f32_e32 v32, 0xbfb8aa3b, v32
	v_exp_f32_e32 v32, v32
	v_cvt_pk_bf16_f32 v83, v76, v77
	v_lshlrev_b64 v[76:77], 12, v[178:179]
	v_lshl_add_u64 v[76:77], s[22:23], 0, v[76:77]
	v_add_f32_e32 v32, 1.0, v32
	v_rcp_f32_e32 v79, v32
	v_lshlrev_b32_e32 v32, 16, v101
	v_mul_f32_e32 v32, 0xbfb8aa3b, v32
	v_exp_f32_e32 v32, v32
	v_pk_mul_f32 v[72:73], v[72:73], v[78:79]
	v_lshl_add_u64 v[76:77], v[76:77], 0, v[34:35]
	v_cvt_pk_bf16_f32 v72, v72, v73
	v_add_f32_e32 v32, 1.0, v32
	v_rcp_f32_e32 v78, v32
	v_and_b32_e32 v32, 0xffff0000, v101
	v_mul_f32_e32 v32, 0xbfb8aa3b, v32
	v_exp_f32_e32 v32, v32
	global_store_dwordx4 v[76:77], v[80:83], off sc1
	v_add_u32_e32 v100, 0x90, v174
	v_ashrrev_i32_e32 v101, 31, v100
	v_add_f32_e32 v32, 1.0, v32
	v_rcp_f32_e32 v79, v32
	v_lshlrev_b32_e32 v32, 16, v102
	v_mul_f32_e32 v32, 0xbfb8aa3b, v32
	v_exp_f32_e32 v32, v32
	v_pk_mul_f32 v[74:75], v[74:75], v[78:79]
	v_add_f32_e32 v32, 1.0, v32
	v_cvt_pk_bf16_f32 v73, v74, v75
	v_rcp_f32_e32 v74, v32
	v_and_b32_e32 v32, 0xffff0000, v102
	v_mul_f32_e32 v32, 0xbfb8aa3b, v32
	v_exp_f32_e32 v32, v32
	s_nop 0
	v_add_f32_e32 v32, 1.0, v32
	v_rcp_f32_e32 v75, v32
	v_lshlrev_b32_e32 v32, 16, v103
	v_mul_f32_e32 v32, 0xbfb8aa3b, v32
	v_exp_f32_e32 v32, v32
	v_pk_mul_f32 v[68:69], v[68:69], v[74:75]
	v_add_f32_e32 v32, 1.0, v32
	v_cvt_pk_bf16_f32 v74, v68, v69
	v_rcp_f32_e32 v68, v32
	v_and_b32_e32 v32, 0xffff0000, v103
	v_mul_f32_e32 v32, 0xbfb8aa3b, v32
	v_exp_f32_e32 v32, v32
	s_nop 0
	v_add_f32_e32 v32, 1.0, v32
	v_rcp_f32_e32 v69, v32
	s_nop 0
	v_pk_mul_f32 v[68:69], v[70:71], v[68:69]
	s_nop 0
	v_cvt_pk_bf16_f32 v75, v68, v69
	global_store_dwordx4 v[76:77], v[72:75], off offset:256 sc1
	v_mad_i64_i32 v[68:69], s[16:17], v96, s67, v[176:177]
	global_load_dwordx4 v[72:75], v[68:69], off
	s_nop 0
	global_load_dwordx4 v[68:71], v[68:69], off offset:256
	s_mov_b64 s[16:17], -1
	s_waitcnt vmcnt(15)
	v_lshlrev_b32_e32 v32, 16, v202
	v_mul_f32_e32 v32, 0xbfb8aa3b, v32
	v_exp_f32_e32 v32, v32
	s_nop 0
	v_add_f32_e32 v32, 1.0, v32
	v_rcp_f32_e32 v108, v32
	v_and_b32_e32 v32, 0xffff0000, v202
	v_mul_f32_e32 v32, 0xbfb8aa3b, v32
	v_exp_f32_e32 v32, v32
	s_nop 0
	v_add_f32_e32 v32, 1.0, v32
	v_rcp_f32_e32 v109, v32
	v_lshlrev_b32_e32 v32, 16, v203
	v_mul_f32_e32 v32, 0xbfb8aa3b, v32
	v_exp_f32_e32 v32, v32
	v_pk_mul_f32 v[64:65], v[64:65], v[108:109]
	v_add_f32_e32 v32, 1.0, v32
	v_rcp_f32_e32 v102, v32
	v_and_b32_e32 v32, 0xffff0000, v203
	v_mul_f32_e32 v32, 0xbfb8aa3b, v32
	v_exp_f32_e32 v32, v32
	v_cvt_pk_bf16_f32 v64, v64, v65
	v_add_f32_e32 v32, 1.0, v32
	v_rcp_f32_e32 v103, v32
	v_lshlrev_b32_e32 v32, 16, v204
	v_mul_f32_e32 v32, 0xbfb8aa3b, v32
	v_exp_f32_e32 v32, v32
	v_pk_mul_f32 v[66:67], v[66:67], v[102:103]
	v_add_f32_e32 v32, 1.0, v32
	v_cvt_pk_bf16_f32 v65, v66, v67
	v_rcp_f32_e32 v66, v32
	v_and_b32_e32 v32, 0xffff0000, v204
	v_mul_f32_e32 v32, 0xbfb8aa3b, v32
	v_exp_f32_e32 v32, v32
	s_nop 0
	v_add_f32_e32 v32, 1.0, v32
	v_rcp_f32_e32 v67, v32
	v_lshlrev_b32_e32 v32, 16, v205
	v_mul_f32_e32 v32, 0xbfb8aa3b, v32
	v_exp_f32_e32 v32, v32
	v_pk_mul_f32 v[60:61], v[60:61], v[66:67]
	v_add_f32_e32 v32, 1.0, v32
	v_cvt_pk_bf16_f32 v66, v60, v61
	v_rcp_f32_e32 v60, v32
	v_and_b32_e32 v32, 0xffff0000, v205
	v_mul_f32_e32 v32, 0xbfb8aa3b, v32
	v_exp_f32_e32 v32, v32
	s_nop 0
	v_add_f32_e32 v32, 1.0, v32
	v_rcp_f32_e32 v61, v32
	s_waitcnt vmcnt(14)
; __device__ __forceinline__ unsigned cvt_pk_bf16(float lo, float hi) { const f32x2_t v = {lo, hi}; const bf16x2_t c = __builtin_convertvector(v, bf16x2_t); return __builtin_bit_cast(unsigned, c); }
; __device__ __forceinline__ float bf_lo(unsigned w) { return __uint_as_float(w << 16); }
; __device__ __forceinline__ float bf_hi(unsigned w) { return __uint_as_float(w & 0xffff0000u); }
; __device__ __forceinline__ float sigmoidf_fast(float x) { return __builtin_amdgcn_rcpf(1.0f + __expf(-x)); }
;     __device__ __forceinline__ void operator()(const f32x4 (&acc)[2][2][4][2], const Unit& u, int wr, int wc, int fr, int fq) const {
;     ...
;             for (int m = 0; m < 4; ++m) { const size_t r = (size_t)(row0 + ai * HALF + m * 16);
; #pragma unroll
;                 for (int bj = 0; bj < 2; ++bj) { const u32x4 gw = gq[m][bj]; const f32x4 a0 = acc[ai][bj][m][0], a1 = acc[ai][bj][m][1];
;                     u32x4 w; w.x = cvt_pk_bf16(sigmoidf_fast(bf_lo(gw.x)) * a0[0], sigmoidf_fast(bf_hi(gw.x)) * a0[1]); w.y = cvt_pk_bf16(sigmoidf_fast(bf_lo(gw.y)) * a0[2], sigmoidf_fast(bf_hi(gw.y)) * a0[3]);
;                     w.z = cvt_pk_bf16(sigmoidf_fast(bf_lo(gw.z)) * a1[0], sigmoidf_fast(bf_hi(gw.z)) * a1[1]); w.w = cvt_pk_bf16(sigmoidf_fast(bf_lo(gw.w)) * a1[2], sigmoidf_fast(bf_hi(gw.w)) * a1[3]);
;                     *(u32x4*)(T + r * ldt + col0 + bj * HALF) = w; } }
;             asm volatile("" ::: "memory"); }
	v_lshlrev_b32_e32 v32, 16, v206
	v_mul_f32_e32 v32, 0xbfb8aa3b, v32
	v_exp_f32_e32 v32, v32
	v_pk_mul_f32 v[60:61], v[62:63], v[60:61]
	v_add_f32_e32 v32, 1.0, v32
	v_rcp_f32_e32 v62, v32
	v_and_b32_e32 v32, 0xffff0000, v206
	v_mul_f32_e32 v32, 0xbfb8aa3b, v32
	v_exp_f32_e32 v32, v32
	v_cvt_pk_bf16_f32 v67, v60, v61
	v_lshlrev_b64 v[60:61], 12, v[106:107]
	v_lshl_add_u64 v[60:61], s[22:23], 0, v[60:61]
	v_add_f32_e32 v32, 1.0, v32
	v_rcp_f32_e32 v63, v32
	v_lshlrev_b32_e32 v32, 16, v207
	v_mul_f32_e32 v32, 0xbfb8aa3b, v32
	v_exp_f32_e32 v32, v32
	v_pk_mul_f32 v[56:57], v[56:57], v[62:63]
	v_lshl_add_u64 v[60:61], v[60:61], 0, v[34:35]
	v_cvt_pk_bf16_f32 v56, v56, v57
	v_add_f32_e32 v32, 1.0, v32
	v_rcp_f32_e32 v62, v32
	v_and_b32_e32 v32, 0xffff0000, v207
	v_mul_f32_e32 v32, 0xbfb8aa3b, v32
	v_exp_f32_e32 v32, v32
	global_store_dwordx4 v[60:61], v[64:67], off sc1
	v_add_f32_e32 v32, 1.0, v32
	v_rcp_f32_e32 v63, v32
	v_lshlrev_b32_e32 v32, 16, v208
	v_mul_f32_e32 v32, 0xbfb8aa3b, v32
	v_exp_f32_e32 v32, v32
	v_pk_mul_f32 v[58:59], v[58:59], v[62:63]
	v_add_f32_e32 v32, 1.0, v32
	v_cvt_pk_bf16_f32 v57, v58, v59
	v_rcp_f32_e32 v58, v32
	v_and_b32_e32 v32, 0xffff0000, v208
	v_mul_f32_e32 v32, 0xbfb8aa3b, v32
	v_exp_f32_e32 v32, v32
	s_nop 0
	v_add_f32_e32 v32, 1.0, v32
	v_rcp_f32_e32 v59, v32
	v_lshlrev_b32_e32 v32, 16, v209
	v_mul_f32_e32 v32, 0xbfb8aa3b, v32
	v_exp_f32_e32 v32, v32
	v_pk_mul_f32 v[52:53], v[52:53], v[58:59]
	v_add_f32_e32 v32, 1.0, v32
	v_cvt_pk_bf16_f32 v58, v52, v53
	v_rcp_f32_e32 v52, v32
	v_and_b32_e32 v32, 0xffff0000, v209
	v_mul_f32_e32 v32, 0xbfb8aa3b, v32
	v_exp_f32_e32 v32, v32
	s_nop 0
	v_add_f32_e32 v32, 1.0, v32
	v_rcp_f32_e32 v53, v32
	s_waitcnt vmcnt(14)
	v_lshlrev_b32_e32 v32, 16, v210
	v_mul_f32_e32 v32, 0xbfb8aa3b, v32
	v_exp_f32_e32 v32, v32
	v_pk_mul_f32 v[52:53], v[54:55], v[52:53]
	v_add_f32_e32 v32, 1.0, v32
	v_cvt_pk_bf16_f32 v59, v52, v53
	v_rcp_f32_e32 v52, v32
	v_and_b32_e32 v32, 0xffff0000, v210
	v_mul_f32_e32 v32, 0xbfb8aa3b, v32
	v_exp_f32_e32 v32, v32
	global_store_dwordx4 v[60:61], v[56:59], off offset:256 sc1
	v_add_f32_e32 v32, 1.0, v32
	v_rcp_f32_e32 v53, v32
	v_lshlrev_b32_e32 v32, 16, v211
	v_mul_f32_e32 v32, 0xbfb8aa3b, v32
	v_exp_f32_e32 v32, v32
	v_pk_mul_f32 v[48:49], v[48:49], v[52:53]
	v_add_f32_e32 v32, 1.0, v32
	v_rcp_f32_e32 v52, v32
	v_and_b32_e32 v32, 0xffff0000, v211
	v_mul_f32_e32 v32, 0xbfb8aa3b, v32
	v_exp_f32_e32 v32, v32
	v_cvt_pk_bf16_f32 v48, v48, v49
	v_add_f32_e32 v32, 1.0, v32
	v_rcp_f32_e32 v53, v32
	v_lshlrev_b32_e32 v32, 16, v212
	v_mul_f32_e32 v32, 0xbfb8aa3b, v32
	v_exp_f32_e32 v32, v32
	v_pk_mul_f32 v[50:51], v[50:51], v[52:53]
	v_add_f32_e32 v32, 1.0, v32
	v_cvt_pk_bf16_f32 v49, v50, v51
	v_rcp_f32_e32 v50, v32
	v_and_b32_e32 v32, 0xffff0000, v212
	v_mul_f32_e32 v32, 0xbfb8aa3b, v32
	v_exp_f32_e32 v32, v32
	s_nop 0
	v_add_f32_e32 v32, 1.0, v32
	v_rcp_f32_e32 v51, v32
	v_lshlrev_b32_e32 v32, 16, v213
	v_mul_f32_e32 v32, 0xbfb8aa3b, v32
	v_exp_f32_e32 v32, v32
	v_pk_mul_f32 v[44:45], v[44:45], v[50:51]
	v_add_f32_e32 v32, 1.0, v32
	v_cvt_pk_bf16_f32 v50, v44, v45
	v_rcp_f32_e32 v44, v32
	v_and_b32_e32 v32, 0xffff0000, v213
	v_mul_f32_e32 v32, 0xbfb8aa3b, v32
	v_exp_f32_e32 v32, v32
	s_nop 0
	v_add_f32_e32 v32, 1.0, v32
	v_rcp_f32_e32 v45, v32
	s_waitcnt vmcnt(14)
	v_lshlrev_b32_e32 v32, 16, v214
	v_mul_f32_e32 v32, 0xbfb8aa3b, v32
	v_exp_f32_e32 v32, v32
	v_pk_mul_f32 v[44:45], v[46:47], v[44:45]
	v_add_f32_e32 v32, 1.0, v32
	v_rcp_f32_e32 v46, v32
	v_and_b32_e32 v32, 0xffff0000, v214
	v_mul_f32_e32 v32, 0xbfb8aa3b, v32
	v_exp_f32_e32 v32, v32
	v_cvt_pk_bf16_f32 v51, v44, v45
	v_lshlrev_b64 v[44:45], 12, v[100:101]
	v_lshl_add_u64 v[44:45], s[22:23], 0, v[44:45]
	v_add_f32_e32 v32, 1.0, v32
	v_rcp_f32_e32 v47, v32
	v_lshlrev_b32_e32 v32, 16, v215
	v_mul_f32_e32 v32, 0xbfb8aa3b, v32
	v_exp_f32_e32 v32, v32
	v_pk_mul_f32 v[40:41], v[40:41], v[46:47]
	v_lshl_add_u64 v[44:45], v[44:45], 0, v[34:35]
	v_cvt_pk_bf16_f32 v40, v40, v41
	v_add_f32_e32 v32, 1.0, v32
	v_rcp_f32_e32 v46, v32
	v_and_b32_e32 v32, 0xffff0000, v215
	v_mul_f32_e32 v32, 0xbfb8aa3b, v32
	v_exp_f32_e32 v32, v32
	global_store_dwordx4 v[44:45], v[48:51], off sc1
	v_add_f32_e32 v32, 1.0, v32
	v_rcp_f32_e32 v47, v32
	v_lshlrev_b32_e32 v32, 16, v216
	v_mul_f32_e32 v32, 0xbfb8aa3b, v32
	v_exp_f32_e32 v32, v32
	v_pk_mul_f32 v[42:43], v[42:43], v[46:47]
	v_add_f32_e32 v32, 1.0, v32
	v_cvt_pk_bf16_f32 v41, v42, v43
	v_rcp_f32_e32 v42, v32
	v_and_b32_e32 v32, 0xffff0000, v216
	v_mul_f32_e32 v32, 0xbfb8aa3b, v32
	v_exp_f32_e32 v32, v32
	s_nop 0
	v_add_f32_e32 v32, 1.0, v32
	v_rcp_f32_e32 v43, v32
	v_lshlrev_b32_e32 v32, 16, v217
	v_mul_f32_e32 v32, 0xbfb8aa3b, v32
	v_exp_f32_e32 v32, v32
	v_pk_mul_f32 v[36:37], v[36:37], v[42:43]
	v_add_f32_e32 v32, 1.0, v32
	v_cvt_pk_bf16_f32 v42, v36, v37
	v_rcp_f32_e32 v36, v32
	v_and_b32_e32 v32, 0xffff0000, v217
	v_mul_f32_e32 v32, 0xbfb8aa3b, v32
	v_exp_f32_e32 v32, v32
	s_nop 0
	v_add_f32_e32 v32, 1.0, v32
	v_rcp_f32_e32 v37, v32
	s_waitcnt vmcnt(14)
; __device__ __forceinline__ unsigned cvt_pk_bf16(float lo, float hi) { const f32x2_t v = {lo, hi}; const bf16x2_t c = __builtin_convertvector(v, bf16x2_t); return __builtin_bit_cast(unsigned, c); }
; __device__ __forceinline__ float bf_lo(unsigned w) { return __uint_as_float(w << 16); }
; __device__ __forceinline__ float bf_hi(unsigned w) { return __uint_as_float(w & 0xffff0000u); }
; __device__ __forceinline__ float sigmoidf_fast(float x) { return __builtin_amdgcn_rcpf(1.0f + __expf(-x)); }
;     __device__ __forceinline__ void operator()(const f32x4 (&acc)[2][2][4][2], const Unit& u, int wr, int wc, int fr, int fq) const {
;     ...
;             for (int m = 0; m < 4; ++m) { const size_t r = (size_t)(row0 + ai * HALF + m * 16);
; #pragma unroll
;                 for (int bj = 0; bj < 2; ++bj) { const u32x4 gw = gq[m][bj]; const f32x4 a0 = acc[ai][bj][m][0], a1 = acc[ai][bj][m][1];
;                     u32x4 w; w.x = cvt_pk_bf16(sigmoidf_fast(bf_lo(gw.x)) * a0[0], sigmoidf_fast(bf_hi(gw.x)) * a0[1]); w.y = cvt_pk_bf16(sigmoidf_fast(bf_lo(gw.y)) * a0[2], sigmoidf_fast(bf_hi(gw.y)) * a0[3]);
;                     w.z = cvt_pk_bf16(sigmoidf_fast(bf_lo(gw.z)) * a1[0], sigmoidf_fast(bf_hi(gw.z)) * a1[1]); w.w = cvt_pk_bf16(sigmoidf_fast(bf_lo(gw.w)) * a1[2], sigmoidf_fast(bf_hi(gw.w)) * a1[3]);
;                     *(u32x4*)(T + r * ldt + col0 + bj * HALF) = w; } }
;             asm volatile("" ::: "memory"); }
	v_lshlrev_b32_e32 v32, 16, v218
	v_mul_f32_e32 v32, 0xbfb8aa3b, v32
	v_exp_f32_e32 v32, v32
	v_pk_mul_f32 v[36:37], v[38:39], v[36:37]
	v_add_f32_e32 v32, 1.0, v32
	v_cvt_pk_bf16_f32 v43, v36, v37
	v_rcp_f32_e32 v36, v32
	v_and_b32_e32 v32, 0xffff0000, v218
	v_mul_f32_e32 v32, 0xbfb8aa3b, v32
	v_exp_f32_e32 v32, v32
	global_store_dwordx4 v[44:45], v[40:43], off offset:256 sc1
	v_add_f32_e32 v32, 1.0, v32
	v_rcp_f32_e32 v37, v32
	s_nop 0
	v_pk_mul_f32 v[28:29], v[28:29], v[36:37]
	s_nop 0
	v_cvt_pk_bf16_f32 v28, v28, v29
	v_lshlrev_b32_e32 v29, 16, v219
	v_mul_f32_e32 v29, 0xbfb8aa3b, v29
	v_exp_f32_e32 v29, v29
	s_nop 0
	v_add_f32_e32 v29, 1.0, v29
	v_rcp_f32_e32 v36, v29
	v_and_b32_e32 v29, 0xffff0000, v219
	v_mul_f32_e32 v29, 0xbfb8aa3b, v29
	v_exp_f32_e32 v29, v29
	s_nop 0
	v_add_f32_e32 v29, 1.0, v29
	v_rcp_f32_e32 v37, v29
	s_nop 0
	v_pk_mul_f32 v[30:31], v[30:31], v[36:37]
	s_nop 0
	v_cvt_pk_bf16_f32 v29, v30, v31
	v_lshlrev_b32_e32 v30, 16, v220
	v_and_b32_e32 v31, 0xffff0000, v220
	v_mul_f32_e32 v30, 0xbfb8aa3b, v30
	v_mul_f32_e32 v31, 0xbfb8aa3b, v31
	v_exp_f32_e32 v30, v30
	v_exp_f32_e32 v31, v31
	v_add_f32_e32 v30, 1.0, v30
	v_add_f32_e32 v31, 1.0, v31
	v_rcp_f32_e32 v30, v30
	v_rcp_f32_e32 v31, v31
	s_nop 0
	v_pk_mul_f32 v[24:25], v[24:25], v[30:31]
	s_nop 0
	v_cvt_pk_bf16_f32 v30, v24, v25
	v_lshlrev_b32_e32 v24, 16, v221
	v_and_b32_e32 v25, 0xffff0000, v221
	v_mul_f32_e32 v24, 0xbfb8aa3b, v24
	v_mul_f32_e32 v25, 0xbfb8aa3b, v25
	v_exp_f32_e32 v24, v24
	v_exp_f32_e32 v25, v25
	v_add_f32_e32 v24, 1.0, v24
	v_add_f32_e32 v25, 1.0, v25
	v_rcp_f32_e32 v24, v24
	v_rcp_f32_e32 v25, v25
	s_nop 0
	v_pk_mul_f32 v[24:25], v[26:27], v[24:25]
	s_waitcnt vmcnt(14)
	v_lshlrev_b32_e32 v26, 16, v222
	v_and_b32_e32 v27, 0xffff0000, v222
	v_mul_f32_e32 v26, 0xbfb8aa3b, v26
	v_mul_f32_e32 v27, 0xbfb8aa3b, v27
	v_exp_f32_e32 v26, v26
	v_exp_f32_e32 v27, v27
	v_cvt_pk_bf16_f32 v31, v24, v25
	v_lshlrev_b64 v[24:25], 12, v[98:99]
	v_add_f32_e32 v26, 1.0, v26
	v_add_f32_e32 v27, 1.0, v27
	v_rcp_f32_e32 v26, v26
	v_rcp_f32_e32 v27, v27
	v_lshl_add_u64 v[24:25], s[22:23], 0, v[24:25]
	v_lshl_add_u64 v[24:25], v[24:25], 0, v[34:35]
	global_store_dwordx4 v[24:25], v[28:31], off sc1
	v_pk_mul_f32 v[20:21], v[20:21], v[26:27]
	s_nop 0
	v_cvt_pk_bf16_f32 v20, v20, v21
	v_lshlrev_b32_e32 v21, 16, v223
	v_mul_f32_e32 v21, 0xbfb8aa3b, v21
	v_exp_f32_e32 v21, v21
	s_nop 0
	v_add_f32_e32 v21, 1.0, v21
	v_rcp_f32_e32 v26, v21
	v_and_b32_e32 v21, 0xffff0000, v223
	v_mul_f32_e32 v21, 0xbfb8aa3b, v21
	v_exp_f32_e32 v21, v21
	s_nop 0
	v_add_f32_e32 v21, 1.0, v21
	v_rcp_f32_e32 v27, v21
	s_nop 0
	v_pk_mul_f32 v[22:23], v[22:23], v[26:27]
	s_nop 0
	v_cvt_pk_bf16_f32 v21, v22, v23
	v_lshlrev_b32_e32 v22, 16, v224
	v_and_b32_e32 v23, 0xffff0000, v224
	v_mul_f32_e32 v22, 0xbfb8aa3b, v22
	v_mul_f32_e32 v23, 0xbfb8aa3b, v23
	v_exp_f32_e32 v22, v22
	v_exp_f32_e32 v23, v23
	v_add_f32_e32 v22, 1.0, v22
	v_add_f32_e32 v23, 1.0, v23
	v_rcp_f32_e32 v22, v22
	v_rcp_f32_e32 v23, v23
	s_nop 0
	v_pk_mul_f32 v[16:17], v[16:17], v[22:23]
	s_nop 0
	v_cvt_pk_bf16_f32 v22, v16, v17
	v_lshlrev_b32_e32 v16, 16, v225
	v_and_b32_e32 v17, 0xffff0000, v225
	v_mul_f32_e32 v16, 0xbfb8aa3b, v16
	v_mul_f32_e32 v17, 0xbfb8aa3b, v17
	v_exp_f32_e32 v16, v16
	v_exp_f32_e32 v17, v17
	v_add_f32_e32 v16, 1.0, v16
	v_add_f32_e32 v17, 1.0, v17
	v_rcp_f32_e32 v16, v16
	v_rcp_f32_e32 v17, v17
	s_nop 0
	v_pk_mul_f32 v[16:17], v[18:19], v[16:17]
	s_nop 0
	v_cvt_pk_bf16_f32 v23, v16, v17
	s_waitcnt vmcnt(6)
	v_lshlrev_b32_e32 v16, 16, v72
	v_and_b32_e32 v17, 0xffff0000, v72
	v_mul_f32_e32 v16, 0xbfb8aa3b, v16
	v_mul_f32_e32 v17, 0xbfb8aa3b, v17
	v_exp_f32_e32 v16, v16
	v_exp_f32_e32 v17, v17
	global_store_dwordx4 v[24:25], v[20:23], off offset:256 sc1
	v_add_f32_e32 v16, 1.0, v16
	v_add_f32_e32 v17, 1.0, v17
	v_rcp_f32_e32 v16, v16
	v_rcp_f32_e32 v17, v17
	s_nop 0
	v_pk_mul_f32 v[12:13], v[12:13], v[16:17]
	s_nop 0
	v_cvt_pk_bf16_f32 v12, v12, v13
	v_lshlrev_b32_e32 v13, 16, v73
	v_mul_f32_e32 v13, 0xbfb8aa3b, v13
	v_exp_f32_e32 v13, v13
	s_nop 0
	v_add_f32_e32 v13, 1.0, v13
	v_rcp_f32_e32 v16, v13
	v_and_b32_e32 v13, 0xffff0000, v73
	v_mul_f32_e32 v13, 0xbfb8aa3b, v13
	v_exp_f32_e32 v13, v13
	s_nop 0
	v_add_f32_e32 v13, 1.0, v13
	v_rcp_f32_e32 v17, v13
	s_nop 0
	v_pk_mul_f32 v[14:15], v[14:15], v[16:17]
	s_nop 0
	v_cvt_pk_bf16_f32 v13, v14, v15
	v_lshlrev_b32_e32 v14, 16, v74
	v_and_b32_e32 v15, 0xffff0000, v74
	v_mul_f32_e32 v14, 0xbfb8aa3b, v14
	v_mul_f32_e32 v15, 0xbfb8aa3b, v15
	v_exp_f32_e32 v14, v14
	v_exp_f32_e32 v15, v15
	v_add_f32_e32 v14, 1.0, v14
	v_add_f32_e32 v15, 1.0, v15
	v_rcp_f32_e32 v14, v14
	v_rcp_f32_e32 v15, v15
	s_nop 0
	v_pk_mul_f32 v[8:9], v[8:9], v[14:15]
	s_nop 0
	v_cvt_pk_bf16_f32 v14, v8, v9
	v_lshlrev_b32_e32 v8, 16, v75
	v_and_b32_e32 v9, 0xffff0000, v75
	v_mul_f32_e32 v8, 0xbfb8aa3b, v8
	v_mul_f32_e32 v9, 0xbfb8aa3b, v9
	v_exp_f32_e32 v8, v8
	v_exp_f32_e32 v9, v9
	v_add_f32_e32 v8, 1.0, v8
	v_add_f32_e32 v9, 1.0, v9
	v_rcp_f32_e32 v8, v8
	v_rcp_f32_e32 v9, v9
	s_nop 0
	v_pk_mul_f32 v[8:9], v[10:11], v[8:9]
	s_waitcnt vmcnt(6)
	v_lshlrev_b32_e32 v10, 16, v68
	v_and_b32_e32 v11, 0xffff0000, v68
	v_mul_f32_e32 v10, 0xbfb8aa3b, v10
	v_mul_f32_e32 v11, 0xbfb8aa3b, v11
	v_exp_f32_e32 v10, v10
	v_exp_f32_e32 v11, v11
	v_cvt_pk_bf16_f32 v15, v8, v9
	v_lshlrev_b64 v[8:9], 12, v[96:97]
	v_add_f32_e32 v10, 1.0, v10
	v_add_f32_e32 v11, 1.0, v11
	v_rcp_f32_e32 v10, v10
	v_rcp_f32_e32 v11, v11
	v_lshl_add_u64 v[8:9], s[22:23], 0, v[8:9]
	v_lshl_add_u64 v[8:9], v[8:9], 0, v[34:35]
	global_store_dwordx4 v[8:9], v[12:15], off sc1
	v_pk_mul_f32 v[4:5], v[4:5], v[10:11]
	s_nop 0
	v_cvt_pk_bf16_f32 v4, v4, v5
	v_lshlrev_b32_e32 v5, 16, v69
	v_mul_f32_e32 v5, 0xbfb8aa3b, v5
	v_exp_f32_e32 v5, v5
	s_nop 0
	v_add_f32_e32 v5, 1.0, v5
	v_rcp_f32_e32 v10, v5
	v_and_b32_e32 v5, 0xffff0000, v69
	v_mul_f32_e32 v5, 0xbfb8aa3b, v5
	v_exp_f32_e32 v5, v5
	s_nop 0
	v_add_f32_e32 v5, 1.0, v5
	v_rcp_f32_e32 v11, v5
	s_nop 0
	v_pk_mul_f32 v[6:7], v[6:7], v[10:11]
	s_nop 0
	v_cvt_pk_bf16_f32 v5, v6, v7
	v_lshlrev_b32_e32 v6, 16, v70
	v_and_b32_e32 v7, 0xffff0000, v70
	v_mul_f32_e32 v6, 0xbfb8aa3b, v6
	v_mul_f32_e32 v7, 0xbfb8aa3b, v7
	v_exp_f32_e32 v6, v6
	v_exp_f32_e32 v7, v7
	v_add_f32_e32 v6, 1.0, v6
	v_add_f32_e32 v7, 1.0, v7
	v_rcp_f32_e32 v6, v6
	v_rcp_f32_e32 v7, v7
	s_nop 0
	v_pk_mul_f32 v[0:1], v[0:1], v[6:7]
	s_nop 0
	v_cvt_pk_bf16_f32 v6, v0, v1
	v_lshlrev_b32_e32 v0, 16, v71
	v_and_b32_e32 v1, 0xffff0000, v71
	v_mul_f32_e32 v0, 0xbfb8aa3b, v0
	v_mul_f32_e32 v1, 0xbfb8aa3b, v1
	v_exp_f32_e32 v0, v0
	v_exp_f32_e32 v1, v1
	v_add_f32_e32 v0, 1.0, v0
	v_add_f32_e32 v1, 1.0, v1
	v_rcp_f32_e32 v0, v0
	v_rcp_f32_e32 v1, v1
	s_nop 0
	v_pk_mul_f32 v[0:1], v[2:3], v[0:1]
	s_nop 0
	v_cvt_pk_bf16_f32 v7, v0, v1
	global_store_dwordx4 v[8:9], v[4:7], off offset:256 sc1
	s_cbranch_vccnz .LBB0_834
; #define PG8_LAS __attribute__((address_space(3)))
; template <class Epi, class Sched, bool ALIGN_EPI = false, bool SP2 = false, bool KHOOK = false>
; __device__ __forceinline__ void gemm_phase(PG8_LAS unsigned char* lds, const Gemm g, const Sched& S, const Epi& E, const int tid_in) {
;     ...
;     auto load_rr = [&](const Unit& uu) { if constexpr (KHOOK) { const int row = tid >> 1, hf = tid & 1; const f32x4 v = *(const f32x4*)(g.rr + ((size_t)(uu.pm * BM + row)) * 8 + 4 * hf);
;         PG8_LAS float* T = (PG8_LAS float*)(lds + 8 * 16384) + (4 * hf) * 256 + row; T[0] = v[0]; T[256] = v[1]; T[512] = v[2]; T[768] = v[3]; } };
;     load_rr(cur);
	v_lshl_add_u32 v0, s8, 8, v184
	v_ashrrev_i32_e32 v1, 31, v0
	v_lshlrev_b64 v[0:1], 5, v[0:1]
	v_lshl_add_u64 v[0:1], v[168:169], 0, v[0:1]
	global_load_dwordx4 v[0:3], v[0:1], off
	s_andn2_b64 vcc, exec, s[0:1]
	s_waitcnt vmcnt(0)
	ds_write2st64_b32 v185, v0, v1 offset1:4
	ds_write2st64_b32 v185, v2, v3 offset0:8 offset1:12
	s_cbranch_vccnz .LBB0_833
	s_barrier
	s_branch .LBB0_833

; __device__ __forceinline__ unsigned cvt_pk_bf16(float lo, float hi) { const f32x2_t v = {lo, hi}; const bf16x2_t c = __builtin_convertvector(v, bf16x2_t); return __builtin_bit_cast(unsigned, c); }
; __device__ __forceinline__ float bf_lo(unsigned w) { return __uint_as_float(w << 16); }
; __device__ __forceinline__ float bf_hi(unsigned w) { return __uint_as_float(w & 0xffff0000u); }
; __device__ __forceinline__ float sigmoidf_fast(float x) { return __builtin_amdgcn_rcpf(1.0f + __expf(-x)); }
;     __device__ __forceinline__ void operator()(const f32x4 (&acc)[2][2][4][2], const Unit& u, int wr, int wc, int fr, int fq) const {
;     ...
;                 for (int bj = 0; bj < 2; ++bj) { const size_t r = (size_t)(row0 + ai * HALF + m * 16); gq[m][bj] = *(const u32x4*)(G + r * ldg + col0 + bj * HALF); tq[m][bj] = *(const u32x4*)(T + r * ldt + col0 + bj * HALF); }
; #pragma unroll
;             for (int m = 0; m < 4; ++m) { const size_t r = (size_t)(row0 + ai * HALF + m * 16);
; #pragma unroll
;                 for (int bj = 0; bj < 2; ++bj) { const u32x4 gw = gq[m][bj], tw = tq[m][bj]; const f32x4 a0 = acc[ai][bj][m][0], a1 = acc[ai][bj][m][1];
;                     u32x4 w;
;                     w.x = cvt_pk_bf16(bf_lo(tw.x) + sigmoidf_fast(bf_lo(gw.x)) * a0[0], bf_hi(tw.x) + sigmoidf_fast(bf_hi(gw.x)) * a0[1]); w.y = cvt_pk_bf16(bf_lo(tw.y) + sigmoidf_fast(bf_lo(gw.y)) * a0[2], bf_hi(tw.y) + sigmoidf_fast(bf_hi(gw.y)) * a0[3]);
;                     w.z = cvt_pk_bf16(bf_lo(tw.z) + sigmoidf_fast(bf_lo(gw.z)) * a1[0], bf_hi(tw.z) + sigmoidf_fast(bf_hi(gw.z)) * a1[1]); w.w = cvt_pk_bf16(bf_lo(tw.w) + sigmoidf_fast(bf_lo(gw.w)) * a1[2], bf_hi(tw.w) + sigmoidf_fast(bf_hi(gw.w)) * a1[3]);
;                     *(u32x4*)(O + r * ldo + col0 + bj * HALF) = w; } }
.LBB0_870:
	v_lshl_or_b32 v106, s25, 8, v248
	v_ashrrev_i32_e32 v107, 31, v106
	v_readlane_b32 s16, v253, 20
	v_lshlrev_b64 v[212:213], 1, v[106:107]
	v_readlane_b32 s17, v253, 21
	v_lshl_add_u32 v214, s24, 8, v246
	v_ashrrev_i32_e32 v215, 31, v214
	v_lshl_add_u64 v[216:217], s[16:17], 0, v[212:213]
	v_readlane_b32 s16, v252, 55
	v_readlane_b32 s17, v252, 56
	v_lshlrev_b64 v[226:227], 12, v[214:215]
	v_readlane_b32 s22, v254, 2
	v_lshl_add_u64 v[218:219], s[16:17], 0, v[212:213]
	v_mad_i64_i32 v[106:107], s[16:17], v214, s67, v[216:217]
	v_lshl_add_u64 v[108:109], v[218:219], 0, v[226:227]
	global_load_dwordx4 v[190:193], v[106:107], off
	global_load_dwordx4 v[186:189], v[108:109], off
	global_load_dwordx4 v[182:185], v[106:107], off offset:256
	global_load_dwordx4 v[178:181], v[108:109], off offset:256
	v_or_b32_e32 v106, 16, v214
	v_ashrrev_i32_e32 v107, 31, v106
	v_mad_i64_i32 v[108:109], s[16:17], v106, s67, v[216:217]
	v_lshlrev_b64 v[224:225], 12, v[106:107]
	v_lshl_add_u64 v[106:107], v[218:219], 0, v[224:225]
	global_load_dwordx4 v[174:177], v[108:109], off
	global_load_dwordx4 v[170:173], v[106:107], off
	global_load_dwordx4 v[162:165], v[108:109], off offset:256
	global_load_dwordx4 v[158:161], v[106:107], off offset:256
	v_or_b32_e32 v106, 32, v214
	v_ashrrev_i32_e32 v107, 31, v106
	v_lshlrev_b64 v[222:223], 12, v[106:107]
	v_mad_i64_i32 v[108:109], s[16:17], v106, s67, v[216:217]
	v_lshl_add_u64 v[106:107], v[218:219], 0, v[222:223]
	global_load_dwordx4 v[154:157], v[108:109], off
	global_load_dwordx4 v[150:153], v[106:107], off
	global_load_dwordx4 v[138:141], v[108:109], off offset:256
	global_load_dwordx4 v[134:137], v[106:107], off offset:256
	v_or_b32_e32 v106, 48, v214
	v_ashrrev_i32_e32 v107, 31, v106
	v_readlane_b32 s23, v254, 3
	v_lshlrev_b64 v[220:221], 12, v[106:107]
	v_mad_i64_i32 v[108:109], s[16:17], v106, s67, v[216:217]
	v_lshl_add_u64 v[106:107], v[218:219], 0, v[220:221]
	global_load_dwordx4 v[130:133], v[108:109], off
	global_load_dwordx4 v[122:125], v[106:107], off
	global_load_dwordx4 v[110:113], v[108:109], off offset:256
	s_nop 0
	global_load_dwordx4 v[106:109], v[106:107], off offset:256
	s_andn2_b64 vcc, exec, s[10:11]
	s_waitcnt vmcnt(0)
	v_lshlrev_b32_e32 v198, 16, v190
	v_and_b32_e32 v190, 0xffff0000, v190
	v_mul_f32_e32 v198, 0xbfb8aa3b, v198
	v_mul_f32_e32 v190, 0xbfb8aa3b, v190
	v_exp_f32_e32 v198, v198
	v_exp_f32_e32 v190, v190
	v_lshlrev_b32_e32 v200, 16, v186
	v_and_b32_e32 v201, 0xffff0000, v186
	v_add_f32_e32 v198, 1.0, v198
	v_add_f32_e32 v190, 1.0, v190
	v_rcp_f32_e32 v198, v198
	v_rcp_f32_e32 v199, v190
	v_lshlrev_b32_e32 v186, 16, v187
	v_and_b32_e32 v187, 0xffff0000, v187
	v_pk_fma_f32 v[166:167], v[166:167], v[198:199], v[200:201]
	s_nop 0
	v_cvt_pk_bf16_f32 v166, v166, v167
	v_lshlrev_b32_e32 v167, 16, v191
	v_mul_f32_e32 v167, 0xbfb8aa3b, v167
	v_exp_f32_e32 v167, v167
	s_nop 0
	v_add_f32_e32 v167, 1.0, v167
	v_rcp_f32_e32 v190, v167
	v_and_b32_e32 v167, 0xffff0000, v191
	v_mul_f32_e32 v167, 0xbfb8aa3b, v167
	v_exp_f32_e32 v167, v167
	s_nop 0
	v_add_f32_e32 v167, 1.0, v167
	v_rcp_f32_e32 v191, v167
	s_nop 0
	v_pk_fma_f32 v[168:169], v[168:169], v[190:191], v[186:187]
	s_nop 0
	v_cvt_pk_bf16_f32 v167, v168, v169
	v_lshlrev_b32_e32 v168, 16, v192
	v_and_b32_e32 v169, 0xffff0000, v192
	v_mul_f32_e32 v168, 0xbfb8aa3b, v168
	v_mul_f32_e32 v169, 0xbfb8aa3b, v169
	v_exp_f32_e32 v168, v168
	v_exp_f32_e32 v169, v169
	v_lshlrev_b32_e32 v186, 16, v188
	v_and_b32_e32 v187, 0xffff0000, v188
	v_add_f32_e32 v168, 1.0, v168
	v_add_f32_e32 v169, 1.0, v169
	v_rcp_f32_e32 v168, v168
	v_rcp_f32_e32 v169, v169
	s_nop 0
	v_pk_fma_f32 v[146:147], v[146:147], v[168:169], v[186:187]
	s_nop 0
	v_cvt_pk_bf16_f32 v168, v146, v147
	v_lshlrev_b32_e32 v146, 16, v193
	v_and_b32_e32 v147, 0xffff0000, v193
	v_mul_f32_e32 v146, 0xbfb8aa3b, v146
	v_mul_f32_e32 v147, 0xbfb8aa3b, v147
	v_exp_f32_e32 v146, v146
	v_exp_f32_e32 v147, v147
	v_lshlrev_b32_e32 v186, 16, v189
	v_and_b32_e32 v187, 0xffff0000, v189
	v_add_f32_e32 v146, 1.0, v146
	v_add_f32_e32 v147, 1.0, v147
	v_rcp_f32_e32 v146, v146
	v_rcp_f32_e32 v147, v147
	s_nop 0
	v_pk_fma_f32 v[146:147], v[148:149], v[146:147], v[186:187]
	v_lshlrev_b32_e32 v148, 16, v182
	v_and_b32_e32 v149, 0xffff0000, v182
	v_mul_f32_e32 v148, 0xbfb8aa3b, v148
	v_mul_f32_e32 v149, 0xbfb8aa3b, v149
	v_exp_f32_e32 v148, v148
	v_exp_f32_e32 v149, v149
	v_cvt_pk_bf16_f32 v169, v146, v147
	v_lshl_add_u64 v[146:147], s[22:23], 0, v[226:227]
	v_add_f32_e32 v148, 1.0, v148
	v_add_f32_e32 v149, 1.0, v149
	v_rcp_f32_e32 v148, v148
	v_rcp_f32_e32 v149, v149
	v_lshl_add_u64 v[146:147], v[146:147], 0, v[212:213]
	global_store_dwordx4 v[146:147], v[166:169], off sc1
	s_nop 1
	v_lshlrev_b32_e32 v166, 16, v178
	v_and_b32_e32 v167, 0xffff0000, v178
	v_pk_fma_f32 v[142:143], v[142:143], v[148:149], v[166:167]
	v_lshlrev_b32_e32 v166, 16, v179
	v_cvt_pk_bf16_f32 v142, v142, v143
	v_lshlrev_b32_e32 v143, 16, v183
	v_mul_f32_e32 v143, 0xbfb8aa3b, v143
	v_exp_f32_e32 v143, v143
	v_and_b32_e32 v167, 0xffff0000, v179
	v_add_f32_e32 v143, 1.0, v143
	v_rcp_f32_e32 v148, v143
	v_and_b32_e32 v143, 0xffff0000, v183
	v_mul_f32_e32 v143, 0xbfb8aa3b, v143
	v_exp_f32_e32 v143, v143
	s_nop 0
	v_add_f32_e32 v143, 1.0, v143
	v_rcp_f32_e32 v149, v143
	s_nop 0
	v_pk_fma_f32 v[144:145], v[144:145], v[148:149], v[166:167]
	s_nop 0
	v_cvt_pk_bf16_f32 v143, v144, v145
	v_lshlrev_b32_e32 v144, 16, v184
	v_and_b32_e32 v145, 0xffff0000, v184
	v_mul_f32_e32 v144, 0xbfb8aa3b, v144
	v_mul_f32_e32 v145, 0xbfb8aa3b, v145
	v_exp_f32_e32 v144, v144
	v_exp_f32_e32 v145, v145
	v_lshlrev_b32_e32 v148, 16, v180
	v_and_b32_e32 v149, 0xffff0000, v180
; __device__ __forceinline__ unsigned cvt_pk_bf16(float lo, float hi) { const f32x2_t v = {lo, hi}; const bf16x2_t c = __builtin_convertvector(v, bf16x2_t); return __builtin_bit_cast(unsigned, c); }
; __device__ __forceinline__ float bf_lo(unsigned w) { return __uint_as_float(w << 16); }
; __device__ __forceinline__ float bf_hi(unsigned w) { return __uint_as_float(w & 0xffff0000u); }
; __device__ __forceinline__ float sigmoidf_fast(float x) { return __builtin_amdgcn_rcpf(1.0f + __expf(-x)); }
;     __device__ __forceinline__ void operator()(const f32x4 (&acc)[2][2][4][2], const Unit& u, int wr, int wc, int fr, int fq) const {
;     ...
;             for (int m = 0; m < 4; ++m) { const size_t r = (size_t)(row0 + ai * HALF + m * 16);
; #pragma unroll
;                 for (int bj = 0; bj < 2; ++bj) { const u32x4 gw = gq[m][bj], tw = tq[m][bj]; const f32x4 a0 = acc[ai][bj][m][0], a1 = acc[ai][bj][m][1];
;                     u32x4 w;
;                     w.x = cvt_pk_bf16(bf_lo(tw.x) + sigmoidf_fast(bf_lo(gw.x)) * a0[0], bf_hi(tw.x) + sigmoidf_fast(bf_hi(gw.x)) * a0[1]); w.y = cvt_pk_bf16(bf_lo(tw.y) + sigmoidf_fast(bf_lo(gw.y)) * a0[2], bf_hi(tw.y) + sigmoidf_fast(bf_hi(gw.y)) * a0[3]);
;                     w.z = cvt_pk_bf16(bf_lo(tw.z) + sigmoidf_fast(bf_lo(gw.z)) * a1[0], bf_hi(tw.z) + sigmoidf_fast(bf_hi(gw.z)) * a1[1]); w.w = cvt_pk_bf16(bf_lo(tw.w) + sigmoidf_fast(bf_lo(gw.w)) * a1[2], bf_hi(tw.w) + sigmoidf_fast(bf_hi(gw.w)) * a1[3]);
;                     *(u32x4*)(O + r * ldo + col0 + bj * HALF) = w; } }
	v_add_f32_e32 v144, 1.0, v144
	v_add_f32_e32 v145, 1.0, v145
	v_rcp_f32_e32 v144, v144
	v_rcp_f32_e32 v145, v145
	s_nop 0
	v_pk_fma_f32 v[126:127], v[126:127], v[144:145], v[148:149]
	s_nop 0
	v_cvt_pk_bf16_f32 v144, v126, v127
	v_lshlrev_b32_e32 v126, 16, v185
	v_and_b32_e32 v127, 0xffff0000, v185
	v_mul_f32_e32 v126, 0xbfb8aa3b, v126
	v_mul_f32_e32 v127, 0xbfb8aa3b, v127
	v_exp_f32_e32 v126, v126
	v_exp_f32_e32 v127, v127
	v_lshlrev_b32_e32 v148, 16, v181
	v_and_b32_e32 v149, 0xffff0000, v181
	v_add_f32_e32 v126, 1.0, v126
	v_add_f32_e32 v127, 1.0, v127
	v_rcp_f32_e32 v126, v126
	v_rcp_f32_e32 v127, v127
	s_nop 0
	v_pk_fma_f32 v[126:127], v[128:129], v[126:127], v[148:149]
	s_nop 0
	v_cvt_pk_bf16_f32 v145, v126, v127
	v_lshlrev_b32_e32 v126, 16, v174
	v_and_b32_e32 v127, 0xffff0000, v174
	v_mul_f32_e32 v126, 0xbfb8aa3b, v126
	v_mul_f32_e32 v127, 0xbfb8aa3b, v127
	v_exp_f32_e32 v126, v126
	v_exp_f32_e32 v127, v127
	v_lshlrev_b32_e32 v128, 16, v170
	v_and_b32_e32 v129, 0xffff0000, v170
	v_add_f32_e32 v126, 1.0, v126
	v_add_f32_e32 v127, 1.0, v127
	v_rcp_f32_e32 v126, v126
	v_rcp_f32_e32 v127, v127
	global_store_dwordx4 v[146:147], v[142:145], off offset:256 sc1
	v_pk_fma_f32 v[118:119], v[118:119], v[126:127], v[128:129]
	s_nop 0
	v_cvt_pk_bf16_f32 v118, v118, v119
	v_lshlrev_b32_e32 v119, 16, v175
	v_mul_f32_e32 v119, 0xbfb8aa3b, v119
	v_exp_f32_e32 v119, v119
	v_lshlrev_b32_e32 v128, 16, v171
	v_and_b32_e32 v129, 0xffff0000, v171
	v_add_f32_e32 v119, 1.0, v119
	v_rcp_f32_e32 v126, v119
	v_and_b32_e32 v119, 0xffff0000, v175
	v_mul_f32_e32 v119, 0xbfb8aa3b, v119
	v_exp_f32_e32 v119, v119
	s_nop 0
	v_add_f32_e32 v119, 1.0, v119
	v_rcp_f32_e32 v127, v119
	s_nop 0
	v_pk_fma_f32 v[120:121], v[120:121], v[126:127], v[128:129]
	s_nop 0
	v_cvt_pk_bf16_f32 v119, v120, v121
	v_lshlrev_b32_e32 v120, 16, v176
	v_and_b32_e32 v121, 0xffff0000, v176
	v_mul_f32_e32 v120, 0xbfb8aa3b, v120
	v_mul_f32_e32 v121, 0xbfb8aa3b, v121
	v_exp_f32_e32 v120, v120
	v_exp_f32_e32 v121, v121
	v_lshlrev_b32_e32 v126, 16, v172
	v_and_b32_e32 v127, 0xffff0000, v172
	v_add_f32_e32 v120, 1.0, v120
	v_add_f32_e32 v121, 1.0, v121
	v_rcp_f32_e32 v120, v120
	v_rcp_f32_e32 v121, v121
	s_nop 0
	v_pk_fma_f32 v[114:115], v[114:115], v[120:121], v[126:127]
	s_nop 0
	v_cvt_pk_bf16_f32 v120, v114, v115
	v_lshlrev_b32_e32 v114, 16, v177
	v_and_b32_e32 v115, 0xffff0000, v177
	v_mul_f32_e32 v114, 0xbfb8aa3b, v114
	v_mul_f32_e32 v115, 0xbfb8aa3b, v115
	v_exp_f32_e32 v114, v114
	v_exp_f32_e32 v115, v115
	v_lshlrev_b32_e32 v126, 16, v173
	v_and_b32_e32 v127, 0xffff0000, v173
	v_add_f32_e32 v114, 1.0, v114
	v_add_f32_e32 v115, 1.0, v115
	v_rcp_f32_e32 v114, v114
	v_rcp_f32_e32 v115, v115
	s_nop 0
	v_pk_fma_f32 v[114:115], v[116:117], v[114:115], v[126:127]
	v_lshlrev_b32_e32 v116, 16, v162
	v_and_b32_e32 v117, 0xffff0000, v162
	v_mul_f32_e32 v116, 0xbfb8aa3b, v116
	v_mul_f32_e32 v117, 0xbfb8aa3b, v117
	v_exp_f32_e32 v116, v116
	v_exp_f32_e32 v117, v117
	v_cvt_pk_bf16_f32 v121, v114, v115
	v_lshl_add_u64 v[114:115], s[22:23], 0, v[224:225]
	v_add_f32_e32 v116, 1.0, v116
	v_add_f32_e32 v117, 1.0, v117
	v_rcp_f32_e32 v116, v116
	v_rcp_f32_e32 v117, v117
	v_lshl_add_u64 v[114:115], v[114:115], 0, v[212:213]
	global_store_dwordx4 v[114:115], v[118:121], off sc1
	s_nop 1
	v_lshlrev_b32_e32 v118, 16, v158
	v_and_b32_e32 v119, 0xffff0000, v158
	v_pk_fma_f32 v[102:103], v[102:103], v[116:117], v[118:119]
	v_lshlrev_b32_e32 v118, 16, v159
	v_cvt_pk_bf16_f32 v102, v102, v103
	v_lshlrev_b32_e32 v103, 16, v163
	v_mul_f32_e32 v103, 0xbfb8aa3b, v103
	v_exp_f32_e32 v103, v103
	v_and_b32_e32 v119, 0xffff0000, v159
	v_add_f32_e32 v103, 1.0, v103
	v_rcp_f32_e32 v116, v103
	v_and_b32_e32 v103, 0xffff0000, v163
	v_mul_f32_e32 v103, 0xbfb8aa3b, v103
	v_exp_f32_e32 v103, v103
	s_nop 0
	v_add_f32_e32 v103, 1.0, v103
	v_rcp_f32_e32 v117, v103
	s_nop 0
	v_pk_fma_f32 v[104:105], v[104:105], v[116:117], v[118:119]
	s_nop 0
	v_cvt_pk_bf16_f32 v103, v104, v105
	v_lshlrev_b32_e32 v104, 16, v164
	v_and_b32_e32 v105, 0xffff0000, v164
	v_mul_f32_e32 v104, 0xbfb8aa3b, v104
	v_mul_f32_e32 v105, 0xbfb8aa3b, v105
	v_exp_f32_e32 v104, v104
	v_exp_f32_e32 v105, v105
	v_lshlrev_b32_e32 v116, 16, v160
	v_and_b32_e32 v117, 0xffff0000, v160
	v_add_f32_e32 v104, 1.0, v104
	v_add_f32_e32 v105, 1.0, v105
	v_rcp_f32_e32 v104, v104
	v_rcp_f32_e32 v105, v105
	s_nop 0
	v_pk_fma_f32 v[98:99], v[98:99], v[104:105], v[116:117]
	s_nop 0
	v_cvt_pk_bf16_f32 v104, v98, v99
	v_lshlrev_b32_e32 v98, 16, v165
	v_and_b32_e32 v99, 0xffff0000, v165
	v_mul_f32_e32 v98, 0xbfb8aa3b, v98
	v_mul_f32_e32 v99, 0xbfb8aa3b, v99
	v_exp_f32_e32 v98, v98
	v_exp_f32_e32 v99, v99
	v_lshlrev_b32_e32 v116, 16, v161
	v_and_b32_e32 v117, 0xffff0000, v161
	v_add_f32_e32 v98, 1.0, v98
	v_add_f32_e32 v99, 1.0, v99
	v_rcp_f32_e32 v98, v98
	v_rcp_f32_e32 v99, v99
	s_nop 0
	v_pk_fma_f32 v[98:99], v[100:101], v[98:99], v[116:117]
	s_nop 0
	v_cvt_pk_bf16_f32 v105, v98, v99
	v_lshlrev_b32_e32 v98, 16, v154
	v_and_b32_e32 v99, 0xffff0000, v154
	v_mul_f32_e32 v98, 0xbfb8aa3b, v98
	v_mul_f32_e32 v99, 0xbfb8aa3b, v99
	v_exp_f32_e32 v98, v98
	v_exp_f32_e32 v99, v99
	v_lshlrev_b32_e32 v100, 16, v150
	v_and_b32_e32 v101, 0xffff0000, v150
	v_add_f32_e32 v98, 1.0, v98
	v_add_f32_e32 v99, 1.0, v99
	v_rcp_f32_e32 v98, v98
	v_rcp_f32_e32 v99, v99
	global_store_dwordx4 v[114:115], v[102:105], off offset:256 sc1
	v_pk_fma_f32 v[94:95], v[94:95], v[98:99], v[100:101]
	s_nop 0
	v_cvt_pk_bf16_f32 v94, v94, v95
	v_lshlrev_b32_e32 v95, 16, v155
	v_mul_f32_e32 v95, 0xbfb8aa3b, v95
	v_exp_f32_e32 v95, v95
	v_lshlrev_b32_e32 v100, 16, v151
	v_and_b32_e32 v101, 0xffff0000, v151
	v_add_f32_e32 v95, 1.0, v95
; __device__ __forceinline__ unsigned cvt_pk_bf16(float lo, float hi) { const f32x2_t v = {lo, hi}; const bf16x2_t c = __builtin_convertvector(v, bf16x2_t); return __builtin_bit_cast(unsigned, c); }
; __device__ __forceinline__ float bf_lo(unsigned w) { return __uint_as_float(w << 16); }
; __device__ __forceinline__ float bf_hi(unsigned w) { return __uint_as_float(w & 0xffff0000u); }
; __device__ __forceinline__ float sigmoidf_fast(float x) { return __builtin_amdgcn_rcpf(1.0f + __expf(-x)); }
;     __device__ __forceinline__ void operator()(const f32x4 (&acc)[2][2][4][2], const Unit& u, int wr, int wc, int fr, int fq) const {
;     ...
;             for (int m = 0; m < 4; ++m) { const size_t r = (size_t)(row0 + ai * HALF + m * 16);
; #pragma unroll
;                 for (int bj = 0; bj < 2; ++bj) { const u32x4 gw = gq[m][bj], tw = tq[m][bj]; const f32x4 a0 = acc[ai][bj][m][0], a1 = acc[ai][bj][m][1];
;                     u32x4 w;
;                     w.x = cvt_pk_bf16(bf_lo(tw.x) + sigmoidf_fast(bf_lo(gw.x)) * a0[0], bf_hi(tw.x) + sigmoidf_fast(bf_hi(gw.x)) * a0[1]); w.y = cvt_pk_bf16(bf_lo(tw.y) + sigmoidf_fast(bf_lo(gw.y)) * a0[2], bf_hi(tw.y) + sigmoidf_fast(bf_hi(gw.y)) * a0[3]);
;                     w.z = cvt_pk_bf16(bf_lo(tw.z) + sigmoidf_fast(bf_lo(gw.z)) * a1[0], bf_hi(tw.z) + sigmoidf_fast(bf_hi(gw.z)) * a1[1]); w.w = cvt_pk_bf16(bf_lo(tw.w) + sigmoidf_fast(bf_lo(gw.w)) * a1[2], bf_hi(tw.w) + sigmoidf_fast(bf_hi(gw.w)) * a1[3]);
;                     *(u32x4*)(O + r * ldo + col0 + bj * HALF) = w; } }
	v_rcp_f32_e32 v98, v95
	v_and_b32_e32 v95, 0xffff0000, v155
	v_mul_f32_e32 v95, 0xbfb8aa3b, v95
	v_exp_f32_e32 v95, v95
	s_nop 0
	v_add_f32_e32 v95, 1.0, v95
	v_rcp_f32_e32 v99, v95
	s_nop 0
	v_pk_fma_f32 v[96:97], v[96:97], v[98:99], v[100:101]
	s_nop 0
	v_cvt_pk_bf16_f32 v95, v96, v97
	v_lshlrev_b32_e32 v96, 16, v156
	v_and_b32_e32 v97, 0xffff0000, v156
	v_mul_f32_e32 v96, 0xbfb8aa3b, v96
	v_mul_f32_e32 v97, 0xbfb8aa3b, v97
	v_exp_f32_e32 v96, v96
	v_exp_f32_e32 v97, v97
	v_lshlrev_b32_e32 v98, 16, v152
	v_and_b32_e32 v99, 0xffff0000, v152
	v_add_f32_e32 v96, 1.0, v96
	v_add_f32_e32 v97, 1.0, v97
	v_rcp_f32_e32 v96, v96
	v_rcp_f32_e32 v97, v97
	s_nop 0
	v_pk_fma_f32 v[90:91], v[90:91], v[96:97], v[98:99]
	s_nop 0
	v_cvt_pk_bf16_f32 v96, v90, v91
	v_lshlrev_b32_e32 v90, 16, v157
	v_and_b32_e32 v91, 0xffff0000, v157
	v_mul_f32_e32 v90, 0xbfb8aa3b, v90
	v_mul_f32_e32 v91, 0xbfb8aa3b, v91
	v_exp_f32_e32 v90, v90
	v_exp_f32_e32 v91, v91
	v_lshlrev_b32_e32 v98, 16, v153
	v_and_b32_e32 v99, 0xffff0000, v153
	v_add_f32_e32 v90, 1.0, v90
	v_add_f32_e32 v91, 1.0, v91
	v_rcp_f32_e32 v90, v90
	v_rcp_f32_e32 v91, v91
	s_nop 0
	v_pk_fma_f32 v[90:91], v[92:93], v[90:91], v[98:99]
	v_lshlrev_b32_e32 v92, 16, v138
	v_and_b32_e32 v93, 0xffff0000, v138
	v_mul_f32_e32 v92, 0xbfb8aa3b, v92
	v_mul_f32_e32 v93, 0xbfb8aa3b, v93
	v_exp_f32_e32 v92, v92
	v_exp_f32_e32 v93, v93
	v_cvt_pk_bf16_f32 v97, v90, v91
	v_lshl_add_u64 v[90:91], s[22:23], 0, v[222:223]
	v_add_f32_e32 v92, 1.0, v92
	v_add_f32_e32 v93, 1.0, v93
	v_rcp_f32_e32 v92, v92
	v_rcp_f32_e32 v93, v93
	v_lshl_add_u64 v[90:91], v[90:91], 0, v[212:213]
	global_store_dwordx4 v[90:91], v[94:97], off sc1
	s_nop 1
	v_lshlrev_b32_e32 v94, 16, v134
	v_and_b32_e32 v95, 0xffff0000, v134
	v_pk_fma_f32 v[86:87], v[86:87], v[92:93], v[94:95]
	v_lshlrev_b32_e32 v94, 16, v135
	v_cvt_pk_bf16_f32 v86, v86, v87
	v_lshlrev_b32_e32 v87, 16, v139
	v_mul_f32_e32 v87, 0xbfb8aa3b, v87
	v_exp_f32_e32 v87, v87
	v_and_b32_e32 v95, 0xffff0000, v135
	v_add_f32_e32 v87, 1.0, v87
	v_rcp_f32_e32 v92, v87
	v_and_b32_e32 v87, 0xffff0000, v139
	v_mul_f32_e32 v87, 0xbfb8aa3b, v87
	v_exp_f32_e32 v87, v87
	s_nop 0
	v_add_f32_e32 v87, 1.0, v87
	v_rcp_f32_e32 v93, v87
	s_nop 0
	v_pk_fma_f32 v[88:89], v[88:89], v[92:93], v[94:95]
	s_nop 0
	v_cvt_pk_bf16_f32 v87, v88, v89
	v_lshlrev_b32_e32 v88, 16, v140
	v_and_b32_e32 v89, 0xffff0000, v140
	v_mul_f32_e32 v88, 0xbfb8aa3b, v88
	v_mul_f32_e32 v89, 0xbfb8aa3b, v89
	v_exp_f32_e32 v88, v88
	v_exp_f32_e32 v89, v89
	v_lshlrev_b32_e32 v92, 16, v136
	v_and_b32_e32 v93, 0xffff0000, v136
	v_add_f32_e32 v88, 1.0, v88
	v_add_f32_e32 v89, 1.0, v89
	v_rcp_f32_e32 v88, v88
	v_rcp_f32_e32 v89, v89
	s_nop 0
	v_pk_fma_f32 v[82:83], v[82:83], v[88:89], v[92:93]
	s_nop 0
	v_cvt_pk_bf16_f32 v88, v82, v83
	v_lshlrev_b32_e32 v82, 16, v141
	v_and_b32_e32 v83, 0xffff0000, v141
	v_mul_f32_e32 v82, 0xbfb8aa3b, v82
	v_mul_f32_e32 v83, 0xbfb8aa3b, v83
	v_exp_f32_e32 v82, v82
	v_exp_f32_e32 v83, v83
	v_lshlrev_b32_e32 v92, 16, v137
	v_and_b32_e32 v93, 0xffff0000, v137
	v_add_f32_e32 v82, 1.0, v82
	v_add_f32_e32 v83, 1.0, v83
	v_rcp_f32_e32 v82, v82
	v_rcp_f32_e32 v83, v83
	s_nop 0
	v_pk_fma_f32 v[82:83], v[84:85], v[82:83], v[92:93]
	s_nop 0
	v_cvt_pk_bf16_f32 v89, v82, v83
	v_lshlrev_b32_e32 v82, 16, v130
	v_and_b32_e32 v83, 0xffff0000, v130
	v_mul_f32_e32 v82, 0xbfb8aa3b, v82
	v_mul_f32_e32 v83, 0xbfb8aa3b, v83
	v_exp_f32_e32 v82, v82
	v_exp_f32_e32 v83, v83
	v_lshlrev_b32_e32 v84, 16, v122
	v_and_b32_e32 v85, 0xffff0000, v122
	v_add_f32_e32 v82, 1.0, v82
	v_add_f32_e32 v83, 1.0, v83
	v_rcp_f32_e32 v82, v82
	v_rcp_f32_e32 v83, v83
	global_store_dwordx4 v[90:91], v[86:89], off offset:256 sc1
	v_pk_fma_f32 v[78:79], v[78:79], v[82:83], v[84:85]
	s_nop 0
	v_cvt_pk_bf16_f32 v78, v78, v79
	v_lshlrev_b32_e32 v79, 16, v131
	v_mul_f32_e32 v79, 0xbfb8aa3b, v79
	v_exp_f32_e32 v79, v79
	v_lshlrev_b32_e32 v84, 16, v123
	v_and_b32_e32 v85, 0xffff0000, v123
	v_add_f32_e32 v79, 1.0, v79
	v_rcp_f32_e32 v82, v79
	v_and_b32_e32 v79, 0xffff0000, v131
	v_mul_f32_e32 v79, 0xbfb8aa3b, v79
	v_exp_f32_e32 v79, v79
	s_nop 0
	v_add_f32_e32 v79, 1.0, v79
	v_rcp_f32_e32 v83, v79
	s_nop 0
	v_pk_fma_f32 v[80:81], v[80:81], v[82:83], v[84:85]
	s_nop 0
	v_cvt_pk_bf16_f32 v79, v80, v81
	v_lshlrev_b32_e32 v80, 16, v132
	v_and_b32_e32 v81, 0xffff0000, v132
	v_mul_f32_e32 v80, 0xbfb8aa3b, v80
	v_mul_f32_e32 v81, 0xbfb8aa3b, v81
	v_exp_f32_e32 v80, v80
	v_exp_f32_e32 v81, v81
	v_lshlrev_b32_e32 v82, 16, v124
	v_and_b32_e32 v83, 0xffff0000, v124
	v_add_f32_e32 v80, 1.0, v80
	v_add_f32_e32 v81, 1.0, v81
	v_rcp_f32_e32 v80, v80
	v_rcp_f32_e32 v81, v81
	s_nop 0
	v_pk_fma_f32 v[74:75], v[74:75], v[80:81], v[82:83]
	s_nop 0
	v_cvt_pk_bf16_f32 v80, v74, v75
	v_lshlrev_b32_e32 v74, 16, v133
	v_and_b32_e32 v75, 0xffff0000, v133
	v_mul_f32_e32 v74, 0xbfb8aa3b, v74
	v_mul_f32_e32 v75, 0xbfb8aa3b, v75
	v_exp_f32_e32 v74, v74
	v_exp_f32_e32 v75, v75
	v_lshlrev_b32_e32 v82, 16, v125
	v_and_b32_e32 v83, 0xffff0000, v125
	v_add_f32_e32 v74, 1.0, v74
	v_add_f32_e32 v75, 1.0, v75
	v_rcp_f32_e32 v74, v74
	v_rcp_f32_e32 v75, v75
	s_nop 0
	v_pk_fma_f32 v[74:75], v[76:77], v[74:75], v[82:83]
	v_lshlrev_b32_e32 v76, 16, v110
	v_and_b32_e32 v77, 0xffff0000, v110
	v_mul_f32_e32 v76, 0xbfb8aa3b, v76
	v_mul_f32_e32 v77, 0xbfb8aa3b, v77
	v_exp_f32_e32 v76, v76
	v_exp_f32_e32 v77, v77
	v_cvt_pk_bf16_f32 v81, v74, v75
	v_lshl_add_u64 v[74:75], s[22:23], 0, v[220:221]
	v_add_f32_e32 v76, 1.0, v76
	v_add_f32_e32 v77, 1.0, v77
	v_rcp_f32_e32 v76, v76
	v_rcp_f32_e32 v77, v77
	v_lshl_add_u64 v[74:75], v[74:75], 0, v[212:213]
	global_store_dwordx4 v[74:75], v[78:81], off sc1
	s_nop 1
; __device__ __forceinline__ unsigned cvt_pk_bf16(float lo, float hi) { const f32x2_t v = {lo, hi}; const bf16x2_t c = __builtin_convertvector(v, bf16x2_t); return __builtin_bit_cast(unsigned, c); }
; __device__ __forceinline__ float bf_lo(unsigned w) { return __uint_as_float(w << 16); }
; __device__ __forceinline__ float bf_hi(unsigned w) { return __uint_as_float(w & 0xffff0000u); }
; __device__ __forceinline__ float sigmoidf_fast(float x) { return __builtin_amdgcn_rcpf(1.0f + __expf(-x)); }
;     __device__ __forceinline__ void operator()(const f32x4 (&acc)[2][2][4][2], const Unit& u, int wr, int wc, int fr, int fq) const {
;     ...
;         for (int ai = 0; ai < 2; ++ai) { u32x4 gq[4][2], tq[4][2];
; #pragma unroll
;             for (int m = 0; m < 4; ++m)
; #pragma unroll
;                 for (int bj = 0; bj < 2; ++bj) { const size_t r = (size_t)(row0 + ai * HALF + m * 16); gq[m][bj] = *(const u32x4*)(G + r * ldg + col0 + bj * HALF); tq[m][bj] = *(const u32x4*)(T + r * ldt + col0 + bj * HALF); }
; #pragma unroll
;             for (int m = 0; m < 4; ++m) { const size_t r = (size_t)(row0 + ai * HALF + m * 16);
; #pragma unroll
;                 for (int bj = 0; bj < 2; ++bj) { const u32x4 gw = gq[m][bj], tw = tq[m][bj]; const f32x4 a0 = acc[ai][bj][m][0], a1 = acc[ai][bj][m][1];
;                     u32x4 w;
;                     w.x = cvt_pk_bf16(bf_lo(tw.x) + sigmoidf_fast(bf_lo(gw.x)) * a0[0], bf_hi(tw.x) + sigmoidf_fast(bf_hi(gw.x)) * a0[1]); w.y = cvt_pk_bf16(bf_lo(tw.y) + sigmoidf_fast(bf_lo(gw.y)) * a0[2], bf_hi(tw.y) + sigmoidf_fast(bf_hi(gw.y)) * a0[3]);
;                     w.z = cvt_pk_bf16(bf_lo(tw.z) + sigmoidf_fast(bf_lo(gw.z)) * a1[0], bf_hi(tw.z) + sigmoidf_fast(bf_hi(gw.z)) * a1[1]); w.w = cvt_pk_bf16(bf_lo(tw.w) + sigmoidf_fast(bf_lo(gw.w)) * a1[2], bf_hi(tw.w) + sigmoidf_fast(bf_hi(gw.w)) * a1[3]);
;                     *(u32x4*)(O + r * ldo + col0 + bj * HALF) = w; } }
	v_lshlrev_b32_e32 v78, 16, v106
	v_and_b32_e32 v79, 0xffff0000, v106
	v_pk_fma_f32 v[70:71], v[70:71], v[76:77], v[78:79]
	v_lshlrev_b32_e32 v78, 16, v107
	v_cvt_pk_bf16_f32 v70, v70, v71
	v_lshlrev_b32_e32 v71, 16, v111
	v_mul_f32_e32 v71, 0xbfb8aa3b, v71
	v_exp_f32_e32 v71, v71
	v_and_b32_e32 v79, 0xffff0000, v107
	v_add_f32_e32 v71, 1.0, v71
	v_rcp_f32_e32 v76, v71
	v_and_b32_e32 v71, 0xffff0000, v111
	v_mul_f32_e32 v71, 0xbfb8aa3b, v71
	v_exp_f32_e32 v71, v71
	s_nop 0
	v_add_f32_e32 v71, 1.0, v71
	v_rcp_f32_e32 v77, v71
	s_nop 0
	v_pk_fma_f32 v[72:73], v[72:73], v[76:77], v[78:79]
	s_nop 0
	v_cvt_pk_bf16_f32 v71, v72, v73
	v_lshlrev_b32_e32 v72, 16, v112
	v_and_b32_e32 v73, 0xffff0000, v112
	v_mul_f32_e32 v72, 0xbfb8aa3b, v72
	v_mul_f32_e32 v73, 0xbfb8aa3b, v73
	v_exp_f32_e32 v72, v72
	v_exp_f32_e32 v73, v73
	v_lshlrev_b32_e32 v76, 16, v108
	v_and_b32_e32 v77, 0xffff0000, v108
	v_add_f32_e32 v72, 1.0, v72
	v_add_f32_e32 v73, 1.0, v73
	v_rcp_f32_e32 v72, v72
	v_rcp_f32_e32 v73, v73
	s_nop 0
	v_pk_fma_f32 v[66:67], v[66:67], v[72:73], v[76:77]
	s_nop 0
	v_cvt_pk_bf16_f32 v72, v66, v67
	v_lshlrev_b32_e32 v66, 16, v113
	v_and_b32_e32 v67, 0xffff0000, v113
	v_mul_f32_e32 v66, 0xbfb8aa3b, v66
	v_mul_f32_e32 v67, 0xbfb8aa3b, v67
	v_exp_f32_e32 v66, v66
	v_exp_f32_e32 v67, v67
	v_lshlrev_b32_e32 v76, 16, v109
	v_and_b32_e32 v77, 0xffff0000, v109
	v_add_f32_e32 v66, 1.0, v66
	v_add_f32_e32 v67, 1.0, v67
	v_rcp_f32_e32 v66, v66
	v_rcp_f32_e32 v67, v67
	s_nop 0
	v_pk_fma_f32 v[66:67], v[68:69], v[66:67], v[76:77]
	s_nop 0
	v_cvt_pk_bf16_f32 v73, v66, v67
	v_add_u32_e32 v66, 0x80, v214
	global_store_dwordx4 v[74:75], v[70:73], off offset:256 sc1
	v_ashrrev_i32_e32 v67, 31, v66
	v_mad_i64_i32 v[68:69], s[16:17], v66, s67, v[216:217]
	v_lshlrev_b64 v[128:129], 12, v[66:67]
	v_lshl_add_u64 v[66:67], v[218:219], 0, v[128:129]
	global_load_dwordx4 v[130:133], v[68:69], off
	global_load_dwordx4 v[134:137], v[66:67], off
	global_load_dwordx4 v[118:121], v[68:69], off offset:256
	global_load_dwordx4 v[114:117], v[66:67], off offset:256
	v_add_u32_e32 v66, 0x90, v214
	v_ashrrev_i32_e32 v67, 31, v66
	v_mad_i64_i32 v[68:69], s[16:17], v66, s67, v[216:217]
	v_lshlrev_b64 v[126:127], 12, v[66:67]
	v_lshl_add_u64 v[66:67], v[218:219], 0, v[126:127]
	global_load_dwordx4 v[110:113], v[68:69], off
	global_load_dwordx4 v[106:109], v[66:67], off
	global_load_dwordx4 v[102:105], v[68:69], off offset:256
	global_load_dwordx4 v[98:101], v[66:67], off offset:256
	v_add_u32_e32 v66, 0xa0, v214
	v_ashrrev_i32_e32 v67, 31, v66
	v_lshlrev_b64 v[124:125], 12, v[66:67]
	v_mad_i64_i32 v[68:69], s[16:17], v66, s67, v[216:217]
	v_lshl_add_u64 v[66:67], v[218:219], 0, v[124:125]
	global_load_dwordx4 v[94:97], v[68:69], off
	global_load_dwordx4 v[90:93], v[66:67], off
	global_load_dwordx4 v[86:89], v[68:69], off offset:256
	global_load_dwordx4 v[82:85], v[66:67], off offset:256
	v_add_u32_e32 v66, 0xb0, v214
	v_ashrrev_i32_e32 v67, 31, v66
	v_lshlrev_b64 v[122:123], 12, v[66:67]
	v_mad_i64_i32 v[68:69], s[16:17], v66, s67, v[216:217]
	v_lshl_add_u64 v[66:67], v[218:219], 0, v[122:123]
	global_load_dwordx4 v[78:81], v[68:69], off
	global_load_dwordx4 v[74:77], v[66:67], off
	global_load_dwordx4 v[70:73], v[68:69], off offset:256
	s_nop 0
	global_load_dwordx4 v[66:69], v[66:67], off offset:256
	s_mov_b64 s[16:17], -1
	s_waitcnt vmcnt(15)
	v_lshlrev_b32_e32 v138, 16, v130
	v_and_b32_e32 v130, 0xffff0000, v130
	v_mul_f32_e32 v138, 0xbfb8aa3b, v138
	v_mul_f32_e32 v130, 0xbfb8aa3b, v130
	v_exp_f32_e32 v138, v138
	v_exp_f32_e32 v130, v130
	s_waitcnt vmcnt(14)
	v_lshlrev_b32_e32 v140, 16, v134
	v_and_b32_e32 v141, 0xffff0000, v134
	v_add_f32_e32 v138, 1.0, v138
	v_add_f32_e32 v130, 1.0, v130
	v_rcp_f32_e32 v138, v138
	v_rcp_f32_e32 v139, v130
	v_lshlrev_b32_e32 v134, 16, v135
	v_and_b32_e32 v135, 0xffff0000, v135
	v_pk_fma_f32 v[62:63], v[62:63], v[138:139], v[140:141]
	s_nop 0
	v_cvt_pk_bf16_f32 v62, v62, v63
	v_lshlrev_b32_e32 v63, 16, v131
	v_mul_f32_e32 v63, 0xbfb8aa3b, v63
	v_exp_f32_e32 v63, v63
	s_nop 0
	v_add_f32_e32 v63, 1.0, v63
	v_rcp_f32_e32 v130, v63
	v_and_b32_e32 v63, 0xffff0000, v131
	v_mul_f32_e32 v63, 0xbfb8aa3b, v63
	v_exp_f32_e32 v63, v63
	s_nop 0
	v_add_f32_e32 v63, 1.0, v63
	v_rcp_f32_e32 v131, v63
	s_nop 0
	v_pk_fma_f32 v[64:65], v[64:65], v[130:131], v[134:135]
	s_nop 0
	v_cvt_pk_bf16_f32 v63, v64, v65
	v_lshlrev_b32_e32 v64, 16, v132
	v_and_b32_e32 v65, 0xffff0000, v132
	v_mul_f32_e32 v64, 0xbfb8aa3b, v64
	v_mul_f32_e32 v65, 0xbfb8aa3b, v65
	v_exp_f32_e32 v64, v64
	v_exp_f32_e32 v65, v65
	v_lshlrev_b32_e32 v130, 16, v136
	v_and_b32_e32 v131, 0xffff0000, v136
	v_add_f32_e32 v64, 1.0, v64
	v_add_f32_e32 v65, 1.0, v65
	v_rcp_f32_e32 v64, v64
	v_rcp_f32_e32 v65, v65
	s_nop 0
	v_pk_fma_f32 v[58:59], v[58:59], v[64:65], v[130:131]
	s_nop 0
	v_cvt_pk_bf16_f32 v64, v58, v59
	v_lshlrev_b32_e32 v58, 16, v133
	v_and_b32_e32 v59, 0xffff0000, v133
	v_mul_f32_e32 v58, 0xbfb8aa3b, v58
	v_mul_f32_e32 v59, 0xbfb8aa3b, v59
	v_exp_f32_e32 v58, v58
	v_exp_f32_e32 v59, v59
	v_lshlrev_b32_e32 v130, 16, v137
	v_and_b32_e32 v131, 0xffff0000, v137
	v_add_f32_e32 v58, 1.0, v58
	v_add_f32_e32 v59, 1.0, v59
	v_rcp_f32_e32 v58, v58
	v_rcp_f32_e32 v59, v59
	s_nop 0
	v_pk_fma_f32 v[58:59], v[60:61], v[58:59], v[130:131]
	s_waitcnt vmcnt(13)
	v_lshlrev_b32_e32 v60, 16, v118
	v_and_b32_e32 v61, 0xffff0000, v118
	v_mul_f32_e32 v60, 0xbfb8aa3b, v60
	v_mul_f32_e32 v61, 0xbfb8aa3b, v61
	v_exp_f32_e32 v60, v60
	v_exp_f32_e32 v61, v61
	v_cvt_pk_bf16_f32 v65, v58, v59
	v_lshl_add_u64 v[58:59], s[22:23], 0, v[128:129]
	v_add_f32_e32 v60, 1.0, v60
	v_add_f32_e32 v61, 1.0, v61
	v_rcp_f32_e32 v60, v60
	v_rcp_f32_e32 v61, v61
	v_lshl_add_u64 v[58:59], v[58:59], 0, v[212:213]
	global_store_dwordx4 v[58:59], v[62:65], off sc1
	s_waitcnt vmcnt(13)
; __device__ __forceinline__ unsigned cvt_pk_bf16(float lo, float hi) { const f32x2_t v = {lo, hi}; const bf16x2_t c = __builtin_convertvector(v, bf16x2_t); return __builtin_bit_cast(unsigned, c); }
; __device__ __forceinline__ float bf_lo(unsigned w) { return __uint_as_float(w << 16); }
; __device__ __forceinline__ float bf_hi(unsigned w) { return __uint_as_float(w & 0xffff0000u); }
; __device__ __forceinline__ float sigmoidf_fast(float x) { return __builtin_amdgcn_rcpf(1.0f + __expf(-x)); }
;     __device__ __forceinline__ void operator()(const f32x4 (&acc)[2][2][4][2], const Unit& u, int wr, int wc, int fr, int fq) const {
;     ...
;             for (int m = 0; m < 4; ++m) { const size_t r = (size_t)(row0 + ai * HALF + m * 16);
; #pragma unroll
;                 for (int bj = 0; bj < 2; ++bj) { const u32x4 gw = gq[m][bj], tw = tq[m][bj]; const f32x4 a0 = acc[ai][bj][m][0], a1 = acc[ai][bj][m][1];
;                     u32x4 w;
;                     w.x = cvt_pk_bf16(bf_lo(tw.x) + sigmoidf_fast(bf_lo(gw.x)) * a0[0], bf_hi(tw.x) + sigmoidf_fast(bf_hi(gw.x)) * a0[1]); w.y = cvt_pk_bf16(bf_lo(tw.y) + sigmoidf_fast(bf_lo(gw.y)) * a0[2], bf_hi(tw.y) + sigmoidf_fast(bf_hi(gw.y)) * a0[3]);
;                     w.z = cvt_pk_bf16(bf_lo(tw.z) + sigmoidf_fast(bf_lo(gw.z)) * a1[0], bf_hi(tw.z) + sigmoidf_fast(bf_hi(gw.z)) * a1[1]); w.w = cvt_pk_bf16(bf_lo(tw.w) + sigmoidf_fast(bf_lo(gw.w)) * a1[2], bf_hi(tw.w) + sigmoidf_fast(bf_hi(gw.w)) * a1[3]);
;                     *(u32x4*)(O + r * ldo + col0 + bj * HALF) = w; } }
	s_nop 0
	v_lshlrev_b32_e32 v62, 16, v114
	v_and_b32_e32 v63, 0xffff0000, v114
	v_pk_fma_f32 v[54:55], v[54:55], v[60:61], v[62:63]
	v_lshlrev_b32_e32 v62, 16, v115
	v_cvt_pk_bf16_f32 v54, v54, v55
	v_lshlrev_b32_e32 v55, 16, v119
	v_mul_f32_e32 v55, 0xbfb8aa3b, v55
	v_exp_f32_e32 v55, v55
	v_and_b32_e32 v63, 0xffff0000, v115
	v_add_f32_e32 v55, 1.0, v55
	v_rcp_f32_e32 v60, v55
	v_and_b32_e32 v55, 0xffff0000, v119
	v_mul_f32_e32 v55, 0xbfb8aa3b, v55
	v_exp_f32_e32 v55, v55
	s_nop 0
	v_add_f32_e32 v55, 1.0, v55
	v_rcp_f32_e32 v61, v55
	s_nop 0
	v_pk_fma_f32 v[56:57], v[56:57], v[60:61], v[62:63]
	s_nop 0
	v_cvt_pk_bf16_f32 v55, v56, v57
	v_lshlrev_b32_e32 v56, 16, v120
	v_and_b32_e32 v57, 0xffff0000, v120
	v_mul_f32_e32 v56, 0xbfb8aa3b, v56
	v_mul_f32_e32 v57, 0xbfb8aa3b, v57
	v_exp_f32_e32 v56, v56
	v_exp_f32_e32 v57, v57
	v_lshlrev_b32_e32 v60, 16, v116
	v_and_b32_e32 v61, 0xffff0000, v116
	v_add_f32_e32 v56, 1.0, v56
	v_add_f32_e32 v57, 1.0, v57
	v_rcp_f32_e32 v56, v56
	v_rcp_f32_e32 v57, v57
	s_nop 0
	v_pk_fma_f32 v[50:51], v[50:51], v[56:57], v[60:61]
	s_nop 0
	v_cvt_pk_bf16_f32 v56, v50, v51
	v_lshlrev_b32_e32 v50, 16, v121
	v_and_b32_e32 v51, 0xffff0000, v121
	v_mul_f32_e32 v50, 0xbfb8aa3b, v50
	v_mul_f32_e32 v51, 0xbfb8aa3b, v51
	v_exp_f32_e32 v50, v50
	v_exp_f32_e32 v51, v51
	v_lshlrev_b32_e32 v60, 16, v117
	v_and_b32_e32 v61, 0xffff0000, v117
	v_add_f32_e32 v50, 1.0, v50
	v_add_f32_e32 v51, 1.0, v51
	v_rcp_f32_e32 v50, v50
	v_rcp_f32_e32 v51, v51
	s_nop 0
	v_pk_fma_f32 v[50:51], v[52:53], v[50:51], v[60:61]
	s_nop 0
	v_cvt_pk_bf16_f32 v57, v50, v51
	s_waitcnt vmcnt(12)
	v_lshlrev_b32_e32 v50, 16, v110
	v_and_b32_e32 v51, 0xffff0000, v110
	v_mul_f32_e32 v50, 0xbfb8aa3b, v50
	v_mul_f32_e32 v51, 0xbfb8aa3b, v51
	v_exp_f32_e32 v50, v50
	v_exp_f32_e32 v51, v51
	s_waitcnt vmcnt(11)
	v_lshlrev_b32_e32 v52, 16, v106
	v_and_b32_e32 v53, 0xffff0000, v106
	v_add_f32_e32 v50, 1.0, v50
	v_add_f32_e32 v51, 1.0, v51
	v_rcp_f32_e32 v50, v50
	v_rcp_f32_e32 v51, v51
	global_store_dwordx4 v[58:59], v[54:57], off offset:256 sc1
	v_pk_fma_f32 v[46:47], v[46:47], v[50:51], v[52:53]
	s_nop 0
	v_cvt_pk_bf16_f32 v46, v46, v47
	v_lshlrev_b32_e32 v47, 16, v111
	v_mul_f32_e32 v47, 0xbfb8aa3b, v47
	v_exp_f32_e32 v47, v47
	v_lshlrev_b32_e32 v52, 16, v107
	v_and_b32_e32 v53, 0xffff0000, v107
	v_add_f32_e32 v47, 1.0, v47
	v_rcp_f32_e32 v50, v47
	v_and_b32_e32 v47, 0xffff0000, v111
	v_mul_f32_e32 v47, 0xbfb8aa3b, v47
	v_exp_f32_e32 v47, v47
	s_nop 0
	v_add_f32_e32 v47, 1.0, v47
	v_rcp_f32_e32 v51, v47
	s_nop 0
	v_pk_fma_f32 v[48:49], v[48:49], v[50:51], v[52:53]
	s_nop 0
	v_cvt_pk_bf16_f32 v47, v48, v49
	v_lshlrev_b32_e32 v48, 16, v112
	v_and_b32_e32 v49, 0xffff0000, v112
	v_mul_f32_e32 v48, 0xbfb8aa3b, v48
	v_mul_f32_e32 v49, 0xbfb8aa3b, v49
	v_exp_f32_e32 v48, v48
	v_exp_f32_e32 v49, v49
	v_lshlrev_b32_e32 v50, 16, v108
	v_and_b32_e32 v51, 0xffff0000, v108
	v_add_f32_e32 v48, 1.0, v48
	v_add_f32_e32 v49, 1.0, v49
	v_rcp_f32_e32 v48, v48
	v_rcp_f32_e32 v49, v49
	s_nop 0
	v_pk_fma_f32 v[42:43], v[42:43], v[48:49], v[50:51]
	s_nop 0
	v_cvt_pk_bf16_f32 v48, v42, v43
	v_lshlrev_b32_e32 v42, 16, v113
	v_and_b32_e32 v43, 0xffff0000, v113
	v_mul_f32_e32 v42, 0xbfb8aa3b, v42
	v_mul_f32_e32 v43, 0xbfb8aa3b, v43
	v_exp_f32_e32 v42, v42
	v_exp_f32_e32 v43, v43
	v_lshlrev_b32_e32 v50, 16, v109
	v_and_b32_e32 v51, 0xffff0000, v109
	v_add_f32_e32 v42, 1.0, v42
	v_add_f32_e32 v43, 1.0, v43
	v_rcp_f32_e32 v42, v42
	v_rcp_f32_e32 v43, v43
	s_nop 0
	v_pk_fma_f32 v[42:43], v[44:45], v[42:43], v[50:51]
	s_waitcnt vmcnt(11)
	v_lshlrev_b32_e32 v44, 16, v102
	v_and_b32_e32 v45, 0xffff0000, v102
	v_mul_f32_e32 v44, 0xbfb8aa3b, v44
	v_mul_f32_e32 v45, 0xbfb8aa3b, v45
	v_exp_f32_e32 v44, v44
	v_exp_f32_e32 v45, v45
	v_cvt_pk_bf16_f32 v49, v42, v43
	v_lshl_add_u64 v[42:43], s[22:23], 0, v[126:127]
	v_add_f32_e32 v44, 1.0, v44
	v_add_f32_e32 v45, 1.0, v45
	v_rcp_f32_e32 v44, v44
	v_rcp_f32_e32 v45, v45
	v_lshl_add_u64 v[42:43], v[42:43], 0, v[212:213]
	global_store_dwordx4 v[42:43], v[46:49], off sc1
	s_waitcnt vmcnt(11)
	s_nop 0
	v_lshlrev_b32_e32 v46, 16, v98
	v_and_b32_e32 v47, 0xffff0000, v98
	v_pk_fma_f32 v[38:39], v[38:39], v[44:45], v[46:47]
	v_lshlrev_b32_e32 v46, 16, v99
	v_cvt_pk_bf16_f32 v38, v38, v39
	v_lshlrev_b32_e32 v39, 16, v103
	v_mul_f32_e32 v39, 0xbfb8aa3b, v39
	v_exp_f32_e32 v39, v39
	v_and_b32_e32 v47, 0xffff0000, v99
	v_add_f32_e32 v39, 1.0, v39
	v_rcp_f32_e32 v44, v39
	v_and_b32_e32 v39, 0xffff0000, v103
	v_mul_f32_e32 v39, 0xbfb8aa3b, v39
	v_exp_f32_e32 v39, v39
	s_nop 0
	v_add_f32_e32 v39, 1.0, v39
	v_rcp_f32_e32 v45, v39
	s_nop 0
	v_pk_fma_f32 v[40:41], v[40:41], v[44:45], v[46:47]
	s_nop 0
	v_cvt_pk_bf16_f32 v39, v40, v41
	v_lshlrev_b32_e32 v40, 16, v104
	v_and_b32_e32 v41, 0xffff0000, v104
	v_mul_f32_e32 v40, 0xbfb8aa3b, v40
	v_mul_f32_e32 v41, 0xbfb8aa3b, v41
	v_exp_f32_e32 v40, v40
	v_exp_f32_e32 v41, v41
	v_lshlrev_b32_e32 v44, 16, v100
	v_and_b32_e32 v45, 0xffff0000, v100
	v_add_f32_e32 v40, 1.0, v40
	v_add_f32_e32 v41, 1.0, v41
	v_rcp_f32_e32 v40, v40
	v_rcp_f32_e32 v41, v41
	s_nop 0
	v_pk_fma_f32 v[34:35], v[34:35], v[40:41], v[44:45]
	s_nop 0
	v_cvt_pk_bf16_f32 v40, v34, v35
	v_lshlrev_b32_e32 v34, 16, v105
	v_and_b32_e32 v35, 0xffff0000, v105
	v_mul_f32_e32 v34, 0xbfb8aa3b, v34
	v_mul_f32_e32 v35, 0xbfb8aa3b, v35
	v_exp_f32_e32 v34, v34
	v_exp_f32_e32 v35, v35
	v_lshlrev_b32_e32 v44, 16, v101
	v_and_b32_e32 v45, 0xffff0000, v101
	v_add_f32_e32 v34, 1.0, v34
	v_add_f32_e32 v35, 1.0, v35
	v_rcp_f32_e32 v34, v34
	v_rcp_f32_e32 v35, v35
	s_nop 0
	v_pk_fma_f32 v[34:35], v[36:37], v[34:35], v[44:45]
	s_nop 0
	v_cvt_pk_bf16_f32 v41, v34, v35
	s_waitcnt vmcnt(10)
; __device__ __forceinline__ unsigned cvt_pk_bf16(float lo, float hi) { const f32x2_t v = {lo, hi}; const bf16x2_t c = __builtin_convertvector(v, bf16x2_t); return __builtin_bit_cast(unsigned, c); }
; __device__ __forceinline__ float bf_lo(unsigned w) { return __uint_as_float(w << 16); }
; __device__ __forceinline__ float bf_hi(unsigned w) { return __uint_as_float(w & 0xffff0000u); }
; __device__ __forceinline__ float sigmoidf_fast(float x) { return __builtin_amdgcn_rcpf(1.0f + __expf(-x)); }
;     __device__ __forceinline__ void operator()(const f32x4 (&acc)[2][2][4][2], const Unit& u, int wr, int wc, int fr, int fq) const {
;     ...
;             for (int m = 0; m < 4; ++m) { const size_t r = (size_t)(row0 + ai * HALF + m * 16);
; #pragma unroll
;                 for (int bj = 0; bj < 2; ++bj) { const u32x4 gw = gq[m][bj], tw = tq[m][bj]; const f32x4 a0 = acc[ai][bj][m][0], a1 = acc[ai][bj][m][1];
;                     u32x4 w;
;                     w.x = cvt_pk_bf16(bf_lo(tw.x) + sigmoidf_fast(bf_lo(gw.x)) * a0[0], bf_hi(tw.x) + sigmoidf_fast(bf_hi(gw.x)) * a0[1]); w.y = cvt_pk_bf16(bf_lo(tw.y) + sigmoidf_fast(bf_lo(gw.y)) * a0[2], bf_hi(tw.y) + sigmoidf_fast(bf_hi(gw.y)) * a0[3]);
;                     w.z = cvt_pk_bf16(bf_lo(tw.z) + sigmoidf_fast(bf_lo(gw.z)) * a1[0], bf_hi(tw.z) + sigmoidf_fast(bf_hi(gw.z)) * a1[1]); w.w = cvt_pk_bf16(bf_lo(tw.w) + sigmoidf_fast(bf_lo(gw.w)) * a1[2], bf_hi(tw.w) + sigmoidf_fast(bf_hi(gw.w)) * a1[3]);
;                     *(u32x4*)(O + r * ldo + col0 + bj * HALF) = w; } }
	v_lshlrev_b32_e32 v34, 16, v94
	v_and_b32_e32 v35, 0xffff0000, v94
	v_mul_f32_e32 v34, 0xbfb8aa3b, v34
	v_mul_f32_e32 v35, 0xbfb8aa3b, v35
	v_exp_f32_e32 v34, v34
	v_exp_f32_e32 v35, v35
	s_waitcnt vmcnt(9)
	v_lshlrev_b32_e32 v36, 16, v90
	v_and_b32_e32 v37, 0xffff0000, v90
	v_add_f32_e32 v34, 1.0, v34
	v_add_f32_e32 v35, 1.0, v35
	v_rcp_f32_e32 v34, v34
	v_rcp_f32_e32 v35, v35
	global_store_dwordx4 v[42:43], v[38:41], off offset:256 sc1
	v_pk_fma_f32 v[28:29], v[28:29], v[34:35], v[36:37]
	s_nop 0
	v_cvt_pk_bf16_f32 v28, v28, v29
	v_lshlrev_b32_e32 v29, 16, v95
	v_mul_f32_e32 v29, 0xbfb8aa3b, v29
	v_exp_f32_e32 v29, v29
	v_lshlrev_b32_e32 v36, 16, v91
	v_and_b32_e32 v37, 0xffff0000, v91
	v_add_f32_e32 v29, 1.0, v29
	v_rcp_f32_e32 v34, v29
	v_and_b32_e32 v29, 0xffff0000, v95
	v_mul_f32_e32 v29, 0xbfb8aa3b, v29
	v_exp_f32_e32 v29, v29
	s_nop 0
	v_add_f32_e32 v29, 1.0, v29
	v_rcp_f32_e32 v35, v29
	s_nop 0
	v_pk_fma_f32 v[30:31], v[30:31], v[34:35], v[36:37]
	s_nop 0
	v_cvt_pk_bf16_f32 v29, v30, v31
	v_lshlrev_b32_e32 v30, 16, v96
	v_and_b32_e32 v31, 0xffff0000, v96
	v_mul_f32_e32 v30, 0xbfb8aa3b, v30
	v_mul_f32_e32 v31, 0xbfb8aa3b, v31
	v_exp_f32_e32 v30, v30
	v_exp_f32_e32 v31, v31
	v_lshlrev_b32_e32 v34, 16, v92
	v_and_b32_e32 v35, 0xffff0000, v92
	v_add_f32_e32 v30, 1.0, v30
	v_add_f32_e32 v31, 1.0, v31
	v_rcp_f32_e32 v30, v30
	v_rcp_f32_e32 v31, v31
	s_nop 0
	v_pk_fma_f32 v[24:25], v[24:25], v[30:31], v[34:35]
	s_nop 0
	v_cvt_pk_bf16_f32 v30, v24, v25
	v_lshlrev_b32_e32 v24, 16, v97
	v_and_b32_e32 v25, 0xffff0000, v97
	v_mul_f32_e32 v24, 0xbfb8aa3b, v24
	v_mul_f32_e32 v25, 0xbfb8aa3b, v25
	v_exp_f32_e32 v24, v24
	v_exp_f32_e32 v25, v25
	v_lshlrev_b32_e32 v34, 16, v93
	v_and_b32_e32 v35, 0xffff0000, v93
	v_add_f32_e32 v24, 1.0, v24
	v_add_f32_e32 v25, 1.0, v25
	v_rcp_f32_e32 v24, v24
	v_rcp_f32_e32 v25, v25
	s_nop 0
	v_pk_fma_f32 v[24:25], v[26:27], v[24:25], v[34:35]
	s_waitcnt vmcnt(9)
	v_lshlrev_b32_e32 v26, 16, v86
	v_and_b32_e32 v27, 0xffff0000, v86
	v_mul_f32_e32 v26, 0xbfb8aa3b, v26
	v_mul_f32_e32 v27, 0xbfb8aa3b, v27
	v_exp_f32_e32 v26, v26
	v_exp_f32_e32 v27, v27
	v_cvt_pk_bf16_f32 v31, v24, v25
	v_lshl_add_u64 v[24:25], s[22:23], 0, v[124:125]
	v_add_f32_e32 v26, 1.0, v26
	v_add_f32_e32 v27, 1.0, v27
	v_rcp_f32_e32 v26, v26
	v_rcp_f32_e32 v27, v27
	v_lshl_add_u64 v[24:25], v[24:25], 0, v[212:213]
	global_store_dwordx4 v[24:25], v[28:31], off sc1
	s_waitcnt vmcnt(9)
	s_nop 0
	v_lshlrev_b32_e32 v28, 16, v82
	v_and_b32_e32 v29, 0xffff0000, v82
	v_pk_fma_f32 v[20:21], v[20:21], v[26:27], v[28:29]
	v_lshlrev_b32_e32 v28, 16, v83
	v_cvt_pk_bf16_f32 v20, v20, v21
	v_lshlrev_b32_e32 v21, 16, v87
	v_mul_f32_e32 v21, 0xbfb8aa3b, v21
	v_exp_f32_e32 v21, v21
	v_and_b32_e32 v29, 0xffff0000, v83
	v_add_f32_e32 v21, 1.0, v21
	v_rcp_f32_e32 v26, v21
	v_and_b32_e32 v21, 0xffff0000, v87
	v_mul_f32_e32 v21, 0xbfb8aa3b, v21
	v_exp_f32_e32 v21, v21
	s_nop 0
	v_add_f32_e32 v21, 1.0, v21
	v_rcp_f32_e32 v27, v21
	s_nop 0
	v_pk_fma_f32 v[22:23], v[22:23], v[26:27], v[28:29]
	s_nop 0
	v_cvt_pk_bf16_f32 v21, v22, v23
	v_lshlrev_b32_e32 v22, 16, v88
	v_and_b32_e32 v23, 0xffff0000, v88
	v_mul_f32_e32 v22, 0xbfb8aa3b, v22
	v_mul_f32_e32 v23, 0xbfb8aa3b, v23
	v_exp_f32_e32 v22, v22
	v_exp_f32_e32 v23, v23
	v_lshlrev_b32_e32 v26, 16, v84
	v_and_b32_e32 v27, 0xffff0000, v84
	v_add_f32_e32 v22, 1.0, v22
	v_add_f32_e32 v23, 1.0, v23
	v_rcp_f32_e32 v22, v22
	v_rcp_f32_e32 v23, v23
	s_nop 0
	v_pk_fma_f32 v[16:17], v[16:17], v[22:23], v[26:27]
	s_nop 0
	v_cvt_pk_bf16_f32 v22, v16, v17
	v_lshlrev_b32_e32 v16, 16, v89
	v_and_b32_e32 v17, 0xffff0000, v89
	v_mul_f32_e32 v16, 0xbfb8aa3b, v16
	v_mul_f32_e32 v17, 0xbfb8aa3b, v17
	v_exp_f32_e32 v16, v16
	v_exp_f32_e32 v17, v17
	v_lshlrev_b32_e32 v26, 16, v85
	v_and_b32_e32 v27, 0xffff0000, v85
	v_add_f32_e32 v16, 1.0, v16
	v_add_f32_e32 v17, 1.0, v17
	v_rcp_f32_e32 v16, v16
	v_rcp_f32_e32 v17, v17
	s_nop 0
	v_pk_fma_f32 v[16:17], v[18:19], v[16:17], v[26:27]
	s_nop 0
	v_cvt_pk_bf16_f32 v23, v16, v17
	s_waitcnt vmcnt(8)
; __device__ __forceinline__ unsigned cvt_pk_bf16(float lo, float hi) { const f32x2_t v = {lo, hi}; const bf16x2_t c = __builtin_convertvector(v, bf16x2_t); return __builtin_bit_cast(unsigned, c); }
; __device__ __forceinline__ float bf_lo(unsigned w) { return __uint_as_float(w << 16); }
; __device__ __forceinline__ float bf_hi(unsigned w) { return __uint_as_float(w & 0xffff0000u); }
; __device__ __forceinline__ float sigmoidf_fast(float x) { return __builtin_amdgcn_rcpf(1.0f + __expf(-x)); }
;     __device__ __forceinline__ void operator()(const f32x4 (&acc)[2][2][4][2], const Unit& u, int wr, int wc, int fr, int fq) const {
;     ...
;             for (int m = 0; m < 4; ++m) { const size_t r = (size_t)(row0 + ai * HALF + m * 16);
; #pragma unroll
;                 for (int bj = 0; bj < 2; ++bj) { const u32x4 gw = gq[m][bj], tw = tq[m][bj]; const f32x4 a0 = acc[ai][bj][m][0], a1 = acc[ai][bj][m][1];
;                     u32x4 w;
;                     w.x = cvt_pk_bf16(bf_lo(tw.x) + sigmoidf_fast(bf_lo(gw.x)) * a0[0], bf_hi(tw.x) + sigmoidf_fast(bf_hi(gw.x)) * a0[1]); w.y = cvt_pk_bf16(bf_lo(tw.y) + sigmoidf_fast(bf_lo(gw.y)) * a0[2], bf_hi(tw.y) + sigmoidf_fast(bf_hi(gw.y)) * a0[3]);
;                     w.z = cvt_pk_bf16(bf_lo(tw.z) + sigmoidf_fast(bf_lo(gw.z)) * a1[0], bf_hi(tw.z) + sigmoidf_fast(bf_hi(gw.z)) * a1[1]); w.w = cvt_pk_bf16(bf_lo(tw.w) + sigmoidf_fast(bf_lo(gw.w)) * a1[2], bf_hi(tw.w) + sigmoidf_fast(bf_hi(gw.w)) * a1[3]);
;                     *(u32x4*)(O + r * ldo + col0 + bj * HALF) = w; } }
;             asm volatile("" ::: "memory"); }
;     }
	v_lshlrev_b32_e32 v16, 16, v78
	v_and_b32_e32 v17, 0xffff0000, v78
	v_mul_f32_e32 v16, 0xbfb8aa3b, v16
	v_mul_f32_e32 v17, 0xbfb8aa3b, v17
	v_exp_f32_e32 v16, v16
	v_exp_f32_e32 v17, v17
	s_waitcnt vmcnt(7)
	v_lshlrev_b32_e32 v18, 16, v74
	v_and_b32_e32 v19, 0xffff0000, v74
	v_add_f32_e32 v16, 1.0, v16
	v_add_f32_e32 v17, 1.0, v17
	v_rcp_f32_e32 v16, v16
	v_rcp_f32_e32 v17, v17
	global_store_dwordx4 v[24:25], v[20:23], off offset:256 sc1
	v_pk_fma_f32 v[12:13], v[12:13], v[16:17], v[18:19]
	s_nop 0
	v_cvt_pk_bf16_f32 v12, v12, v13
	v_lshlrev_b32_e32 v13, 16, v79
	v_mul_f32_e32 v13, 0xbfb8aa3b, v13
	v_exp_f32_e32 v13, v13
	v_lshlrev_b32_e32 v18, 16, v75
	v_and_b32_e32 v19, 0xffff0000, v75
	v_add_f32_e32 v13, 1.0, v13
	v_rcp_f32_e32 v16, v13
	v_and_b32_e32 v13, 0xffff0000, v79
	v_mul_f32_e32 v13, 0xbfb8aa3b, v13
	v_exp_f32_e32 v13, v13
	s_nop 0
	v_add_f32_e32 v13, 1.0, v13
	v_rcp_f32_e32 v17, v13
	s_nop 0
	v_pk_fma_f32 v[14:15], v[14:15], v[16:17], v[18:19]
	s_nop 0
	v_cvt_pk_bf16_f32 v13, v14, v15
	v_lshlrev_b32_e32 v14, 16, v80
	v_and_b32_e32 v15, 0xffff0000, v80
	v_mul_f32_e32 v14, 0xbfb8aa3b, v14
	v_mul_f32_e32 v15, 0xbfb8aa3b, v15
	v_exp_f32_e32 v14, v14
	v_exp_f32_e32 v15, v15
	v_lshlrev_b32_e32 v16, 16, v76
	v_and_b32_e32 v17, 0xffff0000, v76
	v_add_f32_e32 v14, 1.0, v14
	v_add_f32_e32 v15, 1.0, v15
	v_rcp_f32_e32 v14, v14
	v_rcp_f32_e32 v15, v15
	s_nop 0
	v_pk_fma_f32 v[8:9], v[8:9], v[14:15], v[16:17]
	s_nop 0
	v_cvt_pk_bf16_f32 v14, v8, v9
	v_lshlrev_b32_e32 v8, 16, v81
	v_and_b32_e32 v9, 0xffff0000, v81
	v_mul_f32_e32 v8, 0xbfb8aa3b, v8
	v_mul_f32_e32 v9, 0xbfb8aa3b, v9
	v_exp_f32_e32 v8, v8
	v_exp_f32_e32 v9, v9
	v_lshlrev_b32_e32 v16, 16, v77
	v_and_b32_e32 v17, 0xffff0000, v77
	v_add_f32_e32 v8, 1.0, v8
	v_add_f32_e32 v9, 1.0, v9
	v_rcp_f32_e32 v8, v8
	v_rcp_f32_e32 v9, v9
	s_nop 0
	v_pk_fma_f32 v[8:9], v[10:11], v[8:9], v[16:17]
	s_waitcnt vmcnt(7)
	v_lshlrev_b32_e32 v10, 16, v70
	v_and_b32_e32 v11, 0xffff0000, v70
	v_mul_f32_e32 v10, 0xbfb8aa3b, v10
	v_mul_f32_e32 v11, 0xbfb8aa3b, v11
	v_exp_f32_e32 v10, v10
	v_exp_f32_e32 v11, v11
	v_cvt_pk_bf16_f32 v15, v8, v9
	v_lshl_add_u64 v[8:9], s[22:23], 0, v[122:123]
	v_add_f32_e32 v10, 1.0, v10
	v_add_f32_e32 v11, 1.0, v11
	v_rcp_f32_e32 v10, v10
	v_rcp_f32_e32 v11, v11
	v_lshl_add_u64 v[8:9], v[8:9], 0, v[212:213]
	global_store_dwordx4 v[8:9], v[12:15], off sc1
	s_waitcnt vmcnt(7)
	s_nop 0
	v_lshlrev_b32_e32 v12, 16, v66
	v_and_b32_e32 v13, 0xffff0000, v66
	v_pk_fma_f32 v[4:5], v[4:5], v[10:11], v[12:13]
	v_lshlrev_b32_e32 v12, 16, v67
	v_cvt_pk_bf16_f32 v4, v4, v5
	v_lshlrev_b32_e32 v5, 16, v71
	v_mul_f32_e32 v5, 0xbfb8aa3b, v5
	v_exp_f32_e32 v5, v5
	v_and_b32_e32 v13, 0xffff0000, v67
	v_add_f32_e32 v5, 1.0, v5
	v_rcp_f32_e32 v10, v5
	v_and_b32_e32 v5, 0xffff0000, v71
	v_mul_f32_e32 v5, 0xbfb8aa3b, v5
	v_exp_f32_e32 v5, v5
	s_nop 0
	v_add_f32_e32 v5, 1.0, v5
	v_rcp_f32_e32 v11, v5
	s_nop 0
	v_pk_fma_f32 v[6:7], v[6:7], v[10:11], v[12:13]
	s_nop 0
	v_cvt_pk_bf16_f32 v5, v6, v7
	v_lshlrev_b32_e32 v6, 16, v72
	v_and_b32_e32 v7, 0xffff0000, v72
	v_mul_f32_e32 v6, 0xbfb8aa3b, v6
	v_mul_f32_e32 v7, 0xbfb8aa3b, v7
	v_exp_f32_e32 v6, v6
	v_exp_f32_e32 v7, v7
	v_lshlrev_b32_e32 v10, 16, v68
	v_and_b32_e32 v11, 0xffff0000, v68
	v_add_f32_e32 v6, 1.0, v6
	v_add_f32_e32 v7, 1.0, v7
	v_rcp_f32_e32 v6, v6
	v_rcp_f32_e32 v7, v7
	s_nop 0
	v_pk_fma_f32 v[0:1], v[0:1], v[6:7], v[10:11]
	s_nop 0
	v_cvt_pk_bf16_f32 v6, v0, v1
	v_lshlrev_b32_e32 v0, 16, v73
	v_and_b32_e32 v1, 0xffff0000, v73
	v_mul_f32_e32 v0, 0xbfb8aa3b, v0
	v_mul_f32_e32 v1, 0xbfb8aa3b, v1
	v_exp_f32_e32 v0, v0
	v_exp_f32_e32 v1, v1
	v_lshlrev_b32_e32 v10, 16, v69
	v_and_b32_e32 v11, 0xffff0000, v69
	v_add_f32_e32 v0, 1.0, v0
	v_add_f32_e32 v1, 1.0, v1
	v_rcp_f32_e32 v0, v0
	v_rcp_f32_e32 v1, v1
	s_nop 0
	v_pk_fma_f32 v[0:1], v[2:3], v[0:1], v[10:11]
	s_nop 0
	v_cvt_pk_bf16_f32 v7, v0, v1
	global_store_dwordx4 v[8:9], v[4:7], off offset:256 sc1
	s_cbranch_vccnz .LBB0_858
	s_andn2_b64 vcc, exec, s[0:1]
	s_cbranch_vccnz .LBB0_857
	s_barrier
	s_branch .LBB0_857

; __device__ __forceinline__ float bf_lo(unsigned w) { return __uint_as_float(w << 16); }
; __device__ __forceinline__ float bf_hi(unsigned w) { return __uint_as_float(w & 0xffff0000u); }
; __device__ __forceinline__ float sigmoidf_fast(float x) { return __builtin_amdgcn_rcpf(1.0f + __expf(-x)); }
;     __device__ __forceinline__ void fused(f32x4 (&acc)[2][2][4][2], const Unit& u, int wr, int wc, int fr, int fq, PG8_LAS unsigned char* lds, int wid, int lane) const {
;     ...
;         for (int ai = 0; ai < 2; ++ai) {
;             h16x8 hraw[4][2]; u32x4 eraw[4][2];
; #pragma unroll
;             for (int m = 0; m < 4; ++m) { const size_t off = (size_t)(u.pm * BM + ai * HALF + wr * 64 + m * 16 + fr) * ld + col0;
; #pragma unroll
;                 for (int bj = 0; bj < 2; ++bj) { hraw[m][bj] = *(const h16x8*)(H + off + bj * HALF); if (MODE != 0) eraw[m][bj] = *(const u32x4*)(E + off + bj * HALF); } }
; #pragma unroll
;             for (int m = 0; m < 4; ++m) { const size_t off = (size_t)(u.pm * BM + ai * HALF + wr * 64 + m * 16 + fr) * ld + col0;
; #pragma unroll
;                 for (int bj = 0; bj < 2; ++bj) { const f32x8 hv = __builtin_convertvector(hraw[m][bj], f32x8); f32x8 r8;
; #pragma unroll
;                     for (int n = 0; n < 2; ++n) { f32x4 r; const f32x4 a = acc[ai][bj][m][n];
;                         if (MODE == 0) { r[0] = hv[4 * n] + a[0]; r[1] = hv[4 * n + 1] + a[1]; r[2] = hv[4 * n + 2] + a[2]; r[3] = hv[4 * n + 3] + a[3]; }
;                         else { const unsigned e0 = n ? eraw[m][bj].z : eraw[m][bj].x, e1 = n ? eraw[m][bj].w : eraw[m][bj].y;
;                             r[0] = hv[4 * n] + sigmoidf_fast(a[0]) * bf_lo(e0); r[1] = hv[4 * n + 1] + sigmoidf_fast(a[1]) * bf_hi(e0); r[2] = hv[4 * n + 2] + sigmoidf_fast(a[2]) * bf_lo(e1); r[3] = hv[4 * n + 3] + sigmoidf_fast(a[3]) * bf_hi(e1); }
;                         acc[ai][bj][m][n] = r; r8[4 * n] = r[0]; r8[4 * n + 1] = r[1]; r8[4 * n + 2] = r[2]; r8[4 * n + 3] = r[3]; }
;                     *(h16x8*)(H + off + bj * HALF) = __builtin_convertvector(r8, h16x8); }
.LBB0_955:
	s_lshl_b32 s4, s36, 5
	s_lshl_b32 s5, s0, 8
	v_lshrrev_b32_e32 v122, 1, v173
	s_or_b32 s4, s5, s4
	s_lshl_b32 s18, s33, 8
	v_and_or_b32 v160, v122, 24, s4
	s_add_i32 s4, s18, s45
	v_or_b32_e32 v162, s4, v174
	v_ashrrev_i32_e32 v161, 31, v160
	v_readlane_b32 s4, v252, 57
	v_lshlrev_b64 v[158:159], 1, v[160:161]
	v_readlane_b32 s5, v252, 58
	v_ashrrev_i32_e32 v163, 31, v162
	v_lshlrev_b64 v[180:181], 12, v[162:163]
	v_lshl_add_u64 v[164:165], s[4:5], 0, v[158:159]
	v_lshl_add_u64 v[126:127], v[164:165], 0, v[180:181]
	s_barrier
	global_load_dwordx4 v[122:125], v[126:127], off
	s_nop 0
	global_load_dwordx4 v[126:129], v[126:127], off offset:256
	v_or_b32_e32 v138, 16, v162
	v_ashrrev_i32_e32 v139, 31, v138
	v_lshlrev_b64 v[170:171], 12, v[138:139]
	v_lshl_add_u64 v[138:139], v[164:165], 0, v[170:171]
	global_load_dwordx4 v[176:179], v[138:139], off
	global_load_dwordx4 v[154:157], v[138:139], off offset:256
	v_or_b32_e32 v138, 32, v162
	v_ashrrev_i32_e32 v139, 31, v138
	v_lshlrev_b64 v[168:169], 12, v[138:139]
	v_lshl_add_u64 v[138:139], v[164:165], 0, v[168:169]
	global_load_dwordx4 v[150:153], v[138:139], off
	global_load_dwordx4 v[146:149], v[138:139], off offset:256
	v_or_b32_e32 v138, 48, v162
	v_ashrrev_i32_e32 v139, 31, v138
	v_lshlrev_b64 v[166:167], 12, v[138:139]
	v_lshl_add_u64 v[138:139], v[164:165], 0, v[166:167]
	global_load_dwordx4 v[142:145], v[138:139], off
	s_nop 0
	global_load_dwordx4 v[138:141], v[138:139], off offset:256
	v_lshl_add_u64 v[180:181], s[4:5], 0, v[180:181]
	v_lshl_add_u64 v[180:181], v[180:181], 0, v[158:159]
	v_and_b32_e32 v32, 63, v173
	v_add_u32_e32 v188, 0x80, v162
	v_ashrrev_i32_e32 v189, 31, v188
	v_lshlrev_b64 v[190:191], 12, v[188:189]
	v_lshl_add_u64 v[192:193], v[164:165], 0, v[190:191]
	global_load_dwordx4 v[198:201], v[192:193], off
	global_load_dwordx4 v[202:205], v[192:193], off offset:256
	v_add_u32_e32 v188, 0x90, v162
	v_ashrrev_i32_e32 v189, 31, v188
	v_lshlrev_b64 v[190:191], 12, v[188:189]
	v_lshl_add_u64 v[192:193], v[164:165], 0, v[190:191]
	global_load_dwordx4 v[206:209], v[192:193], off
	global_load_dwordx4 v[210:213], v[192:193], off offset:256
	v_add_u32_e32 v188, 0xa0, v162
	v_ashrrev_i32_e32 v189, 31, v188
	v_lshlrev_b64 v[190:191], 12, v[188:189]
	v_lshl_add_u64 v[192:193], v[164:165], 0, v[190:191]
	global_load_dwordx4 v[214:217], v[192:193], off
	global_load_dwordx4 v[218:221], v[192:193], off offset:256
	v_add_u32_e32 v188, 0xb0, v162
	v_ashrrev_i32_e32 v189, 31, v188
	v_lshlrev_b64 v[190:191], 12, v[188:189]
	v_lshl_add_u64 v[192:193], v[164:165], 0, v[190:191]
	global_load_dwordx4 v[222:225], v[192:193], off
	global_load_dwordx4 v[246:249], v[192:193], off offset:256
	s_waitcnt vmcnt(8)
	v_cvt_f32_f16_e32 v182, v125
	v_cvt_f32_f16_sdwa v183, v125 dst_sel:DWORD dst_unused:UNUSED_PAD src0_sel:WORD_1
	v_cvt_f32_f16_e32 v184, v124
	v_cvt_f32_f16_sdwa v185, v124 dst_sel:DWORD dst_unused:UNUSED_PAD src0_sel:WORD_1
	v_cvt_f32_f16_e32 v124, v123
	v_cvt_f32_f16_sdwa v125, v123 dst_sel:DWORD dst_unused:UNUSED_PAD src0_sel:WORD_1
	v_cvt_f32_f16_e32 v186, v122
	v_cvt_f32_f16_sdwa v187, v122 dst_sel:DWORD dst_unused:UNUSED_PAD src0_sel:WORD_1
	v_pk_add_f32 v[114:115], v[114:115], v[184:185]
	v_pk_add_f32 v[120:121], v[120:121], v[124:125]
	v_pk_add_f32 v[116:117], v[116:117], v[182:183]
	v_pk_add_f32 v[118:119], v[118:119], v[186:187]
	v_cvt_pk_f16_f32 v125, v116, v117
	v_cvt_pk_f16_f32 v124, v114, v115
	v_cvt_pk_f16_f32 v123, v120, v121
	v_cvt_pk_f16_f32 v122, v118, v119
	global_store_dwordx4 v[180:181], v[122:125], off sc1
	v_cvt_f32_f16_e32 v182, v126
	v_cvt_f32_f16_sdwa v183, v126 dst_sel:DWORD dst_unused:UNUSED_PAD src0_sel:WORD_1
	v_cvt_f32_f16_e32 v124, v129
	v_cvt_f32_f16_sdwa v125, v129 dst_sel:DWORD dst_unused:UNUSED_PAD src0_sel:WORD_1
	v_cvt_f32_f16_e32 v122, v128
	v_cvt_f32_f16_sdwa v123, v128 dst_sel:DWORD dst_unused:UNUSED_PAD src0_sel:WORD_1
	v_cvt_f32_f16_e32 v128, v127
	v_cvt_f32_f16_sdwa v129, v127 dst_sel:DWORD dst_unused:UNUSED_PAD src0_sel:WORD_1
	v_pk_add_f32 v[126:127], v[106:107], v[182:183]
	v_pk_add_f32 v[122:123], v[102:103], v[122:123]
	v_pk_add_f32 v[124:125], v[104:105], v[124:125]
	v_pk_add_f32 v[128:129], v[108:109], v[128:129]
	v_cvt_pk_f16_f32 v105, v124, v125
	v_cvt_pk_f16_f32 v104, v122, v123
	v_cvt_pk_f16_f32 v103, v128, v129
	v_cvt_pk_f16_f32 v102, v126, v127
	global_store_dwordx4 v[180:181], v[102:105], off offset:256 sc1
	v_cvt_f32_f16_e32 v108, v177
	v_cvt_f32_f16_sdwa v109, v177 dst_sel:DWORD dst_unused:UNUSED_PAD src0_sel:WORD_1
	v_cvt_f32_f16_e32 v104, v179
	v_cvt_f32_f16_sdwa v105, v179 dst_sel:DWORD dst_unused:UNUSED_PAD src0_sel:WORD_1
	v_cvt_f32_f16_e32 v102, v178
	v_cvt_f32_f16_sdwa v103, v178 dst_sel:DWORD dst_unused:UNUSED_PAD src0_sel:WORD_1
	v_cvt_f32_f16_e32 v106, v176
	v_cvt_f32_f16_sdwa v107, v176 dst_sel:DWORD dst_unused:UNUSED_PAD src0_sel:WORD_1
	v_pk_add_f32 v[108:109], v[136:137], v[108:109]
	v_pk_add_f32 v[102:103], v[130:131], v[102:103]
	v_pk_add_f32 v[104:105], v[132:133], v[104:105]
	v_pk_add_f32 v[106:107], v[134:135], v[106:107]
	v_lshl_add_u64 v[130:131], s[4:5], 0, v[170:171]
	v_cvt_pk_f16_f32 v135, v104, v105
	v_cvt_pk_f16_f32 v134, v102, v103
	v_cvt_pk_f16_f32 v133, v108, v109
	v_cvt_pk_f16_f32 v132, v106, v107
	v_lshl_add_u64 v[130:131], v[130:131], 0, v[158:159]
	global_store_dwordx4 v[130:131], v[132:135], off sc1
	v_cvt_f32_f16_e32 v136, v155
	v_cvt_f32_f16_sdwa v137, v155 dst_sel:DWORD dst_unused:UNUSED_PAD src0_sel:WORD_1
	v_cvt_f32_f16_e32 v132, v157
	v_cvt_f32_f16_sdwa v133, v157 dst_sel:DWORD dst_unused:UNUSED_PAD src0_sel:WORD_1
	v_cvt_f32_f16_e32 v134, v156
; __device__ __forceinline__ float bf_lo(unsigned w) { return __uint_as_float(w << 16); }
; __device__ __forceinline__ float bf_hi(unsigned w) { return __uint_as_float(w & 0xffff0000u); }
; __device__ __forceinline__ float sigmoidf_fast(float x) { return __builtin_amdgcn_rcpf(1.0f + __expf(-x)); }
;     __device__ __forceinline__ void fused(f32x4 (&acc)[2][2][4][2], const Unit& u, int wr, int wc, int fr, int fq, PG8_LAS unsigned char* lds, int wid, int lane) const {
;     ...
;             for (int m = 0; m < 4; ++m) { const size_t off = (size_t)(u.pm * BM + ai * HALF + wr * 64 + m * 16 + fr) * ld + col0;
; #pragma unroll
;                 for (int bj = 0; bj < 2; ++bj) { const f32x8 hv = __builtin_convertvector(hraw[m][bj], f32x8); f32x8 r8;
; #pragma unroll
;                     for (int n = 0; n < 2; ++n) { f32x4 r; const f32x4 a = acc[ai][bj][m][n];
;                         if (MODE == 0) { r[0] = hv[4 * n] + a[0]; r[1] = hv[4 * n + 1] + a[1]; r[2] = hv[4 * n + 2] + a[2]; r[3] = hv[4 * n + 3] + a[3]; }
;                         else { const unsigned e0 = n ? eraw[m][bj].z : eraw[m][bj].x, e1 = n ? eraw[m][bj].w : eraw[m][bj].y;
;                             r[0] = hv[4 * n] + sigmoidf_fast(a[0]) * bf_lo(e0); r[1] = hv[4 * n + 1] + sigmoidf_fast(a[1]) * bf_hi(e0); r[2] = hv[4 * n + 2] + sigmoidf_fast(a[2]) * bf_lo(e1); r[3] = hv[4 * n + 3] + sigmoidf_fast(a[3]) * bf_hi(e1); }
;                         acc[ai][bj][m][n] = r; r8[4 * n] = r[0]; r8[4 * n + 1] = r[1]; r8[4 * n + 2] = r[2]; r8[4 * n + 3] = r[3]; }
;                     *(h16x8*)(H + off + bj * HALF) = __builtin_convertvector(r8, h16x8); }
	v_cvt_f32_f16_sdwa v135, v156 dst_sel:DWORD dst_unused:UNUSED_PAD src0_sel:WORD_1
	v_cvt_f32_f16_e32 v156, v154
	v_cvt_f32_f16_sdwa v157, v154 dst_sel:DWORD dst_unused:UNUSED_PAD src0_sel:WORD_1
	v_pk_add_f32 v[112:113], v[112:113], v[136:137]
	v_pk_add_f32 v[98:99], v[98:99], v[134:135]
	v_pk_add_f32 v[100:101], v[100:101], v[132:133]
	v_pk_add_f32 v[110:111], v[110:111], v[156:157]
	v_cvt_pk_f16_f32 v135, v100, v101
	v_cvt_pk_f16_f32 v134, v98, v99
	v_cvt_pk_f16_f32 v133, v112, v113
	v_cvt_pk_f16_f32 v132, v110, v111
	global_store_dwordx4 v[130:131], v[132:135], off offset:256 sc1
	v_cvt_f32_f16_e32 v130, v153
	v_cvt_f32_f16_sdwa v131, v153 dst_sel:DWORD dst_unused:UNUSED_PAD src0_sel:WORD_1
	v_cvt_f32_f16_e32 v132, v152
	v_cvt_f32_f16_sdwa v133, v152 dst_sel:DWORD dst_unused:UNUSED_PAD src0_sel:WORD_1
	v_cvt_f32_f16_e32 v134, v151
	v_cvt_f32_f16_sdwa v135, v151 dst_sel:DWORD dst_unused:UNUSED_PAD src0_sel:WORD_1
	v_cvt_f32_f16_e32 v136, v150
	v_cvt_f32_f16_sdwa v137, v150 dst_sel:DWORD dst_unused:UNUSED_PAD src0_sel:WORD_1
	v_pk_add_f32 v[90:91], v[90:91], v[132:133]
	v_pk_add_f32 v[96:97], v[96:97], v[134:135]
	v_pk_add_f32 v[92:93], v[92:93], v[130:131]
	v_pk_add_f32 v[94:95], v[94:95], v[136:137]
	v_lshl_add_u64 v[134:135], s[4:5], 0, v[168:169]
	v_cvt_pk_f16_f32 v133, v92, v93
	v_cvt_pk_f16_f32 v132, v90, v91
	v_cvt_pk_f16_f32 v131, v96, v97
	v_cvt_pk_f16_f32 v130, v94, v95
	v_lshl_add_u64 v[134:135], v[134:135], 0, v[158:159]
	global_store_dwordx4 v[134:135], v[130:133], off sc1
	v_cvt_f32_f16_e32 v136, v147
	v_cvt_f32_f16_sdwa v137, v147 dst_sel:DWORD dst_unused:UNUSED_PAD src0_sel:WORD_1
	v_cvt_f32_f16_e32 v130, v149
	v_cvt_f32_f16_sdwa v131, v149 dst_sel:DWORD dst_unused:UNUSED_PAD src0_sel:WORD_1
	v_cvt_f32_f16_e32 v132, v148
	v_cvt_f32_f16_sdwa v133, v148 dst_sel:DWORD dst_unused:UNUSED_PAD src0_sel:WORD_1
	v_cvt_f32_f16_e32 v148, v146
	v_cvt_f32_f16_sdwa v149, v146 dst_sel:DWORD dst_unused:UNUSED_PAD src0_sel:WORD_1
	v_pk_add_f32 v[88:89], v[88:89], v[136:137]
	v_pk_add_f32 v[82:83], v[82:83], v[132:133]
	v_pk_add_f32 v[84:85], v[84:85], v[130:131]
	v_pk_add_f32 v[86:87], v[86:87], v[148:149]
	v_cvt_pk_f16_f32 v133, v84, v85
	v_cvt_pk_f16_f32 v132, v82, v83
	v_cvt_pk_f16_f32 v131, v88, v89
	v_cvt_pk_f16_f32 v130, v86, v87
	global_store_dwordx4 v[134:135], v[130:133], off offset:256 sc1
	v_cvt_f32_f16_e32 v134, v143
	v_cvt_f32_f16_sdwa v135, v143 dst_sel:DWORD dst_unused:UNUSED_PAD src0_sel:WORD_1
	v_cvt_f32_f16_e32 v130, v145
	v_cvt_f32_f16_sdwa v131, v145 dst_sel:DWORD dst_unused:UNUSED_PAD src0_sel:WORD_1
	v_cvt_f32_f16_e32 v132, v144
	v_cvt_f32_f16_sdwa v133, v144 dst_sel:DWORD dst_unused:UNUSED_PAD src0_sel:WORD_1
	v_cvt_f32_f16_e32 v136, v142
	v_cvt_f32_f16_sdwa v137, v142 dst_sel:DWORD dst_unused:UNUSED_PAD src0_sel:WORD_1
	v_pk_add_f32 v[80:81], v[80:81], v[134:135]
	v_pk_add_f32 v[74:75], v[74:75], v[132:133]
	v_pk_add_f32 v[76:77], v[76:77], v[130:131]
	v_pk_add_f32 v[78:79], v[78:79], v[136:137]
	v_lshl_add_u64 v[134:135], s[4:5], 0, v[166:167]
	v_cvt_pk_f16_f32 v133, v76, v77
	v_cvt_pk_f16_f32 v132, v74, v75
	v_cvt_pk_f16_f32 v131, v80, v81
	v_cvt_pk_f16_f32 v130, v78, v79
	v_lshl_add_u64 v[134:135], v[134:135], 0, v[158:159]
	global_store_dwordx4 v[134:135], v[130:133], off sc1
	v_cvt_f32_f16_e32 v136, v139
	v_cvt_f32_f16_sdwa v137, v139 dst_sel:DWORD dst_unused:UNUSED_PAD src0_sel:WORD_1
	v_cvt_f32_f16_e32 v130, v141
	v_cvt_f32_f16_sdwa v131, v141 dst_sel:DWORD dst_unused:UNUSED_PAD src0_sel:WORD_1
	v_cvt_f32_f16_e32 v132, v140
	v_cvt_f32_f16_sdwa v133, v140 dst_sel:DWORD dst_unused:UNUSED_PAD src0_sel:WORD_1
	v_cvt_f32_f16_e32 v140, v138
	v_cvt_f32_f16_sdwa v141, v138 dst_sel:DWORD dst_unused:UNUSED_PAD src0_sel:WORD_1
	v_pk_add_f32 v[72:73], v[72:73], v[136:137]
	v_pk_add_f32 v[66:67], v[66:67], v[132:133]
	v_pk_add_f32 v[68:69], v[68:69], v[130:131]
	v_pk_add_f32 v[70:71], v[70:71], v[140:141]
	v_cvt_pk_f16_f32 v133, v68, v69
	v_cvt_pk_f16_f32 v132, v66, v67
	v_cvt_pk_f16_f32 v131, v72, v73
	v_cvt_pk_f16_f32 v130, v70, v71
	global_store_dwordx4 v[134:135], v[130:133], off offset:256 sc1
	s_nop 1
	v_add_u32_e32 v130, 0x80, v162
	v_ashrrev_i32_e32 v131, 31, v130
	v_lshlrev_b64 v[170:171], 12, v[130:131]
	v_lshl_add_u64 v[130:131], v[164:165], 0, v[170:171]
	v_add_u32_e32 v130, 0x90, v162
	v_ashrrev_i32_e32 v131, 31, v130
	v_lshlrev_b64 v[180:181], 12, v[130:131]
	v_lshl_add_u64 v[130:131], v[164:165], 0, v[180:181]
	v_add_u32_e32 v130, 0xa0, v162
	v_ashrrev_i32_e32 v131, 31, v130
	v_lshlrev_b64 v[148:149], 12, v[130:131]
	v_lshl_add_u64 v[130:131], v[164:165], 0, v[148:149]
	v_add_u32_e32 v130, 0xb0, v162
	v_ashrrev_i32_e32 v131, 31, v130
	v_lshlrev_b64 v[146:147], 12, v[130:131]
	v_lshl_add_u64 v[130:131], v[164:165], 0, v[146:147]
	s_nop 0
	v_lshl_add_u64 v[148:149], s[4:5], 0, v[148:149]
	v_lshl_add_u64 v[148:149], v[148:149], 0, v[158:159]
	s_waitcnt vmcnt(15)
	v_cvt_f32_f16_e32 v162, v201
	v_cvt_f32_f16_sdwa v163, v201 dst_sel:DWORD dst_unused:UNUSED_PAD src0_sel:WORD_1
	v_cvt_f32_f16_e32 v164, v200
	v_cvt_f32_f16_sdwa v165, v200 dst_sel:DWORD dst_unused:UNUSED_PAD src0_sel:WORD_1
	v_cvt_f32_f16_e32 v152, v199
	v_cvt_f32_f16_sdwa v153, v199 dst_sel:DWORD dst_unused:UNUSED_PAD src0_sel:WORD_1
	v_cvt_f32_f16_e32 v182, v198
	v_cvt_f32_f16_sdwa v183, v198 dst_sel:DWORD dst_unused:UNUSED_PAD src0_sel:WORD_1
	v_pk_add_f32 v[58:59], v[58:59], v[164:165]
	v_pk_add_f32 v[64:65], v[64:65], v[152:153]
	v_pk_add_f32 v[60:61], v[60:61], v[162:163]
	v_pk_add_f32 v[62:63], v[62:63], v[182:183]
	v_lshl_add_u64 v[162:163], s[4:5], 0, v[170:171]
	v_cvt_pk_f16_f32 v153, v60, v61
	v_cvt_pk_f16_f32 v152, v58, v59
	v_cvt_pk_f16_f32 v151, v64, v65
	v_cvt_pk_f16_f32 v150, v62, v63
	v_lshl_add_u64 v[162:163], v[162:163], 0, v[158:159]
	global_store_dwordx4 v[162:163], v[150:153], off sc1
	s_waitcnt vmcnt(15)
; __device__ __forceinline__ float bf_lo(unsigned w) { return __uint_as_float(w << 16); }
; __device__ __forceinline__ float bf_hi(unsigned w) { return __uint_as_float(w & 0xffff0000u); }
; __device__ __forceinline__ float sigmoidf_fast(float x) { return __builtin_amdgcn_rcpf(1.0f + __expf(-x)); }
;     __device__ __forceinline__ void fused(f32x4 (&acc)[2][2][4][2], const Unit& u, int wr, int wc, int fr, int fq, PG8_LAS unsigned char* lds, int wid, int lane) const {
;     ...
;             for (int m = 0; m < 4; ++m) { const size_t off = (size_t)(u.pm * BM + ai * HALF + wr * 64 + m * 16 + fr) * ld + col0;
; #pragma unroll
;                 for (int bj = 0; bj < 2; ++bj) { const f32x8 hv = __builtin_convertvector(hraw[m][bj], f32x8); f32x8 r8;
; #pragma unroll
;                     for (int n = 0; n < 2; ++n) { f32x4 r; const f32x4 a = acc[ai][bj][m][n];
;                         if (MODE == 0) { r[0] = hv[4 * n] + a[0]; r[1] = hv[4 * n + 1] + a[1]; r[2] = hv[4 * n + 2] + a[2]; r[3] = hv[4 * n + 3] + a[3]; }
;                         else { const unsigned e0 = n ? eraw[m][bj].z : eraw[m][bj].x, e1 = n ? eraw[m][bj].w : eraw[m][bj].y;
;                             r[0] = hv[4 * n] + sigmoidf_fast(a[0]) * bf_lo(e0); r[1] = hv[4 * n + 1] + sigmoidf_fast(a[1]) * bf_hi(e0); r[2] = hv[4 * n + 2] + sigmoidf_fast(a[2]) * bf_lo(e1); r[3] = hv[4 * n + 3] + sigmoidf_fast(a[3]) * bf_hi(e1); }
;                         acc[ai][bj][m][n] = r; r8[4 * n] = r[0]; r8[4 * n + 1] = r[1]; r8[4 * n + 2] = r[2]; r8[4 * n + 3] = r[3]; }
;                     *(h16x8*)(H + off + bj * HALF) = __builtin_convertvector(r8, h16x8); }
	v_cvt_f32_f16_e32 v164, v202
	v_cvt_f32_f16_sdwa v165, v202 dst_sel:DWORD dst_unused:UNUSED_PAD src0_sel:WORD_1
	v_cvt_f32_f16_e32 v150, v205
	v_cvt_f32_f16_sdwa v151, v205 dst_sel:DWORD dst_unused:UNUSED_PAD src0_sel:WORD_1
	v_cvt_f32_f16_e32 v152, v204
	v_cvt_f32_f16_sdwa v153, v204 dst_sel:DWORD dst_unused:UNUSED_PAD src0_sel:WORD_1
	v_cvt_f32_f16_e32 v156, v203
	v_cvt_f32_f16_sdwa v157, v203 dst_sel:DWORD dst_unused:UNUSED_PAD src0_sel:WORD_1
	v_pk_add_f32 v[54:55], v[54:55], v[164:165]
	v_pk_add_f32 v[50:51], v[50:51], v[152:153]
	v_pk_add_f32 v[52:53], v[52:53], v[150:151]
	v_pk_add_f32 v[56:57], v[56:57], v[156:157]
	v_cvt_pk_f16_f32 v153, v52, v53
	v_cvt_pk_f16_f32 v152, v50, v51
	v_cvt_pk_f16_f32 v151, v56, v57
	v_cvt_pk_f16_f32 v150, v54, v55
	global_store_dwordx4 v[162:163], v[150:153], off offset:256 sc1
	s_waitcnt vmcnt(15)
	v_cvt_f32_f16_e32 v154, v207
	v_cvt_f32_f16_sdwa v155, v207 dst_sel:DWORD dst_unused:UNUSED_PAD src0_sel:WORD_1
	v_cvt_f32_f16_e32 v150, v209
	v_cvt_f32_f16_sdwa v151, v209 dst_sel:DWORD dst_unused:UNUSED_PAD src0_sel:WORD_1
	v_cvt_f32_f16_e32 v152, v208
	v_cvt_f32_f16_sdwa v153, v208 dst_sel:DWORD dst_unused:UNUSED_PAD src0_sel:WORD_1
	v_cvt_f32_f16_e32 v156, v206
	v_cvt_f32_f16_sdwa v157, v206 dst_sel:DWORD dst_unused:UNUSED_PAD src0_sel:WORD_1
	v_pk_add_f32 v[48:49], v[48:49], v[154:155]
	v_pk_add_f32 v[42:43], v[42:43], v[152:153]
	v_pk_add_f32 v[44:45], v[44:45], v[150:151]
	v_pk_add_f32 v[46:47], v[46:47], v[156:157]
	v_lshl_add_u64 v[154:155], s[4:5], 0, v[180:181]
	v_cvt_pk_f16_f32 v153, v44, v45
	v_cvt_pk_f16_f32 v152, v42, v43
	v_cvt_pk_f16_f32 v151, v48, v49
	v_cvt_pk_f16_f32 v150, v46, v47
	v_lshl_add_u64 v[154:155], v[154:155], 0, v[158:159]
	global_store_dwordx4 v[154:155], v[150:153], off sc1
	s_waitcnt vmcnt(15)
	v_cvt_f32_f16_e32 v156, v211
	v_cvt_f32_f16_sdwa v157, v211 dst_sel:DWORD dst_unused:UNUSED_PAD src0_sel:WORD_1
	v_cvt_f32_f16_e32 v150, v213
	v_cvt_f32_f16_sdwa v151, v213 dst_sel:DWORD dst_unused:UNUSED_PAD src0_sel:WORD_1
	v_cvt_f32_f16_e32 v152, v212
	v_cvt_f32_f16_sdwa v153, v212 dst_sel:DWORD dst_unused:UNUSED_PAD src0_sel:WORD_1
	v_cvt_f32_f16_e32 v162, v210
	v_cvt_f32_f16_sdwa v163, v210 dst_sel:DWORD dst_unused:UNUSED_PAD src0_sel:WORD_1
	v_pk_add_f32 v[40:41], v[40:41], v[156:157]
	v_pk_add_f32 v[34:35], v[34:35], v[152:153]
	v_pk_add_f32 v[36:37], v[36:37], v[150:151]
	v_pk_add_f32 v[38:39], v[38:39], v[162:163]
	v_cvt_pk_f16_f32 v153, v36, v37
	v_cvt_pk_f16_f32 v152, v34, v35
	v_cvt_pk_f16_f32 v151, v40, v41
	v_cvt_pk_f16_f32 v150, v38, v39
	global_store_dwordx4 v[154:155], v[150:153], off offset:256 sc1
	s_waitcnt vmcnt(15)
	v_cvt_f32_f16_e32 v154, v214
	v_cvt_f32_f16_sdwa v155, v214 dst_sel:DWORD dst_unused:UNUSED_PAD src0_sel:WORD_1
	v_cvt_f32_f16_e32 v150, v217
	v_cvt_f32_f16_sdwa v151, v217 dst_sel:DWORD dst_unused:UNUSED_PAD src0_sel:WORD_1
	v_cvt_f32_f16_e32 v152, v216
	v_cvt_f32_f16_sdwa v153, v216 dst_sel:DWORD dst_unused:UNUSED_PAD src0_sel:WORD_1
	v_cvt_f32_f16_e32 v144, v215
	v_cvt_f32_f16_sdwa v145, v215 dst_sel:DWORD dst_unused:UNUSED_PAD src0_sel:WORD_1
	v_pk_add_f32 v[28:29], v[28:29], v[154:155]
	v_pk_add_f32 v[24:25], v[24:25], v[152:153]
	v_pk_add_f32 v[26:27], v[26:27], v[150:151]
	v_pk_add_f32 v[30:31], v[30:31], v[144:145]
	v_cvt_pk_f16_f32 v145, v26, v27
	v_cvt_pk_f16_f32 v144, v24, v25
	v_cvt_pk_f16_f32 v143, v30, v31
	v_cvt_pk_f16_f32 v142, v28, v29
	global_store_dwordx4 v[148:149], v[142:145], off sc1
	s_waitcnt vmcnt(15)
; __device__ __forceinline__ float bf_lo(unsigned w) { return __uint_as_float(w << 16); }
; __device__ __forceinline__ float bf_hi(unsigned w) { return __uint_as_float(w & 0xffff0000u); }
; __device__ __forceinline__ float sigmoidf_fast(float x) { return __builtin_amdgcn_rcpf(1.0f + __expf(-x)); }
;     __device__ __forceinline__ void run(const f32x4 (&v)[2][2][4][2], const Unit& u, int wr, int wc, int fr, int fq, PG8_LAS unsigned char* lds, int wid, int lane, float inv_n, float eps) const {
;     ...
;                 float s = 0.f;
; #pragma unroll
;                 for (int bj = 0; bj < 2; ++bj)
; #pragma unroll
;                     for (int n = 0; n < 2; ++n) { const f32x4 x = v[ai][bj][m][n]; s += (x[0] * x[0] + x[1] * x[1]) + (x[2] * x[2] + x[3] * x[3]); }
;                 s += __shfl_xor(s, 16); s += __shfl_xor(s, 32);
;                 if (fq == 0) P[(ai * HALF + wr * 64 + m * 16 + fr) * 4 + wc] = s;
;     __device__ __forceinline__ void fused(f32x4 (&acc)[2][2][4][2], const Unit& u, int wr, int wc, int fr, int fq, PG8_LAS unsigned char* lds, int wid, int lane) const {
;     ...
;             for (int m = 0; m < 4; ++m) { const size_t off = (size_t)(u.pm * BM + ai * HALF + wr * 64 + m * 16 + fr) * ld + col0;
; #pragma unroll
;                 for (int bj = 0; bj < 2; ++bj) { const f32x8 hv = __builtin_convertvector(hraw[m][bj], f32x8); f32x8 r8;
; #pragma unroll
;                     for (int n = 0; n < 2; ++n) { f32x4 r; const f32x4 a = acc[ai][bj][m][n];
;                         if (MODE == 0) { r[0] = hv[4 * n] + a[0]; r[1] = hv[4 * n + 1] + a[1]; r[2] = hv[4 * n + 2] + a[2]; r[3] = hv[4 * n + 3] + a[3]; }
;                         else { const unsigned e0 = n ? eraw[m][bj].z : eraw[m][bj].x, e1 = n ? eraw[m][bj].w : eraw[m][bj].y;
;                             r[0] = hv[4 * n] + sigmoidf_fast(a[0]) * bf_lo(e0); r[1] = hv[4 * n + 1] + sigmoidf_fast(a[1]) * bf_hi(e0); r[2] = hv[4 * n + 2] + sigmoidf_fast(a[2]) * bf_lo(e1); r[3] = hv[4 * n + 3] + sigmoidf_fast(a[3]) * bf_hi(e1); }
;                         acc[ai][bj][m][n] = r; r8[4 * n] = r[0]; r8[4 * n + 1] = r[1]; r8[4 * n + 2] = r[2]; r8[4 * n + 3] = r[3]; }
;                     *(h16x8*)(H + off + bj * HALF) = __builtin_convertvector(r8, h16x8); }
	v_cvt_f32_f16_e32 v150, v218
	v_cvt_f32_f16_sdwa v151, v218 dst_sel:DWORD dst_unused:UNUSED_PAD src0_sel:WORD_1
	v_cvt_f32_f16_e32 v142, v221
	v_cvt_f32_f16_sdwa v143, v221 dst_sel:DWORD dst_unused:UNUSED_PAD src0_sel:WORD_1
	v_cvt_f32_f16_e32 v144, v220
	v_cvt_f32_f16_sdwa v145, v220 dst_sel:DWORD dst_unused:UNUSED_PAD src0_sel:WORD_1
	v_cvt_f32_f16_e32 v140, v219
	v_cvt_f32_f16_sdwa v141, v219 dst_sel:DWORD dst_unused:UNUSED_PAD src0_sel:WORD_1
	v_pk_add_f32 v[20:21], v[20:21], v[150:151]
	v_pk_add_f32 v[16:17], v[16:17], v[144:145]
	v_pk_add_f32 v[18:19], v[18:19], v[142:143]
	v_pk_add_f32 v[22:23], v[22:23], v[140:141]
	v_cvt_pk_f16_f32 v141, v18, v19
	v_cvt_pk_f16_f32 v140, v16, v17
	v_cvt_pk_f16_f32 v139, v22, v23
	v_cvt_pk_f16_f32 v138, v20, v21
	global_store_dwordx4 v[148:149], v[138:141], off offset:256 sc1
	s_waitcnt vmcnt(15)
	v_cvt_f32_f16_e32 v142, v222
	v_cvt_f32_f16_sdwa v143, v222 dst_sel:DWORD dst_unused:UNUSED_PAD src0_sel:WORD_1
	v_cvt_f32_f16_e32 v138, v225
	v_cvt_f32_f16_sdwa v139, v225 dst_sel:DWORD dst_unused:UNUSED_PAD src0_sel:WORD_1
	v_cvt_f32_f16_e32 v140, v224
	v_cvt_f32_f16_sdwa v141, v224 dst_sel:DWORD dst_unused:UNUSED_PAD src0_sel:WORD_1
	v_cvt_f32_f16_e32 v136, v223
	v_cvt_f32_f16_sdwa v137, v223 dst_sel:DWORD dst_unused:UNUSED_PAD src0_sel:WORD_1
	v_pk_add_f32 v[12:13], v[12:13], v[142:143]
	v_pk_add_f32 v[8:9], v[8:9], v[140:141]
	v_pk_add_f32 v[10:11], v[10:11], v[138:139]
	v_pk_add_f32 v[14:15], v[14:15], v[136:137]
	v_lshl_add_u64 v[138:139], s[4:5], 0, v[146:147]
	v_cvt_pk_f16_f32 v137, v10, v11
	v_cvt_pk_f16_f32 v136, v8, v9
	v_cvt_pk_f16_f32 v135, v14, v15
	v_cvt_pk_f16_f32 v134, v12, v13
	v_lshl_add_u64 v[138:139], v[138:139], 0, v[158:159]
	global_store_dwordx4 v[138:139], v[134:137], off sc1
	s_waitcnt vmcnt(15)
	v_cvt_f32_f16_e32 v140, v246
	v_cvt_f32_f16_sdwa v141, v246 dst_sel:DWORD dst_unused:UNUSED_PAD src0_sel:WORD_1
	v_cvt_f32_f16_e32 v134, v249
	v_cvt_f32_f16_sdwa v135, v249 dst_sel:DWORD dst_unused:UNUSED_PAD src0_sel:WORD_1
	v_cvt_f32_f16_e32 v136, v248
	v_cvt_f32_f16_sdwa v137, v248 dst_sel:DWORD dst_unused:UNUSED_PAD src0_sel:WORD_1
	v_cvt_f32_f16_e32 v132, v247
	v_cvt_f32_f16_sdwa v133, v247 dst_sel:DWORD dst_unused:UNUSED_PAD src0_sel:WORD_1
	v_pk_add_f32 v[4:5], v[4:5], v[140:141]
	v_pk_add_f32 v[0:1], v[0:1], v[136:137]
	v_pk_add_f32 v[2:3], v[2:3], v[134:135]
	v_pk_add_f32 v[6:7], v[6:7], v[132:133]
	v_cvt_pk_f16_f32 v133, v2, v3
	v_cvt_pk_f16_f32 v132, v0, v1
	v_cvt_pk_f16_f32 v131, v6, v7
	v_cvt_pk_f16_f32 v130, v4, v5
	global_store_dwordx4 v[138:139], v[130:133], off offset:256 sc1
	v_mul_f32_e32 v134, v117, v117
	v_fmac_f32_e32 v134, v116, v116
	v_and_b32_e32 v131, 64, v236
	v_xor_b32_e32 v130, 16, v236
	v_add_u32_e32 v131, 64, v131
	v_cmp_lt_i32_e32 vcc, v130, v131
	v_xor_b32_e32 v132, 32, v236
	v_mul_f32_e32 v133, v121, v121
	v_cndmask_b32_e32 v130, v236, v130, vcc
	v_cmp_lt_i32_e32 vcc, v132, v131
	v_fmac_f32_e32 v133, v120, v120
	v_lshlrev_b32_e32 v130, 2, v130
	v_cndmask_b32_e32 v131, v236, v132, vcc
	v_mul_f32_e32 v132, v119, v119
	v_fmac_f32_e32 v132, v118, v118
	v_add_f32_e32 v132, v132, v133
	v_mul_f32_e32 v133, v115, v115
	v_fmac_f32_e32 v133, v114, v114
	v_add_f32_e32 v133, v133, v134
	v_add_f32_e32 v132, v132, v133
	v_mul_f32_e32 v133, v127, v127
	v_mul_f32_e32 v134, v129, v129
	v_fmac_f32_e32 v133, v126, v126
	v_fmac_f32_e32 v134, v128, v128
	v_add_f32_e32 v133, v133, v134
	v_add_f32_e32 v132, v133, v132
	v_mul_f32_e32 v133, v123, v123
	v_mul_f32_e32 v134, v125, v125
	v_fmac_f32_e32 v133, v122, v122
	v_fmac_f32_e32 v134, v124, v124
	v_add_f32_e32 v133, v133, v134
	v_add_f32_e32 v132, v133, v132
	ds_bpermute_b32 v133, v130, v132
	v_lshlrev_b32_e32 v131, 2, v131
	s_lshl_b32 s4, s36, 2
	s_waitcnt lgkmcnt(0)
	v_add_f32_e32 v132, v132, v133
	ds_bpermute_b32 v133, v131, v132
	v_cmp_gt_u32_e32 vcc, 16, v32
	s_add_i32 s10, s4, 0
	s_and_saveexec_b64 s[4:5], vcc
	s_cbranch_execz .LBB0_957
	s_lshl_b32 s11, s20, 10
	s_add_i32 s11, s10, s11
	v_lshl_add_u32 v134, v174, 4, s11
	s_waitcnt lgkmcnt(0)
	v_add_f32_e32 v132, v132, v133
	ds_write_b32 v134, v132

; __device__ __forceinline__ unsigned cvt_pk_bf16(float lo, float hi) { const f32x2_t v = {lo, hi}; const bf16x2_t c = __builtin_convertvector(v, bf16x2_t); return __builtin_bit_cast(unsigned, c); }
;     __device__ __forceinline__ void fused(f32x4 (&acc)[2][2][4][2], const Unit& u, int wr, int wc, int fr, int fq, PG8_LAS unsigned char* lds, int wid, int lane) const {
;     ...
;         f32x4 gv[2][2];
; #pragma unroll
;         for (int bj = 0; bj < 2; ++bj)
; #pragma unroll
;             for (int n = 0; n < 2; ++n) gv[bj][n] = *(const f32x4*)(g + col0 + bj * HALF + n * 4);
; #pragma unroll
;         for (int ai = 0; ai < 2; ++ai)
; #pragma unroll
;             for (int m = 0; m < 4; ++m) { const int r = ai * HALF + wr * 64 + m * 16 + fr; const float rs = S[r]; const size_t off = (size_t)(u.pm * BM + r) * ld + col0;
; #pragma unroll
;                 for (int bj = 0; bj < 2; ++bj)
; #pragma unroll
;                     for (int n = 0; n < 2; ++n) { const f32x4 o = acc[ai][bj][m][n] * rs * gv[bj][n];
;                         if (final_) *(f32x4*)(OUT + off + bj * HALF + n * 4) = o;
;                         else { u32x2 w; w.x = cvt_pk_bf16(o[0], o[1]); w.y = cvt_pk_bf16(o[2], o[3]); *(u32x2*)(XN + off + bj * HALF + n * 4) = w; } } }
.LBB0_990:
	s_or_b64 exec, exec, s[10:11]
	s_lshl_b64 s[0:1], s[8:9], 2
	v_readlane_b32 s2, v253, 26
	s_add_u32 s0, s2, s0
	v_readlane_b32 s2, v253, 27
	s_addc_u32 s1, s2, s1
	s_waitcnt lgkmcnt(0)
	s_barrier
	v_lshl_add_u64 v[138:139], v[160:161], 2, s[0:1]
	global_load_dwordx4 v[134:137], v[138:139], off offset:16
	global_load_dwordx4 v[142:145], v[138:139], off
	global_load_dwordx4 v[130:133], v[138:139], off offset:528
	s_nop 0
	global_load_dwordx4 v[138:141], v[138:139], off offset:512
	v_lshl_add_u32 v32, v172, 2, 0
	v_add_u32_e32 v32, 0x1000, v32
	ds_read2_b32 v[148:149], v32 offset1:16
	v_add_u32_e32 v146, s18, v172
	v_ashrrev_i32_e32 v147, 31, v146
	v_readlane_b32 s0, v254, 34
	v_readlane_b32 s1, v254, 35
	s_waitcnt lgkmcnt(0)
	v_pk_mul_f32 v[118:119], v[118:119], v[148:149] op_sel_hi:[1,0]
	v_pk_mul_f32 v[120:121], v[120:121], v[148:149] op_sel_hi:[1,0]
	v_pk_mul_f32 v[114:115], v[114:115], v[148:149] op_sel_hi:[1,0]
	v_pk_mul_f32 v[116:117], v[116:117], v[148:149] op_sel_hi:[1,0]
	s_waitcnt vmcnt(3)
	v_pk_mul_f32 v[114:115], v[134:135], v[114:115]
	s_waitcnt vmcnt(2)
	v_pk_mul_f32 v[120:121], v[144:145], v[120:121]
	v_pk_mul_f32 v[118:119], v[142:143], v[118:119]
	v_pk_mul_f32 v[116:117], v[136:137], v[116:117]
	v_cvt_pk_bf16_f32 v118, v118, v119
	v_cvt_pk_bf16_f32 v119, v120, v121
	v_lshlrev_b64 v[120:121], 12, v[146:147]
	v_lshl_add_u64 v[120:121], s[0:1], 0, v[120:121]
	v_lshl_add_u64 v[150:151], v[120:121], 0, v[158:159]
	v_cvt_pk_bf16_f32 v120, v114, v115
	v_cvt_pk_bf16_f32 v121, v116, v117
	v_pk_mul_f32 v[114:115], v[126:127], v[148:149] op_sel_hi:[1,0]
	v_pk_mul_f32 v[116:117], v[128:129], v[148:149] op_sel_hi:[1,0]
	s_waitcnt vmcnt(0)
	v_pk_mul_f32 v[114:115], v[138:139], v[114:115]
	v_pk_mul_f32 v[116:117], v[140:141], v[116:117]
	global_store_dwordx4 v[150:151], v[118:121], off sc1
	v_cvt_pk_bf16_f32 v114, v114, v115
	v_cvt_pk_bf16_f32 v115, v116, v117
	v_pk_mul_f32 v[116:117], v[122:123], v[148:149] op_sel_hi:[1,0]
	v_pk_mul_f32 v[118:119], v[124:125], v[148:149] op_sel_hi:[1,0]
	v_pk_mul_f32 v[116:117], v[130:131], v[116:117]
	v_pk_mul_f32 v[118:119], v[132:133], v[118:119]
	v_cvt_pk_bf16_f32 v116, v116, v117
	v_cvt_pk_bf16_f32 v117, v118, v119
	global_store_dwordx4 v[150:151], v[114:117], off offset:256 sc1
	s_nop 1
	v_mov_b32_e32 v116, v149
	v_add_u32_e32 v114, 16, v146
	v_pk_mul_f32 v[106:107], v[106:107], v[116:117] op_sel_hi:[1,0]
	v_pk_mul_f32 v[108:109], v[108:109], v[116:117] op_sel_hi:[1,0]
	v_ashrrev_i32_e32 v115, 31, v114
	v_pk_mul_f32 v[108:109], v[144:145], v[108:109]
	v_pk_mul_f32 v[106:107], v[142:143], v[106:107]
	v_pk_mul_f32 v[102:103], v[102:103], v[116:117] op_sel_hi:[1,0]
	v_cvt_pk_bf16_f32 v106, v106, v107
	v_cvt_pk_bf16_f32 v107, v108, v109
	v_lshlrev_b64 v[108:109], 12, v[114:115]
	v_pk_mul_f32 v[104:105], v[104:105], v[116:117] op_sel_hi:[1,0]
	v_lshl_add_u64 v[108:109], s[0:1], 0, v[108:109]
	v_pk_mul_f32 v[104:105], v[136:137], v[104:105]
	v_pk_mul_f32 v[102:103], v[134:135], v[102:103]
	v_lshl_add_u64 v[114:115], v[108:109], 0, v[158:159]
	v_cvt_pk_bf16_f32 v108, v102, v103
	v_cvt_pk_bf16_f32 v109, v104, v105
	v_pk_mul_f32 v[102:103], v[110:111], v[116:117] op_sel_hi:[1,0]
	v_pk_mul_f32 v[104:105], v[112:113], v[116:117] op_sel_hi:[1,0]
	v_pk_mul_f32 v[98:99], v[98:99], v[116:117] op_sel_hi:[1,0]
	v_pk_mul_f32 v[104:105], v[140:141], v[104:105]
	v_pk_mul_f32 v[102:103], v[138:139], v[102:103]
	v_pk_mul_f32 v[98:99], v[130:131], v[98:99]
	v_cvt_pk_bf16_f32 v102, v102, v103
	v_cvt_pk_bf16_f32 v103, v104, v105
	v_cvt_pk_bf16_f32 v104, v98, v99
	ds_read2_b32 v[98:99], v32 offset0:32 offset1:48
	v_pk_mul_f32 v[100:101], v[100:101], v[116:117] op_sel_hi:[1,0]
	global_store_dwordx4 v[114:115], v[106:109], off sc1
	v_pk_mul_f32 v[100:101], v[132:133], v[100:101]
	s_waitcnt lgkmcnt(0)
	v_pk_mul_f32 v[86:87], v[86:87], v[98:99] op_sel_hi:[1,0]
	v_pk_mul_f32 v[88:89], v[88:89], v[98:99] op_sel_hi:[1,0]
	v_pk_mul_f32 v[84:85], v[84:85], v[98:99] op_sel_hi:[1,0]
	v_pk_mul_f32 v[88:89], v[140:141], v[88:89]
	v_pk_mul_f32 v[86:87], v[138:139], v[86:87]
	v_pk_mul_f32 v[84:85], v[132:133], v[84:85]
	v_cvt_pk_bf16_f32 v86, v86, v87
	v_cvt_pk_bf16_f32 v87, v88, v89
	v_cvt_pk_bf16_f32 v89, v84, v85
	v_mov_b32_e32 v84, v99
	v_pk_mul_f32 v[70:71], v[70:71], v[84:85] op_sel_hi:[1,0]
	v_pk_mul_f32 v[72:73], v[72:73], v[84:85] op_sel_hi:[1,0]
	v_pk_mul_f32 v[66:67], v[66:67], v[84:85] op_sel_hi:[1,0]
	v_pk_mul_f32 v[72:73], v[140:141], v[72:73]
	v_pk_mul_f32 v[70:71], v[138:139], v[70:71]
	v_pk_mul_f32 v[66:67], v[130:131], v[66:67]
	v_cvt_pk_bf16_f32 v70, v70, v71
	v_cvt_pk_bf16_f32 v71, v72, v73
	v_cvt_pk_bf16_f32 v72, v66, v67
	ds_read2_b32 v[66:67], v32 offset0:128 offset1:144
	v_pk_mul_f32 v[82:83], v[82:83], v[98:99] op_sel_hi:[1,0]
	v_pk_mul_f32 v[68:69], v[68:69], v[84:85] op_sel_hi:[1,0]
	v_pk_mul_f32 v[82:83], v[130:131], v[82:83]
	v_pk_mul_f32 v[68:69], v[132:133], v[68:69]
	s_waitcnt lgkmcnt(0)
	v_pk_mul_f32 v[54:55], v[54:55], v[66:67] op_sel_hi:[1,0]
	v_pk_mul_f32 v[56:57], v[56:57], v[66:67] op_sel_hi:[1,0]
	v_pk_mul_f32 v[52:53], v[52:53], v[66:67] op_sel_hi:[1,0]
	v_pk_mul_f32 v[56:57], v[140:141], v[56:57]
	v_pk_mul_f32 v[54:55], v[138:139], v[54:55]
	v_pk_mul_f32 v[52:53], v[132:133], v[52:53]
	v_cvt_pk_bf16_f32 v54, v54, v55
	v_cvt_pk_bf16_f32 v55, v56, v57
	v_cvt_pk_bf16_f32 v57, v52, v53
	v_mov_b32_e32 v52, v67
	v_pk_mul_f32 v[38:39], v[38:39], v[52:53] op_sel_hi:[1,0]
	v_pk_mul_f32 v[40:41], v[40:41], v[52:53] op_sel_hi:[1,0]
	v_pk_mul_f32 v[34:35], v[34:35], v[52:53] op_sel_hi:[1,0]
	v_pk_mul_f32 v[40:41], v[140:141], v[40:41]
	v_pk_mul_f32 v[38:39], v[138:139], v[38:39]
	v_pk_mul_f32 v[34:35], v[130:131], v[34:35]
	v_cvt_pk_bf16_f32 v38, v38, v39
	v_cvt_pk_bf16_f32 v39, v40, v41
	v_cvt_pk_bf16_f32 v40, v34, v35
	ds_read2_b32 v[34:35], v32 offset0:160 offset1:176
	v_pk_mul_f32 v[50:51], v[50:51], v[66:67] op_sel_hi:[1,0]
	v_pk_mul_f32 v[36:37], v[36:37], v[52:53] op_sel_hi:[1,0]
	v_pk_mul_f32 v[50:51], v[130:131], v[50:51]
	v_pk_mul_f32 v[36:37], v[132:133], v[36:37]
	s_waitcnt lgkmcnt(0)
; __device__ __forceinline__ unsigned cvt_pk_bf16(float lo, float hi) { const f32x2_t v = {lo, hi}; const bf16x2_t c = __builtin_convertvector(v, bf16x2_t); return __builtin_bit_cast(unsigned, c); }
;     __device__ __forceinline__ void fused(f32x4 (&acc)[2][2][4][2], const Unit& u, int wr, int wc, int fr, int fq, PG8_LAS unsigned char* lds, int wid, int lane) const {
;     ...
;         for (int ai = 0; ai < 2; ++ai)
; #pragma unroll
;             for (int m = 0; m < 4; ++m) { const int r = ai * HALF + wr * 64 + m * 16 + fr; const float rs = S[r]; const size_t off = (size_t)(u.pm * BM + r) * ld + col0;
; #pragma unroll
;                 for (int bj = 0; bj < 2; ++bj)
; #pragma unroll
;                     for (int n = 0; n < 2; ++n) { const f32x4 o = acc[ai][bj][m][n] * rs * gv[bj][n];
;                         if (final_) *(f32x4*)(OUT + off + bj * HALF + n * 4) = o;
;                         else { u32x2 w; w.x = cvt_pk_bf16(o[0], o[1]); w.y = cvt_pk_bf16(o[2], o[3]); *(u32x2*)(XN + off + bj * HALF + n * 4) = w; } } }
	v_pk_mul_f32 v[20:21], v[20:21], v[34:35] op_sel_hi:[1,0]
	v_pk_mul_f32 v[22:23], v[22:23], v[34:35] op_sel_hi:[1,0]
	v_pk_mul_f32 v[18:19], v[18:19], v[34:35] op_sel_hi:[1,0]
	v_pk_mul_f32 v[22:23], v[140:141], v[22:23]
	v_pk_mul_f32 v[20:21], v[138:139], v[20:21]
	v_pk_mul_f32 v[16:17], v[16:17], v[34:35] op_sel_hi:[1,0]
	v_pk_mul_f32 v[18:19], v[132:133], v[18:19]
	v_cvt_pk_bf16_f32 v20, v20, v21
	v_cvt_pk_bf16_f32 v21, v22, v23
	v_pk_mul_f32 v[16:17], v[130:131], v[16:17]
	v_cvt_pk_bf16_f32 v23, v18, v19
	v_mov_b32_e32 v18, v35
	v_cvt_pk_bf16_f32 v105, v100, v101
	v_add_u32_e32 v100, 32, v146
	v_pk_mul_f32 v[94:95], v[94:95], v[98:99] op_sel_hi:[1,0]
	v_pk_mul_f32 v[96:97], v[96:97], v[98:99] op_sel_hi:[1,0]
	v_cvt_pk_bf16_f32 v88, v82, v83
	v_add_u32_e32 v82, 48, v146
	v_pk_mul_f32 v[78:79], v[78:79], v[84:85] op_sel_hi:[1,0]
	v_pk_mul_f32 v[80:81], v[80:81], v[84:85] op_sel_hi:[1,0]
	v_cvt_pk_bf16_f32 v73, v68, v69
	v_add_u32_e32 v68, 0x80, v146
	v_pk_mul_f32 v[62:63], v[62:63], v[66:67] op_sel_hi:[1,0]
	v_pk_mul_f32 v[64:65], v[64:65], v[66:67] op_sel_hi:[1,0]
	v_cvt_pk_bf16_f32 v56, v50, v51
	v_add_u32_e32 v50, 0x90, v146
	v_pk_mul_f32 v[46:47], v[46:47], v[52:53] op_sel_hi:[1,0]
	v_pk_mul_f32 v[48:49], v[48:49], v[52:53] op_sel_hi:[1,0]
	v_cvt_pk_bf16_f32 v41, v36, v37
	v_add_u32_e32 v36, 0xa0, v146
	v_pk_mul_f32 v[28:29], v[28:29], v[34:35] op_sel_hi:[1,0]
	v_pk_mul_f32 v[30:31], v[30:31], v[34:35] op_sel_hi:[1,0]
	v_cvt_pk_bf16_f32 v22, v16, v17
	v_add_u32_e32 v16, 0xb0, v146
	v_pk_mul_f32 v[12:13], v[12:13], v[18:19] op_sel_hi:[1,0]
	v_pk_mul_f32 v[14:15], v[14:15], v[18:19] op_sel_hi:[1,0]
	v_ashrrev_i32_e32 v101, 31, v100
	v_pk_mul_f32 v[96:97], v[144:145], v[96:97]
	v_pk_mul_f32 v[94:95], v[142:143], v[94:95]
	v_ashrrev_i32_e32 v83, 31, v82
	v_pk_mul_f32 v[80:81], v[144:145], v[80:81]
	v_pk_mul_f32 v[78:79], v[142:143], v[78:79]
	v_ashrrev_i32_e32 v69, 31, v68
	v_pk_mul_f32 v[64:65], v[144:145], v[64:65]
	v_pk_mul_f32 v[62:63], v[142:143], v[62:63]
	v_ashrrev_i32_e32 v51, 31, v50
	v_pk_mul_f32 v[48:49], v[144:145], v[48:49]
	v_pk_mul_f32 v[46:47], v[142:143], v[46:47]
	v_ashrrev_i32_e32 v37, 31, v36
	v_pk_mul_f32 v[30:31], v[144:145], v[30:31]
	v_pk_mul_f32 v[28:29], v[142:143], v[28:29]
	v_ashrrev_i32_e32 v17, 31, v16
	v_pk_mul_f32 v[14:15], v[144:145], v[14:15]
	v_pk_mul_f32 v[12:13], v[142:143], v[12:13]
	v_cvt_pk_bf16_f32 v94, v94, v95
	v_cvt_pk_bf16_f32 v95, v96, v97
	v_lshlrev_b64 v[96:97], 12, v[100:101]
	v_pk_mul_f32 v[90:91], v[90:91], v[98:99] op_sel_hi:[1,0]
	v_pk_mul_f32 v[92:93], v[92:93], v[98:99] op_sel_hi:[1,0]
	v_cvt_pk_bf16_f32 v78, v78, v79
	v_cvt_pk_bf16_f32 v79, v80, v81
	v_lshlrev_b64 v[80:81], 12, v[82:83]
	v_pk_mul_f32 v[74:75], v[74:75], v[84:85] op_sel_hi:[1,0]
	v_pk_mul_f32 v[76:77], v[76:77], v[84:85] op_sel_hi:[1,0]
	v_cvt_pk_bf16_f32 v62, v62, v63
	v_cvt_pk_bf16_f32 v63, v64, v65
	v_lshlrev_b64 v[64:65], 12, v[68:69]
	v_pk_mul_f32 v[58:59], v[58:59], v[66:67] op_sel_hi:[1,0]
	v_pk_mul_f32 v[60:61], v[60:61], v[66:67] op_sel_hi:[1,0]
	v_cvt_pk_bf16_f32 v46, v46, v47
	v_cvt_pk_bf16_f32 v47, v48, v49
	v_lshlrev_b64 v[48:49], 12, v[50:51]
	v_pk_mul_f32 v[42:43], v[42:43], v[52:53] op_sel_hi:[1,0]
	v_pk_mul_f32 v[44:45], v[44:45], v[52:53] op_sel_hi:[1,0]
	v_cvt_pk_bf16_f32 v28, v28, v29
	v_cvt_pk_bf16_f32 v29, v30, v31
	v_lshlrev_b64 v[30:31], 12, v[36:37]
	v_pk_mul_f32 v[24:25], v[24:25], v[34:35] op_sel_hi:[1,0]
	v_pk_mul_f32 v[26:27], v[26:27], v[34:35] op_sel_hi:[1,0]
	v_cvt_pk_bf16_f32 v12, v12, v13
	v_cvt_pk_bf16_f32 v13, v14, v15
	v_lshlrev_b64 v[14:15], 12, v[16:17]
	v_pk_mul_f32 v[8:9], v[8:9], v[18:19] op_sel_hi:[1,0]
	v_pk_mul_f32 v[10:11], v[10:11], v[18:19] op_sel_hi:[1,0]
	v_pk_mul_f32 v[4:5], v[4:5], v[18:19] op_sel_hi:[1,0]
	v_pk_mul_f32 v[6:7], v[6:7], v[18:19] op_sel_hi:[1,0]
	v_pk_mul_f32 v[0:1], v[0:1], v[18:19] op_sel_hi:[1,0]
	v_pk_mul_f32 v[2:3], v[2:3], v[18:19] op_sel_hi:[1,0]
	v_lshl_add_u64 v[96:97], s[0:1], 0, v[96:97]
	v_pk_mul_f32 v[92:93], v[136:137], v[92:93]
	v_pk_mul_f32 v[90:91], v[134:135], v[90:91]
	v_lshl_add_u64 v[80:81], s[0:1], 0, v[80:81]
	v_pk_mul_f32 v[76:77], v[136:137], v[76:77]
	v_pk_mul_f32 v[74:75], v[134:135], v[74:75]
	v_lshl_add_u64 v[64:65], s[0:1], 0, v[64:65]
	v_pk_mul_f32 v[60:61], v[136:137], v[60:61]
	v_pk_mul_f32 v[58:59], v[134:135], v[58:59]
	v_lshl_add_u64 v[48:49], s[0:1], 0, v[48:49]
	v_pk_mul_f32 v[44:45], v[136:137], v[44:45]
	v_pk_mul_f32 v[42:43], v[134:135], v[42:43]
	v_lshl_add_u64 v[30:31], s[0:1], 0, v[30:31]
	v_pk_mul_f32 v[26:27], v[136:137], v[26:27]
	v_pk_mul_f32 v[24:25], v[134:135], v[24:25]
	v_lshl_add_u64 v[14:15], s[0:1], 0, v[14:15]
	v_pk_mul_f32 v[10:11], v[136:137], v[10:11]
	v_pk_mul_f32 v[8:9], v[134:135], v[8:9]
	v_pk_mul_f32 v[6:7], v[140:141], v[6:7]
	v_pk_mul_f32 v[4:5], v[138:139], v[4:5]
	v_pk_mul_f32 v[2:3], v[132:133], v[2:3]
	v_pk_mul_f32 v[0:1], v[130:131], v[0:1]
	v_lshl_add_u64 v[100:101], v[96:97], 0, v[158:159]
	v_cvt_pk_bf16_f32 v96, v90, v91
	v_cvt_pk_bf16_f32 v97, v92, v93
	v_lshl_add_u64 v[82:83], v[80:81], 0, v[158:159]
	v_cvt_pk_bf16_f32 v80, v74, v75
	v_cvt_pk_bf16_f32 v81, v76, v77
	v_lshl_add_u64 v[68:69], v[64:65], 0, v[158:159]
	v_cvt_pk_bf16_f32 v64, v58, v59
	v_cvt_pk_bf16_f32 v65, v60, v61
	v_lshl_add_u64 v[50:51], v[48:49], 0, v[158:159]
	v_cvt_pk_bf16_f32 v48, v42, v43
	v_cvt_pk_bf16_f32 v49, v44, v45
	v_lshl_add_u64 v[36:37], v[30:31], 0, v[158:159]
	v_cvt_pk_bf16_f32 v30, v24, v25
	v_cvt_pk_bf16_f32 v31, v26, v27
	v_lshl_add_u64 v[16:17], v[14:15], 0, v[158:159]
	v_cvt_pk_bf16_f32 v14, v8, v9
	v_cvt_pk_bf16_f32 v15, v10, v11
	v_cvt_pk_bf16_f32 v4, v4, v5
	v_cvt_pk_bf16_f32 v5, v6, v7
	v_cvt_pk_bf16_f32 v6, v0, v1
	v_cvt_pk_bf16_f32 v7, v2, v3
	global_store_dwordx4 v[114:115], v[102:105], off offset:256 sc1
	global_store_dwordx4 v[100:101], v[94:97], off sc1
	global_store_dwordx4 v[100:101], v[86:89], off offset:256 sc1
	global_store_dwordx4 v[82:83], v[78:81], off sc1
	global_store_dwordx4 v[82:83], v[70:73], off offset:256 sc1
	global_store_dwordx4 v[68:69], v[62:65], off sc1
	global_store_dwordx4 v[68:69], v[54:57], off offset:256 sc1
	global_store_dwordx4 v[50:51], v[46:49], off sc1
	global_store_dwordx4 v[50:51], v[38:41], off offset:256 sc1
	global_store_dwordx4 v[36:37], v[28:31], off sc1
	global_store_dwordx4 v[36:37], v[20:23], off offset:256 sc1
	global_store_dwordx4 v[16:17], v[12:15], off sc1
	global_store_dwordx4 v[16:17], v[4:7], off offset:256 sc1

; __device__ __forceinline__ unsigned cvt_pk_bf16(float lo, float hi) { const f32x2_t v = {lo, hi}; const bf16x2_t c = __builtin_convertvector(v, bf16x2_t); return __builtin_bit_cast(unsigned, c); }
; __device__ __forceinline__ float siluf_fast(float x) { return x * sigmoidf_fast(x); }
;     __device__ __forceinline__ void operator()(const f32x4 (&acc)[2][2][4][2], const Unit& u, int wr, int wc, int fr, int fq) const {
;         const int row0 = u.pm * BM + wr * 64 + fr, col0 = u.pn * HALF + wc * 32 + 8 * fq;
; #pragma unroll
;         for (int ai = 0; ai < 2; ++ai)
; #pragma unroll
;             for (int m = 0; m < 4; ++m) { const size_t r = (size_t)(row0 + ai * HALF + m * 16);
;                 const f32x4 g0 = acc[ai][0][m][0], u0 = acc[ai][0][m][1], g1 = acc[ai][1][m][0], u1 = acc[ai][1][m][1];
;                 u32x4 w; w.x = cvt_pk_bf16(siluf_fast(g0[0]) * u0[0], siluf_fast(g0[1]) * u0[1]); w.y = cvt_pk_bf16(siluf_fast(g0[2]) * u0[2], siluf_fast(g0[3]) * u0[3]);
;                 w.z = cvt_pk_bf16(siluf_fast(g1[0]) * u1[0], siluf_fast(g1[1]) * u1[1]); w.w = cvt_pk_bf16(siluf_fast(g1[2]) * u1[2], siluf_fast(g1[3]) * u1[3]);
;                 *(u32x4*)(O + r * ldo + col0) = w; }
.LBB0_1066:
	v_mul_f32_e32 v141, 0xbfb8aa3b, v126
	v_exp_f32_e32 v141, v141
	v_lshl_add_u32 v140, s18, 8, v136
	v_lshl_or_b32 v142, s19, 7, v138
	v_readlane_b32 s18, v254, 28
	v_add_f32_e32 v141, 1.0, v141
	v_rcp_f32_e32 v144, v141
	v_mul_f32_e32 v141, 0xbfb8aa3b, v127
	v_exp_f32_e32 v141, v141
	v_readlane_b32 s19, v254, 29
	v_ashrrev_i32_e32 v143, 31, v142
	s_movk_i32 s11, 0x2c00
	v_add_f32_e32 v141, 1.0, v141
	v_rcp_f32_e32 v145, v141
	s_andn2_b64 vcc, exec, s[14:15]
	v_pk_mul_f32 v[126:127], v[126:127], v[144:145]
	s_nop 0
	v_pk_mul_f32 v[122:123], v[122:123], v[126:127]
	s_nop 0
	v_cvt_pk_bf16_f32 v122, v122, v123
	v_mul_f32_e32 v123, 0xbfb8aa3b, v128
	v_exp_f32_e32 v123, v123
	s_nop 0
	v_add_f32_e32 v123, 1.0, v123
	v_rcp_f32_e32 v126, v123
	v_mul_f32_e32 v123, 0xbfb8aa3b, v129
	v_exp_f32_e32 v123, v123
	s_nop 0
	v_add_f32_e32 v123, 1.0, v123
	v_rcp_f32_e32 v127, v123
	s_nop 0
	v_pk_mul_f32 v[126:127], v[128:129], v[126:127]
	s_nop 0
	v_pk_mul_f32 v[124:125], v[124:125], v[126:127]
	s_nop 0
	v_cvt_pk_bf16_f32 v123, v124, v125
	v_mul_f32_e32 v124, 0xbfb8aa3b, v118
	v_mul_f32_e32 v125, 0xbfb8aa3b, v119
	v_exp_f32_e32 v124, v124
	v_exp_f32_e32 v125, v125
	v_add_f32_e32 v124, 1.0, v124
	v_add_f32_e32 v125, 1.0, v125
	v_rcp_f32_e32 v124, v124
	v_rcp_f32_e32 v125, v125
	s_nop 0
	v_pk_mul_f32 v[118:119], v[118:119], v[124:125]
	s_nop 0
	v_pk_mul_f32 v[114:115], v[114:115], v[118:119]
	s_nop 0
	v_cvt_pk_bf16_f32 v124, v114, v115
	v_mul_f32_e32 v114, 0xbfb8aa3b, v120
	v_mul_f32_e32 v115, 0xbfb8aa3b, v121
	v_exp_f32_e32 v114, v114
	v_exp_f32_e32 v115, v115
	v_add_f32_e32 v114, 1.0, v114
	v_add_f32_e32 v115, 1.0, v115
	v_rcp_f32_e32 v114, v114
	v_rcp_f32_e32 v115, v115
	s_nop 0
	v_pk_mul_f32 v[114:115], v[120:121], v[114:115]
	s_nop 0
	v_pk_mul_f32 v[114:115], v[116:117], v[114:115]
	v_lshlrev_b64 v[116:117], 1, v[142:143]
	v_cvt_pk_bf16_f32 v125, v114, v115
	v_mov_b64_e32 v[114:115], s[18:19]
	v_mad_i64_i32 v[118:119], s[18:19], v140, s11, v[114:115]
	v_lshl_add_u64 v[118:119], v[118:119], 0, v[116:117]
	global_store_dwordx4 v[118:119], v[122:125], off sc1
	v_mul_f32_e32 v118, 0xbfb8aa3b, v110
	v_mul_f32_e32 v119, 0xbfb8aa3b, v111
	v_exp_f32_e32 v118, v118
	v_exp_f32_e32 v119, v119
	v_or_b32_e32 v120, 16, v140
	v_add_f32_e32 v118, 1.0, v118
	v_add_f32_e32 v119, 1.0, v119
	v_rcp_f32_e32 v118, v118
	v_rcp_f32_e32 v119, v119
	s_nop 0
	v_pk_mul_f32 v[110:111], v[110:111], v[118:119]
	s_nop 0
	v_pk_mul_f32 v[106:107], v[106:107], v[110:111]
	s_nop 0
	v_cvt_pk_bf16_f32 v106, v106, v107
	v_mul_f32_e32 v107, 0xbfb8aa3b, v112
	v_exp_f32_e32 v107, v107
	s_nop 0
	v_add_f32_e32 v107, 1.0, v107
	v_rcp_f32_e32 v110, v107
	v_mul_f32_e32 v107, 0xbfb8aa3b, v113
	v_exp_f32_e32 v107, v107
	s_nop 0
	v_add_f32_e32 v107, 1.0, v107
	v_rcp_f32_e32 v111, v107
	s_nop 0
	v_pk_mul_f32 v[110:111], v[112:113], v[110:111]
	s_nop 0
	v_pk_mul_f32 v[108:109], v[108:109], v[110:111]
	s_nop 0
	v_cvt_pk_bf16_f32 v107, v108, v109
	v_mul_f32_e32 v108, 0xbfb8aa3b, v102
	v_mul_f32_e32 v109, 0xbfb8aa3b, v103
	v_exp_f32_e32 v108, v108
	v_exp_f32_e32 v109, v109
	v_add_f32_e32 v108, 1.0, v108
	v_add_f32_e32 v109, 1.0, v109
	v_rcp_f32_e32 v108, v108
	v_rcp_f32_e32 v109, v109
	s_nop 0
	v_pk_mul_f32 v[102:103], v[102:103], v[108:109]
	s_nop 0
	v_pk_mul_f32 v[98:99], v[98:99], v[102:103]
	s_nop 0
	v_cvt_pk_bf16_f32 v108, v98, v99
	v_mul_f32_e32 v98, 0xbfb8aa3b, v104
	v_mul_f32_e32 v99, 0xbfb8aa3b, v105
	v_exp_f32_e32 v98, v98
	v_exp_f32_e32 v99, v99
	v_add_f32_e32 v98, 1.0, v98
	v_add_f32_e32 v99, 1.0, v99
	v_rcp_f32_e32 v98, v98
	v_rcp_f32_e32 v99, v99
	s_nop 0
	v_pk_mul_f32 v[98:99], v[104:105], v[98:99]
	s_nop 0
	v_pk_mul_f32 v[98:99], v[100:101], v[98:99]
	v_or_b32_e32 v100, 32, v140
	v_cvt_pk_bf16_f32 v109, v98, v99
	v_mad_i64_i32 v[98:99], s[18:19], v120, s11, v[114:115]
	v_lshl_add_u64 v[98:99], v[98:99], 0, v[116:117]
	global_store_dwordx4 v[98:99], v[106:109], off sc1
	v_mul_f32_e32 v98, 0xbfb8aa3b, v94
	v_mul_f32_e32 v99, 0xbfb8aa3b, v95
	v_exp_f32_e32 v98, v98
	v_exp_f32_e32 v99, v99
	v_add_f32_e32 v98, 1.0, v98
	v_add_f32_e32 v99, 1.0, v99
	v_rcp_f32_e32 v98, v98
	v_rcp_f32_e32 v99, v99
	s_nop 0
	v_pk_mul_f32 v[94:95], v[94:95], v[98:99]
	s_nop 0
	v_pk_mul_f32 v[90:91], v[90:91], v[94:95]
	s_nop 0
	v_cvt_pk_bf16_f32 v90, v90, v91
	v_mul_f32_e32 v91, 0xbfb8aa3b, v96
	v_exp_f32_e32 v91, v91
	s_nop 0
	v_add_f32_e32 v91, 1.0, v91
	v_rcp_f32_e32 v94, v91
	v_mul_f32_e32 v91, 0xbfb8aa3b, v97
	v_exp_f32_e32 v91, v91
	s_nop 0
	v_add_f32_e32 v91, 1.0, v91
	v_rcp_f32_e32 v95, v91
	s_nop 0
	v_pk_mul_f32 v[94:95], v[96:97], v[94:95]
	s_nop 0
	v_pk_mul_f32 v[92:93], v[92:93], v[94:95]
	s_nop 0
	v_cvt_pk_bf16_f32 v91, v92, v93
	v_mul_f32_e32 v92, 0xbfb8aa3b, v86
	v_mul_f32_e32 v93, 0xbfb8aa3b, v87
	v_exp_f32_e32 v92, v92
	v_exp_f32_e32 v93, v93
	v_add_f32_e32 v92, 1.0, v92
	v_add_f32_e32 v93, 1.0, v93
	v_rcp_f32_e32 v92, v92
	v_rcp_f32_e32 v93, v93
	s_nop 0
	v_pk_mul_f32 v[86:87], v[86:87], v[92:93]
	s_nop 0
	v_pk_mul_f32 v[82:83], v[82:83], v[86:87]
	s_nop 0
	v_cvt_pk_bf16_f32 v92, v82, v83
	v_mul_f32_e32 v82, 0xbfb8aa3b, v88
	v_mul_f32_e32 v83, 0xbfb8aa3b, v89
	v_exp_f32_e32 v82, v82
	v_exp_f32_e32 v83, v83
	v_add_f32_e32 v82, 1.0, v82
	v_add_f32_e32 v83, 1.0, v83
	v_rcp_f32_e32 v82, v82
	v_rcp_f32_e32 v83, v83
	s_nop 0
	v_pk_mul_f32 v[82:83], v[88:89], v[82:83]
	s_nop 0
	v_pk_mul_f32 v[82:83], v[84:85], v[82:83]
	v_or_b32_e32 v84, 48, v140
	v_cvt_pk_bf16_f32 v93, v82, v83
	v_mad_i64_i32 v[82:83], s[18:19], v100, s11, v[114:115]
	v_lshl_add_u64 v[82:83], v[82:83], 0, v[116:117]
	global_store_dwordx4 v[82:83], v[90:93], off sc1
	v_mul_f32_e32 v82, 0xbfb8aa3b, v78
	v_mul_f32_e32 v83, 0xbfb8aa3b, v79
; __device__ __forceinline__ unsigned cvt_pk_bf16(float lo, float hi) { const f32x2_t v = {lo, hi}; const bf16x2_t c = __builtin_convertvector(v, bf16x2_t); return __builtin_bit_cast(unsigned, c); }
; __device__ __forceinline__ float siluf_fast(float x) { return x * sigmoidf_fast(x); }
;     __device__ __forceinline__ void operator()(const f32x4 (&acc)[2][2][4][2], const Unit& u, int wr, int wc, int fr, int fq) const {
;         const int row0 = u.pm * BM + wr * 64 + fr, col0 = u.pn * HALF + wc * 32 + 8 * fq;
; #pragma unroll
;         for (int ai = 0; ai < 2; ++ai)
; #pragma unroll
;             for (int m = 0; m < 4; ++m) { const size_t r = (size_t)(row0 + ai * HALF + m * 16);
;                 const f32x4 g0 = acc[ai][0][m][0], u0 = acc[ai][0][m][1], g1 = acc[ai][1][m][0], u1 = acc[ai][1][m][1];
;                 u32x4 w; w.x = cvt_pk_bf16(siluf_fast(g0[0]) * u0[0], siluf_fast(g0[1]) * u0[1]); w.y = cvt_pk_bf16(siluf_fast(g0[2]) * u0[2], siluf_fast(g0[3]) * u0[3]);
;                 w.z = cvt_pk_bf16(siluf_fast(g1[0]) * u1[0], siluf_fast(g1[1]) * u1[1]); w.w = cvt_pk_bf16(siluf_fast(g1[2]) * u1[2], siluf_fast(g1[3]) * u1[3]);
;                 *(u32x4*)(O + r * ldo + col0) = w; }
	v_exp_f32_e32 v82, v82
	v_exp_f32_e32 v83, v83
	v_add_f32_e32 v82, 1.0, v82
	v_add_f32_e32 v83, 1.0, v83
	v_rcp_f32_e32 v82, v82
	v_rcp_f32_e32 v83, v83
	s_nop 0
	v_pk_mul_f32 v[78:79], v[78:79], v[82:83]
	s_nop 0
	v_pk_mul_f32 v[74:75], v[74:75], v[78:79]
	s_nop 0
	v_cvt_pk_bf16_f32 v74, v74, v75
	v_mul_f32_e32 v75, 0xbfb8aa3b, v80
	v_exp_f32_e32 v75, v75
	s_nop 0
	v_add_f32_e32 v75, 1.0, v75
	v_rcp_f32_e32 v78, v75
	v_mul_f32_e32 v75, 0xbfb8aa3b, v81
	v_exp_f32_e32 v75, v75
	s_nop 0
	v_add_f32_e32 v75, 1.0, v75
	v_rcp_f32_e32 v79, v75
	s_nop 0
	v_pk_mul_f32 v[78:79], v[80:81], v[78:79]
	s_nop 0
	v_pk_mul_f32 v[76:77], v[76:77], v[78:79]
	s_nop 0
	v_cvt_pk_bf16_f32 v75, v76, v77
	v_mul_f32_e32 v76, 0xbfb8aa3b, v70
	v_mul_f32_e32 v77, 0xbfb8aa3b, v71
	v_exp_f32_e32 v76, v76
	v_exp_f32_e32 v77, v77
	v_add_f32_e32 v76, 1.0, v76
	v_add_f32_e32 v77, 1.0, v77
	v_rcp_f32_e32 v76, v76
	v_rcp_f32_e32 v77, v77
	s_nop 0
	v_pk_mul_f32 v[70:71], v[70:71], v[76:77]
	s_nop 0
	v_pk_mul_f32 v[66:67], v[66:67], v[70:71]
	s_nop 0
	v_cvt_pk_bf16_f32 v76, v66, v67
	v_mul_f32_e32 v66, 0xbfb8aa3b, v72
	v_mul_f32_e32 v67, 0xbfb8aa3b, v73
	v_exp_f32_e32 v66, v66
	v_exp_f32_e32 v67, v67
	v_add_f32_e32 v66, 1.0, v66
	v_add_f32_e32 v67, 1.0, v67
	v_rcp_f32_e32 v66, v66
	v_rcp_f32_e32 v67, v67
	s_nop 0
	v_pk_mul_f32 v[66:67], v[72:73], v[66:67]
	s_nop 0
	v_pk_mul_f32 v[66:67], v[68:69], v[66:67]
	v_add_u32_e32 v68, 0x80, v140
	v_cvt_pk_bf16_f32 v77, v66, v67
	v_mad_i64_i32 v[66:67], s[18:19], v84, s11, v[114:115]
	v_lshl_add_u64 v[66:67], v[66:67], 0, v[116:117]
	global_store_dwordx4 v[66:67], v[74:77], off sc1
	v_mul_f32_e32 v66, 0xbfb8aa3b, v62
	v_mul_f32_e32 v67, 0xbfb8aa3b, v63
	v_exp_f32_e32 v66, v66
	v_exp_f32_e32 v67, v67
	v_add_f32_e32 v66, 1.0, v66
	v_add_f32_e32 v67, 1.0, v67
	v_rcp_f32_e32 v66, v66
	v_rcp_f32_e32 v67, v67
	s_nop 0
	v_pk_mul_f32 v[62:63], v[62:63], v[66:67]
	s_nop 0
	v_pk_mul_f32 v[58:59], v[58:59], v[62:63]
	s_nop 0
	v_cvt_pk_bf16_f32 v58, v58, v59
	v_mul_f32_e32 v59, 0xbfb8aa3b, v64
	v_exp_f32_e32 v59, v59
	s_nop 0
	v_add_f32_e32 v59, 1.0, v59
	v_rcp_f32_e32 v62, v59
	v_mul_f32_e32 v59, 0xbfb8aa3b, v65
	v_exp_f32_e32 v59, v59
	s_nop 0
	v_add_f32_e32 v59, 1.0, v59
	v_rcp_f32_e32 v63, v59
	s_nop 0
	v_pk_mul_f32 v[62:63], v[64:65], v[62:63]
	s_nop 0
	v_pk_mul_f32 v[60:61], v[60:61], v[62:63]
	s_nop 0
	v_cvt_pk_bf16_f32 v59, v60, v61
	v_mul_f32_e32 v60, 0xbfb8aa3b, v54
	v_mul_f32_e32 v61, 0xbfb8aa3b, v55
	v_exp_f32_e32 v60, v60
	v_exp_f32_e32 v61, v61
	v_add_f32_e32 v60, 1.0, v60
	v_add_f32_e32 v61, 1.0, v61
	v_rcp_f32_e32 v60, v60
	v_rcp_f32_e32 v61, v61
	s_nop 0
	v_pk_mul_f32 v[54:55], v[54:55], v[60:61]
	s_nop 0
	v_pk_mul_f32 v[50:51], v[50:51], v[54:55]
	s_nop 0
	v_cvt_pk_bf16_f32 v60, v50, v51
	v_mul_f32_e32 v50, 0xbfb8aa3b, v56
	v_mul_f32_e32 v51, 0xbfb8aa3b, v57
	v_exp_f32_e32 v50, v50
	v_exp_f32_e32 v51, v51
	v_add_f32_e32 v50, 1.0, v50
	v_add_f32_e32 v51, 1.0, v51
	v_rcp_f32_e32 v50, v50
	v_rcp_f32_e32 v51, v51
	s_nop 0
	v_pk_mul_f32 v[50:51], v[56:57], v[50:51]
	s_nop 0
	v_pk_mul_f32 v[50:51], v[52:53], v[50:51]
	v_add_u32_e32 v52, 0x90, v140
	v_cvt_pk_bf16_f32 v61, v50, v51
	v_mad_i64_i32 v[50:51], s[18:19], v68, s11, v[114:115]
	v_lshl_add_u64 v[50:51], v[50:51], 0, v[116:117]
	global_store_dwordx4 v[50:51], v[58:61], off sc1
	v_mul_f32_e32 v50, 0xbfb8aa3b, v46
	v_mul_f32_e32 v51, 0xbfb8aa3b, v47
	v_exp_f32_e32 v50, v50
	v_exp_f32_e32 v51, v51
	v_add_f32_e32 v50, 1.0, v50
	v_add_f32_e32 v51, 1.0, v51
	v_rcp_f32_e32 v50, v50
	v_rcp_f32_e32 v51, v51
	s_nop 0
	v_pk_mul_f32 v[46:47], v[46:47], v[50:51]
	s_nop 0
	v_pk_mul_f32 v[42:43], v[42:43], v[46:47]
	s_nop 0
	v_cvt_pk_bf16_f32 v42, v42, v43
	v_mul_f32_e32 v43, 0xbfb8aa3b, v48
	v_exp_f32_e32 v43, v43
	s_nop 0
	v_add_f32_e32 v43, 1.0, v43
	v_rcp_f32_e32 v46, v43
	v_mul_f32_e32 v43, 0xbfb8aa3b, v49
	v_exp_f32_e32 v43, v43
	s_nop 0
	v_add_f32_e32 v43, 1.0, v43
	v_rcp_f32_e32 v47, v43
	s_nop 0
	v_pk_mul_f32 v[46:47], v[48:49], v[46:47]
	s_nop 0
	v_pk_mul_f32 v[44:45], v[44:45], v[46:47]
	s_nop 0
	v_cvt_pk_bf16_f32 v43, v44, v45
	v_mul_f32_e32 v44, 0xbfb8aa3b, v38
	v_mul_f32_e32 v45, 0xbfb8aa3b, v39
	v_exp_f32_e32 v44, v44
	v_exp_f32_e32 v45, v45
	v_add_f32_e32 v44, 1.0, v44
; __device__ __forceinline__ unsigned cvt_pk_bf16(float lo, float hi) { const f32x2_t v = {lo, hi}; const bf16x2_t c = __builtin_convertvector(v, bf16x2_t); return __builtin_bit_cast(unsigned, c); }
; __device__ __forceinline__ float siluf_fast(float x) { return x * sigmoidf_fast(x); }
; #define PG8_BAR __builtin_amdgcn_s_barrier()
;     __device__ __forceinline__ void operator()(const f32x4 (&acc)[2][2][4][2], const Unit& u, int wr, int wc, int fr, int fq) const {
;         const int row0 = u.pm * BM + wr * 64 + fr, col0 = u.pn * HALF + wc * 32 + 8 * fq;
; #pragma unroll
;         for (int ai = 0; ai < 2; ++ai)
; #pragma unroll
;             for (int m = 0; m < 4; ++m) { const size_t r = (size_t)(row0 + ai * HALF + m * 16);
;                 const f32x4 g0 = acc[ai][0][m][0], u0 = acc[ai][0][m][1], g1 = acc[ai][1][m][0], u1 = acc[ai][1][m][1];
;                 u32x4 w; w.x = cvt_pk_bf16(siluf_fast(g0[0]) * u0[0], siluf_fast(g0[1]) * u0[1]); w.y = cvt_pk_bf16(siluf_fast(g0[2]) * u0[2], siluf_fast(g0[3]) * u0[3]);
;                 w.z = cvt_pk_bf16(siluf_fast(g1[0]) * u1[0], siluf_fast(g1[1]) * u1[1]); w.w = cvt_pk_bf16(siluf_fast(g1[2]) * u1[2], siluf_fast(g1[3]) * u1[3]);
;                 *(u32x4*)(O + r * ldo + col0) = w; }
; template <class Epi, class Sched, bool ALIGN_EPI = false, bool SP2 = false, bool KHOOK = false>
; __device__ __forceinline__ void gemm_phase(PG8_LAS unsigned char* lds, const Gemm g, const Sched& S, const Epi& E, const int tid_in) {
;     ...
;         cur = nxt; cA = nA; cB = nB; ++ui; load_rr(cur);
;         if constexpr (ALIGN_EPI) { if (wr == 1) PG8_BAR; }
	v_add_f32_e32 v45, 1.0, v45
	v_rcp_f32_e32 v44, v44
	v_rcp_f32_e32 v45, v45
	s_nop 0
	v_pk_mul_f32 v[38:39], v[38:39], v[44:45]
	s_nop 0
	v_pk_mul_f32 v[34:35], v[34:35], v[38:39]
	s_nop 0
	v_cvt_pk_bf16_f32 v44, v34, v35
	v_mul_f32_e32 v34, 0xbfb8aa3b, v40
	v_mul_f32_e32 v35, 0xbfb8aa3b, v41
	v_exp_f32_e32 v34, v34
	v_exp_f32_e32 v35, v35
	v_add_f32_e32 v34, 1.0, v34
	v_add_f32_e32 v35, 1.0, v35
	v_rcp_f32_e32 v34, v34
	v_rcp_f32_e32 v35, v35
	s_nop 0
	v_pk_mul_f32 v[34:35], v[40:41], v[34:35]
	s_nop 0
	v_pk_mul_f32 v[34:35], v[36:37], v[34:35]
	v_add_u32_e32 v36, 0xa0, v140
	v_cvt_pk_bf16_f32 v45, v34, v35
	v_mad_i64_i32 v[34:35], s[18:19], v52, s11, v[114:115]
	v_lshl_add_u64 v[34:35], v[34:35], 0, v[116:117]
	global_store_dwordx4 v[34:35], v[42:45], off sc1
	v_mul_f32_e32 v34, 0xbfb8aa3b, v28
	v_mul_f32_e32 v35, 0xbfb8aa3b, v29
	v_exp_f32_e32 v34, v34
	v_exp_f32_e32 v35, v35
	v_add_f32_e32 v34, 1.0, v34
	v_add_f32_e32 v35, 1.0, v35
	v_rcp_f32_e32 v34, v34
	v_rcp_f32_e32 v35, v35
	s_nop 0
	v_pk_mul_f32 v[28:29], v[28:29], v[34:35]
	s_nop 0
	v_pk_mul_f32 v[24:25], v[24:25], v[28:29]
	s_nop 0
	v_cvt_pk_bf16_f32 v24, v24, v25
	v_mul_f32_e32 v25, 0xbfb8aa3b, v30
	v_exp_f32_e32 v25, v25
	s_nop 0
	v_add_f32_e32 v25, 1.0, v25
	v_rcp_f32_e32 v28, v25
	v_mul_f32_e32 v25, 0xbfb8aa3b, v31
	v_exp_f32_e32 v25, v25
	s_nop 0
	v_add_f32_e32 v25, 1.0, v25
	v_rcp_f32_e32 v29, v25
	s_nop 0
	v_pk_mul_f32 v[28:29], v[30:31], v[28:29]
	s_nop 0
	v_pk_mul_f32 v[26:27], v[26:27], v[28:29]
	s_nop 0
	v_cvt_pk_bf16_f32 v25, v26, v27
	v_mul_f32_e32 v26, 0xbfb8aa3b, v20
	v_mul_f32_e32 v27, 0xbfb8aa3b, v21
	v_exp_f32_e32 v26, v26
	v_exp_f32_e32 v27, v27
	v_add_f32_e32 v26, 1.0, v26
	v_add_f32_e32 v27, 1.0, v27
	v_rcp_f32_e32 v26, v26
	v_rcp_f32_e32 v27, v27
	s_nop 0
	v_pk_mul_f32 v[20:21], v[20:21], v[26:27]
	s_nop 0
	v_pk_mul_f32 v[16:17], v[16:17], v[20:21]
	s_nop 0
	v_cvt_pk_bf16_f32 v26, v16, v17
	v_mul_f32_e32 v16, 0xbfb8aa3b, v22
	v_mul_f32_e32 v17, 0xbfb8aa3b, v23
	v_exp_f32_e32 v16, v16
	v_exp_f32_e32 v17, v17
	v_add_f32_e32 v16, 1.0, v16
	v_add_f32_e32 v17, 1.0, v17
	v_rcp_f32_e32 v16, v16
	v_rcp_f32_e32 v17, v17
	s_nop 0
	v_pk_mul_f32 v[16:17], v[22:23], v[16:17]
	s_nop 0
	v_pk_mul_f32 v[16:17], v[18:19], v[16:17]
	v_add_u32_e32 v18, 0xb0, v140
	v_cvt_pk_bf16_f32 v27, v16, v17
	v_mad_i64_i32 v[16:17], s[18:19], v36, s11, v[114:115]
	v_lshl_add_u64 v[16:17], v[16:17], 0, v[116:117]
	global_store_dwordx4 v[16:17], v[24:27], off sc1
	v_mul_f32_e32 v16, 0xbfb8aa3b, v12
	v_mul_f32_e32 v17, 0xbfb8aa3b, v13
	v_exp_f32_e32 v16, v16
	v_exp_f32_e32 v17, v17
	v_add_f32_e32 v16, 1.0, v16
	v_add_f32_e32 v17, 1.0, v17
	v_rcp_f32_e32 v16, v16
	v_rcp_f32_e32 v17, v17
	s_nop 0
	v_pk_mul_f32 v[12:13], v[12:13], v[16:17]
	s_nop 0
	v_pk_mul_f32 v[8:9], v[8:9], v[12:13]
	s_nop 0
	v_cvt_pk_bf16_f32 v8, v8, v9
	v_mul_f32_e32 v9, 0xbfb8aa3b, v14
	v_exp_f32_e32 v9, v9
	s_nop 0
	v_add_f32_e32 v9, 1.0, v9
	v_rcp_f32_e32 v12, v9
	v_mul_f32_e32 v9, 0xbfb8aa3b, v15
	v_exp_f32_e32 v9, v9
	s_nop 0
	v_add_f32_e32 v9, 1.0, v9
	v_rcp_f32_e32 v13, v9
	s_nop 0
	v_pk_mul_f32 v[12:13], v[14:15], v[12:13]
	s_nop 0
	v_pk_mul_f32 v[10:11], v[10:11], v[12:13]
	s_nop 0
	v_cvt_pk_bf16_f32 v9, v10, v11
	v_mul_f32_e32 v10, 0xbfb8aa3b, v4
	v_mul_f32_e32 v11, 0xbfb8aa3b, v5
	v_exp_f32_e32 v10, v10
	v_exp_f32_e32 v11, v11
	v_add_f32_e32 v10, 1.0, v10
	v_add_f32_e32 v11, 1.0, v11
	v_rcp_f32_e32 v10, v10
	v_rcp_f32_e32 v11, v11
	s_nop 0
	v_pk_mul_f32 v[4:5], v[4:5], v[10:11]
	s_nop 0
	v_pk_mul_f32 v[0:1], v[0:1], v[4:5]
	s_nop 0
	v_cvt_pk_bf16_f32 v10, v0, v1
	v_mul_f32_e32 v0, 0xbfb8aa3b, v6
	v_mul_f32_e32 v1, 0xbfb8aa3b, v7
	v_exp_f32_e32 v0, v0
	v_exp_f32_e32 v1, v1
	v_add_f32_e32 v0, 1.0, v0
	v_add_f32_e32 v1, 1.0, v1
	v_rcp_f32_e32 v0, v0
	v_rcp_f32_e32 v1, v1
	s_nop 0
	v_pk_mul_f32 v[0:1], v[6:7], v[0:1]
	s_nop 0
	v_pk_mul_f32 v[0:1], v[2:3], v[0:1]
	s_nop 0
	v_cvt_pk_bf16_f32 v11, v0, v1
	v_mad_i64_i32 v[0:1], s[18:19], v18, s11, v[114:115]
	v_lshl_add_u64 v[0:1], v[0:1], 0, v[116:117]
	s_mov_b64 s[18:19], -1
	global_store_dwordx4 v[0:1], v[8:11], off sc1
	s_cbranch_vccnz .LBB0_1058
	s_andn2_b64 vcc, exec, s[0:1]
	s_cbranch_vccnz .LBB0_1057
	s_barrier
	s_branch .LBB0_1057

; __device__ __forceinline__ unsigned cvt_pk_bf16(float lo, float hi) { const f32x2_t v = {lo, hi}; const bf16x2_t c = __builtin_convertvector(v, bf16x2_t); return __builtin_bit_cast(unsigned, c); }
; #define PG8_BAR __builtin_amdgcn_s_barrier()
;     __device__ __forceinline__ void operator()(const f32x4 (&acc)[2][2][4][2], const Unit& u, int wr, int wc, int fr, int fq) const {
;         const int row0 = u.pm * BM + wr * 64 + fr, col0 = u.pn * BM + wc * 32 + 8 * fq;
; #pragma unroll
;         for (int ai = 0; ai < 2; ++ai)
; #pragma unroll
;             for (int m = 0; m < 4; ++m) { bf16_t* rowp = O + (size_t)(row0 + ai * HALF + m * 16) * ldc + col0;
; #pragma unroll
;                 for (int bj = 0; bj < 2; ++bj) { const f32x4 v0 = acc[ai][bj][m][0], v1 = acc[ai][bj][m][1];
;                     u32x4 w; w.x = cvt_pk_bf16(v0[0], v0[1]); w.y = cvt_pk_bf16(v0[2], v0[3]); w.z = cvt_pk_bf16(v1[0], v1[1]); w.w = cvt_pk_bf16(v1[2], v1[3]);
;                     *(u32x4*)(rowp + bj * HALF) = w; } }
; template <class Epi, class Sched, bool ALIGN_EPI = false, bool SP2 = false, bool KHOOK = false>
; __device__ __forceinline__ void gemm_phase(PG8_LAS unsigned char* lds, const Gemm g, const Sched& S, const Epi& E, const int tid_in) {
;     ...
;         cur = nxt; cA = nA; cB = nB; ++ui; load_rr(cur);
;         if constexpr (ALIGN_EPI) { if (wr == 1) PG8_BAR; }
.LBB0_1089:
	v_lshl_add_u32 v140, s44, 8, v136
	v_lshl_or_b32 v142, s45, 8, v138
	v_ashrrev_i32_e32 v141, 31, v140
	v_ashrrev_i32_e32 v143, 31, v142
	v_lshlrev_b64 v[144:145], 12, v[140:141]
	v_lshl_add_u64 v[144:145], s[4:5], 0, v[144:145]
	v_lshlrev_b64 v[142:143], 1, v[142:143]
	v_lshl_add_u64 v[144:145], v[144:145], 0, v[142:143]
	s_mov_b64 s[12:13], 0x80000
	v_cvt_pk_bf16_f32 v70, v70, v71
	v_cvt_pk_bf16_f32 v71, v72, v73
	v_cvt_pk_bf16_f32 v72, v66, v67
	v_lshl_add_u64 v[66:67], v[144:145], 0, s[12:13]
	s_mov_b32 s12, 0x80000
	v_cvt_pk_bf16_f32 v62, v62, v63
	v_cvt_pk_bf16_f32 v63, v64, v65
	v_cvt_pk_bf16_f32 v64, v58, v59
	v_add_co_u32_e32 v58, vcc, s12, v144
	v_cvt_pk_bf16_f32 v46, v46, v47
	v_cvt_pk_bf16_f32 v47, v48, v49
	v_cvt_pk_bf16_f32 v48, v42, v43
	v_cvt_pk_bf16_f32 v49, v44, v45
	s_mov_b64 s[12:13], 0x90000
	v_addc_co_u32_e32 v59, vcc, 0, v145, vcc
	global_store_dwordx4 v[66:67], v[46:49], off offset:256 sc1
	v_cvt_pk_bf16_f32 v110, v110, v111
	v_cvt_pk_bf16_f32 v111, v112, v113
	v_lshl_add_u64 v[46:47], v[144:145], 0, s[12:13]
	s_mov_b32 s12, 0x90000
	v_cvt_pk_bf16_f32 v112, v106, v107
	v_or_b32_e32 v106, 16, v140
	v_add_co_u32_e32 v48, vcc, s12, v144
	v_cvt_pk_bf16_f32 v28, v28, v29
	v_cvt_pk_bf16_f32 v29, v30, v31
	v_cvt_pk_bf16_f32 v30, v24, v25
	v_cvt_pk_bf16_f32 v31, v26, v27
	s_mov_b64 s[12:13], 0xa0000
	v_ashrrev_i32_e32 v107, 31, v106
	v_cvt_pk_bf16_f32 v94, v94, v95
	v_cvt_pk_bf16_f32 v95, v96, v97
	v_cvt_pk_bf16_f32 v96, v90, v91
	v_or_b32_e32 v90, 32, v140
	v_addc_co_u32_e32 v49, vcc, 0, v145, vcc
	global_store_dwordx4 v[46:47], v[28:31], off offset:256 sc1
	v_lshlrev_b64 v[106:107], 12, v[106:107]
	v_ashrrev_i32_e32 v91, 31, v90
	v_lshl_add_u64 v[28:29], v[144:145], 0, s[12:13]
	s_mov_b32 s12, 0xa0000
	v_cvt_pk_bf16_f32 v78, v78, v79
	v_cvt_pk_bf16_f32 v79, v80, v81
	v_cvt_pk_bf16_f32 v80, v74, v75
	v_or_b32_e32 v74, 48, v140
	v_add_co_u32_e32 v30, vcc, s12, v144
	v_cvt_pk_bf16_f32 v12, v12, v13
	v_cvt_pk_bf16_f32 v13, v14, v15
	v_cvt_pk_bf16_f32 v14, v8, v9
	v_cvt_pk_bf16_f32 v15, v10, v11
	s_mov_b64 s[12:13], 0xb0000
	v_cvt_pk_bf16_f32 v113, v108, v109
	v_lshl_add_u64 v[106:107], s[4:5], 0, v[106:107]
	v_lshlrev_b64 v[90:91], 12, v[90:91]
	v_ashrrev_i32_e32 v75, 31, v74
	v_addc_co_u32_e32 v31, vcc, 0, v145, vcc
	global_store_dwordx4 v[28:29], v[12:15], off offset:256 sc1
	global_store_dwordx4 v[144:145], v[110:113], off offset:256 sc1
	v_cvt_pk_bf16_f32 v97, v92, v93
	v_lshl_add_u64 v[12:13], v[144:145], 0, s[12:13]
	s_mov_b32 s12, 0xb0000
	v_lshl_add_u64 v[110:111], v[106:107], 0, v[142:143]
	v_lshl_add_u64 v[90:91], s[4:5], 0, v[90:91]
	v_lshlrev_b64 v[74:75], 12, v[74:75]
	v_add_co_u32_e32 v14, vcc, s12, v144
	global_store_dwordx4 v[110:111], v[94:97], off offset:256 sc1
	v_cvt_pk_bf16_f32 v81, v76, v77
	v_lshl_add_u64 v[74:75], s[4:5], 0, v[74:75]
	v_lshl_add_u64 v[94:95], v[90:91], 0, v[142:143]
	v_addc_co_u32_e32 v15, vcc, 0, v145, vcc
	v_readlane_b32 s78, v255, 9
	v_cvt_pk_bf16_f32 v126, v126, v127
	v_cvt_pk_bf16_f32 v127, v128, v129
	v_cvt_pk_bf16_f32 v128, v122, v123
	v_cvt_pk_bf16_f32 v129, v124, v125
	v_cvt_pk_bf16_f32 v106, v118, v119
	v_cvt_pk_bf16_f32 v107, v120, v121
	v_cvt_pk_bf16_f32 v108, v114, v115
	v_cvt_pk_bf16_f32 v109, v116, v117
	v_cvt_pk_bf16_f32 v90, v102, v103
	v_cvt_pk_bf16_f32 v91, v104, v105
	v_cvt_pk_bf16_f32 v92, v98, v99
	v_cvt_pk_bf16_f32 v93, v100, v101
	global_store_dwordx4 v[94:95], v[78:81], off offset:256 sc1
	v_cvt_pk_bf16_f32 v76, v82, v83
	v_cvt_pk_bf16_f32 v77, v84, v85
	v_lshl_add_u64 v[78:79], v[74:75], 0, v[142:143]
	v_cvt_pk_bf16_f32 v74, v86, v87
	v_cvt_pk_bf16_f32 v75, v88, v89
	v_cvt_pk_bf16_f32 v73, v68, v69
	v_cvt_pk_bf16_f32 v65, v60, v61
	v_cvt_pk_bf16_f32 v42, v54, v55
	v_cvt_pk_bf16_f32 v43, v56, v57
	v_cvt_pk_bf16_f32 v44, v50, v51
	v_cvt_pk_bf16_f32 v45, v52, v53
	v_cvt_pk_bf16_f32 v24, v38, v39
	v_cvt_pk_bf16_f32 v25, v40, v41
	v_cvt_pk_bf16_f32 v26, v34, v35
	v_cvt_pk_bf16_f32 v27, v36, v37
	v_cvt_pk_bf16_f32 v8, v20, v21
	v_cvt_pk_bf16_f32 v9, v22, v23
	v_cvt_pk_bf16_f32 v10, v16, v17
	v_cvt_pk_bf16_f32 v11, v18, v19
	v_cvt_pk_bf16_f32 v4, v4, v5
	v_cvt_pk_bf16_f32 v5, v6, v7
	v_cvt_pk_bf16_f32 v6, v0, v1
	v_cvt_pk_bf16_f32 v7, v2, v3
	s_andn2_b64 vcc, exec, s[26:27]
	s_mov_b64 s[12:13], -1
	v_readlane_b32 s79, v255, 10
	v_readlane_b32 s61, v255, 11
	v_readlane_b32 s66, v255, 12
	global_store_dwordx4 v[144:145], v[126:129], off sc1
	global_store_dwordx4 v[110:111], v[106:109], off sc1
	global_store_dwordx4 v[94:95], v[90:93], off sc1
	global_store_dwordx4 v[78:79], v[74:77], off sc1
	global_store_dwordx4 v[78:79], v[70:73], off offset:256 sc1
	global_store_dwordx4 v[58:59], v[62:65], off sc1
	global_store_dwordx4 v[48:49], v[42:45], off sc1
	global_store_dwordx4 v[30:31], v[24:27], off sc1
	global_store_dwordx4 v[14:15], v[8:11], off sc1
	global_store_dwordx4 v[12:13], v[4:7], off offset:256 sc1
	s_cbranch_vccnz .LBB0_1076
	s_andn2_b64 vcc, exec, s[0:1]
	s_cbranch_vccnz .LBB0_1075
	s_barrier
	s_branch .LBB0_1075

; __device__ __forceinline__ float bf_lo(unsigned w) { return __uint_as_float(w << 16); }
; __device__ __forceinline__ float bf_hi(unsigned w) { return __uint_as_float(w & 0xffff0000u); }
; __device__ __forceinline__ float sigmoidf_fast(float x) { return __builtin_amdgcn_rcpf(1.0f + __expf(-x)); }
;     __device__ __forceinline__ void fused(f32x4 (&acc)[2][2][4][2], const Unit& u, int wr, int wc, int fr, int fq, PG8_LAS unsigned char* lds, int wid, int lane) const {
;     ...
;         for (int ai = 0; ai < 2; ++ai) {
;             h16x8 hraw[4][2]; u32x4 eraw[4][2];
; #pragma unroll
;             for (int m = 0; m < 4; ++m) { const size_t off = (size_t)(u.pm * BM + ai * HALF + wr * 64 + m * 16 + fr) * ld + col0;
; #pragma unroll
;                 for (int bj = 0; bj < 2; ++bj) { hraw[m][bj] = *(const h16x8*)(H + off + bj * HALF); if (MODE != 0) eraw[m][bj] = *(const u32x4*)(E + off + bj * HALF); } }
; #pragma unroll
;             for (int m = 0; m < 4; ++m) { const size_t off = (size_t)(u.pm * BM + ai * HALF + wr * 64 + m * 16 + fr) * ld + col0;
; #pragma unroll
;                 for (int bj = 0; bj < 2; ++bj) { const f32x8 hv = __builtin_convertvector(hraw[m][bj], f32x8); f32x8 r8;
; #pragma unroll
;                     for (int n = 0; n < 2; ++n) { f32x4 r; const f32x4 a = acc[ai][bj][m][n];
;                         if (MODE == 0) { r[0] = hv[4 * n] + a[0]; r[1] = hv[4 * n + 1] + a[1]; r[2] = hv[4 * n + 2] + a[2]; r[3] = hv[4 * n + 3] + a[3]; }
;                         else { const unsigned e0 = n ? eraw[m][bj].z : eraw[m][bj].x, e1 = n ? eraw[m][bj].w : eraw[m][bj].y;
;                             r[0] = hv[4 * n] + sigmoidf_fast(a[0]) * bf_lo(e0); r[1] = hv[4 * n + 1] + sigmoidf_fast(a[1]) * bf_hi(e0); r[2] = hv[4 * n + 2] + sigmoidf_fast(a[2]) * bf_lo(e1); r[3] = hv[4 * n + 3] + sigmoidf_fast(a[3]) * bf_hi(e1); }
;                         acc[ai][bj][m][n] = r; r8[4 * n] = r[0]; r8[4 * n + 1] = r[1]; r8[4 * n + 2] = r[2]; r8[4 * n + 3] = r[3]; }
;                     *(h16x8*)(H + off + bj * HALF) = __builtin_convertvector(r8, h16x8); }
.LBB0_1177:
	s_lshl_b32 s4, s36, 5
	s_lshl_b32 s5, s0, 8
	v_lshrrev_b32_e32 v122, 1, v173
	s_or_b32 s4, s5, s4
	s_lshl_b32 s22, s33, 8
	v_and_or_b32 v160, v122, 24, s4
	s_add_i32 s4, s22, s45
	v_or_b32_e32 v162, s4, v174
	v_ashrrev_i32_e32 v161, 31, v160
	v_readlane_b32 s4, v252, 57
	v_lshlrev_b64 v[158:159], 1, v[160:161]
	v_readlane_b32 s5, v252, 58
	v_ashrrev_i32_e32 v163, 31, v162
	v_lshlrev_b64 v[180:181], 12, v[162:163]
	v_lshl_add_u64 v[164:165], s[4:5], 0, v[158:159]
	v_lshl_add_u64 v[126:127], v[164:165], 0, v[180:181]
	s_barrier
	global_load_dwordx4 v[122:125], v[126:127], off
	s_nop 0
	global_load_dwordx4 v[126:129], v[126:127], off offset:256
	v_or_b32_e32 v138, 16, v162
	v_ashrrev_i32_e32 v139, 31, v138
	v_lshlrev_b64 v[170:171], 12, v[138:139]
	v_lshl_add_u64 v[138:139], v[164:165], 0, v[170:171]
	global_load_dwordx4 v[176:179], v[138:139], off
	global_load_dwordx4 v[154:157], v[138:139], off offset:256
	v_or_b32_e32 v138, 32, v162
	v_ashrrev_i32_e32 v139, 31, v138
	v_lshlrev_b64 v[168:169], 12, v[138:139]
	v_lshl_add_u64 v[138:139], v[164:165], 0, v[168:169]
	global_load_dwordx4 v[150:153], v[138:139], off
	global_load_dwordx4 v[146:149], v[138:139], off offset:256
	v_or_b32_e32 v138, 48, v162
	v_ashrrev_i32_e32 v139, 31, v138
	v_lshlrev_b64 v[166:167], 12, v[138:139]
	v_lshl_add_u64 v[138:139], v[164:165], 0, v[166:167]
	global_load_dwordx4 v[142:145], v[138:139], off
	s_nop 0
	global_load_dwordx4 v[138:141], v[138:139], off offset:256
	v_lshl_add_u64 v[180:181], s[4:5], 0, v[180:181]
	v_lshl_add_u64 v[180:181], v[180:181], 0, v[158:159]
	v_and_b32_e32 v32, 63, v173
	v_add_u32_e32 v188, 0x80, v162
	v_ashrrev_i32_e32 v189, 31, v188
	v_lshlrev_b64 v[190:191], 12, v[188:189]
	v_lshl_add_u64 v[192:193], v[164:165], 0, v[190:191]
	global_load_dwordx4 v[198:201], v[192:193], off
	global_load_dwordx4 v[202:205], v[192:193], off offset:256
	v_add_u32_e32 v188, 0x90, v162
	v_ashrrev_i32_e32 v189, 31, v188
	v_lshlrev_b64 v[190:191], 12, v[188:189]
	v_lshl_add_u64 v[192:193], v[164:165], 0, v[190:191]
	global_load_dwordx4 v[206:209], v[192:193], off
	global_load_dwordx4 v[210:213], v[192:193], off offset:256
	v_add_u32_e32 v188, 0xa0, v162
	v_ashrrev_i32_e32 v189, 31, v188
	v_lshlrev_b64 v[190:191], 12, v[188:189]
	v_lshl_add_u64 v[192:193], v[164:165], 0, v[190:191]
	global_load_dwordx4 v[214:217], v[192:193], off
	global_load_dwordx4 v[218:221], v[192:193], off offset:256
	v_add_u32_e32 v188, 0xb0, v162
	v_ashrrev_i32_e32 v189, 31, v188
	v_lshlrev_b64 v[190:191], 12, v[188:189]
	v_lshl_add_u64 v[192:193], v[164:165], 0, v[190:191]
	global_load_dwordx4 v[222:225], v[192:193], off
	global_load_dwordx4 v[246:249], v[192:193], off offset:256
	s_waitcnt vmcnt(8)
	v_cvt_f32_f16_e32 v182, v125
	v_cvt_f32_f16_sdwa v183, v125 dst_sel:DWORD dst_unused:UNUSED_PAD src0_sel:WORD_1
	v_cvt_f32_f16_e32 v184, v124
	v_cvt_f32_f16_sdwa v185, v124 dst_sel:DWORD dst_unused:UNUSED_PAD src0_sel:WORD_1
	v_cvt_f32_f16_e32 v124, v123
	v_cvt_f32_f16_sdwa v125, v123 dst_sel:DWORD dst_unused:UNUSED_PAD src0_sel:WORD_1
	v_cvt_f32_f16_e32 v186, v122
	v_cvt_f32_f16_sdwa v187, v122 dst_sel:DWORD dst_unused:UNUSED_PAD src0_sel:WORD_1
	v_pk_add_f32 v[114:115], v[114:115], v[184:185]
	v_pk_add_f32 v[120:121], v[120:121], v[124:125]
	v_pk_add_f32 v[116:117], v[116:117], v[182:183]
	v_pk_add_f32 v[118:119], v[118:119], v[186:187]
	v_cvt_pk_f16_f32 v125, v116, v117
	v_cvt_pk_f16_f32 v124, v114, v115
	v_cvt_pk_f16_f32 v123, v120, v121
	v_cvt_pk_f16_f32 v122, v118, v119
	global_store_dwordx4 v[180:181], v[122:125], off sc1
	v_cvt_f32_f16_e32 v182, v126
	v_cvt_f32_f16_sdwa v183, v126 dst_sel:DWORD dst_unused:UNUSED_PAD src0_sel:WORD_1
	v_cvt_f32_f16_e32 v124, v129
	v_cvt_f32_f16_sdwa v125, v129 dst_sel:DWORD dst_unused:UNUSED_PAD src0_sel:WORD_1
	v_cvt_f32_f16_e32 v122, v128
	v_cvt_f32_f16_sdwa v123, v128 dst_sel:DWORD dst_unused:UNUSED_PAD src0_sel:WORD_1
	v_cvt_f32_f16_e32 v128, v127
	v_cvt_f32_f16_sdwa v129, v127 dst_sel:DWORD dst_unused:UNUSED_PAD src0_sel:WORD_1
	v_pk_add_f32 v[126:127], v[102:103], v[182:183]
	v_pk_add_f32 v[122:123], v[98:99], v[122:123]
	v_pk_add_f32 v[124:125], v[100:101], v[124:125]
	v_pk_add_f32 v[128:129], v[104:105], v[128:129]
	v_cvt_pk_f16_f32 v101, v124, v125
	v_cvt_pk_f16_f32 v100, v122, v123
	v_cvt_pk_f16_f32 v99, v128, v129
	v_cvt_pk_f16_f32 v98, v126, v127
	global_store_dwordx4 v[180:181], v[98:101], off offset:256 sc1
	v_cvt_f32_f16_e32 v104, v177
	v_cvt_f32_f16_sdwa v105, v177 dst_sel:DWORD dst_unused:UNUSED_PAD src0_sel:WORD_1
	v_cvt_f32_f16_e32 v100, v179
	v_cvt_f32_f16_sdwa v101, v179 dst_sel:DWORD dst_unused:UNUSED_PAD src0_sel:WORD_1
	v_cvt_f32_f16_e32 v98, v178
	v_cvt_f32_f16_sdwa v99, v178 dst_sel:DWORD dst_unused:UNUSED_PAD src0_sel:WORD_1
	v_cvt_f32_f16_e32 v102, v176
	v_cvt_f32_f16_sdwa v103, v176 dst_sel:DWORD dst_unused:UNUSED_PAD src0_sel:WORD_1
	v_pk_add_f32 v[104:105], v[136:137], v[104:105]
	v_pk_add_f32 v[98:99], v[130:131], v[98:99]
	v_pk_add_f32 v[100:101], v[132:133], v[100:101]
	v_pk_add_f32 v[102:103], v[134:135], v[102:103]
	v_lshl_add_u64 v[130:131], s[4:5], 0, v[170:171]
	v_cvt_pk_f16_f32 v135, v100, v101
	v_cvt_pk_f16_f32 v134, v98, v99
	v_cvt_pk_f16_f32 v133, v104, v105
	v_cvt_pk_f16_f32 v132, v102, v103
	v_lshl_add_u64 v[130:131], v[130:131], 0, v[158:159]
	global_store_dwordx4 v[130:131], v[132:135], off sc1
	v_cvt_f32_f16_e32 v136, v155
	v_cvt_f32_f16_sdwa v137, v155 dst_sel:DWORD dst_unused:UNUSED_PAD src0_sel:WORD_1
	v_cvt_f32_f16_e32 v132, v157
	v_cvt_f32_f16_sdwa v133, v157 dst_sel:DWORD dst_unused:UNUSED_PAD src0_sel:WORD_1
	v_cvt_f32_f16_e32 v134, v156
	v_cvt_f32_f16_sdwa v135, v156 dst_sel:DWORD dst_unused:UNUSED_PAD src0_sel:WORD_1
; __device__ __forceinline__ float bf_lo(unsigned w) { return __uint_as_float(w << 16); }
; __device__ __forceinline__ float bf_hi(unsigned w) { return __uint_as_float(w & 0xffff0000u); }
; __device__ __forceinline__ float sigmoidf_fast(float x) { return __builtin_amdgcn_rcpf(1.0f + __expf(-x)); }
;     __device__ __forceinline__ void fused(f32x4 (&acc)[2][2][4][2], const Unit& u, int wr, int wc, int fr, int fq, PG8_LAS unsigned char* lds, int wid, int lane) const {
;     ...
;             for (int m = 0; m < 4; ++m) { const size_t off = (size_t)(u.pm * BM + ai * HALF + wr * 64 + m * 16 + fr) * ld + col0;
; #pragma unroll
;                 for (int bj = 0; bj < 2; ++bj) { const f32x8 hv = __builtin_convertvector(hraw[m][bj], f32x8); f32x8 r8;
; #pragma unroll
;                     for (int n = 0; n < 2; ++n) { f32x4 r; const f32x4 a = acc[ai][bj][m][n];
;                         if (MODE == 0) { r[0] = hv[4 * n] + a[0]; r[1] = hv[4 * n + 1] + a[1]; r[2] = hv[4 * n + 2] + a[2]; r[3] = hv[4 * n + 3] + a[3]; }
;                         else { const unsigned e0 = n ? eraw[m][bj].z : eraw[m][bj].x, e1 = n ? eraw[m][bj].w : eraw[m][bj].y;
;                             r[0] = hv[4 * n] + sigmoidf_fast(a[0]) * bf_lo(e0); r[1] = hv[4 * n + 1] + sigmoidf_fast(a[1]) * bf_hi(e0); r[2] = hv[4 * n + 2] + sigmoidf_fast(a[2]) * bf_lo(e1); r[3] = hv[4 * n + 3] + sigmoidf_fast(a[3]) * bf_hi(e1); }
;                         acc[ai][bj][m][n] = r; r8[4 * n] = r[0]; r8[4 * n + 1] = r[1]; r8[4 * n + 2] = r[2]; r8[4 * n + 3] = r[3]; }
;                     *(h16x8*)(H + off + bj * HALF) = __builtin_convertvector(r8, h16x8); }
	v_cvt_f32_f16_e32 v156, v154
	v_cvt_f32_f16_sdwa v157, v154 dst_sel:DWORD dst_unused:UNUSED_PAD src0_sel:WORD_1
	v_pk_add_f32 v[112:113], v[112:113], v[136:137]
	v_pk_add_f32 v[106:107], v[106:107], v[134:135]
	v_pk_add_f32 v[108:109], v[108:109], v[132:133]
	v_pk_add_f32 v[110:111], v[110:111], v[156:157]
	v_cvt_pk_f16_f32 v135, v108, v109
	v_cvt_pk_f16_f32 v134, v106, v107
	v_cvt_pk_f16_f32 v133, v112, v113
	v_cvt_pk_f16_f32 v132, v110, v111
	global_store_dwordx4 v[130:131], v[132:135], off offset:256 sc1
	v_cvt_f32_f16_e32 v130, v153
	v_cvt_f32_f16_sdwa v131, v153 dst_sel:DWORD dst_unused:UNUSED_PAD src0_sel:WORD_1
	v_cvt_f32_f16_e32 v132, v152
	v_cvt_f32_f16_sdwa v133, v152 dst_sel:DWORD dst_unused:UNUSED_PAD src0_sel:WORD_1
	v_cvt_f32_f16_e32 v134, v151
	v_cvt_f32_f16_sdwa v135, v151 dst_sel:DWORD dst_unused:UNUSED_PAD src0_sel:WORD_1
	v_cvt_f32_f16_e32 v136, v150
	v_cvt_f32_f16_sdwa v137, v150 dst_sel:DWORD dst_unused:UNUSED_PAD src0_sel:WORD_1
	v_pk_add_f32 v[90:91], v[90:91], v[132:133]
	v_pk_add_f32 v[96:97], v[96:97], v[134:135]
	v_pk_add_f32 v[92:93], v[92:93], v[130:131]
	v_pk_add_f32 v[94:95], v[94:95], v[136:137]
	v_lshl_add_u64 v[134:135], s[4:5], 0, v[168:169]
	v_cvt_pk_f16_f32 v133, v92, v93
	v_cvt_pk_f16_f32 v132, v90, v91
	v_cvt_pk_f16_f32 v131, v96, v97
	v_cvt_pk_f16_f32 v130, v94, v95
	v_lshl_add_u64 v[134:135], v[134:135], 0, v[158:159]
	global_store_dwordx4 v[134:135], v[130:133], off sc1
	v_cvt_f32_f16_e32 v136, v147
	v_cvt_f32_f16_sdwa v137, v147 dst_sel:DWORD dst_unused:UNUSED_PAD src0_sel:WORD_1
	v_cvt_f32_f16_e32 v130, v149
	v_cvt_f32_f16_sdwa v131, v149 dst_sel:DWORD dst_unused:UNUSED_PAD src0_sel:WORD_1
	v_cvt_f32_f16_e32 v132, v148
	v_cvt_f32_f16_sdwa v133, v148 dst_sel:DWORD dst_unused:UNUSED_PAD src0_sel:WORD_1
	v_cvt_f32_f16_e32 v148, v146
	v_cvt_f32_f16_sdwa v149, v146 dst_sel:DWORD dst_unused:UNUSED_PAD src0_sel:WORD_1
	v_pk_add_f32 v[88:89], v[88:89], v[136:137]
	v_pk_add_f32 v[82:83], v[82:83], v[132:133]
	v_pk_add_f32 v[84:85], v[84:85], v[130:131]
	v_pk_add_f32 v[86:87], v[86:87], v[148:149]
	v_cvt_pk_f16_f32 v133, v84, v85
	v_cvt_pk_f16_f32 v132, v82, v83
	v_cvt_pk_f16_f32 v131, v88, v89
	v_cvt_pk_f16_f32 v130, v86, v87
	global_store_dwordx4 v[134:135], v[130:133], off offset:256 sc1
	v_cvt_f32_f16_e32 v134, v143
	v_cvt_f32_f16_sdwa v135, v143 dst_sel:DWORD dst_unused:UNUSED_PAD src0_sel:WORD_1
	v_cvt_f32_f16_e32 v130, v145
	v_cvt_f32_f16_sdwa v131, v145 dst_sel:DWORD dst_unused:UNUSED_PAD src0_sel:WORD_1
	v_cvt_f32_f16_e32 v132, v144
	v_cvt_f32_f16_sdwa v133, v144 dst_sel:DWORD dst_unused:UNUSED_PAD src0_sel:WORD_1
	v_cvt_f32_f16_e32 v136, v142
	v_cvt_f32_f16_sdwa v137, v142 dst_sel:DWORD dst_unused:UNUSED_PAD src0_sel:WORD_1
	v_pk_add_f32 v[80:81], v[80:81], v[134:135]
	v_pk_add_f32 v[74:75], v[74:75], v[132:133]
	v_pk_add_f32 v[76:77], v[76:77], v[130:131]
	v_pk_add_f32 v[78:79], v[78:79], v[136:137]
	v_lshl_add_u64 v[134:135], s[4:5], 0, v[166:167]
	v_cvt_pk_f16_f32 v133, v76, v77
	v_cvt_pk_f16_f32 v132, v74, v75
	v_cvt_pk_f16_f32 v131, v80, v81
	v_cvt_pk_f16_f32 v130, v78, v79
	v_lshl_add_u64 v[134:135], v[134:135], 0, v[158:159]
	global_store_dwordx4 v[134:135], v[130:133], off sc1
	v_cvt_f32_f16_e32 v136, v139
	v_cvt_f32_f16_sdwa v137, v139 dst_sel:DWORD dst_unused:UNUSED_PAD src0_sel:WORD_1
	v_cvt_f32_f16_e32 v130, v141
	v_cvt_f32_f16_sdwa v131, v141 dst_sel:DWORD dst_unused:UNUSED_PAD src0_sel:WORD_1
	v_cvt_f32_f16_e32 v132, v140
	v_cvt_f32_f16_sdwa v133, v140 dst_sel:DWORD dst_unused:UNUSED_PAD src0_sel:WORD_1
	v_cvt_f32_f16_e32 v140, v138
	v_cvt_f32_f16_sdwa v141, v138 dst_sel:DWORD dst_unused:UNUSED_PAD src0_sel:WORD_1
	v_pk_add_f32 v[72:73], v[72:73], v[136:137]
	v_pk_add_f32 v[66:67], v[66:67], v[132:133]
	v_pk_add_f32 v[68:69], v[68:69], v[130:131]
	v_pk_add_f32 v[70:71], v[70:71], v[140:141]
	v_cvt_pk_f16_f32 v133, v68, v69
	v_cvt_pk_f16_f32 v132, v66, v67
	v_cvt_pk_f16_f32 v131, v72, v73
	v_cvt_pk_f16_f32 v130, v70, v71
	global_store_dwordx4 v[134:135], v[130:133], off offset:256 sc1
	s_nop 1
	v_add_u32_e32 v130, 0x80, v162
	v_ashrrev_i32_e32 v131, 31, v130
	v_lshlrev_b64 v[170:171], 12, v[130:131]
	v_lshl_add_u64 v[130:131], v[164:165], 0, v[170:171]
	v_add_u32_e32 v130, 0x90, v162
	v_ashrrev_i32_e32 v131, 31, v130
	v_lshlrev_b64 v[180:181], 12, v[130:131]
	v_lshl_add_u64 v[130:131], v[164:165], 0, v[180:181]
	v_add_u32_e32 v130, 0xa0, v162
	v_ashrrev_i32_e32 v131, 31, v130
	v_lshlrev_b64 v[148:149], 12, v[130:131]
	v_lshl_add_u64 v[130:131], v[164:165], 0, v[148:149]
	v_add_u32_e32 v130, 0xb0, v162
	v_ashrrev_i32_e32 v131, 31, v130
	v_lshlrev_b64 v[146:147], 12, v[130:131]
	v_lshl_add_u64 v[130:131], v[164:165], 0, v[146:147]
	s_nop 0
	v_lshl_add_u64 v[148:149], s[4:5], 0, v[148:149]
	v_lshl_add_u64 v[148:149], v[148:149], 0, v[158:159]
	s_waitcnt vmcnt(15)
	v_cvt_f32_f16_e32 v162, v201
	v_cvt_f32_f16_sdwa v163, v201 dst_sel:DWORD dst_unused:UNUSED_PAD src0_sel:WORD_1
	v_cvt_f32_f16_e32 v164, v200
	v_cvt_f32_f16_sdwa v165, v200 dst_sel:DWORD dst_unused:UNUSED_PAD src0_sel:WORD_1
	v_cvt_f32_f16_e32 v152, v199
	v_cvt_f32_f16_sdwa v153, v199 dst_sel:DWORD dst_unused:UNUSED_PAD src0_sel:WORD_1
	v_cvt_f32_f16_e32 v182, v198
	v_cvt_f32_f16_sdwa v183, v198 dst_sel:DWORD dst_unused:UNUSED_PAD src0_sel:WORD_1
	v_pk_add_f32 v[58:59], v[58:59], v[164:165]
	v_pk_add_f32 v[64:65], v[64:65], v[152:153]
	v_pk_add_f32 v[60:61], v[60:61], v[162:163]
	v_pk_add_f32 v[62:63], v[62:63], v[182:183]
	v_lshl_add_u64 v[162:163], s[4:5], 0, v[170:171]
	v_cvt_pk_f16_f32 v153, v60, v61
	v_cvt_pk_f16_f32 v152, v58, v59
	v_cvt_pk_f16_f32 v151, v64, v65
	v_cvt_pk_f16_f32 v150, v62, v63
	v_lshl_add_u64 v[162:163], v[162:163], 0, v[158:159]
	global_store_dwordx4 v[162:163], v[150:153], off sc1
	s_waitcnt vmcnt(15)
; __device__ __forceinline__ float bf_lo(unsigned w) { return __uint_as_float(w << 16); }
; __device__ __forceinline__ float bf_hi(unsigned w) { return __uint_as_float(w & 0xffff0000u); }
; __device__ __forceinline__ float sigmoidf_fast(float x) { return __builtin_amdgcn_rcpf(1.0f + __expf(-x)); }
;     __device__ __forceinline__ void fused(f32x4 (&acc)[2][2][4][2], const Unit& u, int wr, int wc, int fr, int fq, PG8_LAS unsigned char* lds, int wid, int lane) const {
;     ...
;             for (int m = 0; m < 4; ++m) { const size_t off = (size_t)(u.pm * BM + ai * HALF + wr * 64 + m * 16 + fr) * ld + col0;
; #pragma unroll
;                 for (int bj = 0; bj < 2; ++bj) { const f32x8 hv = __builtin_convertvector(hraw[m][bj], f32x8); f32x8 r8;
; #pragma unroll
;                     for (int n = 0; n < 2; ++n) { f32x4 r; const f32x4 a = acc[ai][bj][m][n];
;                         if (MODE == 0) { r[0] = hv[4 * n] + a[0]; r[1] = hv[4 * n + 1] + a[1]; r[2] = hv[4 * n + 2] + a[2]; r[3] = hv[4 * n + 3] + a[3]; }
;                         else { const unsigned e0 = n ? eraw[m][bj].z : eraw[m][bj].x, e1 = n ? eraw[m][bj].w : eraw[m][bj].y;
;                             r[0] = hv[4 * n] + sigmoidf_fast(a[0]) * bf_lo(e0); r[1] = hv[4 * n + 1] + sigmoidf_fast(a[1]) * bf_hi(e0); r[2] = hv[4 * n + 2] + sigmoidf_fast(a[2]) * bf_lo(e1); r[3] = hv[4 * n + 3] + sigmoidf_fast(a[3]) * bf_hi(e1); }
;                         acc[ai][bj][m][n] = r; r8[4 * n] = r[0]; r8[4 * n + 1] = r[1]; r8[4 * n + 2] = r[2]; r8[4 * n + 3] = r[3]; }
;                     *(h16x8*)(H + off + bj * HALF) = __builtin_convertvector(r8, h16x8); }
	v_cvt_f32_f16_e32 v164, v202
	v_cvt_f32_f16_sdwa v165, v202 dst_sel:DWORD dst_unused:UNUSED_PAD src0_sel:WORD_1
	v_cvt_f32_f16_e32 v150, v205
	v_cvt_f32_f16_sdwa v151, v205 dst_sel:DWORD dst_unused:UNUSED_PAD src0_sel:WORD_1
	v_cvt_f32_f16_e32 v152, v204
	v_cvt_f32_f16_sdwa v153, v204 dst_sel:DWORD dst_unused:UNUSED_PAD src0_sel:WORD_1
	v_cvt_f32_f16_e32 v156, v203
	v_cvt_f32_f16_sdwa v157, v203 dst_sel:DWORD dst_unused:UNUSED_PAD src0_sel:WORD_1
	v_pk_add_f32 v[54:55], v[54:55], v[164:165]
	v_pk_add_f32 v[50:51], v[50:51], v[152:153]
	v_pk_add_f32 v[52:53], v[52:53], v[150:151]
	v_pk_add_f32 v[56:57], v[56:57], v[156:157]
	v_cvt_pk_f16_f32 v153, v52, v53
	v_cvt_pk_f16_f32 v152, v50, v51
	v_cvt_pk_f16_f32 v151, v56, v57
	v_cvt_pk_f16_f32 v150, v54, v55
	global_store_dwordx4 v[162:163], v[150:153], off offset:256 sc1
	s_waitcnt vmcnt(15)
	v_cvt_f32_f16_e32 v154, v207
	v_cvt_f32_f16_sdwa v155, v207 dst_sel:DWORD dst_unused:UNUSED_PAD src0_sel:WORD_1
	v_cvt_f32_f16_e32 v150, v209
	v_cvt_f32_f16_sdwa v151, v209 dst_sel:DWORD dst_unused:UNUSED_PAD src0_sel:WORD_1
	v_cvt_f32_f16_e32 v152, v208
	v_cvt_f32_f16_sdwa v153, v208 dst_sel:DWORD dst_unused:UNUSED_PAD src0_sel:WORD_1
	v_cvt_f32_f16_e32 v156, v206
	v_cvt_f32_f16_sdwa v157, v206 dst_sel:DWORD dst_unused:UNUSED_PAD src0_sel:WORD_1
	v_pk_add_f32 v[48:49], v[48:49], v[154:155]
	v_pk_add_f32 v[42:43], v[42:43], v[152:153]
	v_pk_add_f32 v[44:45], v[44:45], v[150:151]
	v_pk_add_f32 v[46:47], v[46:47], v[156:157]
	v_lshl_add_u64 v[154:155], s[4:5], 0, v[180:181]
	v_cvt_pk_f16_f32 v153, v44, v45
	v_cvt_pk_f16_f32 v152, v42, v43
	v_cvt_pk_f16_f32 v151, v48, v49
	v_cvt_pk_f16_f32 v150, v46, v47
	v_lshl_add_u64 v[154:155], v[154:155], 0, v[158:159]
	global_store_dwordx4 v[154:155], v[150:153], off sc1
	s_waitcnt vmcnt(15)
	v_cvt_f32_f16_e32 v156, v211
	v_cvt_f32_f16_sdwa v157, v211 dst_sel:DWORD dst_unused:UNUSED_PAD src0_sel:WORD_1
	v_cvt_f32_f16_e32 v150, v213
	v_cvt_f32_f16_sdwa v151, v213 dst_sel:DWORD dst_unused:UNUSED_PAD src0_sel:WORD_1
	v_cvt_f32_f16_e32 v152, v212
	v_cvt_f32_f16_sdwa v153, v212 dst_sel:DWORD dst_unused:UNUSED_PAD src0_sel:WORD_1
	v_cvt_f32_f16_e32 v162, v210
	v_cvt_f32_f16_sdwa v163, v210 dst_sel:DWORD dst_unused:UNUSED_PAD src0_sel:WORD_1
	v_pk_add_f32 v[40:41], v[40:41], v[156:157]
	v_pk_add_f32 v[34:35], v[34:35], v[152:153]
	v_pk_add_f32 v[36:37], v[36:37], v[150:151]
	v_pk_add_f32 v[38:39], v[38:39], v[162:163]
	v_cvt_pk_f16_f32 v153, v36, v37
	v_cvt_pk_f16_f32 v152, v34, v35
	v_cvt_pk_f16_f32 v151, v40, v41
	v_cvt_pk_f16_f32 v150, v38, v39
	global_store_dwordx4 v[154:155], v[150:153], off offset:256 sc1
	s_waitcnt vmcnt(15)
	v_cvt_f32_f16_e32 v154, v214
	v_cvt_f32_f16_sdwa v155, v214 dst_sel:DWORD dst_unused:UNUSED_PAD src0_sel:WORD_1
	v_cvt_f32_f16_e32 v150, v217
	v_cvt_f32_f16_sdwa v151, v217 dst_sel:DWORD dst_unused:UNUSED_PAD src0_sel:WORD_1
	v_cvt_f32_f16_e32 v152, v216
	v_cvt_f32_f16_sdwa v153, v216 dst_sel:DWORD dst_unused:UNUSED_PAD src0_sel:WORD_1
	v_cvt_f32_f16_e32 v144, v215
	v_cvt_f32_f16_sdwa v145, v215 dst_sel:DWORD dst_unused:UNUSED_PAD src0_sel:WORD_1
	v_pk_add_f32 v[28:29], v[28:29], v[154:155]
	v_pk_add_f32 v[24:25], v[24:25], v[152:153]
	v_pk_add_f32 v[26:27], v[26:27], v[150:151]
	v_pk_add_f32 v[30:31], v[30:31], v[144:145]
	v_cvt_pk_f16_f32 v145, v26, v27
	v_cvt_pk_f16_f32 v144, v24, v25
	v_cvt_pk_f16_f32 v143, v30, v31
	v_cvt_pk_f16_f32 v142, v28, v29
	global_store_dwordx4 v[148:149], v[142:145], off sc1
	s_waitcnt vmcnt(15)
; __device__ __forceinline__ float bf_lo(unsigned w) { return __uint_as_float(w << 16); }
; __device__ __forceinline__ float bf_hi(unsigned w) { return __uint_as_float(w & 0xffff0000u); }
; __device__ __forceinline__ float sigmoidf_fast(float x) { return __builtin_amdgcn_rcpf(1.0f + __expf(-x)); }
;     __device__ __forceinline__ void run(const f32x4 (&v)[2][2][4][2], const Unit& u, int wr, int wc, int fr, int fq, PG8_LAS unsigned char* lds, int wid, int lane, float inv_n, float eps) const {
;     ...
;                 float s = 0.f;
; #pragma unroll
;                 for (int bj = 0; bj < 2; ++bj)
; #pragma unroll
;                     for (int n = 0; n < 2; ++n) { const f32x4 x = v[ai][bj][m][n]; s += (x[0] * x[0] + x[1] * x[1]) + (x[2] * x[2] + x[3] * x[3]); }
;                 s += __shfl_xor(s, 16); s += __shfl_xor(s, 32);
;                 if (fq == 0) P[(ai * HALF + wr * 64 + m * 16 + fr) * 4 + wc] = s;
;     __device__ __forceinline__ void fused(f32x4 (&acc)[2][2][4][2], const Unit& u, int wr, int wc, int fr, int fq, PG8_LAS unsigned char* lds, int wid, int lane) const {
;     ...
;             for (int m = 0; m < 4; ++m) { const size_t off = (size_t)(u.pm * BM + ai * HALF + wr * 64 + m * 16 + fr) * ld + col0;
; #pragma unroll
;                 for (int bj = 0; bj < 2; ++bj) { const f32x8 hv = __builtin_convertvector(hraw[m][bj], f32x8); f32x8 r8;
; #pragma unroll
;                     for (int n = 0; n < 2; ++n) { f32x4 r; const f32x4 a = acc[ai][bj][m][n];
;                         if (MODE == 0) { r[0] = hv[4 * n] + a[0]; r[1] = hv[4 * n + 1] + a[1]; r[2] = hv[4 * n + 2] + a[2]; r[3] = hv[4 * n + 3] + a[3]; }
;                         else { const unsigned e0 = n ? eraw[m][bj].z : eraw[m][bj].x, e1 = n ? eraw[m][bj].w : eraw[m][bj].y;
;                             r[0] = hv[4 * n] + sigmoidf_fast(a[0]) * bf_lo(e0); r[1] = hv[4 * n + 1] + sigmoidf_fast(a[1]) * bf_hi(e0); r[2] = hv[4 * n + 2] + sigmoidf_fast(a[2]) * bf_lo(e1); r[3] = hv[4 * n + 3] + sigmoidf_fast(a[3]) * bf_hi(e1); }
;                         acc[ai][bj][m][n] = r; r8[4 * n] = r[0]; r8[4 * n + 1] = r[1]; r8[4 * n + 2] = r[2]; r8[4 * n + 3] = r[3]; }
;                     *(h16x8*)(H + off + bj * HALF) = __builtin_convertvector(r8, h16x8); }
	v_cvt_f32_f16_e32 v150, v218
	v_cvt_f32_f16_sdwa v151, v218 dst_sel:DWORD dst_unused:UNUSED_PAD src0_sel:WORD_1
	v_cvt_f32_f16_e32 v142, v221
	v_cvt_f32_f16_sdwa v143, v221 dst_sel:DWORD dst_unused:UNUSED_PAD src0_sel:WORD_1
	v_cvt_f32_f16_e32 v144, v220
	v_cvt_f32_f16_sdwa v145, v220 dst_sel:DWORD dst_unused:UNUSED_PAD src0_sel:WORD_1
	v_cvt_f32_f16_e32 v140, v219
	v_cvt_f32_f16_sdwa v141, v219 dst_sel:DWORD dst_unused:UNUSED_PAD src0_sel:WORD_1
	v_pk_add_f32 v[20:21], v[20:21], v[150:151]
	v_pk_add_f32 v[16:17], v[16:17], v[144:145]
	v_pk_add_f32 v[18:19], v[18:19], v[142:143]
	v_pk_add_f32 v[22:23], v[22:23], v[140:141]
	v_cvt_pk_f16_f32 v141, v18, v19
	v_cvt_pk_f16_f32 v140, v16, v17
	v_cvt_pk_f16_f32 v139, v22, v23
	v_cvt_pk_f16_f32 v138, v20, v21
	global_store_dwordx4 v[148:149], v[138:141], off offset:256 sc1
	s_waitcnt vmcnt(15)
	v_cvt_f32_f16_e32 v142, v222
	v_cvt_f32_f16_sdwa v143, v222 dst_sel:DWORD dst_unused:UNUSED_PAD src0_sel:WORD_1
	v_cvt_f32_f16_e32 v138, v225
	v_cvt_f32_f16_sdwa v139, v225 dst_sel:DWORD dst_unused:UNUSED_PAD src0_sel:WORD_1
	v_cvt_f32_f16_e32 v140, v224
	v_cvt_f32_f16_sdwa v141, v224 dst_sel:DWORD dst_unused:UNUSED_PAD src0_sel:WORD_1
	v_cvt_f32_f16_e32 v136, v223
	v_cvt_f32_f16_sdwa v137, v223 dst_sel:DWORD dst_unused:UNUSED_PAD src0_sel:WORD_1
	v_pk_add_f32 v[12:13], v[12:13], v[142:143]
	v_pk_add_f32 v[8:9], v[8:9], v[140:141]
	v_pk_add_f32 v[10:11], v[10:11], v[138:139]
	v_pk_add_f32 v[14:15], v[14:15], v[136:137]
	v_lshl_add_u64 v[138:139], s[4:5], 0, v[146:147]
	v_cvt_pk_f16_f32 v137, v10, v11
	v_cvt_pk_f16_f32 v136, v8, v9
	v_cvt_pk_f16_f32 v135, v14, v15
	v_cvt_pk_f16_f32 v134, v12, v13
	v_lshl_add_u64 v[138:139], v[138:139], 0, v[158:159]
	global_store_dwordx4 v[138:139], v[134:137], off sc1
	s_waitcnt vmcnt(15)
	v_cvt_f32_f16_e32 v140, v246
	v_cvt_f32_f16_sdwa v141, v246 dst_sel:DWORD dst_unused:UNUSED_PAD src0_sel:WORD_1
	v_cvt_f32_f16_e32 v134, v249
	v_cvt_f32_f16_sdwa v135, v249 dst_sel:DWORD dst_unused:UNUSED_PAD src0_sel:WORD_1
	v_cvt_f32_f16_e32 v136, v248
	v_cvt_f32_f16_sdwa v137, v248 dst_sel:DWORD dst_unused:UNUSED_PAD src0_sel:WORD_1
	v_cvt_f32_f16_e32 v132, v247
	v_cvt_f32_f16_sdwa v133, v247 dst_sel:DWORD dst_unused:UNUSED_PAD src0_sel:WORD_1
	v_pk_add_f32 v[4:5], v[4:5], v[140:141]
	v_pk_add_f32 v[0:1], v[0:1], v[136:137]
	v_pk_add_f32 v[2:3], v[2:3], v[134:135]
	v_pk_add_f32 v[6:7], v[6:7], v[132:133]
	v_cvt_pk_f16_f32 v133, v2, v3
	v_cvt_pk_f16_f32 v132, v0, v1
	v_cvt_pk_f16_f32 v131, v6, v7
	v_cvt_pk_f16_f32 v130, v4, v5
	global_store_dwordx4 v[138:139], v[130:133], off offset:256 sc1
	v_mul_f32_e32 v134, v117, v117
	v_fmac_f32_e32 v134, v116, v116
	v_and_b32_e32 v131, 64, v236
	v_xor_b32_e32 v130, 16, v236
	v_add_u32_e32 v131, 64, v131
	v_cmp_lt_i32_e32 vcc, v130, v131
	v_xor_b32_e32 v132, 32, v236
	v_mul_f32_e32 v133, v121, v121
	v_cndmask_b32_e32 v130, v236, v130, vcc
	v_cmp_lt_i32_e32 vcc, v132, v131
	v_fmac_f32_e32 v133, v120, v120
	v_lshlrev_b32_e32 v130, 2, v130
	v_cndmask_b32_e32 v131, v236, v132, vcc
	v_mul_f32_e32 v132, v119, v119
	v_fmac_f32_e32 v132, v118, v118
	v_add_f32_e32 v132, v132, v133
	v_mul_f32_e32 v133, v115, v115
	v_fmac_f32_e32 v133, v114, v114
	v_add_f32_e32 v133, v133, v134
	v_add_f32_e32 v132, v132, v133
	v_mul_f32_e32 v133, v127, v127
	v_mul_f32_e32 v134, v129, v129
	v_fmac_f32_e32 v133, v126, v126
	v_fmac_f32_e32 v134, v128, v128
	v_add_f32_e32 v133, v133, v134
	v_add_f32_e32 v132, v133, v132
	v_mul_f32_e32 v133, v123, v123
	v_mul_f32_e32 v134, v125, v125
	v_fmac_f32_e32 v133, v122, v122
	v_fmac_f32_e32 v134, v124, v124
	v_add_f32_e32 v133, v133, v134
	v_add_f32_e32 v132, v133, v132
	ds_bpermute_b32 v133, v130, v132
	v_lshlrev_b32_e32 v131, 2, v131
	s_lshl_b32 s4, s36, 2
	s_waitcnt lgkmcnt(0)
	v_add_f32_e32 v132, v132, v133
	ds_bpermute_b32 v133, v131, v132
	v_cmp_gt_u32_e32 vcc, 16, v32
	s_add_i32 s10, s4, 0
	s_and_saveexec_b64 s[4:5], vcc
	s_cbranch_execz .LBB0_1179
	s_lshl_b32 s11, s20, 10
	s_add_i32 s11, s10, s11
	v_lshl_add_u32 v134, v174, 4, s11
	s_waitcnt lgkmcnt(0)
	v_add_f32_e32 v132, v132, v133
	ds_write_b32 v134, v132

; __device__ __forceinline__ unsigned cvt_pk_bf16(float lo, float hi) { const f32x2_t v = {lo, hi}; const bf16x2_t c = __builtin_convertvector(v, bf16x2_t); return __builtin_bit_cast(unsigned, c); }
;     __device__ __forceinline__ void fused(f32x4 (&acc)[2][2][4][2], const Unit& u, int wr, int wc, int fr, int fq, PG8_LAS unsigned char* lds, int wid, int lane) const {
;     ...
;         f32x4 gv[2][2];
; #pragma unroll
;         for (int bj = 0; bj < 2; ++bj)
; #pragma unroll
;             for (int n = 0; n < 2; ++n) gv[bj][n] = *(const f32x4*)(g + col0 + bj * HALF + n * 4);
; #pragma unroll
;         for (int ai = 0; ai < 2; ++ai)
; #pragma unroll
;             for (int m = 0; m < 4; ++m) { const int r = ai * HALF + wr * 64 + m * 16 + fr; const float rs = S[r]; const size_t off = (size_t)(u.pm * BM + r) * ld + col0;
; #pragma unroll
;                 for (int bj = 0; bj < 2; ++bj)
; #pragma unroll
;                     for (int n = 0; n < 2; ++n) { const f32x4 o = acc[ai][bj][m][n] * rs * gv[bj][n];
;                         if (final_) *(f32x4*)(OUT + off + bj * HALF + n * 4) = o;
;                         else { u32x2 w; w.x = cvt_pk_bf16(o[0], o[1]); w.y = cvt_pk_bf16(o[2], o[3]); *(u32x2*)(XN + off + bj * HALF + n * 4) = w; } } }
.LBB0_1212:
	s_or_b64 exec, exec, s[12:13]
	s_lshl_b64 s[0:1], s[8:9], 2
	v_readlane_b32 s2, v253, 38
	s_add_u32 s0, s2, s0
	v_readlane_b32 s2, v253, 39
	s_addc_u32 s1, s2, s1
	s_waitcnt lgkmcnt(0)
	s_barrier
	v_lshl_add_u64 v[138:139], v[160:161], 2, s[0:1]
	global_load_dwordx4 v[134:137], v[138:139], off offset:16
	global_load_dwordx4 v[142:145], v[138:139], off
	global_load_dwordx4 v[130:133], v[138:139], off offset:528
	s_nop 0
	global_load_dwordx4 v[138:141], v[138:139], off offset:512
	v_lshl_add_u32 v32, v172, 2, 0
	v_add_u32_e32 v32, 0x1000, v32
	ds_read2_b32 v[148:149], v32 offset1:16
	v_add_u32_e32 v146, s22, v172
	v_ashrrev_i32_e32 v147, 31, v146
	v_readlane_b32 s0, v254, 34
	v_readlane_b32 s1, v254, 35
	s_waitcnt lgkmcnt(0)
	v_pk_mul_f32 v[118:119], v[118:119], v[148:149] op_sel_hi:[1,0]
	v_pk_mul_f32 v[120:121], v[120:121], v[148:149] op_sel_hi:[1,0]
	v_pk_mul_f32 v[114:115], v[114:115], v[148:149] op_sel_hi:[1,0]
	v_pk_mul_f32 v[116:117], v[116:117], v[148:149] op_sel_hi:[1,0]
	s_waitcnt vmcnt(3)
	v_pk_mul_f32 v[114:115], v[134:135], v[114:115]
	s_waitcnt vmcnt(2)
	v_pk_mul_f32 v[120:121], v[144:145], v[120:121]
	v_pk_mul_f32 v[118:119], v[142:143], v[118:119]
	v_pk_mul_f32 v[116:117], v[136:137], v[116:117]
	v_cvt_pk_bf16_f32 v118, v118, v119
	v_cvt_pk_bf16_f32 v119, v120, v121
	v_lshlrev_b64 v[120:121], 12, v[146:147]
	v_lshl_add_u64 v[120:121], s[0:1], 0, v[120:121]
	v_lshl_add_u64 v[150:151], v[120:121], 0, v[158:159]
	v_cvt_pk_bf16_f32 v120, v114, v115
	v_cvt_pk_bf16_f32 v121, v116, v117
	v_pk_mul_f32 v[114:115], v[126:127], v[148:149] op_sel_hi:[1,0]
	v_pk_mul_f32 v[116:117], v[128:129], v[148:149] op_sel_hi:[1,0]
	s_waitcnt vmcnt(0)
	v_pk_mul_f32 v[114:115], v[138:139], v[114:115]
	v_pk_mul_f32 v[116:117], v[140:141], v[116:117]
	global_store_dwordx4 v[150:151], v[118:121], off sc1
	v_cvt_pk_bf16_f32 v114, v114, v115
	v_cvt_pk_bf16_f32 v115, v116, v117
	v_pk_mul_f32 v[116:117], v[122:123], v[148:149] op_sel_hi:[1,0]
	v_pk_mul_f32 v[118:119], v[124:125], v[148:149] op_sel_hi:[1,0]
	v_pk_mul_f32 v[116:117], v[130:131], v[116:117]
	v_pk_mul_f32 v[118:119], v[132:133], v[118:119]
	v_cvt_pk_bf16_f32 v116, v116, v117
	v_cvt_pk_bf16_f32 v117, v118, v119
	global_store_dwordx4 v[150:151], v[114:117], off offset:256 sc1
	s_nop 1
	v_mov_b32_e32 v116, v149
	v_add_u32_e32 v114, 16, v146
	v_pk_mul_f32 v[102:103], v[102:103], v[116:117] op_sel_hi:[1,0]
	v_pk_mul_f32 v[104:105], v[104:105], v[116:117] op_sel_hi:[1,0]
	v_ashrrev_i32_e32 v115, 31, v114
	v_pk_mul_f32 v[104:105], v[144:145], v[104:105]
	v_pk_mul_f32 v[102:103], v[142:143], v[102:103]
	v_pk_mul_f32 v[98:99], v[98:99], v[116:117] op_sel_hi:[1,0]
	v_cvt_pk_bf16_f32 v102, v102, v103
	v_cvt_pk_bf16_f32 v103, v104, v105
	v_lshlrev_b64 v[104:105], 12, v[114:115]
	v_pk_mul_f32 v[100:101], v[100:101], v[116:117] op_sel_hi:[1,0]
	v_lshl_add_u64 v[104:105], s[0:1], 0, v[104:105]
	v_pk_mul_f32 v[100:101], v[136:137], v[100:101]
	v_pk_mul_f32 v[98:99], v[134:135], v[98:99]
	v_lshl_add_u64 v[114:115], v[104:105], 0, v[158:159]
	v_cvt_pk_bf16_f32 v104, v98, v99
	v_cvt_pk_bf16_f32 v105, v100, v101
	v_pk_mul_f32 v[98:99], v[110:111], v[116:117] op_sel_hi:[1,0]
	v_pk_mul_f32 v[100:101], v[112:113], v[116:117] op_sel_hi:[1,0]
	v_pk_mul_f32 v[98:99], v[138:139], v[98:99]
	v_pk_mul_f32 v[100:101], v[140:141], v[100:101]
	global_store_dwordx4 v[114:115], v[102:105], off sc1
	v_cvt_pk_bf16_f32 v98, v98, v99
	v_cvt_pk_bf16_f32 v99, v100, v101
	v_pk_mul_f32 v[100:101], v[106:107], v[116:117] op_sel_hi:[1,0]
	v_pk_mul_f32 v[102:103], v[108:109], v[116:117] op_sel_hi:[1,0]
	v_pk_mul_f32 v[100:101], v[130:131], v[100:101]
	v_pk_mul_f32 v[102:103], v[132:133], v[102:103]
	v_cvt_pk_bf16_f32 v100, v100, v101
	v_cvt_pk_bf16_f32 v101, v102, v103
	global_store_dwordx4 v[114:115], v[98:101], off offset:256 sc1
	ds_read2_b32 v[98:99], v32 offset0:32 offset1:48
	s_waitcnt lgkmcnt(0)
	v_pk_mul_f32 v[86:87], v[86:87], v[98:99] op_sel_hi:[1,0]
	v_pk_mul_f32 v[88:89], v[88:89], v[98:99] op_sel_hi:[1,0]
	v_pk_mul_f32 v[84:85], v[84:85], v[98:99] op_sel_hi:[1,0]
	v_pk_mul_f32 v[88:89], v[140:141], v[88:89]
	v_pk_mul_f32 v[86:87], v[138:139], v[86:87]
	v_pk_mul_f32 v[84:85], v[132:133], v[84:85]
	v_cvt_pk_bf16_f32 v86, v86, v87
	v_cvt_pk_bf16_f32 v87, v88, v89
	v_cvt_pk_bf16_f32 v89, v84, v85
	v_mov_b32_e32 v84, v99
	v_pk_mul_f32 v[70:71], v[70:71], v[84:85] op_sel_hi:[1,0]
	v_pk_mul_f32 v[72:73], v[72:73], v[84:85] op_sel_hi:[1,0]
	v_pk_mul_f32 v[66:67], v[66:67], v[84:85] op_sel_hi:[1,0]
	v_pk_mul_f32 v[72:73], v[140:141], v[72:73]
	v_pk_mul_f32 v[70:71], v[138:139], v[70:71]
	v_pk_mul_f32 v[66:67], v[130:131], v[66:67]
	v_cvt_pk_bf16_f32 v70, v70, v71
	v_cvt_pk_bf16_f32 v71, v72, v73
	v_cvt_pk_bf16_f32 v72, v66, v67
	ds_read2_b32 v[66:67], v32 offset0:128 offset1:144
	v_pk_mul_f32 v[82:83], v[82:83], v[98:99] op_sel_hi:[1,0]
	v_pk_mul_f32 v[68:69], v[68:69], v[84:85] op_sel_hi:[1,0]
	v_pk_mul_f32 v[82:83], v[130:131], v[82:83]
	v_pk_mul_f32 v[68:69], v[132:133], v[68:69]
	s_waitcnt lgkmcnt(0)
	v_pk_mul_f32 v[54:55], v[54:55], v[66:67] op_sel_hi:[1,0]
	v_pk_mul_f32 v[56:57], v[56:57], v[66:67] op_sel_hi:[1,0]
	v_pk_mul_f32 v[52:53], v[52:53], v[66:67] op_sel_hi:[1,0]
	v_pk_mul_f32 v[56:57], v[140:141], v[56:57]
	v_pk_mul_f32 v[54:55], v[138:139], v[54:55]
	v_pk_mul_f32 v[52:53], v[132:133], v[52:53]
	v_cvt_pk_bf16_f32 v54, v54, v55
	v_cvt_pk_bf16_f32 v55, v56, v57
	v_cvt_pk_bf16_f32 v57, v52, v53
	v_mov_b32_e32 v52, v67
	v_pk_mul_f32 v[38:39], v[38:39], v[52:53] op_sel_hi:[1,0]
	v_pk_mul_f32 v[40:41], v[40:41], v[52:53] op_sel_hi:[1,0]
	v_pk_mul_f32 v[34:35], v[34:35], v[52:53] op_sel_hi:[1,0]
	v_pk_mul_f32 v[40:41], v[140:141], v[40:41]
	v_pk_mul_f32 v[38:39], v[138:139], v[38:39]
	v_pk_mul_f32 v[34:35], v[130:131], v[34:35]
	v_cvt_pk_bf16_f32 v38, v38, v39
	v_cvt_pk_bf16_f32 v39, v40, v41
	v_cvt_pk_bf16_f32 v40, v34, v35
	ds_read2_b32 v[34:35], v32 offset0:160 offset1:176
	v_pk_mul_f32 v[50:51], v[50:51], v[66:67] op_sel_hi:[1,0]
	v_pk_mul_f32 v[36:37], v[36:37], v[52:53] op_sel_hi:[1,0]
	v_pk_mul_f32 v[50:51], v[130:131], v[50:51]
	v_pk_mul_f32 v[36:37], v[132:133], v[36:37]
	s_waitcnt lgkmcnt(0)
; __device__ __forceinline__ unsigned cvt_pk_bf16(float lo, float hi) { const f32x2_t v = {lo, hi}; const bf16x2_t c = __builtin_convertvector(v, bf16x2_t); return __builtin_bit_cast(unsigned, c); }
;     __device__ __forceinline__ void fused(f32x4 (&acc)[2][2][4][2], const Unit& u, int wr, int wc, int fr, int fq, PG8_LAS unsigned char* lds, int wid, int lane) const {
;     ...
;         for (int ai = 0; ai < 2; ++ai)
; #pragma unroll
;             for (int m = 0; m < 4; ++m) { const int r = ai * HALF + wr * 64 + m * 16 + fr; const float rs = S[r]; const size_t off = (size_t)(u.pm * BM + r) * ld + col0;
; #pragma unroll
;                 for (int bj = 0; bj < 2; ++bj)
; #pragma unroll
;                     for (int n = 0; n < 2; ++n) { const f32x4 o = acc[ai][bj][m][n] * rs * gv[bj][n];
;                         if (final_) *(f32x4*)(OUT + off + bj * HALF + n * 4) = o;
;                         else { u32x2 w; w.x = cvt_pk_bf16(o[0], o[1]); w.y = cvt_pk_bf16(o[2], o[3]); *(u32x2*)(XN + off + bj * HALF + n * 4) = w; } } }
	v_pk_mul_f32 v[20:21], v[20:21], v[34:35] op_sel_hi:[1,0]
	v_pk_mul_f32 v[22:23], v[22:23], v[34:35] op_sel_hi:[1,0]
	v_pk_mul_f32 v[18:19], v[18:19], v[34:35] op_sel_hi:[1,0]
	v_pk_mul_f32 v[22:23], v[140:141], v[22:23]
	v_pk_mul_f32 v[20:21], v[138:139], v[20:21]
	v_pk_mul_f32 v[16:17], v[16:17], v[34:35] op_sel_hi:[1,0]
	v_pk_mul_f32 v[18:19], v[132:133], v[18:19]
	v_cvt_pk_bf16_f32 v20, v20, v21
	v_cvt_pk_bf16_f32 v21, v22, v23
	v_pk_mul_f32 v[16:17], v[130:131], v[16:17]
	v_cvt_pk_bf16_f32 v23, v18, v19
	v_mov_b32_e32 v18, v35
	v_add_u32_e32 v100, 32, v146
	v_pk_mul_f32 v[94:95], v[94:95], v[98:99] op_sel_hi:[1,0]
	v_pk_mul_f32 v[96:97], v[96:97], v[98:99] op_sel_hi:[1,0]
	v_cvt_pk_bf16_f32 v88, v82, v83
	v_add_u32_e32 v82, 48, v146
	v_pk_mul_f32 v[78:79], v[78:79], v[84:85] op_sel_hi:[1,0]
	v_pk_mul_f32 v[80:81], v[80:81], v[84:85] op_sel_hi:[1,0]
	v_cvt_pk_bf16_f32 v73, v68, v69
	v_add_u32_e32 v68, 0x80, v146
	v_pk_mul_f32 v[62:63], v[62:63], v[66:67] op_sel_hi:[1,0]
	v_pk_mul_f32 v[64:65], v[64:65], v[66:67] op_sel_hi:[1,0]
	v_cvt_pk_bf16_f32 v56, v50, v51
	v_add_u32_e32 v50, 0x90, v146
	v_pk_mul_f32 v[46:47], v[46:47], v[52:53] op_sel_hi:[1,0]
	v_pk_mul_f32 v[48:49], v[48:49], v[52:53] op_sel_hi:[1,0]
	v_cvt_pk_bf16_f32 v41, v36, v37
	v_add_u32_e32 v36, 0xa0, v146
	v_pk_mul_f32 v[28:29], v[28:29], v[34:35] op_sel_hi:[1,0]
	v_pk_mul_f32 v[30:31], v[30:31], v[34:35] op_sel_hi:[1,0]
	v_cvt_pk_bf16_f32 v22, v16, v17
	v_add_u32_e32 v16, 0xb0, v146
	v_pk_mul_f32 v[12:13], v[12:13], v[18:19] op_sel_hi:[1,0]
	v_pk_mul_f32 v[14:15], v[14:15], v[18:19] op_sel_hi:[1,0]
	v_ashrrev_i32_e32 v101, 31, v100
	v_pk_mul_f32 v[96:97], v[144:145], v[96:97]
	v_pk_mul_f32 v[94:95], v[142:143], v[94:95]
	v_ashrrev_i32_e32 v83, 31, v82
	v_pk_mul_f32 v[80:81], v[144:145], v[80:81]
	v_pk_mul_f32 v[78:79], v[142:143], v[78:79]
	v_ashrrev_i32_e32 v69, 31, v68
	v_pk_mul_f32 v[64:65], v[144:145], v[64:65]
	v_pk_mul_f32 v[62:63], v[142:143], v[62:63]
	v_ashrrev_i32_e32 v51, 31, v50
	v_pk_mul_f32 v[48:49], v[144:145], v[48:49]
	v_pk_mul_f32 v[46:47], v[142:143], v[46:47]
	v_ashrrev_i32_e32 v37, 31, v36
	v_pk_mul_f32 v[30:31], v[144:145], v[30:31]
	v_pk_mul_f32 v[28:29], v[142:143], v[28:29]
	v_ashrrev_i32_e32 v17, 31, v16
	v_pk_mul_f32 v[14:15], v[144:145], v[14:15]
	v_pk_mul_f32 v[12:13], v[142:143], v[12:13]
	v_cvt_pk_bf16_f32 v94, v94, v95
	v_cvt_pk_bf16_f32 v95, v96, v97
	v_lshlrev_b64 v[96:97], 12, v[100:101]
	v_pk_mul_f32 v[90:91], v[90:91], v[98:99] op_sel_hi:[1,0]
	v_pk_mul_f32 v[92:93], v[92:93], v[98:99] op_sel_hi:[1,0]
	v_cvt_pk_bf16_f32 v78, v78, v79
	v_cvt_pk_bf16_f32 v79, v80, v81
	v_lshlrev_b64 v[80:81], 12, v[82:83]
	v_pk_mul_f32 v[74:75], v[74:75], v[84:85] op_sel_hi:[1,0]
	v_pk_mul_f32 v[76:77], v[76:77], v[84:85] op_sel_hi:[1,0]
	v_cvt_pk_bf16_f32 v62, v62, v63
	v_cvt_pk_bf16_f32 v63, v64, v65
	v_lshlrev_b64 v[64:65], 12, v[68:69]
	v_pk_mul_f32 v[58:59], v[58:59], v[66:67] op_sel_hi:[1,0]
	v_pk_mul_f32 v[60:61], v[60:61], v[66:67] op_sel_hi:[1,0]
	v_cvt_pk_bf16_f32 v46, v46, v47
	v_cvt_pk_bf16_f32 v47, v48, v49
	v_lshlrev_b64 v[48:49], 12, v[50:51]
	v_pk_mul_f32 v[42:43], v[42:43], v[52:53] op_sel_hi:[1,0]
	v_pk_mul_f32 v[44:45], v[44:45], v[52:53] op_sel_hi:[1,0]
	v_cvt_pk_bf16_f32 v28, v28, v29
	v_cvt_pk_bf16_f32 v29, v30, v31
	v_lshlrev_b64 v[30:31], 12, v[36:37]
	v_pk_mul_f32 v[24:25], v[24:25], v[34:35] op_sel_hi:[1,0]
	v_pk_mul_f32 v[26:27], v[26:27], v[34:35] op_sel_hi:[1,0]
	v_cvt_pk_bf16_f32 v12, v12, v13
	v_cvt_pk_bf16_f32 v13, v14, v15
	v_lshlrev_b64 v[14:15], 12, v[16:17]
	v_pk_mul_f32 v[8:9], v[8:9], v[18:19] op_sel_hi:[1,0]
	v_pk_mul_f32 v[10:11], v[10:11], v[18:19] op_sel_hi:[1,0]
	v_pk_mul_f32 v[4:5], v[4:5], v[18:19] op_sel_hi:[1,0]
	v_pk_mul_f32 v[6:7], v[6:7], v[18:19] op_sel_hi:[1,0]
	v_pk_mul_f32 v[0:1], v[0:1], v[18:19] op_sel_hi:[1,0]
	v_pk_mul_f32 v[2:3], v[2:3], v[18:19] op_sel_hi:[1,0]
	v_lshl_add_u64 v[96:97], s[0:1], 0, v[96:97]
	v_pk_mul_f32 v[92:93], v[136:137], v[92:93]
	v_pk_mul_f32 v[90:91], v[134:135], v[90:91]
	v_lshl_add_u64 v[80:81], s[0:1], 0, v[80:81]
	v_pk_mul_f32 v[76:77], v[136:137], v[76:77]
	v_pk_mul_f32 v[74:75], v[134:135], v[74:75]
	v_lshl_add_u64 v[64:65], s[0:1], 0, v[64:65]
	v_pk_mul_f32 v[60:61], v[136:137], v[60:61]
	v_pk_mul_f32 v[58:59], v[134:135], v[58:59]
	v_lshl_add_u64 v[48:49], s[0:1], 0, v[48:49]
	v_pk_mul_f32 v[44:45], v[136:137], v[44:45]
	v_pk_mul_f32 v[42:43], v[134:135], v[42:43]
	v_lshl_add_u64 v[30:31], s[0:1], 0, v[30:31]
	v_pk_mul_f32 v[26:27], v[136:137], v[26:27]
	v_pk_mul_f32 v[24:25], v[134:135], v[24:25]
	v_lshl_add_u64 v[14:15], s[0:1], 0, v[14:15]
	v_pk_mul_f32 v[10:11], v[136:137], v[10:11]
	v_pk_mul_f32 v[8:9], v[134:135], v[8:9]
	v_pk_mul_f32 v[6:7], v[140:141], v[6:7]
	v_pk_mul_f32 v[4:5], v[138:139], v[4:5]
	v_pk_mul_f32 v[2:3], v[132:133], v[2:3]
	v_pk_mul_f32 v[0:1], v[130:131], v[0:1]
	v_lshl_add_u64 v[100:101], v[96:97], 0, v[158:159]
	v_cvt_pk_bf16_f32 v96, v90, v91
	v_cvt_pk_bf16_f32 v97, v92, v93
	v_lshl_add_u64 v[82:83], v[80:81], 0, v[158:159]
	v_cvt_pk_bf16_f32 v80, v74, v75
	v_cvt_pk_bf16_f32 v81, v76, v77
	v_lshl_add_u64 v[68:69], v[64:65], 0, v[158:159]
	v_cvt_pk_bf16_f32 v64, v58, v59
	v_cvt_pk_bf16_f32 v65, v60, v61
	v_lshl_add_u64 v[50:51], v[48:49], 0, v[158:159]
	v_cvt_pk_bf16_f32 v48, v42, v43
	v_cvt_pk_bf16_f32 v49, v44, v45
	v_lshl_add_u64 v[36:37], v[30:31], 0, v[158:159]
	v_cvt_pk_bf16_f32 v30, v24, v25
	v_cvt_pk_bf16_f32 v31, v26, v27
	v_lshl_add_u64 v[16:17], v[14:15], 0, v[158:159]
	v_cvt_pk_bf16_f32 v14, v8, v9
	v_cvt_pk_bf16_f32 v15, v10, v11
	v_cvt_pk_bf16_f32 v4, v4, v5
	v_cvt_pk_bf16_f32 v5, v6, v7
	v_cvt_pk_bf16_f32 v6, v0, v1
	v_cvt_pk_bf16_f32 v7, v2, v3
	global_store_dwordx4 v[100:101], v[94:97], off sc1
	global_store_dwordx4 v[100:101], v[86:89], off offset:256 sc1
	global_store_dwordx4 v[82:83], v[78:81], off sc1
	global_store_dwordx4 v[82:83], v[70:73], off offset:256 sc1
	global_store_dwordx4 v[68:69], v[62:65], off sc1
	global_store_dwordx4 v[68:69], v[54:57], off offset:256 sc1
	global_store_dwordx4 v[50:51], v[46:49], off sc1
	global_store_dwordx4 v[50:51], v[38:41], off offset:256 sc1
	global_store_dwordx4 v[36:37], v[28:31], off sc1
	global_store_dwordx4 v[36:37], v[20:23], off offset:256 sc1
	global_store_dwordx4 v[16:17], v[12:15], off sc1
	global_store_dwordx4 v[16:17], v[4:7], off offset:256 sc1

; __device__ __forceinline__ float bf_lo(unsigned w) { return __uint_as_float(w << 16); }
; __device__ __forceinline__ float bf_hi(unsigned w) { return __uint_as_float(w & 0xffff0000u); }
; __device__ __forceinline__ float sigmoidf_fast(float x) { return __builtin_amdgcn_rcpf(1.0f + __expf(-x)); }
;     __device__ __forceinline__ void fused(f32x4 (&acc)[2][2][4][2], const Unit& u, int wr, int wc, int fr, int fq, PG8_LAS unsigned char* lds, int wid, int lane) const {
;     ...
;             for (int m = 0; m < 4; ++m) { const size_t off = (size_t)(u.pm * BM + ai * HALF + wr * 64 + m * 16 + fr) * ld + col0;
; #pragma unroll
;                 for (int bj = 0; bj < 2; ++bj) { hraw[m][bj] = *(const h16x8*)(H + off + bj * HALF); if (MODE != 0) eraw[m][bj] = *(const u32x4*)(E + off + bj * HALF); } }
; #pragma unroll
;             for (int m = 0; m < 4; ++m) { const size_t off = (size_t)(u.pm * BM + ai * HALF + wr * 64 + m * 16 + fr) * ld + col0;
; #pragma unroll
;                 for (int bj = 0; bj < 2; ++bj) { const f32x8 hv = __builtin_convertvector(hraw[m][bj], f32x8); f32x8 r8;
; #pragma unroll
;                     for (int n = 0; n < 2; ++n) { f32x4 r; const f32x4 a = acc[ai][bj][m][n];
;                         if (MODE == 0) { r[0] = hv[4 * n] + a[0]; r[1] = hv[4 * n + 1] + a[1]; r[2] = hv[4 * n + 2] + a[2]; r[3] = hv[4 * n + 3] + a[3]; }
;                         else { const unsigned e0 = n ? eraw[m][bj].z : eraw[m][bj].x, e1 = n ? eraw[m][bj].w : eraw[m][bj].y;
;                             r[0] = hv[4 * n] + sigmoidf_fast(a[0]) * bf_lo(e0); r[1] = hv[4 * n + 1] + sigmoidf_fast(a[1]) * bf_hi(e0); r[2] = hv[4 * n + 2] + sigmoidf_fast(a[2]) * bf_lo(e1); r[3] = hv[4 * n + 3] + sigmoidf_fast(a[3]) * bf_hi(e1); }
;                         acc[ai][bj][m][n] = r; r8[4 * n] = r[0]; r8[4 * n + 1] = r[1]; r8[4 * n + 2] = r[2]; r8[4 * n + 3] = r[3]; }
;                     *(h16x8*)(H + off + bj * HALF) = __builtin_convertvector(r8, h16x8); }
.LBB0_1294:
	s_lshl_b64 s[4:5], s[96:97], 25
	v_readlane_b32 s8, v252, 59
	s_add_u32 s4, s8, s4
	v_readlane_b32 s8, v252, 60
	s_addc_u32 s5, s8, s5
	s_lshl_b32 s8, s2, 5
	s_lshl_b32 s9, s0, 8
	v_lshrrev_b32_e32 v130, 1, v215
	s_or_b32 s8, s9, s8
	s_lshl_b32 s16, s20, 8
	v_and_or_b32 v190, v130, 24, s8
	s_add_i32 s8, s16, s41
	v_or_b32_e32 v192, s8, v216
	v_ashrrev_i32_e32 v193, 31, v192
	v_ashrrev_i32_e32 v191, 31, v190
	v_lshlrev_b64 v[130:131], 11, v[192:193]
	v_lshl_add_u64 v[130:131], v[130:131], 0, v[190:191]
	v_readlane_b32 s8, v252, 57
	v_lshlrev_b64 v[130:131], 1, v[130:131]
	v_readlane_b32 s9, v252, 58
	s_barrier
	v_or_b32_e32 v206, 16, v192
	v_lshl_add_u64 v[132:133], s[8:9], 0, v[130:131]
	v_lshl_add_u64 v[130:131], s[4:5], 0, v[130:131]
	global_load_dwordx4 v[198:201], v[132:133], off
	global_load_dwordx4 v[186:189], v[130:131], off
	global_load_dwordx4 v[182:185], v[132:133], off offset:256
	global_load_dwordx4 v[178:181], v[130:131], off offset:256
	v_ashrrev_i32_e32 v207, 31, v206
	v_lshlrev_b64 v[130:131], 11, v[206:207]
	v_lshl_add_u64 v[130:131], v[130:131], 0, v[190:191]
	v_lshlrev_b64 v[130:131], 1, v[130:131]
	v_lshl_add_u64 v[132:133], s[8:9], 0, v[130:131]
	v_lshl_add_u64 v[130:131], s[4:5], 0, v[130:131]
	global_load_dwordx4 v[174:177], v[132:133], off
	global_load_dwordx4 v[170:173], v[130:131], off
	global_load_dwordx4 v[166:169], v[132:133], off offset:256
	global_load_dwordx4 v[162:165], v[130:131], off offset:256
	v_or_b32_e32 v204, 32, v192
	v_ashrrev_i32_e32 v205, 31, v204
	v_lshlrev_b64 v[130:131], 11, v[204:205]
	v_lshl_add_u64 v[130:131], v[130:131], 0, v[190:191]
	v_lshlrev_b64 v[130:131], 1, v[130:131]
	v_lshl_add_u64 v[132:133], s[8:9], 0, v[130:131]
	v_lshl_add_u64 v[130:131], s[4:5], 0, v[130:131]
	global_load_dwordx4 v[158:161], v[132:133], off
	global_load_dwordx4 v[154:157], v[130:131], off
	global_load_dwordx4 v[150:153], v[132:133], off offset:256
	global_load_dwordx4 v[146:149], v[130:131], off offset:256
	v_or_b32_e32 v202, 48, v192
	v_ashrrev_i32_e32 v203, 31, v202
	v_lshlrev_b64 v[130:131], 11, v[202:203]
	v_lshl_add_u64 v[130:131], v[130:131], 0, v[190:191]
	v_lshlrev_b64 v[130:131], 1, v[130:131]
	v_lshl_add_u64 v[132:133], s[8:9], 0, v[130:131]
	v_lshl_add_u64 v[130:131], s[4:5], 0, v[130:131]
	global_load_dwordx4 v[142:145], v[132:133], off
	global_load_dwordx4 v[138:141], v[130:131], off
	global_load_dwordx4 v[134:137], v[132:133], off offset:256
	s_nop 0
	global_load_dwordx4 v[130:133], v[130:131], off offset:256
	v_mul_f32_e32 v56, 0xbfb8aa3b, v56
	v_mul_f32_e32 v57, 0xbfb8aa3b, v57
	v_exp_f32_e32 v56, v56
	v_exp_f32_e32 v57, v57
	v_mul_f32_e32 v62, 0xbfb8aa3b, v62
	v_mul_f32_e32 v63, 0xbfb8aa3b, v63
	v_exp_f32_e32 v62, v62
	v_exp_f32_e32 v63, v63
	v_mul_f32_e32 v64, 0xbfb8aa3b, v64
	v_mul_f32_e32 v65, 0xbfb8aa3b, v65
	v_mul_f32_e32 v54, 0xbfb8aa3b, v54
	v_mul_f32_e32 v55, 0xbfb8aa3b, v55
	v_exp_f32_e32 v64, v64
	v_exp_f32_e32 v65, v65
	v_exp_f32_e32 v54, v54
	v_exp_f32_e32 v55, v55
	v_add_f32_e32 v56, 1.0, v56
	v_add_f32_e32 v57, 1.0, v57
	v_rcp_f32_e32 v56, v56
	v_rcp_f32_e32 v57, v57
	v_add_f32_e32 v62, 1.0, v62
	v_add_f32_e32 v63, 1.0, v63
	v_rcp_f32_e32 v62, v62
	v_rcp_f32_e32 v63, v63
	v_add_f32_e32 v64, 1.0, v64
	v_add_f32_e32 v65, 1.0, v65
	v_add_f32_e32 v54, 1.0, v54
	v_add_f32_e32 v55, 1.0, v55
	v_rcp_f32_e32 v64, v64
	v_rcp_f32_e32 v65, v65
	v_rcp_f32_e32 v54, v54
	v_rcp_f32_e32 v55, v55
	v_mul_f32_e32 v72, 0xbfb8aa3b, v72
	v_mul_f32_e32 v73, 0xbfb8aa3b, v73
	v_exp_f32_e32 v72, v72
	v_exp_f32_e32 v73, v73
	v_mul_f32_e32 v78, 0xbfb8aa3b, v78
	v_mul_f32_e32 v79, 0xbfb8aa3b, v79
	v_mul_f32_e32 v70, 0xbfb8aa3b, v70
	v_mul_f32_e32 v71, 0xbfb8aa3b, v71
	v_exp_f32_e32 v78, v78
	v_exp_f32_e32 v79, v79
	v_mul_f32_e32 v80, 0xbfb8aa3b, v80
	v_mul_f32_e32 v81, 0xbfb8aa3b, v81
	v_exp_f32_e32 v70, v70
	v_exp_f32_e32 v71, v71
	v_exp_f32_e32 v80, v80
	v_exp_f32_e32 v81, v81
	v_add_f32_e32 v72, 1.0, v72
	v_add_f32_e32 v73, 1.0, v73
	v_rcp_f32_e32 v72, v72
	v_rcp_f32_e32 v73, v73
	v_add_f32_e32 v78, 1.0, v78
	s_waitcnt vmcnt(0)
	v_cvt_f32_f16_e32 v212, v199
	v_cvt_f32_f16_sdwa v213, v199 dst_sel:DWORD dst_unused:UNUSED_PAD src0_sel:WORD_1
	v_cvt_f32_f16_e32 v210, v200
	v_cvt_f32_f16_sdwa v211, v200 dst_sel:DWORD dst_unused:UNUSED_PAD src0_sel:WORD_1
	v_cvt_f32_f16_e32 v208, v201
	v_cvt_f32_f16_sdwa v209, v201 dst_sel:DWORD dst_unused:UNUSED_PAD src0_sel:WORD_1
	v_cvt_f32_f16_e32 v200, v198
	v_cvt_f32_f16_sdwa v201, v198 dst_sel:DWORD dst_unused:UNUSED_PAD src0_sel:WORD_1
	v_lshlrev_b32_e32 v198, 16, v186
	v_and_b32_e32 v199, 0xffff0000, v186
	v_lshlrev_b32_e32 v186, 16, v187
	v_and_b32_e32 v187, 0xffff0000, v187
	v_pk_fma_f32 v[56:57], v[56:57], v[186:187], v[212:213]
	v_lshlrev_b32_e32 v186, 16, v188
	v_and_b32_e32 v187, 0xffff0000, v188
	v_pk_fma_f32 v[62:63], v[62:63], v[186:187], v[210:211]
	v_lshlrev_b32_e32 v186, 16, v189
	v_and_b32_e32 v187, 0xffff0000, v189
	v_pk_fma_f32 v[64:65], v[64:65], v[186:187], v[208:209]
	v_lshlrev_b64 v[186:187], 12, v[192:193]
	v_pk_fma_f32 v[54:55], v[54:55], v[198:199], v[200:201]
	v_lshl_add_u64 v[188:189], s[8:9], 0, v[186:187]
	v_lshlrev_b64 v[186:187], 1, v[190:191]
	v_cvt_pk_f16_f32 v201, v64, v65
	v_cvt_pk_f16_f32 v200, v62, v63
	v_cvt_pk_f16_f32 v199, v56, v57
	v_cvt_pk_f16_f32 v198, v54, v55
	v_lshl_add_u64 v[188:189], v[188:189], 0, v[186:187]
	global_store_dwordx4 v[188:189], v[198:201], off sc1
	v_add_f32_e32 v79, 1.0, v79
	v_add_f32_e32 v70, 1.0, v70
	v_cvt_f32_f16_e32 v198, v185
	v_cvt_f32_f16_sdwa v199, v185 dst_sel:DWORD dst_unused:UNUSED_PAD src0_sel:WORD_1
	v_cvt_f32_f16_e32 v200, v184
	v_cvt_f32_f16_sdwa v201, v184 dst_sel:DWORD dst_unused:UNUSED_PAD src0_sel:WORD_1
; __device__ __forceinline__ float bf_lo(unsigned w) { return __uint_as_float(w << 16); }
; __device__ __forceinline__ float bf_hi(unsigned w) { return __uint_as_float(w & 0xffff0000u); }
; __device__ __forceinline__ float sigmoidf_fast(float x) { return __builtin_amdgcn_rcpf(1.0f + __expf(-x)); }
;     __device__ __forceinline__ void fused(f32x4 (&acc)[2][2][4][2], const Unit& u, int wr, int wc, int fr, int fq, PG8_LAS unsigned char* lds, int wid, int lane) const {
;     ...
;             for (int m = 0; m < 4; ++m) { const size_t off = (size_t)(u.pm * BM + ai * HALF + wr * 64 + m * 16 + fr) * ld + col0;
; #pragma unroll
;                 for (int bj = 0; bj < 2; ++bj) { const f32x8 hv = __builtin_convertvector(hraw[m][bj], f32x8); f32x8 r8;
; #pragma unroll
;                     for (int n = 0; n < 2; ++n) { f32x4 r; const f32x4 a = acc[ai][bj][m][n];
;                         if (MODE == 0) { r[0] = hv[4 * n] + a[0]; r[1] = hv[4 * n + 1] + a[1]; r[2] = hv[4 * n + 2] + a[2]; r[3] = hv[4 * n + 3] + a[3]; }
;                         else { const unsigned e0 = n ? eraw[m][bj].z : eraw[m][bj].x, e1 = n ? eraw[m][bj].w : eraw[m][bj].y;
;                             r[0] = hv[4 * n] + sigmoidf_fast(a[0]) * bf_lo(e0); r[1] = hv[4 * n + 1] + sigmoidf_fast(a[1]) * bf_hi(e0); r[2] = hv[4 * n + 2] + sigmoidf_fast(a[2]) * bf_lo(e1); r[3] = hv[4 * n + 3] + sigmoidf_fast(a[3]) * bf_hi(e1); }
;                         acc[ai][bj][m][n] = r; r8[4 * n] = r[0]; r8[4 * n + 1] = r[1]; r8[4 * n + 2] = r[2]; r8[4 * n + 3] = r[3]; }
;                     *(h16x8*)(H + off + bj * HALF) = __builtin_convertvector(r8, h16x8); }
	v_cvt_f32_f16_e32 v184, v183
	v_cvt_f32_f16_sdwa v185, v183 dst_sel:DWORD dst_unused:UNUSED_PAD src0_sel:WORD_1
	v_add_f32_e32 v71, 1.0, v71
	v_rcp_f32_e32 v78, v78
	v_rcp_f32_e32 v79, v79
	v_add_f32_e32 v80, 1.0, v80
	v_add_f32_e32 v81, 1.0, v81
	v_cvt_f32_f16_e32 v208, v182
	v_cvt_f32_f16_sdwa v209, v182 dst_sel:DWORD dst_unused:UNUSED_PAD src0_sel:WORD_1
	v_rcp_f32_e32 v70, v70
	v_rcp_f32_e32 v71, v71
	v_rcp_f32_e32 v80, v80
	v_rcp_f32_e32 v81, v81
	v_mul_f32_e32 v84, 0xbfb8aa3b, v84
	v_mul_f32_e32 v85, 0xbfb8aa3b, v85
	v_lshlrev_b32_e32 v182, 16, v178
	v_and_b32_e32 v183, 0xffff0000, v178
	v_lshlrev_b32_e32 v178, 16, v179
	v_and_b32_e32 v179, 0xffff0000, v179
	v_mul_f32_e32 v82, 0xbfb8aa3b, v82
	v_mul_f32_e32 v83, 0xbfb8aa3b, v83
	v_exp_f32_e32 v84, v84
	v_exp_f32_e32 v85, v85
	v_mul_f32_e32 v86, 0xbfb8aa3b, v86
	v_mul_f32_e32 v87, 0xbfb8aa3b, v87
	v_pk_fma_f32 v[72:73], v[72:73], v[178:179], v[184:185]
	v_lshlrev_b32_e32 v178, 16, v180
	v_and_b32_e32 v179, 0xffff0000, v180
	v_exp_f32_e32 v82, v82
	v_exp_f32_e32 v83, v83
	v_exp_f32_e32 v86, v86
	v_exp_f32_e32 v87, v87
	v_mul_f32_e32 v88, 0xbfb8aa3b, v88
	v_mul_f32_e32 v89, 0xbfb8aa3b, v89
	v_pk_fma_f32 v[78:79], v[78:79], v[178:179], v[200:201]
	v_lshlrev_b32_e32 v178, 16, v181
	v_and_b32_e32 v179, 0xffff0000, v181
	v_exp_f32_e32 v88, v88
	v_exp_f32_e32 v89, v89
	v_pk_fma_f32 v[70:71], v[70:71], v[182:183], v[208:209]
	v_pk_fma_f32 v[80:81], v[80:81], v[178:179], v[198:199]
	v_cvt_pk_f16_f32 v180, v78, v79
	v_cvt_pk_f16_f32 v181, v80, v81
	v_cvt_pk_f16_f32 v179, v72, v73
	v_cvt_pk_f16_f32 v178, v70, v71
	v_add_f32_e32 v84, 1.0, v84
	v_add_f32_e32 v85, 1.0, v85
	global_store_dwordx4 v[188:189], v[178:181], off offset:256 sc1
	v_add_f32_e32 v82, 1.0, v82
	v_add_f32_e32 v83, 1.0, v83
	v_cvt_f32_f16_e32 v178, v177
	v_cvt_f32_f16_sdwa v179, v177 dst_sel:DWORD dst_unused:UNUSED_PAD src0_sel:WORD_1
	v_cvt_f32_f16_e32 v180, v176
	v_cvt_f32_f16_sdwa v181, v176 dst_sel:DWORD dst_unused:UNUSED_PAD src0_sel:WORD_1
	v_cvt_f32_f16_e32 v176, v175
	v_cvt_f32_f16_sdwa v177, v175 dst_sel:DWORD dst_unused:UNUSED_PAD src0_sel:WORD_1
	v_rcp_f32_e32 v84, v84
	v_rcp_f32_e32 v85, v85
	v_add_f32_e32 v86, 1.0, v86
	v_add_f32_e32 v87, 1.0, v87
	v_cvt_f32_f16_e32 v182, v174
	v_cvt_f32_f16_sdwa v183, v174 dst_sel:DWORD dst_unused:UNUSED_PAD src0_sel:WORD_1
	v_rcp_f32_e32 v82, v82
	v_rcp_f32_e32 v83, v83
	v_rcp_f32_e32 v86, v86
	v_rcp_f32_e32 v87, v87
	v_add_f32_e32 v88, 1.0, v88
	v_add_f32_e32 v89, 1.0, v89
	v_rcp_f32_e32 v88, v88
	v_rcp_f32_e32 v89, v89
	v_mul_f32_e32 v92, 0xbfb8aa3b, v92
	v_mul_f32_e32 v93, 0xbfb8aa3b, v93
	v_lshlrev_b32_e32 v174, 16, v170
	v_and_b32_e32 v175, 0xffff0000, v170
	v_lshlrev_b32_e32 v170, 16, v171
	v_and_b32_e32 v171, 0xffff0000, v171
	v_exp_f32_e32 v92, v92
	v_exp_f32_e32 v93, v93
	v_mul_f32_e32 v98, 0xbfb8aa3b, v98
	v_mul_f32_e32 v99, 0xbfb8aa3b, v99
	v_pk_fma_f32 v[84:85], v[84:85], v[170:171], v[176:177]
	v_lshlrev_b32_e32 v170, 16, v172
	v_and_b32_e32 v171, 0xffff0000, v172
	v_mul_f32_e32 v90, 0xbfb8aa3b, v90
	v_mul_f32_e32 v91, 0xbfb8aa3b, v91
	v_exp_f32_e32 v98, v98
	v_exp_f32_e32 v99, v99
	v_mul_f32_e32 v100, 0xbfb8aa3b, v100
	v_mul_f32_e32 v101, 0xbfb8aa3b, v101
	v_pk_fma_f32 v[82:83], v[82:83], v[174:175], v[182:183]
	v_pk_fma_f32 v[86:87], v[86:87], v[170:171], v[180:181]
	v_lshlrev_b32_e32 v170, 16, v173
	v_and_b32_e32 v171, 0xffff0000, v173
	v_lshlrev_b64 v[174:175], 12, v[206:207]
	v_exp_f32_e32 v90, v90
	v_exp_f32_e32 v91, v91
	v_exp_f32_e32 v100, v100
	v_exp_f32_e32 v101, v101
	v_pk_fma_f32 v[88:89], v[88:89], v[170:171], v[178:179]
	v_lshl_add_u64 v[174:175], s[8:9], 0, v[174:175]
	v_cvt_pk_f16_f32 v173, v88, v89
	v_cvt_pk_f16_f32 v172, v86, v87
	v_cvt_pk_f16_f32 v171, v84, v85
	v_cvt_pk_f16_f32 v170, v82, v83
	v_lshl_add_u64 v[174:175], v[174:175], 0, v[186:187]
	v_add_f32_e32 v92, 1.0, v92
	v_add_f32_e32 v93, 1.0, v93
	global_store_dwordx4 v[174:175], v[170:173], off sc1
	v_rcp_f32_e32 v92, v92
	v_rcp_f32_e32 v93, v93
	v_cvt_f32_f16_e32 v170, v169
	v_cvt_f32_f16_sdwa v171, v169 dst_sel:DWORD dst_unused:UNUSED_PAD src0_sel:WORD_1
	v_cvt_f32_f16_e32 v172, v168
	v_cvt_f32_f16_sdwa v173, v168 dst_sel:DWORD dst_unused:UNUSED_PAD src0_sel:WORD_1
	v_cvt_f32_f16_e32 v168, v167
	v_cvt_f32_f16_sdwa v169, v167 dst_sel:DWORD dst_unused:UNUSED_PAD src0_sel:WORD_1
	v_add_f32_e32 v98, 1.0, v98
	v_add_f32_e32 v99, 1.0, v99
	v_add_f32_e32 v90, 1.0, v90
	v_add_f32_e32 v91, 1.0, v91
	v_rcp_f32_e32 v98, v98
	v_rcp_f32_e32 v99, v99
	v_add_f32_e32 v100, 1.0, v100
	v_add_f32_e32 v101, 1.0, v101
	v_cvt_f32_f16_e32 v176, v166
	v_cvt_f32_f16_sdwa v177, v166 dst_sel:DWORD dst_unused:UNUSED_PAD src0_sel:WORD_1
	v_rcp_f32_e32 v90, v90
	v_rcp_f32_e32 v91, v91
	v_rcp_f32_e32 v100, v100
	v_rcp_f32_e32 v101, v101
	v_mul_f32_e32 v108, 0xbfb8aa3b, v108
	v_mul_f32_e32 v109, 0xbfb8aa3b, v109
	v_lshlrev_b32_e32 v166, 16, v162
	v_and_b32_e32 v167, 0xffff0000, v162
	v_lshlrev_b32_e32 v162, 16, v163
	v_and_b32_e32 v163, 0xffff0000, v163
	v_mul_f32_e32 v106, 0xbfb8aa3b, v106
	v_mul_f32_e32 v107, 0xbfb8aa3b, v107
	v_exp_f32_e32 v108, v108
	v_exp_f32_e32 v109, v109
	v_mul_f32_e32 v110, 0xbfb8aa3b, v110
	v_mul_f32_e32 v111, 0xbfb8aa3b, v111
	v_pk_fma_f32 v[92:93], v[92:93], v[162:163], v[168:169]
	v_lshlrev_b32_e32 v162, 16, v164
	v_and_b32_e32 v163, 0xffff0000, v164
	v_exp_f32_e32 v106, v106
	v_exp_f32_e32 v107, v107
	v_exp_f32_e32 v110, v110
	v_exp_f32_e32 v111, v111
	v_mul_f32_e32 v112, 0xbfb8aa3b, v112
	v_mul_f32_e32 v113, 0xbfb8aa3b, v113
	v_pk_fma_f32 v[98:99], v[98:99], v[162:163], v[172:173]
	v_lshlrev_b32_e32 v162, 16, v165
	v_and_b32_e32 v163, 0xffff0000, v165
	v_exp_f32_e32 v112, v112
; __device__ __forceinline__ float bf_lo(unsigned w) { return __uint_as_float(w << 16); }
; __device__ __forceinline__ float bf_hi(unsigned w) { return __uint_as_float(w & 0xffff0000u); }
; __device__ __forceinline__ float sigmoidf_fast(float x) { return __builtin_amdgcn_rcpf(1.0f + __expf(-x)); }
;     __device__ __forceinline__ void fused(f32x4 (&acc)[2][2][4][2], const Unit& u, int wr, int wc, int fr, int fq, PG8_LAS unsigned char* lds, int wid, int lane) const {
;     ...
;             for (int m = 0; m < 4; ++m) { const size_t off = (size_t)(u.pm * BM + ai * HALF + wr * 64 + m * 16 + fr) * ld + col0;
; #pragma unroll
;                 for (int bj = 0; bj < 2; ++bj) { const f32x8 hv = __builtin_convertvector(hraw[m][bj], f32x8); f32x8 r8;
; #pragma unroll
;                     for (int n = 0; n < 2; ++n) { f32x4 r; const f32x4 a = acc[ai][bj][m][n];
;                         if (MODE == 0) { r[0] = hv[4 * n] + a[0]; r[1] = hv[4 * n + 1] + a[1]; r[2] = hv[4 * n + 2] + a[2]; r[3] = hv[4 * n + 3] + a[3]; }
;                         else { const unsigned e0 = n ? eraw[m][bj].z : eraw[m][bj].x, e1 = n ? eraw[m][bj].w : eraw[m][bj].y;
;                             r[0] = hv[4 * n] + sigmoidf_fast(a[0]) * bf_lo(e0); r[1] = hv[4 * n + 1] + sigmoidf_fast(a[1]) * bf_hi(e0); r[2] = hv[4 * n + 2] + sigmoidf_fast(a[2]) * bf_lo(e1); r[3] = hv[4 * n + 3] + sigmoidf_fast(a[3]) * bf_hi(e1); }
;                         acc[ai][bj][m][n] = r; r8[4 * n] = r[0]; r8[4 * n + 1] = r[1]; r8[4 * n + 2] = r[2]; r8[4 * n + 3] = r[3]; }
;                     *(h16x8*)(H + off + bj * HALF) = __builtin_convertvector(r8, h16x8); }
	v_exp_f32_e32 v113, v113
	v_pk_fma_f32 v[90:91], v[90:91], v[166:167], v[176:177]
	v_pk_fma_f32 v[100:101], v[100:101], v[162:163], v[170:171]
	v_cvt_pk_f16_f32 v164, v98, v99
	v_cvt_pk_f16_f32 v165, v100, v101
	v_cvt_pk_f16_f32 v163, v92, v93
	v_cvt_pk_f16_f32 v162, v90, v91
	v_add_f32_e32 v108, 1.0, v108
	v_add_f32_e32 v109, 1.0, v109
	global_store_dwordx4 v[174:175], v[162:165], off offset:256 sc1
	v_add_f32_e32 v106, 1.0, v106
	v_add_f32_e32 v107, 1.0, v107
	v_cvt_f32_f16_e32 v162, v161
	v_cvt_f32_f16_sdwa v163, v161 dst_sel:DWORD dst_unused:UNUSED_PAD src0_sel:WORD_1
	v_cvt_f32_f16_e32 v164, v160
	v_cvt_f32_f16_sdwa v165, v160 dst_sel:DWORD dst_unused:UNUSED_PAD src0_sel:WORD_1
	v_cvt_f32_f16_e32 v160, v159
	v_cvt_f32_f16_sdwa v161, v159 dst_sel:DWORD dst_unused:UNUSED_PAD src0_sel:WORD_1
	v_rcp_f32_e32 v108, v108
	v_rcp_f32_e32 v109, v109
	v_add_f32_e32 v110, 1.0, v110
	v_add_f32_e32 v111, 1.0, v111
	v_cvt_f32_f16_e32 v166, v158
	v_cvt_f32_f16_sdwa v167, v158 dst_sel:DWORD dst_unused:UNUSED_PAD src0_sel:WORD_1
	v_rcp_f32_e32 v106, v106
	v_rcp_f32_e32 v107, v107
	v_rcp_f32_e32 v110, v110
	v_rcp_f32_e32 v111, v111
	v_add_f32_e32 v112, 1.0, v112
	v_add_f32_e32 v113, 1.0, v113
	v_rcp_f32_e32 v112, v112
	v_rcp_f32_e32 v113, v113
	v_mul_f32_e32 v116, 0xbfb8aa3b, v116
	v_mul_f32_e32 v117, 0xbfb8aa3b, v117
	v_lshlrev_b32_e32 v158, 16, v154
	v_and_b32_e32 v159, 0xffff0000, v154
	v_lshlrev_b32_e32 v154, 16, v155
	v_and_b32_e32 v155, 0xffff0000, v155
	v_exp_f32_e32 v116, v116
	v_exp_f32_e32 v117, v117
	v_mul_f32_e32 v118, 0xbfb8aa3b, v118
	v_mul_f32_e32 v119, 0xbfb8aa3b, v119
	v_pk_fma_f32 v[108:109], v[108:109], v[154:155], v[160:161]
	v_lshlrev_b32_e32 v154, 16, v156
	v_and_b32_e32 v155, 0xffff0000, v156
	v_mul_f32_e32 v114, 0xbfb8aa3b, v114
	v_mul_f32_e32 v115, 0xbfb8aa3b, v115
	v_exp_f32_e32 v118, v118
	v_exp_f32_e32 v119, v119
	v_mul_f32_e32 v120, 0xbfb8aa3b, v120
	v_mul_f32_e32 v121, 0xbfb8aa3b, v121
	v_pk_fma_f32 v[106:107], v[106:107], v[158:159], v[166:167]
	v_pk_fma_f32 v[110:111], v[110:111], v[154:155], v[164:165]
	v_lshlrev_b32_e32 v154, 16, v157
	v_and_b32_e32 v155, 0xffff0000, v157
	v_lshlrev_b64 v[158:159], 12, v[204:205]
	v_exp_f32_e32 v114, v114
	v_exp_f32_e32 v115, v115
	v_exp_f32_e32 v120, v120
	v_exp_f32_e32 v121, v121
	v_pk_fma_f32 v[112:113], v[112:113], v[154:155], v[162:163]
	v_lshl_add_u64 v[158:159], s[8:9], 0, v[158:159]
	v_cvt_pk_f16_f32 v157, v112, v113
	v_cvt_pk_f16_f32 v156, v110, v111
	v_cvt_pk_f16_f32 v155, v108, v109
	v_cvt_pk_f16_f32 v154, v106, v107
	v_lshl_add_u64 v[158:159], v[158:159], 0, v[186:187]
	v_add_f32_e32 v116, 1.0, v116
	v_add_f32_e32 v117, 1.0, v117
	global_store_dwordx4 v[158:159], v[154:157], off sc1
	v_rcp_f32_e32 v116, v116
	v_rcp_f32_e32 v117, v117
	v_cvt_f32_f16_e32 v154, v153
	v_cvt_f32_f16_sdwa v155, v153 dst_sel:DWORD dst_unused:UNUSED_PAD src0_sel:WORD_1
	v_cvt_f32_f16_e32 v156, v152
	v_cvt_f32_f16_sdwa v157, v152 dst_sel:DWORD dst_unused:UNUSED_PAD src0_sel:WORD_1
	v_cvt_f32_f16_e32 v152, v151
	v_cvt_f32_f16_sdwa v153, v151 dst_sel:DWORD dst_unused:UNUSED_PAD src0_sel:WORD_1
	v_add_f32_e32 v118, 1.0, v118
	v_add_f32_e32 v119, 1.0, v119
	v_add_f32_e32 v114, 1.0, v114
	v_add_f32_e32 v115, 1.0, v115
	v_rcp_f32_e32 v118, v118
	v_rcp_f32_e32 v119, v119
	v_add_f32_e32 v120, 1.0, v120
	v_add_f32_e32 v121, 1.0, v121
	v_cvt_f32_f16_e32 v160, v150
	v_cvt_f32_f16_sdwa v161, v150 dst_sel:DWORD dst_unused:UNUSED_PAD src0_sel:WORD_1
	v_rcp_f32_e32 v114, v114
	v_rcp_f32_e32 v115, v115
	v_rcp_f32_e32 v120, v120
	v_rcp_f32_e32 v121, v121
	v_mul_f32_e32 v128, 0xbfb8aa3b, v128
	v_mul_f32_e32 v129, 0xbfb8aa3b, v129
	v_lshlrev_b32_e32 v150, 16, v146
	v_and_b32_e32 v151, 0xffff0000, v146
	v_lshlrev_b32_e32 v146, 16, v147
	v_and_b32_e32 v147, 0xffff0000, v147
	v_mul_f32_e32 v126, 0xbfb8aa3b, v126
	v_mul_f32_e32 v127, 0xbfb8aa3b, v127
	v_exp_f32_e32 v128, v128
	v_exp_f32_e32 v129, v129
	v_mul_f32_e32 v122, 0xbfb8aa3b, v122
	v_mul_f32_e32 v123, 0xbfb8aa3b, v123
	v_pk_fma_f32 v[116:117], v[116:117], v[146:147], v[152:153]
	v_lshlrev_b32_e32 v146, 16, v148
	v_and_b32_e32 v147, 0xffff0000, v148
	v_exp_f32_e32 v126, v126
	v_exp_f32_e32 v127, v127
	v_exp_f32_e32 v122, v122
	v_exp_f32_e32 v123, v123
	v_mul_f32_e32 v124, 0xbfb8aa3b, v124
	v_mul_f32_e32 v125, 0xbfb8aa3b, v125
	v_pk_fma_f32 v[118:119], v[118:119], v[146:147], v[156:157]
	v_lshlrev_b32_e32 v146, 16, v149
	v_and_b32_e32 v147, 0xffff0000, v149
	v_exp_f32_e32 v124, v124
	v_exp_f32_e32 v125, v125
	v_pk_fma_f32 v[114:115], v[114:115], v[150:151], v[160:161]
	v_pk_fma_f32 v[120:121], v[120:121], v[146:147], v[154:155]
	v_cvt_pk_f16_f32 v148, v118, v119
	v_cvt_pk_f16_f32 v149, v120, v121
	v_cvt_pk_f16_f32 v147, v116, v117
	v_cvt_pk_f16_f32 v146, v114, v115
	v_add_f32_e32 v128, 1.0, v128
	v_add_f32_e32 v129, 1.0, v129
	global_store_dwordx4 v[158:159], v[146:149], off offset:256 sc1
	v_add_f32_e32 v126, 1.0, v126
	v_add_f32_e32 v127, 1.0, v127
	v_cvt_f32_f16_e32 v146, v145
	v_cvt_f32_f16_sdwa v147, v145 dst_sel:DWORD dst_unused:UNUSED_PAD src0_sel:WORD_1
	v_cvt_f32_f16_e32 v148, v144
	v_cvt_f32_f16_sdwa v149, v144 dst_sel:DWORD dst_unused:UNUSED_PAD src0_sel:WORD_1
	v_cvt_f32_f16_e32 v144, v143
	v_cvt_f32_f16_sdwa v145, v143 dst_sel:DWORD dst_unused:UNUSED_PAD src0_sel:WORD_1
	v_rcp_f32_e32 v128, v128
	v_rcp_f32_e32 v129, v129
	v_add_f32_e32 v122, 1.0, v122
	v_add_f32_e32 v123, 1.0, v123
	v_cvt_f32_f16_e32 v150, v142
	v_cvt_f32_f16_sdwa v151, v142 dst_sel:DWORD dst_unused:UNUSED_PAD src0_sel:WORD_1
	v_rcp_f32_e32 v126, v126
	v_rcp_f32_e32 v127, v127
	v_rcp_f32_e32 v122, v122
	v_rcp_f32_e32 v123, v123
	v_add_f32_e32 v124, 1.0, v124
	v_add_f32_e32 v125, 1.0, v125
; __device__ __forceinline__ float bf_lo(unsigned w) { return __uint_as_float(w << 16); }
; __device__ __forceinline__ float bf_hi(unsigned w) { return __uint_as_float(w & 0xffff0000u); }
; __device__ __forceinline__ float sigmoidf_fast(float x) { return __builtin_amdgcn_rcpf(1.0f + __expf(-x)); }
;     __device__ __forceinline__ void fused(f32x4 (&acc)[2][2][4][2], const Unit& u, int wr, int wc, int fr, int fq, PG8_LAS unsigned char* lds, int wid, int lane) const {
;     ...
;             for (int m = 0; m < 4; ++m) { const size_t off = (size_t)(u.pm * BM + ai * HALF + wr * 64 + m * 16 + fr) * ld + col0;
; #pragma unroll
;                 for (int bj = 0; bj < 2; ++bj) { hraw[m][bj] = *(const h16x8*)(H + off + bj * HALF); if (MODE != 0) eraw[m][bj] = *(const u32x4*)(E + off + bj * HALF); } }
; #pragma unroll
;             for (int m = 0; m < 4; ++m) { const size_t off = (size_t)(u.pm * BM + ai * HALF + wr * 64 + m * 16 + fr) * ld + col0;
; #pragma unroll
;                 for (int bj = 0; bj < 2; ++bj) { const f32x8 hv = __builtin_convertvector(hraw[m][bj], f32x8); f32x8 r8;
; #pragma unroll
;                     for (int n = 0; n < 2; ++n) { f32x4 r; const f32x4 a = acc[ai][bj][m][n];
;                         if (MODE == 0) { r[0] = hv[4 * n] + a[0]; r[1] = hv[4 * n + 1] + a[1]; r[2] = hv[4 * n + 2] + a[2]; r[3] = hv[4 * n + 3] + a[3]; }
;                         else { const unsigned e0 = n ? eraw[m][bj].z : eraw[m][bj].x, e1 = n ? eraw[m][bj].w : eraw[m][bj].y;
;                             r[0] = hv[4 * n] + sigmoidf_fast(a[0]) * bf_lo(e0); r[1] = hv[4 * n + 1] + sigmoidf_fast(a[1]) * bf_hi(e0); r[2] = hv[4 * n + 2] + sigmoidf_fast(a[2]) * bf_lo(e1); r[3] = hv[4 * n + 3] + sigmoidf_fast(a[3]) * bf_hi(e1); }
;                         acc[ai][bj][m][n] = r; r8[4 * n] = r[0]; r8[4 * n + 1] = r[1]; r8[4 * n + 2] = r[2]; r8[4 * n + 3] = r[3]; }
;                     *(h16x8*)(H + off + bj * HALF) = __builtin_convertvector(r8, h16x8); }
	v_rcp_f32_e32 v124, v124
	v_rcp_f32_e32 v125, v125
	v_mul_f32_e32 v104, 0xbfb8aa3b, v104
	v_mul_f32_e32 v105, 0xbfb8aa3b, v105
	v_lshlrev_b32_e32 v142, 16, v138
	v_and_b32_e32 v143, 0xffff0000, v138
	v_lshlrev_b32_e32 v138, 16, v139
	v_and_b32_e32 v139, 0xffff0000, v139
	v_exp_f32_e32 v104, v104
	v_exp_f32_e32 v105, v105
	v_mul_f32_e32 v94, 0xbfb8aa3b, v94
	v_mul_f32_e32 v95, 0xbfb8aa3b, v95
	v_pk_fma_f32 v[128:129], v[128:129], v[138:139], v[144:145]
	v_lshlrev_b32_e32 v138, 16, v140
	v_and_b32_e32 v139, 0xffff0000, v140
	v_mul_f32_e32 v102, 0xbfb8aa3b, v102
	v_mul_f32_e32 v103, 0xbfb8aa3b, v103
	v_exp_f32_e32 v94, v94
	v_exp_f32_e32 v95, v95
	v_mul_f32_e32 v96, 0xbfb8aa3b, v96
	v_mul_f32_e32 v97, 0xbfb8aa3b, v97
	v_pk_fma_f32 v[126:127], v[126:127], v[142:143], v[150:151]
	v_pk_fma_f32 v[122:123], v[122:123], v[138:139], v[148:149]
	v_lshlrev_b32_e32 v138, 16, v141
	v_and_b32_e32 v139, 0xffff0000, v141
	v_lshlrev_b64 v[142:143], 12, v[202:203]
	v_exp_f32_e32 v102, v102
	v_exp_f32_e32 v103, v103
	v_exp_f32_e32 v96, v96
	v_exp_f32_e32 v97, v97
	v_pk_fma_f32 v[124:125], v[124:125], v[138:139], v[146:147]
	v_lshl_add_u64 v[142:143], s[8:9], 0, v[142:143]
	v_cvt_pk_f16_f32 v141, v124, v125
	v_cvt_pk_f16_f32 v140, v122, v123
	v_cvt_pk_f16_f32 v139, v128, v129
	v_cvt_pk_f16_f32 v138, v126, v127
	v_lshl_add_u64 v[142:143], v[142:143], 0, v[186:187]
	v_add_f32_e32 v104, 1.0, v104
	v_add_f32_e32 v105, 1.0, v105
	global_store_dwordx4 v[142:143], v[138:141], off sc1
	v_rcp_f32_e32 v104, v104
	v_rcp_f32_e32 v105, v105
	v_cvt_f32_f16_e32 v138, v137
	v_cvt_f32_f16_sdwa v139, v137 dst_sel:DWORD dst_unused:UNUSED_PAD src0_sel:WORD_1
	v_cvt_f32_f16_e32 v140, v136
	v_cvt_f32_f16_sdwa v141, v136 dst_sel:DWORD dst_unused:UNUSED_PAD src0_sel:WORD_1
	v_cvt_f32_f16_e32 v136, v135
	v_cvt_f32_f16_sdwa v137, v135 dst_sel:DWORD dst_unused:UNUSED_PAD src0_sel:WORD_1
	v_add_f32_e32 v94, 1.0, v94
	v_add_f32_e32 v95, 1.0, v95
	v_add_f32_e32 v102, 1.0, v102
	v_add_f32_e32 v103, 1.0, v103
	v_rcp_f32_e32 v94, v94
	v_rcp_f32_e32 v95, v95
	v_add_f32_e32 v96, 1.0, v96
	v_add_f32_e32 v97, 1.0, v97
	v_cvt_f32_f16_e32 v144, v134
	v_cvt_f32_f16_sdwa v145, v134 dst_sel:DWORD dst_unused:UNUSED_PAD src0_sel:WORD_1
	v_rcp_f32_e32 v102, v102
	v_rcp_f32_e32 v103, v103
	v_rcp_f32_e32 v96, v96
	v_rcp_f32_e32 v97, v97
	v_lshlrev_b32_e32 v134, 16, v130
	v_and_b32_e32 v135, 0xffff0000, v130
	v_lshlrev_b32_e32 v130, 16, v131
	v_and_b32_e32 v131, 0xffff0000, v131
	v_pk_fma_f32 v[104:105], v[104:105], v[130:131], v[136:137]
	v_lshlrev_b32_e32 v130, 16, v132
	v_and_b32_e32 v131, 0xffff0000, v132
	v_pk_fma_f32 v[94:95], v[94:95], v[130:131], v[140:141]
	v_lshlrev_b32_e32 v130, 16, v133
	v_and_b32_e32 v131, 0xffff0000, v133
	v_pk_fma_f32 v[102:103], v[102:103], v[134:135], v[144:145]
	v_pk_fma_f32 v[96:97], v[96:97], v[130:131], v[138:139]
	v_add_u32_e32 v206, 0x80, v192
	v_cvt_pk_f16_f32 v133, v96, v97
	v_cvt_pk_f16_f32 v132, v94, v95
	v_cvt_pk_f16_f32 v131, v104, v105
	v_cvt_pk_f16_f32 v130, v102, v103
	v_ashrrev_i32_e32 v207, 31, v206
	global_store_dwordx4 v[142:143], v[130:133], off offset:256 sc1
	v_add_u32_e32 v204, 0x90, v192
	v_ashrrev_i32_e32 v205, 31, v204
	v_lshlrev_b64 v[130:131], 11, v[206:207]
	v_lshl_add_u64 v[130:131], v[130:131], 0, v[190:191]
	v_lshlrev_b64 v[130:131], 1, v[130:131]
	v_lshl_add_u64 v[132:133], s[8:9], 0, v[130:131]
	v_lshl_add_u64 v[130:131], s[4:5], 0, v[130:131]
	global_load_dwordx4 v[198:201], v[132:133], off
	global_load_dwordx4 v[208:211], v[130:131], off
	global_load_dwordx4 v[182:185], v[132:133], off offset:256
	global_load_dwordx4 v[178:181], v[130:131], off offset:256
	v_lshlrev_b64 v[130:131], 11, v[204:205]
	v_lshl_add_u64 v[130:131], v[130:131], 0, v[190:191]
	v_lshlrev_b64 v[130:131], 1, v[130:131]
	v_lshl_add_u64 v[132:133], s[8:9], 0, v[130:131]
	v_lshl_add_u64 v[130:131], s[4:5], 0, v[130:131]
	global_load_dwordx4 v[174:177], v[132:133], off
	global_load_dwordx4 v[170:173], v[130:131], off
	global_load_dwordx4 v[166:169], v[132:133], off offset:256
	global_load_dwordx4 v[162:165], v[130:131], off offset:256
	v_add_u32_e32 v202, 0xa0, v192
	v_ashrrev_i32_e32 v203, 31, v202
	v_lshlrev_b64 v[130:131], 11, v[202:203]
	v_lshl_add_u64 v[130:131], v[130:131], 0, v[190:191]
	v_lshlrev_b64 v[130:131], 1, v[130:131]
	v_lshl_add_u64 v[132:133], s[8:9], 0, v[130:131]
	v_lshl_add_u64 v[130:131], s[4:5], 0, v[130:131]
	global_load_dwordx4 v[158:161], v[132:133], off
	global_load_dwordx4 v[154:157], v[130:131], off
	global_load_dwordx4 v[150:153], v[132:133], off offset:256
	global_load_dwordx4 v[146:149], v[130:131], off offset:256
	v_add_u32_e32 v188, 0xb0, v192
	v_ashrrev_i32_e32 v189, 31, v188
	v_lshlrev_b64 v[130:131], 11, v[188:189]
	v_lshl_add_u64 v[130:131], v[130:131], 0, v[190:191]
	v_lshlrev_b64 v[130:131], 1, v[130:131]
	v_lshl_add_u64 v[132:133], s[8:9], 0, v[130:131]
	v_lshl_add_u64 v[130:131], s[4:5], 0, v[130:131]
	global_load_dwordx4 v[142:145], v[132:133], off
	global_load_dwordx4 v[138:141], v[130:131], off
	global_load_dwordx4 v[134:137], v[132:133], off offset:256
	s_nop 0
	global_load_dwordx4 v[130:133], v[130:131], off offset:256
	v_mul_f32_e32 v74, 0xbfb8aa3b, v74
	v_mul_f32_e32 v75, 0xbfb8aa3b, v75
	v_exp_f32_e32 v74, v74
	v_exp_f32_e32 v75, v75
	v_mul_f32_e32 v76, 0xbfb8aa3b, v76
	v_mul_f32_e32 v77, 0xbfb8aa3b, v77
	v_exp_f32_e32 v76, v76
	v_exp_f32_e32 v77, v77
	v_mul_f32_e32 v66, 0xbfb8aa3b, v66
	v_mul_f32_e32 v67, 0xbfb8aa3b, v67
	v_exp_f32_e32 v66, v66
	v_exp_f32_e32 v67, v67
	v_mul_f32_e32 v68, 0xbfb8aa3b, v68
	v_mul_f32_e32 v69, 0xbfb8aa3b, v69
	v_exp_f32_e32 v68, v68
	v_exp_f32_e32 v69, v69
	v_add_f32_e32 v74, 1.0, v74
	v_add_f32_e32 v75, 1.0, v75
	v_rcp_f32_e32 v74, v74
	v_rcp_f32_e32 v75, v75
	v_add_f32_e32 v76, 1.0, v76
	v_add_f32_e32 v77, 1.0, v77
	v_rcp_f32_e32 v76, v76
	v_rcp_f32_e32 v77, v77
	v_add_f32_e32 v66, 1.0, v66
	v_add_f32_e32 v67, 1.0, v67
	v_rcp_f32_e32 v66, v66
	v_rcp_f32_e32 v67, v67
	v_add_f32_e32 v68, 1.0, v68
	v_add_f32_e32 v69, 1.0, v69
	v_rcp_f32_e32 v68, v68
	v_rcp_f32_e32 v69, v69
	v_mul_f32_e32 v60, 0xbfb8aa3b, v60
	v_mul_f32_e32 v61, 0xbfb8aa3b, v61
	v_exp_f32_e32 v60, v60
	v_exp_f32_e32 v61, v61
	v_mul_f32_e32 v50, 0xbfb8aa3b, v50
	v_mul_f32_e32 v51, 0xbfb8aa3b, v51
	v_mul_f32_e32 v58, 0xbfb8aa3b, v58
	v_mul_f32_e32 v59, 0xbfb8aa3b, v59
	v_exp_f32_e32 v50, v50
	v_exp_f32_e32 v51, v51
	v_mul_f32_e32 v52, 0xbfb8aa3b, v52
	v_mul_f32_e32 v53, 0xbfb8aa3b, v53
	v_exp_f32_e32 v58, v58
	v_exp_f32_e32 v59, v59
	v_exp_f32_e32 v52, v52
	v_exp_f32_e32 v53, v53
	v_add_f32_e32 v60, 1.0, v60
	v_add_f32_e32 v61, 1.0, v61
	v_rcp_f32_e32 v60, v60
	v_rcp_f32_e32 v61, v61
	v_add_f32_e32 v50, 1.0, v50
	v_add_f32_e32 v51, 1.0, v51
	s_waitcnt vmcnt(15)
; __device__ __forceinline__ float bf_lo(unsigned w) { return __uint_as_float(w << 16); }
; __device__ __forceinline__ float bf_hi(unsigned w) { return __uint_as_float(w & 0xffff0000u); }
; __device__ __forceinline__ float sigmoidf_fast(float x) { return __builtin_amdgcn_rcpf(1.0f + __expf(-x)); }
;     __device__ __forceinline__ void fused(f32x4 (&acc)[2][2][4][2], const Unit& u, int wr, int wc, int fr, int fq, PG8_LAS unsigned char* lds, int wid, int lane) const {
;     ...
;             for (int m = 0; m < 4; ++m) { const size_t off = (size_t)(u.pm * BM + ai * HALF + wr * 64 + m * 16 + fr) * ld + col0;
; #pragma unroll
;                 for (int bj = 0; bj < 2; ++bj) { const f32x8 hv = __builtin_convertvector(hraw[m][bj], f32x8); f32x8 r8;
; #pragma unroll
;                     for (int n = 0; n < 2; ++n) { f32x4 r; const f32x4 a = acc[ai][bj][m][n];
;                         if (MODE == 0) { r[0] = hv[4 * n] + a[0]; r[1] = hv[4 * n + 1] + a[1]; r[2] = hv[4 * n + 2] + a[2]; r[3] = hv[4 * n + 3] + a[3]; }
;                         else { const unsigned e0 = n ? eraw[m][bj].z : eraw[m][bj].x, e1 = n ? eraw[m][bj].w : eraw[m][bj].y;
;                             r[0] = hv[4 * n] + sigmoidf_fast(a[0]) * bf_lo(e0); r[1] = hv[4 * n + 1] + sigmoidf_fast(a[1]) * bf_hi(e0); r[2] = hv[4 * n + 2] + sigmoidf_fast(a[2]) * bf_lo(e1); r[3] = hv[4 * n + 3] + sigmoidf_fast(a[3]) * bf_hi(e1); }
;                         acc[ai][bj][m][n] = r; r8[4 * n] = r[0]; r8[4 * n + 1] = r[1]; r8[4 * n + 2] = r[2]; r8[4 * n + 3] = r[3]; }
;                     *(h16x8*)(H + off + bj * HALF) = __builtin_convertvector(r8, h16x8); }
	v_cvt_f32_f16_e32 v218, v198
	v_cvt_f32_f16_sdwa v219, v198 dst_sel:DWORD dst_unused:UNUSED_PAD src0_sel:WORD_1
	v_cvt_f32_f16_e32 v192, v201
	v_cvt_f32_f16_sdwa v193, v201 dst_sel:DWORD dst_unused:UNUSED_PAD src0_sel:WORD_1
	v_cvt_f32_f16_e32 v212, v200
	v_cvt_f32_f16_sdwa v213, v200 dst_sel:DWORD dst_unused:UNUSED_PAD src0_sel:WORD_1
	v_cvt_f32_f16_e32 v200, v199
	v_cvt_f32_f16_sdwa v201, v199 dst_sel:DWORD dst_unused:UNUSED_PAD src0_sel:WORD_1
	s_waitcnt vmcnt(14)
	v_lshlrev_b32_e32 v198, 16, v208
	v_and_b32_e32 v199, 0xffff0000, v208
	v_pk_fma_f32 v[74:75], v[74:75], v[198:199], v[218:219]
	v_lshlrev_b32_e32 v198, 16, v209
	v_and_b32_e32 v199, 0xffff0000, v209
	v_pk_fma_f32 v[76:77], v[76:77], v[198:199], v[200:201]
	v_lshlrev_b32_e32 v198, 16, v210
	v_and_b32_e32 v199, 0xffff0000, v210
	v_pk_fma_f32 v[66:67], v[66:67], v[198:199], v[212:213]
	v_lshlrev_b32_e32 v198, 16, v211
	v_and_b32_e32 v199, 0xffff0000, v211
	v_pk_fma_f32 v[68:69], v[68:69], v[198:199], v[192:193]
	v_lshlrev_b64 v[192:193], 12, v[206:207]
	v_lshl_add_u64 v[192:193], s[8:9], 0, v[192:193]
	v_cvt_pk_f16_f32 v201, v68, v69
	v_cvt_pk_f16_f32 v200, v66, v67
	v_cvt_pk_f16_f32 v199, v76, v77
	v_cvt_pk_f16_f32 v198, v74, v75
	v_lshl_add_u64 v[192:193], v[192:193], 0, v[186:187]
	global_store_dwordx4 v[192:193], v[198:201], off sc1
	v_add_f32_e32 v58, 1.0, v58
	v_add_f32_e32 v59, 1.0, v59
	s_waitcnt vmcnt(14)
	v_cvt_f32_f16_e32 v198, v185
	v_cvt_f32_f16_sdwa v199, v185 dst_sel:DWORD dst_unused:UNUSED_PAD src0_sel:WORD_1
	v_cvt_f32_f16_e32 v200, v184
	v_cvt_f32_f16_sdwa v201, v184 dst_sel:DWORD dst_unused:UNUSED_PAD src0_sel:WORD_1
	v_cvt_f32_f16_e32 v184, v183
	v_cvt_f32_f16_sdwa v185, v183 dst_sel:DWORD dst_unused:UNUSED_PAD src0_sel:WORD_1
	v_rcp_f32_e32 v50, v50
	v_rcp_f32_e32 v51, v51
	v_add_f32_e32 v52, 1.0, v52
	v_add_f32_e32 v53, 1.0, v53
	v_cvt_f32_f16_e32 v206, v182
	v_cvt_f32_f16_sdwa v207, v182 dst_sel:DWORD dst_unused:UNUSED_PAD src0_sel:WORD_1
	v_rcp_f32_e32 v58, v58
	v_rcp_f32_e32 v59, v59
	v_rcp_f32_e32 v52, v52
	v_rcp_f32_e32 v53, v53
	v_mul_f32_e32 v48, 0xbfb8aa3b, v48
	v_mul_f32_e32 v49, 0xbfb8aa3b, v49
	s_waitcnt vmcnt(13)
	v_lshlrev_b32_e32 v182, 16, v178
	v_and_b32_e32 v183, 0xffff0000, v178
	v_lshlrev_b32_e32 v178, 16, v179
	v_and_b32_e32 v179, 0xffff0000, v179
	v_mul_f32_e32 v46, 0xbfb8aa3b, v46
	v_mul_f32_e32 v47, 0xbfb8aa3b, v47
	v_exp_f32_e32 v48, v48
	v_exp_f32_e32 v49, v49
	v_mul_f32_e32 v42, 0xbfb8aa3b, v42
	v_mul_f32_e32 v43, 0xbfb8aa3b, v43
	v_pk_fma_f32 v[60:61], v[60:61], v[178:179], v[184:185]
	v_lshlrev_b32_e32 v178, 16, v180
	v_and_b32_e32 v179, 0xffff0000, v180
	v_exp_f32_e32 v46, v46
	v_exp_f32_e32 v47, v47
	v_exp_f32_e32 v42, v42
	v_exp_f32_e32 v43, v43
	v_mul_f32_e32 v44, 0xbfb8aa3b, v44
	v_mul_f32_e32 v45, 0xbfb8aa3b, v45
	v_pk_fma_f32 v[50:51], v[50:51], v[178:179], v[200:201]
	v_lshlrev_b32_e32 v178, 16, v181
	v_and_b32_e32 v179, 0xffff0000, v181
	v_exp_f32_e32 v44, v44
	v_exp_f32_e32 v45, v45
	v_pk_fma_f32 v[58:59], v[58:59], v[182:183], v[206:207]
	v_pk_fma_f32 v[52:53], v[52:53], v[178:179], v[198:199]
	v_cvt_pk_f16_f32 v180, v50, v51
	v_cvt_pk_f16_f32 v181, v52, v53
	v_cvt_pk_f16_f32 v179, v60, v61
	v_cvt_pk_f16_f32 v178, v58, v59
	v_add_f32_e32 v48, 1.0, v48
	v_add_f32_e32 v49, 1.0, v49
	global_store_dwordx4 v[192:193], v[178:181], off offset:256 sc1
	v_add_f32_e32 v46, 1.0, v46
	v_add_f32_e32 v47, 1.0, v47
	s_waitcnt vmcnt(13)
	v_cvt_f32_f16_e32 v178, v177
	v_cvt_f32_f16_sdwa v179, v177 dst_sel:DWORD dst_unused:UNUSED_PAD src0_sel:WORD_1
	v_cvt_f32_f16_e32 v180, v176
	v_cvt_f32_f16_sdwa v181, v176 dst_sel:DWORD dst_unused:UNUSED_PAD src0_sel:WORD_1
	v_cvt_f32_f16_e32 v176, v175
	v_cvt_f32_f16_sdwa v177, v175 dst_sel:DWORD dst_unused:UNUSED_PAD src0_sel:WORD_1
	v_rcp_f32_e32 v48, v48
	v_rcp_f32_e32 v49, v49
	v_add_f32_e32 v42, 1.0, v42
	v_add_f32_e32 v43, 1.0, v43
	v_cvt_f32_f16_e32 v182, v174
	v_cvt_f32_f16_sdwa v183, v174 dst_sel:DWORD dst_unused:UNUSED_PAD src0_sel:WORD_1
	v_rcp_f32_e32 v46, v46
	v_rcp_f32_e32 v47, v47
	v_rcp_f32_e32 v42, v42
	v_rcp_f32_e32 v43, v43
	v_add_f32_e32 v44, 1.0, v44
	v_add_f32_e32 v45, 1.0, v45
	v_rcp_f32_e32 v44, v44
	v_rcp_f32_e32 v45, v45
	v_mul_f32_e32 v40, 0xbfb8aa3b, v40
	v_mul_f32_e32 v41, 0xbfb8aa3b, v41
	s_waitcnt vmcnt(12)
	v_lshlrev_b32_e32 v174, 16, v170
	v_and_b32_e32 v175, 0xffff0000, v170
	v_lshlrev_b32_e32 v170, 16, v171
	v_and_b32_e32 v171, 0xffff0000, v171
	v_exp_f32_e32 v40, v40
	v_exp_f32_e32 v41, v41
	v_mul_f32_e32 v34, 0xbfb8aa3b, v34
	v_mul_f32_e32 v35, 0xbfb8aa3b, v35
	v_pk_fma_f32 v[48:49], v[48:49], v[170:171], v[176:177]
	v_lshlrev_b32_e32 v170, 16, v172
	v_and_b32_e32 v171, 0xffff0000, v172
	v_mul_f32_e32 v38, 0xbfb8aa3b, v38
	v_mul_f32_e32 v39, 0xbfb8aa3b, v39
	v_exp_f32_e32 v34, v34
	v_exp_f32_e32 v35, v35
	v_mul_f32_e32 v36, 0xbfb8aa3b, v36
	v_mul_f32_e32 v37, 0xbfb8aa3b, v37
	v_pk_fma_f32 v[46:47], v[46:47], v[174:175], v[182:183]
	v_pk_fma_f32 v[42:43], v[42:43], v[170:171], v[180:181]
	v_lshlrev_b32_e32 v170, 16, v173
	v_and_b32_e32 v171, 0xffff0000, v173
	v_lshlrev_b64 v[174:175], 12, v[204:205]
	v_exp_f32_e32 v38, v38
	v_exp_f32_e32 v39, v39
	v_exp_f32_e32 v36, v36
	v_exp_f32_e32 v37, v37
	v_pk_fma_f32 v[44:45], v[44:45], v[170:171], v[178:179]
	v_lshl_add_u64 v[174:175], s[8:9], 0, v[174:175]
	v_cvt_pk_f16_f32 v173, v44, v45
	v_cvt_pk_f16_f32 v172, v42, v43
	v_cvt_pk_f16_f32 v171, v48, v49
	v_cvt_pk_f16_f32 v170, v46, v47
	v_lshl_add_u64 v[174:175], v[174:175], 0, v[186:187]
	v_add_f32_e32 v40, 1.0, v40
	v_add_f32_e32 v41, 1.0, v41
	global_store_dwordx4 v[174:175], v[170:173], off sc1
	v_rcp_f32_e32 v40, v40
	v_rcp_f32_e32 v41, v41
	s_waitcnt vmcnt(12)
; __device__ __forceinline__ float bf_lo(unsigned w) { return __uint_as_float(w << 16); }
; __device__ __forceinline__ float bf_hi(unsigned w) { return __uint_as_float(w & 0xffff0000u); }
; __device__ __forceinline__ float sigmoidf_fast(float x) { return __builtin_amdgcn_rcpf(1.0f + __expf(-x)); }
;     __device__ __forceinline__ void fused(f32x4 (&acc)[2][2][4][2], const Unit& u, int wr, int wc, int fr, int fq, PG8_LAS unsigned char* lds, int wid, int lane) const {
;     ...
;             for (int m = 0; m < 4; ++m) { const size_t off = (size_t)(u.pm * BM + ai * HALF + wr * 64 + m * 16 + fr) * ld + col0;
; #pragma unroll
;                 for (int bj = 0; bj < 2; ++bj) { const f32x8 hv = __builtin_convertvector(hraw[m][bj], f32x8); f32x8 r8;
; #pragma unroll
;                     for (int n = 0; n < 2; ++n) { f32x4 r; const f32x4 a = acc[ai][bj][m][n];
;                         if (MODE == 0) { r[0] = hv[4 * n] + a[0]; r[1] = hv[4 * n + 1] + a[1]; r[2] = hv[4 * n + 2] + a[2]; r[3] = hv[4 * n + 3] + a[3]; }
;                         else { const unsigned e0 = n ? eraw[m][bj].z : eraw[m][bj].x, e1 = n ? eraw[m][bj].w : eraw[m][bj].y;
;                             r[0] = hv[4 * n] + sigmoidf_fast(a[0]) * bf_lo(e0); r[1] = hv[4 * n + 1] + sigmoidf_fast(a[1]) * bf_hi(e0); r[2] = hv[4 * n + 2] + sigmoidf_fast(a[2]) * bf_lo(e1); r[3] = hv[4 * n + 3] + sigmoidf_fast(a[3]) * bf_hi(e1); }
;                         acc[ai][bj][m][n] = r; r8[4 * n] = r[0]; r8[4 * n + 1] = r[1]; r8[4 * n + 2] = r[2]; r8[4 * n + 3] = r[3]; }
;                     *(h16x8*)(H + off + bj * HALF) = __builtin_convertvector(r8, h16x8); }
	v_cvt_f32_f16_e32 v170, v169
	v_cvt_f32_f16_sdwa v171, v169 dst_sel:DWORD dst_unused:UNUSED_PAD src0_sel:WORD_1
	v_cvt_f32_f16_e32 v172, v168
	v_cvt_f32_f16_sdwa v173, v168 dst_sel:DWORD dst_unused:UNUSED_PAD src0_sel:WORD_1
	v_cvt_f32_f16_e32 v168, v167
	v_cvt_f32_f16_sdwa v169, v167 dst_sel:DWORD dst_unused:UNUSED_PAD src0_sel:WORD_1
	v_add_f32_e32 v34, 1.0, v34
	v_add_f32_e32 v35, 1.0, v35
	v_add_f32_e32 v38, 1.0, v38
	v_add_f32_e32 v39, 1.0, v39
	v_rcp_f32_e32 v34, v34
	v_rcp_f32_e32 v35, v35
	v_add_f32_e32 v36, 1.0, v36
	v_add_f32_e32 v37, 1.0, v37
	v_cvt_f32_f16_e32 v176, v166
	v_cvt_f32_f16_sdwa v177, v166 dst_sel:DWORD dst_unused:UNUSED_PAD src0_sel:WORD_1
	v_rcp_f32_e32 v38, v38
	v_rcp_f32_e32 v39, v39
	v_rcp_f32_e32 v36, v36
	v_rcp_f32_e32 v37, v37
	v_mul_f32_e32 v30, 0xbfb8aa3b, v30
	v_mul_f32_e32 v31, 0xbfb8aa3b, v31
	s_waitcnt vmcnt(11)
	v_lshlrev_b32_e32 v166, 16, v162
	v_and_b32_e32 v167, 0xffff0000, v162
	v_lshlrev_b32_e32 v162, 16, v163
	v_and_b32_e32 v163, 0xffff0000, v163
	v_mul_f32_e32 v28, 0xbfb8aa3b, v28
	v_mul_f32_e32 v29, 0xbfb8aa3b, v29
	v_exp_f32_e32 v30, v30
	v_exp_f32_e32 v31, v31
	v_mul_f32_e32 v24, 0xbfb8aa3b, v24
	v_mul_f32_e32 v25, 0xbfb8aa3b, v25
	v_pk_fma_f32 v[40:41], v[40:41], v[162:163], v[168:169]
	v_lshlrev_b32_e32 v162, 16, v164
	v_and_b32_e32 v163, 0xffff0000, v164
	v_exp_f32_e32 v28, v28
	v_exp_f32_e32 v29, v29
	v_exp_f32_e32 v24, v24
	v_exp_f32_e32 v25, v25
	v_mul_f32_e32 v26, 0xbfb8aa3b, v26
	v_mul_f32_e32 v27, 0xbfb8aa3b, v27
	v_pk_fma_f32 v[34:35], v[34:35], v[162:163], v[172:173]
	v_lshlrev_b32_e32 v162, 16, v165
	v_and_b32_e32 v163, 0xffff0000, v165
	v_exp_f32_e32 v26, v26
	v_exp_f32_e32 v27, v27
	v_pk_fma_f32 v[38:39], v[38:39], v[166:167], v[176:177]
	v_pk_fma_f32 v[36:37], v[36:37], v[162:163], v[170:171]
	v_cvt_pk_f16_f32 v164, v34, v35
	v_cvt_pk_f16_f32 v165, v36, v37
	v_cvt_pk_f16_f32 v163, v40, v41
	v_cvt_pk_f16_f32 v162, v38, v39
	v_add_f32_e32 v30, 1.0, v30
	v_add_f32_e32 v31, 1.0, v31
	global_store_dwordx4 v[174:175], v[162:165], off offset:256 sc1
	v_add_f32_e32 v28, 1.0, v28
	v_add_f32_e32 v29, 1.0, v29
	s_waitcnt vmcnt(11)
	v_cvt_f32_f16_e32 v162, v161
	v_cvt_f32_f16_sdwa v163, v161 dst_sel:DWORD dst_unused:UNUSED_PAD src0_sel:WORD_1
	v_cvt_f32_f16_e32 v164, v160
	v_cvt_f32_f16_sdwa v165, v160 dst_sel:DWORD dst_unused:UNUSED_PAD src0_sel:WORD_1
	v_cvt_f32_f16_e32 v160, v159
	v_cvt_f32_f16_sdwa v161, v159 dst_sel:DWORD dst_unused:UNUSED_PAD src0_sel:WORD_1
	v_rcp_f32_e32 v30, v30
	v_rcp_f32_e32 v31, v31
	v_add_f32_e32 v24, 1.0, v24
	v_add_f32_e32 v25, 1.0, v25
	v_cvt_f32_f16_e32 v166, v158
	v_cvt_f32_f16_sdwa v167, v158 dst_sel:DWORD dst_unused:UNUSED_PAD src0_sel:WORD_1
	v_rcp_f32_e32 v28, v28
	v_rcp_f32_e32 v29, v29
	v_rcp_f32_e32 v24, v24
	v_rcp_f32_e32 v25, v25
	v_add_f32_e32 v26, 1.0, v26
	v_add_f32_e32 v27, 1.0, v27
	v_rcp_f32_e32 v26, v26
	v_rcp_f32_e32 v27, v27
	v_mul_f32_e32 v22, 0xbfb8aa3b, v22
	v_mul_f32_e32 v23, 0xbfb8aa3b, v23
	s_waitcnt vmcnt(10)
	v_lshlrev_b32_e32 v158, 16, v154
	v_and_b32_e32 v159, 0xffff0000, v154
	v_lshlrev_b32_e32 v154, 16, v155
	v_and_b32_e32 v155, 0xffff0000, v155
	v_exp_f32_e32 v22, v22
	v_exp_f32_e32 v23, v23
	v_mul_f32_e32 v16, 0xbfb8aa3b, v16
	v_mul_f32_e32 v17, 0xbfb8aa3b, v17
	v_pk_fma_f32 v[30:31], v[30:31], v[154:155], v[160:161]
	v_lshlrev_b32_e32 v154, 16, v156
	v_and_b32_e32 v155, 0xffff0000, v156
	v_mul_f32_e32 v20, 0xbfb8aa3b, v20
	v_mul_f32_e32 v21, 0xbfb8aa3b, v21
	v_exp_f32_e32 v16, v16
	v_exp_f32_e32 v17, v17
	v_mul_f32_e32 v18, 0xbfb8aa3b, v18
	v_mul_f32_e32 v19, 0xbfb8aa3b, v19
	v_pk_fma_f32 v[28:29], v[28:29], v[158:159], v[166:167]
	v_pk_fma_f32 v[24:25], v[24:25], v[154:155], v[164:165]
	v_lshlrev_b32_e32 v154, 16, v157
	v_and_b32_e32 v155, 0xffff0000, v157
	v_lshlrev_b64 v[158:159], 12, v[202:203]
	v_exp_f32_e32 v20, v20
	v_exp_f32_e32 v21, v21
	v_exp_f32_e32 v18, v18
	v_exp_f32_e32 v19, v19
	v_pk_fma_f32 v[26:27], v[26:27], v[154:155], v[162:163]
	v_lshl_add_u64 v[158:159], s[8:9], 0, v[158:159]
	v_cvt_pk_f16_f32 v157, v26, v27
	v_cvt_pk_f16_f32 v156, v24, v25
	v_cvt_pk_f16_f32 v155, v30, v31
	v_cvt_pk_f16_f32 v154, v28, v29
	v_lshl_add_u64 v[158:159], v[158:159], 0, v[186:187]
	v_add_f32_e32 v22, 1.0, v22
	v_add_f32_e32 v23, 1.0, v23
	global_store_dwordx4 v[158:159], v[154:157], off sc1
	v_rcp_f32_e32 v22, v22
	v_rcp_f32_e32 v23, v23
	s_waitcnt vmcnt(10)
	v_cvt_f32_f16_e32 v154, v153
	v_cvt_f32_f16_sdwa v155, v153 dst_sel:DWORD dst_unused:UNUSED_PAD src0_sel:WORD_1
	v_cvt_f32_f16_e32 v156, v152
	v_cvt_f32_f16_sdwa v157, v152 dst_sel:DWORD dst_unused:UNUSED_PAD src0_sel:WORD_1
	v_cvt_f32_f16_e32 v152, v151
	v_cvt_f32_f16_sdwa v153, v151 dst_sel:DWORD dst_unused:UNUSED_PAD src0_sel:WORD_1
	v_add_f32_e32 v16, 1.0, v16
	v_add_f32_e32 v17, 1.0, v17
	v_add_f32_e32 v20, 1.0, v20
	v_add_f32_e32 v21, 1.0, v21
	v_rcp_f32_e32 v16, v16
	v_rcp_f32_e32 v17, v17
	v_add_f32_e32 v18, 1.0, v18
	v_add_f32_e32 v19, 1.0, v19
	v_cvt_f32_f16_e32 v160, v150
	v_cvt_f32_f16_sdwa v161, v150 dst_sel:DWORD dst_unused:UNUSED_PAD src0_sel:WORD_1
	v_rcp_f32_e32 v20, v20
	v_rcp_f32_e32 v21, v21
	v_rcp_f32_e32 v18, v18
	v_rcp_f32_e32 v19, v19
	v_mul_f32_e32 v14, 0xbfb8aa3b, v14
	v_mul_f32_e32 v15, 0xbfb8aa3b, v15
	s_waitcnt vmcnt(9)
; __device__ __forceinline__ float bf_lo(unsigned w) { return __uint_as_float(w << 16); }
; __device__ __forceinline__ float bf_hi(unsigned w) { return __uint_as_float(w & 0xffff0000u); }
; __device__ __forceinline__ float sigmoidf_fast(float x) { return __builtin_amdgcn_rcpf(1.0f + __expf(-x)); }
;     __device__ __forceinline__ void run(const f32x4 (&v)[2][2][4][2], const Unit& u, int wr, int wc, int fr, int fq, PG8_LAS unsigned char* lds, int wid, int lane, float inv_n, float eps) const {
;     ...
;                 float s = 0.f;
; #pragma unroll
;                 for (int bj = 0; bj < 2; ++bj)
; #pragma unroll
;                     for (int n = 0; n < 2; ++n) { const f32x4 x = v[ai][bj][m][n]; s += (x[0] * x[0] + x[1] * x[1]) + (x[2] * x[2] + x[3] * x[3]); }
;                 s += __shfl_xor(s, 16); s += __shfl_xor(s, 32);
;                 if (fq == 0) P[(ai * HALF + wr * 64 + m * 16 + fr) * 4 + wc] = s;
;     __device__ __forceinline__ void fused(f32x4 (&acc)[2][2][4][2], const Unit& u, int wr, int wc, int fr, int fq, PG8_LAS unsigned char* lds, int wid, int lane) const {
;     ...
;                     for (int n = 0; n < 2; ++n) { f32x4 r; const f32x4 a = acc[ai][bj][m][n];
;                         if (MODE == 0) { r[0] = hv[4 * n] + a[0]; r[1] = hv[4 * n + 1] + a[1]; r[2] = hv[4 * n + 2] + a[2]; r[3] = hv[4 * n + 3] + a[3]; }
;                         else { const unsigned e0 = n ? eraw[m][bj].z : eraw[m][bj].x, e1 = n ? eraw[m][bj].w : eraw[m][bj].y;
;                             r[0] = hv[4 * n] + sigmoidf_fast(a[0]) * bf_lo(e0); r[1] = hv[4 * n + 1] + sigmoidf_fast(a[1]) * bf_hi(e0); r[2] = hv[4 * n + 2] + sigmoidf_fast(a[2]) * bf_lo(e1); r[3] = hv[4 * n + 3] + sigmoidf_fast(a[3]) * bf_hi(e1); }
;                         acc[ai][bj][m][n] = r; r8[4 * n] = r[0]; r8[4 * n + 1] = r[1]; r8[4 * n + 2] = r[2]; r8[4 * n + 3] = r[3]; }
;                     *(h16x8*)(H + off + bj * HALF) = __builtin_convertvector(r8, h16x8); }
;                 asm volatile("" : "+v"(acc[ai][0][m][0]), "+v"(acc[ai][0][m][1]), "+v"(acc[ai][1][m][0]), "+v"(acc[ai][1][m][1])); }
	v_lshlrev_b32_e32 v150, 16, v146
	v_and_b32_e32 v151, 0xffff0000, v146
	v_lshlrev_b32_e32 v146, 16, v147
	v_and_b32_e32 v147, 0xffff0000, v147
	v_mul_f32_e32 v12, 0xbfb8aa3b, v12
	v_mul_f32_e32 v13, 0xbfb8aa3b, v13
	v_exp_f32_e32 v14, v14
	v_exp_f32_e32 v15, v15
	v_mul_f32_e32 v8, 0xbfb8aa3b, v8
	v_mul_f32_e32 v9, 0xbfb8aa3b, v9
	v_pk_fma_f32 v[22:23], v[22:23], v[146:147], v[152:153]
	v_lshlrev_b32_e32 v146, 16, v148
	v_and_b32_e32 v147, 0xffff0000, v148
	v_exp_f32_e32 v12, v12
	v_exp_f32_e32 v13, v13
	v_exp_f32_e32 v8, v8
	v_exp_f32_e32 v9, v9
	v_mul_f32_e32 v10, 0xbfb8aa3b, v10
	v_mul_f32_e32 v11, 0xbfb8aa3b, v11
	v_pk_fma_f32 v[16:17], v[16:17], v[146:147], v[156:157]
	v_lshlrev_b32_e32 v146, 16, v149
	v_and_b32_e32 v147, 0xffff0000, v149
	v_exp_f32_e32 v10, v10
	v_exp_f32_e32 v11, v11
	v_pk_fma_f32 v[20:21], v[20:21], v[150:151], v[160:161]
	v_pk_fma_f32 v[18:19], v[18:19], v[146:147], v[154:155]
	v_cvt_pk_f16_f32 v148, v16, v17
	v_cvt_pk_f16_f32 v149, v18, v19
	v_cvt_pk_f16_f32 v147, v22, v23
	v_cvt_pk_f16_f32 v146, v20, v21
	v_add_f32_e32 v14, 1.0, v14
	v_add_f32_e32 v15, 1.0, v15
	global_store_dwordx4 v[158:159], v[146:149], off offset:256 sc1
	v_add_f32_e32 v12, 1.0, v12
	v_add_f32_e32 v13, 1.0, v13
	s_waitcnt vmcnt(9)
	v_cvt_f32_f16_e32 v146, v145
	v_cvt_f32_f16_sdwa v147, v145 dst_sel:DWORD dst_unused:UNUSED_PAD src0_sel:WORD_1
	v_cvt_f32_f16_e32 v148, v144
	v_cvt_f32_f16_sdwa v149, v144 dst_sel:DWORD dst_unused:UNUSED_PAD src0_sel:WORD_1
	v_cvt_f32_f16_e32 v144, v143
	v_cvt_f32_f16_sdwa v145, v143 dst_sel:DWORD dst_unused:UNUSED_PAD src0_sel:WORD_1
	v_rcp_f32_e32 v14, v14
	v_rcp_f32_e32 v15, v15
	v_add_f32_e32 v8, 1.0, v8
	v_add_f32_e32 v9, 1.0, v9
	v_cvt_f32_f16_e32 v150, v142
	v_cvt_f32_f16_sdwa v151, v142 dst_sel:DWORD dst_unused:UNUSED_PAD src0_sel:WORD_1
	v_rcp_f32_e32 v12, v12
	v_rcp_f32_e32 v13, v13
	v_rcp_f32_e32 v8, v8
	v_rcp_f32_e32 v9, v9
	v_add_f32_e32 v10, 1.0, v10
	v_add_f32_e32 v11, 1.0, v11
	v_rcp_f32_e32 v10, v10
	v_rcp_f32_e32 v11, v11
	v_mul_f32_e32 v6, 0xbfb8aa3b, v6
	v_mul_f32_e32 v7, 0xbfb8aa3b, v7
	s_waitcnt vmcnt(8)
	v_lshlrev_b32_e32 v142, 16, v138
	v_and_b32_e32 v143, 0xffff0000, v138
	v_lshlrev_b32_e32 v138, 16, v139
	v_and_b32_e32 v139, 0xffff0000, v139
	v_exp_f32_e32 v6, v6
	v_exp_f32_e32 v7, v7
	v_mul_f32_e32 v0, 0xbfb8aa3b, v0
	v_mul_f32_e32 v1, 0xbfb8aa3b, v1
	v_pk_fma_f32 v[14:15], v[14:15], v[138:139], v[144:145]
	v_lshlrev_b32_e32 v138, 16, v140
	v_and_b32_e32 v139, 0xffff0000, v140
	v_mul_f32_e32 v4, 0xbfb8aa3b, v4
	v_mul_f32_e32 v5, 0xbfb8aa3b, v5
	v_exp_f32_e32 v0, v0
	v_exp_f32_e32 v1, v1
	v_mul_f32_e32 v2, 0xbfb8aa3b, v2
	v_mul_f32_e32 v3, 0xbfb8aa3b, v3
	v_pk_fma_f32 v[12:13], v[12:13], v[142:143], v[150:151]
	v_pk_fma_f32 v[8:9], v[8:9], v[138:139], v[148:149]
	v_lshlrev_b32_e32 v138, 16, v141
	v_and_b32_e32 v139, 0xffff0000, v141
	v_lshlrev_b64 v[142:143], 12, v[188:189]
	v_exp_f32_e32 v4, v4
	v_exp_f32_e32 v5, v5
	v_exp_f32_e32 v2, v2
	v_exp_f32_e32 v3, v3
	v_pk_fma_f32 v[10:11], v[10:11], v[138:139], v[146:147]
	v_lshl_add_u64 v[142:143], s[8:9], 0, v[142:143]
	v_cvt_pk_f16_f32 v141, v10, v11
	v_cvt_pk_f16_f32 v140, v8, v9
	v_cvt_pk_f16_f32 v139, v14, v15
	v_cvt_pk_f16_f32 v138, v12, v13
	v_lshl_add_u64 v[142:143], v[142:143], 0, v[186:187]
	v_add_f32_e32 v6, 1.0, v6
	v_add_f32_e32 v7, 1.0, v7
	global_store_dwordx4 v[142:143], v[138:141], off sc1
	v_rcp_f32_e32 v6, v6
	v_rcp_f32_e32 v7, v7
	s_waitcnt vmcnt(8)
	v_cvt_f32_f16_e32 v138, v137
	v_cvt_f32_f16_sdwa v139, v137 dst_sel:DWORD dst_unused:UNUSED_PAD src0_sel:WORD_1
	v_cvt_f32_f16_e32 v140, v136
	v_cvt_f32_f16_sdwa v141, v136 dst_sel:DWORD dst_unused:UNUSED_PAD src0_sel:WORD_1
	v_cvt_f32_f16_e32 v136, v135
	v_cvt_f32_f16_sdwa v137, v135 dst_sel:DWORD dst_unused:UNUSED_PAD src0_sel:WORD_1
	v_add_f32_e32 v0, 1.0, v0
	v_add_f32_e32 v1, 1.0, v1
	v_add_f32_e32 v4, 1.0, v4
	v_add_f32_e32 v5, 1.0, v5
	v_rcp_f32_e32 v0, v0
	v_rcp_f32_e32 v1, v1
	v_add_f32_e32 v2, 1.0, v2
	v_add_f32_e32 v3, 1.0, v3
	v_cvt_f32_f16_e32 v144, v134
	v_cvt_f32_f16_sdwa v145, v134 dst_sel:DWORD dst_unused:UNUSED_PAD src0_sel:WORD_1
	v_rcp_f32_e32 v4, v4
	v_rcp_f32_e32 v5, v5
	v_rcp_f32_e32 v2, v2
	v_rcp_f32_e32 v3, v3
	s_waitcnt vmcnt(7)
	v_lshlrev_b32_e32 v134, 16, v130
	v_and_b32_e32 v135, 0xffff0000, v130
	v_lshlrev_b32_e32 v130, 16, v131
	v_and_b32_e32 v131, 0xffff0000, v131
	v_pk_fma_f32 v[6:7], v[6:7], v[130:131], v[136:137]
	v_lshlrev_b32_e32 v130, 16, v132
	v_and_b32_e32 v131, 0xffff0000, v132
	v_pk_fma_f32 v[0:1], v[0:1], v[130:131], v[140:141]
	v_lshlrev_b32_e32 v130, 16, v133
	v_and_b32_e32 v131, 0xffff0000, v133
	v_pk_fma_f32 v[4:5], v[4:5], v[134:135], v[144:145]
	v_pk_fma_f32 v[2:3], v[2:3], v[130:131], v[138:139]
	v_cvt_pk_f16_f32 v132, v0, v1
	v_cvt_pk_f16_f32 v133, v2, v3
	v_cvt_pk_f16_f32 v131, v6, v7
	v_cvt_pk_f16_f32 v130, v4, v5
	global_store_dwordx4 v[142:143], v[130:133], off offset:256 sc1
	v_mul_f32_e32 v134, v65, v65
	v_fmac_f32_e32 v134, v64, v64
	v_and_b32_e32 v131, 64, v236
	v_xor_b32_e32 v130, 16, v236
	v_add_u32_e32 v131, 64, v131
	v_cmp_lt_i32_e32 vcc, v130, v131
	v_xor_b32_e32 v132, 32, v236
	v_mul_f32_e32 v133, v57, v57
	v_cndmask_b32_e32 v130, v236, v130, vcc
	v_cmp_lt_i32_e32 vcc, v132, v131
	v_fmac_f32_e32 v133, v56, v56
	v_lshlrev_b32_e32 v130, 2, v130
	v_cndmask_b32_e32 v131, v236, v132, vcc
	v_mul_f32_e32 v132, v55, v55
	v_fmac_f32_e32 v132, v54, v54
	v_add_f32_e32 v132, v132, v133
	v_mul_f32_e32 v133, v63, v63
	v_fmac_f32_e32 v133, v62, v62
	v_add_f32_e32 v133, v133, v134
	v_add_f32_e32 v132, v132, v133
	v_mul_f32_e32 v133, v71, v71
	v_mul_f32_e32 v134, v73, v73
	v_fmac_f32_e32 v133, v70, v70
	v_fmac_f32_e32 v134, v72, v72
	v_add_f32_e32 v133, v133, v134
	v_add_f32_e32 v132, v133, v132
	v_mul_f32_e32 v133, v79, v79
	v_mul_f32_e32 v134, v81, v81
	v_fmac_f32_e32 v133, v78, v78
	v_fmac_f32_e32 v134, v80, v80
	v_add_f32_e32 v133, v133, v134
	v_add_f32_e32 v132, v133, v132
	ds_bpermute_b32 v133, v130, v132
	v_lshlrev_b32_e32 v131, 2, v131
	v_and_b32_e32 v32, 63, v215
	s_waitcnt lgkmcnt(0)
	v_add_f32_e32 v132, v132, v133
	ds_bpermute_b32 v133, v131, v132
	s_lshl_b32 s2, s2, 2
	v_cmp_gt_u32_e32 vcc, 16, v32
	s_add_i32 s2, s2, 0
	s_and_saveexec_b64 s[4:5], vcc
	v_readlane_b32 s36, v255, 23
	v_readlane_b32 s37, v255, 24
	s_cbranch_execz .LBB0_1296
	s_lshl_b32 s8, s19, 10
	s_add_i32 s8, s2, s8
	v_lshl_add_u32 v134, v216, 4, s8
	s_waitcnt lgkmcnt(0)
	v_add_f32_e32 v132, v132, v133
	ds_write_b32 v134, v132

;     __device__ __forceinline__ void fused(f32x4 (&acc)[2][2][4][2], const Unit& u, int wr, int wc, int fr, int fq, PG8_LAS unsigned char* lds, int wid, int lane) const {
;     ...
;                     for (int n = 0; n < 2; ++n) { const f32x4 o = acc[ai][bj][m][n] * rs * gv[bj][n];
;                         if (final_) *(f32x4*)(OUT + off + bj * HALF + n * 4) = o;
.LBB0_1331:
	s_andn2_b64 vcc, exec, s[4:5]
	v_lshl_add_u64 v[152:153], v[152:153], 2, s[86:87]
	s_cbranch_vccnz .LBB0_1333
	global_store_dwordx4 v[152:153], v[54:57], off sc1

;     __device__ __forceinline__ void fused(f32x4 (&acc)[2][2][4][2], const Unit& u, int wr, int wc, int fr, int fq, PG8_LAS unsigned char* lds, int wid, int lane) const {
;     ...
;                     for (int n = 0; n < 2; ++n) { const f32x4 o = acc[ai][bj][m][n] * rs * gv[bj][n];
;                         if (final_) *(f32x4*)(OUT + off + bj * HALF + n * 4) = o;
.LBB0_1335:
	s_andn2_b64 vcc, exec, s[4:5]
	s_cbranch_vccnz .LBB0_1337
	global_store_dwordx4 v[152:153], v[54:57], off offset:16 sc1

;     __device__ __forceinline__ void fused(f32x4 (&acc)[2][2][4][2], const Unit& u, int wr, int wc, int fr, int fq, PG8_LAS unsigned char* lds, int wid, int lane) const {
;     ...
;                     for (int n = 0; n < 2; ++n) { const f32x4 o = acc[ai][bj][m][n] * rs * gv[bj][n];
;                         if (final_) *(f32x4*)(OUT + off + bj * HALF + n * 4) = o;
.LBB0_1339:
	s_andn2_b64 vcc, exec, s[4:5]
	s_cbranch_vccnz .LBB0_1341
	global_store_dwordx4 v[152:153], v[54:57], off offset:512 sc1

;     __device__ __forceinline__ void fused(f32x4 (&acc)[2][2][4][2], const Unit& u, int wr, int wc, int fr, int fq, PG8_LAS unsigned char* lds, int wid, int lane) const {
;     ...
;                     for (int n = 0; n < 2; ++n) { const f32x4 o = acc[ai][bj][m][n] * rs * gv[bj][n];
;                         if (final_) *(f32x4*)(OUT + off + bj * HALF + n * 4) = o;
.LBB0_1343:
	s_andn2_b64 vcc, exec, s[4:5]
	s_cbranch_vccnz .LBB0_1345
	global_store_dwordx4 v[152:153], v[54:57], off offset:528 sc1

;     __device__ __forceinline__ void fused(f32x4 (&acc)[2][2][4][2], const Unit& u, int wr, int wc, int fr, int fq, PG8_LAS unsigned char* lds, int wid, int lane) const {
;     ...
;                     for (int n = 0; n < 2; ++n) { const f32x4 o = acc[ai][bj][m][n] * rs * gv[bj][n];
;                         if (final_) *(f32x4*)(OUT + off + bj * HALF + n * 4) = o;
.LBB0_1347:
	s_andn2_b64 vcc, exec, s[4:5]
	v_lshl_add_u64 v[70:71], v[70:71], 2, s[86:87]
	s_cbranch_vccnz .LBB0_1349
	global_store_dwordx4 v[70:71], v[54:57], off sc1

;     __device__ __forceinline__ void fused(f32x4 (&acc)[2][2][4][2], const Unit& u, int wr, int wc, int fr, int fq, PG8_LAS unsigned char* lds, int wid, int lane) const {
;     ...
;                     for (int n = 0; n < 2; ++n) { const f32x4 o = acc[ai][bj][m][n] * rs * gv[bj][n];
;                         if (final_) *(f32x4*)(OUT + off + bj * HALF + n * 4) = o;
.LBB0_1351:
	s_andn2_b64 vcc, exec, s[4:5]
	s_cbranch_vccnz .LBB0_1353
	global_store_dwordx4 v[70:71], v[54:57], off offset:16 sc1

;     __device__ __forceinline__ void fused(f32x4 (&acc)[2][2][4][2], const Unit& u, int wr, int wc, int fr, int fq, PG8_LAS unsigned char* lds, int wid, int lane) const {
;     ...
;                     for (int n = 0; n < 2; ++n) { const f32x4 o = acc[ai][bj][m][n] * rs * gv[bj][n];
;                         if (final_) *(f32x4*)(OUT + off + bj * HALF + n * 4) = o;
.LBB0_1355:
	s_andn2_b64 vcc, exec, s[4:5]
	s_cbranch_vccnz .LBB0_1357
	global_store_dwordx4 v[70:71], v[54:57], off offset:512 sc1

;     __device__ __forceinline__ void fused(f32x4 (&acc)[2][2][4][2], const Unit& u, int wr, int wc, int fr, int fq, PG8_LAS unsigned char* lds, int wid, int lane) const {
;     ...
;                     for (int n = 0; n < 2; ++n) { const f32x4 o = acc[ai][bj][m][n] * rs * gv[bj][n];
;                         if (final_) *(f32x4*)(OUT + off + bj * HALF + n * 4) = o;
.LBB0_1359:
	s_andn2_b64 vcc, exec, s[4:5]
	s_cbranch_vccnz .LBB0_1361
	global_store_dwordx4 v[70:71], v[54:57], off offset:528 sc1

;     __device__ __forceinline__ void fused(f32x4 (&acc)[2][2][4][2], const Unit& u, int wr, int wc, int fr, int fq, PG8_LAS unsigned char* lds, int wid, int lane) const {
;     ...
;                     for (int n = 0; n < 2; ++n) { const f32x4 o = acc[ai][bj][m][n] * rs * gv[bj][n];
;                         if (final_) *(f32x4*)(OUT + off + bj * HALF + n * 4) = o;
.LBB0_1407:
	s_andn2_b64 vcc, exec, s[4:5]
	s_cbranch_vccnz .LBB0_1409
	global_store_dwordx4 v[70:71], v[50:53], off offset:528 sc1

;     __device__ __forceinline__ void fused(f32x4 (&acc)[2][2][4][2], const Unit& u, int wr, int wc, int fr, int fq, PG8_LAS unsigned char* lds, int wid, int lane) const {
;     ...
;                     for (int n = 0; n < 2; ++n) { const f32x4 o = acc[ai][bj][m][n] * rs * gv[bj][n];
;                         if (final_) *(f32x4*)(OUT + off + bj * HALF + n * 4) = o;
.LBB0_1411:
	s_andn2_b64 vcc, exec, s[4:5]
	v_lshl_add_u64 v[54:55], v[54:55], 2, s[86:87]
	s_cbranch_vccnz .LBB0_1413
	global_store_dwordx4 v[54:55], v[46:49], off sc1

;     __device__ __forceinline__ void fused(f32x4 (&acc)[2][2][4][2], const Unit& u, int wr, int wc, int fr, int fq, PG8_LAS unsigned char* lds, int wid, int lane) const {
;     ...
;                     for (int n = 0; n < 2; ++n) { const f32x4 o = acc[ai][bj][m][n] * rs * gv[bj][n];
;                         if (final_) *(f32x4*)(OUT + off + bj * HALF + n * 4) = o;
.LBB0_1415:
	s_andn2_b64 vcc, exec, s[4:5]
	s_cbranch_vccnz .LBB0_1417
	global_store_dwordx4 v[54:55], v[42:45], off offset:16 sc1

;     __device__ __forceinline__ void fused(f32x4 (&acc)[2][2][4][2], const Unit& u, int wr, int wc, int fr, int fq, PG8_LAS unsigned char* lds, int wid, int lane) const {
;     ...
;                     for (int n = 0; n < 2; ++n) { const f32x4 o = acc[ai][bj][m][n] * rs * gv[bj][n];
;                         if (final_) *(f32x4*)(OUT + off + bj * HALF + n * 4) = o;
.LBB0_1419:
	s_andn2_b64 vcc, exec, s[4:5]
	s_cbranch_vccnz .LBB0_1421
	global_store_dwordx4 v[54:55], v[38:41], off offset:512 sc1

;     __device__ __forceinline__ void fused(f32x4 (&acc)[2][2][4][2], const Unit& u, int wr, int wc, int fr, int fq, PG8_LAS unsigned char* lds, int wid, int lane) const {
;     ...
;                     for (int n = 0; n < 2; ++n) { const f32x4 o = acc[ai][bj][m][n] * rs * gv[bj][n];
;                         if (final_) *(f32x4*)(OUT + off + bj * HALF + n * 4) = o;
.LBB0_1423:
	s_andn2_b64 vcc, exec, s[4:5]
	s_cbranch_vccnz .LBB0_1425
	global_store_dwordx4 v[54:55], v[34:37], off offset:528 sc1

;     __device__ __forceinline__ void fused(f32x4 (&acc)[2][2][4][2], const Unit& u, int wr, int wc, int fr, int fq, PG8_LAS unsigned char* lds, int wid, int lane) const {
;     ...
;                     for (int n = 0; n < 2; ++n) { const f32x4 o = acc[ai][bj][m][n] * rs * gv[bj][n];
;                         if (final_) *(f32x4*)(OUT + off + bj * HALF + n * 4) = o;
.LBB0_1427:
	s_andn2_b64 vcc, exec, s[4:5]
	v_lshl_add_u64 v[38:39], v[38:39], 2, s[86:87]
	s_cbranch_vccnz .LBB0_1429
	global_store_dwordx4 v[38:39], v[28:31], off sc1

;     __device__ __forceinline__ void fused(f32x4 (&acc)[2][2][4][2], const Unit& u, int wr, int wc, int fr, int fq, PG8_LAS unsigned char* lds, int wid, int lane) const {
;     ...
;                     for (int n = 0; n < 2; ++n) { const f32x4 o = acc[ai][bj][m][n] * rs * gv[bj][n];
;                         if (final_) *(f32x4*)(OUT + off + bj * HALF + n * 4) = o;
.LBB0_1431:
	s_andn2_b64 vcc, exec, s[4:5]
	s_cbranch_vccnz .LBB0_1433
	global_store_dwordx4 v[38:39], v[24:27], off offset:16 sc1

;     __device__ __forceinline__ void fused(f32x4 (&acc)[2][2][4][2], const Unit& u, int wr, int wc, int fr, int fq, PG8_LAS unsigned char* lds, int wid, int lane) const {
;     ...
;                     for (int n = 0; n < 2; ++n) { const f32x4 o = acc[ai][bj][m][n] * rs * gv[bj][n];
;                         if (final_) *(f32x4*)(OUT + off + bj * HALF + n * 4) = o;
.LBB0_1435:
	s_andn2_b64 vcc, exec, s[4:5]
	s_cbranch_vccnz .LBB0_1437
	global_store_dwordx4 v[38:39], v[20:23], off offset:512 sc1

;     __device__ __forceinline__ void fused(f32x4 (&acc)[2][2][4][2], const Unit& u, int wr, int wc, int fr, int fq, PG8_LAS unsigned char* lds, int wid, int lane) const {
;     ...
;                     for (int n = 0; n < 2; ++n) { const f32x4 o = acc[ai][bj][m][n] * rs * gv[bj][n];
;                         if (final_) *(f32x4*)(OUT + off + bj * HALF + n * 4) = o;
.LBB0_1439:
	s_andn2_b64 vcc, exec, s[4:5]
	s_cbranch_vccnz .LBB0_1441
	global_store_dwordx4 v[38:39], v[16:19], off offset:528 sc1

;     __device__ __forceinline__ void fused(f32x4 (&acc)[2][2][4][2], const Unit& u, int wr, int wc, int fr, int fq, PG8_LAS unsigned char* lds, int wid, int lane) const {
;     ...
;                     for (int n = 0; n < 2; ++n) { const f32x4 o = acc[ai][bj][m][n] * rs * gv[bj][n];
;                         if (final_) *(f32x4*)(OUT + off + bj * HALF + n * 4) = o;
.LBB0_1443:
	s_andn2_b64 vcc, exec, s[4:5]
	v_lshl_add_u64 v[20:21], v[20:21], 2, s[86:87]
	s_cbranch_vccnz .LBB0_1445
	global_store_dwordx4 v[20:21], v[12:15], off sc1

;     __device__ __forceinline__ void fused(f32x4 (&acc)[2][2][4][2], const Unit& u, int wr, int wc, int fr, int fq, PG8_LAS unsigned char* lds, int wid, int lane) const {
;     ...
;                     for (int n = 0; n < 2; ++n) { const f32x4 o = acc[ai][bj][m][n] * rs * gv[bj][n];
;                         if (final_) *(f32x4*)(OUT + off + bj * HALF + n * 4) = o;
.LBB0_1447:
	s_andn2_b64 vcc, exec, s[4:5]
	s_cbranch_vccnz .LBB0_1449
	global_store_dwordx4 v[20:21], v[8:11], off offset:16 sc1

;     __device__ __forceinline__ void fused(f32x4 (&acc)[2][2][4][2], const Unit& u, int wr, int wc, int fr, int fq, PG8_LAS unsigned char* lds, int wid, int lane) const {
;     ...
;                     for (int n = 0; n < 2; ++n) { const f32x4 o = acc[ai][bj][m][n] * rs * gv[bj][n];
;                         if (final_) *(f32x4*)(OUT + off + bj * HALF + n * 4) = o;
.LBB0_1451:
	s_andn2_b64 vcc, exec, s[4:5]
	s_cbranch_vccnz .LBB0_1453
	global_store_dwordx4 v[20:21], v[4:7], off offset:512 sc1

;     __device__ __forceinline__ void fused(f32x4 (&acc)[2][2][4][2], const Unit& u, int wr, int wc, int fr, int fq, PG8_LAS unsigned char* lds, int wid, int lane) const {
;     ...
;                     for (int n = 0; n < 2; ++n) { const f32x4 o = acc[ai][bj][m][n] * rs * gv[bj][n];
;                         if (final_) *(f32x4*)(OUT + off + bj * HALF + n * 4) = o;
.LBB0_1455:
	s_andn2_b64 vcc, exec, s[4:5]
	s_cbranch_vccnz .LBB0_1457
	global_store_dwordx4 v[20:21], v[0:3], off offset:528 sc1
